# all loads of in-kernel-produced data in the layer phases are agent-scope (sc1); grid-barrier followers skip the L1 invalidate after the prologue barriers
# speedup vs baseline: 1.0037x; 1.0037x over previous
.LBB0_221:
	s_cmpk_gt_u32 s67, 0xff
	s_cbranch_scc0 .LBB0_235
	s_cmpk_gt_u32 s67, 0x1ff
	s_cbranch_scc0 .LBB0_230
	s_cmpk_gt_u32 s67, 0x2ff
	s_cbranch_scc0 .LBB0_225
	s_and_b32 s9, s67, 3
	s_lshl_b32 s8, s9, 7
	s_lshl_b32 s10, s9, 8
	s_add_u32 s70, s17, s10
	s_addc_u32 s71, s18, 0
	s_or_b32 s30, s9, s13
	s_lshl_b32 s9, s67, 5
	s_and_b32 s9, s9, 0x7fffff80
	s_lshl_b64 s[10:11], s[30:31], 15
	s_add_i32 s30, s9, 0xffffa000
	s_lshl_b64 s[68:69], s[30:31], 10
	s_add_u32 s68, s70, s68
	s_addc_u32 s69, s71, s69
	v_lshl_add_u64 v[0:1], s[68:69], 0, v[100:101]
	v_mov_b32_e32 v147, v117
	v_readfirstlane_b32 s9, v99
	v_add_u32_e32 v2, 0x400, v99
	v_lshl_add_u64 v[16:17], v[0:1], 0, v[146:147]
	s_mov_b32 m0, s9
	v_readfirstlane_b32 s9, v2
	global_load_lds_dwordx4 v[16:17], off sc1
	v_lshl_add_u64 v[0:1], v[16:17], 0, s[28:29]
	s_mov_b32 m0, s9
	v_add_u32_e32 v2, 0x2400, v99
	global_load_lds_dwordx4 v[0:1], off sc1
	v_add_u32_e32 v0, 0x2000, v99
	v_lshl_add_u64 v[18:19], v[134:135], 0, s[10:11]
	v_readfirstlane_b32 s9, v0
	s_mov_b32 m0, s9
	s_mov_b64 s[10:11], 0x400
	v_readfirstlane_b32 s9, v2
	v_add_u32_e32 v2, 0x4000, v99
	global_load_lds_dwordx4 v[18:19], off sc1
	v_lshl_add_u64 v[0:1], v[18:19], 0, s[10:11]
	s_mov_b32 m0, s9
	v_readfirstlane_b32 s9, v2
	v_add_u32_e32 v2, 0x4400, v99
	global_load_lds_dwordx4 v[0:1], off sc1
	v_lshl_add_u64 v[0:1], v[16:17], 0, 64
	s_mov_b32 m0, s9
	s_mov_b64 s[10:11], 0x4040
	v_readfirstlane_b32 s9, v2
	v_add_u32_e32 v2, 0x6000, v99
	global_load_lds_dwordx4 v[0:1], off sc1
	v_lshl_add_u64 v[0:1], v[16:17], 0, s[10:11]
	s_mov_b32 m0, s9
	v_readfirstlane_b32 s9, v2
	v_add_u32_e32 v2, 0x6400, v99
	global_load_lds_dwordx4 v[0:1], off sc1
	v_lshl_add_u64 v[0:1], v[18:19], 0, s[44:45]
	s_mov_b32 m0, s9
	s_mov_b64 s[10:11], 0x2400
	v_readfirstlane_b32 s9, v2
	v_add_u32_e32 v2, 0x8000, v99
	global_load_lds_dwordx4 v[0:1], off sc1
	v_lshl_add_u64 v[0:1], v[18:19], 0, s[10:11]
	s_mov_b32 m0, s9
	v_readfirstlane_b32 s9, v2
	v_add_u32_e32 v2, 0x8400, v99
	global_load_lds_dwordx4 v[0:1], off sc1
	v_lshl_add_u64 v[0:1], v[16:17], 0, s[24:25]
	s_mov_b32 m0, s9
	s_mov_b64 s[10:11], 0x4080
	v_readfirstlane_b32 s9, v2
	v_add_u32_e32 v2, 0xa000, v99
	global_load_lds_dwordx4 v[0:1], off sc1
	v_lshl_add_u64 v[0:1], v[16:17], 0, s[10:11]
	s_mov_b32 m0, s9
	v_readfirstlane_b32 s9, v2
	v_add_u32_e32 v2, 0xa400, v99
	global_load_lds_dwordx4 v[0:1], off sc1
	v_lshl_add_u64 v[0:1], v[18:19], 0, s[28:29]
	s_mov_b32 m0, s9
	s_mov_b64 s[10:11], 0x4400
	v_readfirstlane_b32 s9, v2
	global_load_lds_dwordx4 v[0:1], off sc1
	v_lshl_add_u64 v[0:1], v[18:19], 0, s[10:11]
	s_mov_b32 m0, s9
	v_add_u32_e32 v116, v121, v107
	global_load_lds_dwordx4 v[0:1], off sc1
	s_waitcnt vmcnt(8)
	v_add_u32_e32 v147, v119, v107
	v_add_u32_e32 v148, v121, v103
	v_add_u32_e32 v149, v119, v103
	s_waitcnt lgkmcnt(0)
	s_barrier
	ds_read_b128 v[0:3], v116
	ds_read_b128 v[4:7], v116 offset:2048
	ds_read_b128 v[8:11], v147 offset:8192
	ds_read_b128 v[12:15], v147 offset:10240
	ds_read_b128 v[64:67], v148
	ds_read_b128 v[68:71], v148 offset:2048
	ds_read_b128 v[72:75], v149 offset:8192
	ds_read_b128 v[76:79], v149 offset:10240
	s_mov_b64 s[10:11], 0x6400
	v_lshl_add_u64 v[20:21], v[18:19], 0, s[10:11]
	s_mov_b64 s[10:11], 0x6000
	v_lshl_add_u64 v[18:19], v[18:19], 0, s[10:11]
	s_mov_b64 s[10:11], 0x40c0
	v_add_u32_e32 v24, 0xc000, v99
	v_lshl_add_u64 v[22:23], v[16:17], 0, s[10:11]
	s_mov_b64 s[10:11], 0xc0
	v_readfirstlane_b32 s9, v24
	v_lshl_add_u64 v[16:17], v[16:17], 0, s[10:11]
	s_mov_b32 m0, s9
	s_nop 0
	global_load_lds_dwordx4 v[16:17], off sc1
	v_add_u32_e32 v16, 0xc400, v99
	s_nop 0
	v_readfirstlane_b32 s9, v16
	v_add_u32_e32 v16, 0xe000, v99
	s_mov_b32 m0, s9
	v_readfirstlane_b32 s9, v16
	v_add_u32_e32 v16, 0xe400, v99
	global_load_lds_dwordx4 v[22:23], off sc1
	s_mov_b32 m0, s9
	v_readfirstlane_b32 s9, v16
	global_load_lds_dwordx4 v[18:19], off sc1
	s_mov_b32 m0, s9
	s_nop 0
	global_load_lds_dwordx4 v[20:21], off sc1
	s_waitcnt lgkmcnt(0)
	v_mfma_f32_32x32x16_bf16 v[48:63], v[0:3], v[8:11], 0
	s_waitcnt vmcnt(8)
	s_waitcnt lgkmcnt(0)
	s_barrier
	s_waitcnt vmcnt(0)
	v_mfma_f32_32x32x16_bf16 v[32:47], v[0:3], v[12:15], 0
	v_mfma_f32_32x32x16_bf16 v[16:31], v[4:7], v[8:11], 0
	v_mfma_f32_32x32x16_bf16 v[0:15], v[4:7], v[12:15], 0
	v_mfma_f32_32x32x16_bf16 v[48:63], v[64:67], v[72:75], v[48:63]
	v_mfma_f32_32x32x16_bf16 v[32:47], v[64:67], v[76:79], v[32:47]
	v_mfma_f32_32x32x16_bf16 v[16:31], v[68:71], v[72:75], v[16:31]
	v_mfma_f32_32x32x16_bf16 v[0:15], v[68:71], v[76:79], v[0:15]
	ds_read_b128 v[64:67], v116 offset:16384
	ds_read_b128 v[68:71], v116 offset:18432
	ds_read_b128 v[72:75], v147 offset:24576
	ds_read_b128 v[76:79], v147 offset:26624
	ds_read_b128 v[80:83], v148 offset:16384
	ds_read_b128 v[84:87], v148 offset:18432
	ds_read_b128 v[88:91], v149 offset:24576
	ds_read_b128 v[92:95], v149 offset:26624
	s_waitcnt lgkmcnt(5)
	v_mfma_f32_32x32x16_bf16 v[48:63], v[64:67], v[72:75], v[48:63]
	s_waitcnt vmcnt(4)
	s_waitcnt lgkmcnt(0)
	s_barrier
	s_waitcnt lgkmcnt(4)
	v_mfma_f32_32x32x16_bf16 v[32:47], v[64:67], v[76:79], v[32:47]
	v_mfma_f32_32x32x16_bf16 v[16:31], v[68:71], v[72:75], v[16:31]
	v_mfma_f32_32x32x16_bf16 v[0:15], v[68:71], v[76:79], v[0:15]
	s_waitcnt lgkmcnt(1)
	v_mfma_f32_32x32x16_bf16 v[48:63], v[80:83], v[88:91], v[48:63]
	s_waitcnt lgkmcnt(0)
	v_mfma_f32_32x32x16_bf16 v[32:47], v[80:83], v[92:95], v[32:47]
	v_mfma_f32_32x32x16_bf16 v[16:31], v[84:87], v[88:91], v[16:31]
	v_mfma_f32_32x32x16_bf16 v[0:15], v[84:87], v[92:95], v[0:15]
	ds_read_b128 v[64:67], v116 offset:32768
	ds_read_b128 v[68:71], v116 offset:34816
	ds_read_b128 v[72:75], v147 offset:40960
	ds_read_b128 v[76:79], v147 offset:43008
	ds_read_b128 v[80:83], v148 offset:32768
	ds_read_b128 v[84:87], v148 offset:34816
	ds_read_b128 v[88:91], v149 offset:40960
	ds_read_b128 v[92:95], v149 offset:43008
	s_waitcnt lgkmcnt(5)
	v_mfma_f32_32x32x16_bf16 v[48:63], v[64:67], v[72:75], v[48:63]
	s_waitcnt vmcnt(0)
	s_waitcnt lgkmcnt(0)
	s_barrier
	s_waitcnt lgkmcnt(4)
	v_mfma_f32_32x32x16_bf16 v[32:47], v[64:67], v[76:79], v[32:47]
	v_mfma_f32_32x32x16_bf16 v[16:31], v[68:71], v[72:75], v[16:31]
	v_mfma_f32_32x32x16_bf16 v[0:15], v[68:71], v[76:79], v[0:15]
	s_waitcnt lgkmcnt(1)
	v_mfma_f32_32x32x16_bf16 v[48:63], v[80:83], v[88:91], v[48:63]
	s_waitcnt lgkmcnt(0)
	v_mfma_f32_32x32x16_bf16 v[32:47], v[80:83], v[92:95], v[32:47]
	v_mfma_f32_32x32x16_bf16 v[16:31], v[84:87], v[88:91], v[16:31]
	v_mfma_f32_32x32x16_bf16 v[0:15], v[84:87], v[92:95], v[0:15]
	ds_read_b128 v[64:67], v116 offset:49152
	ds_read_b128 v[68:71], v116 offset:51200
	ds_read_b128 v[72:75], v147 offset:57344
	ds_read_b128 v[76:79], v147 offset:59392
	ds_read_b128 v[80:83], v148 offset:49152
	ds_read_b128 v[84:87], v148 offset:51200
	ds_read_b128 v[88:91], v149 offset:57344
	ds_read_b128 v[92:95], v149 offset:59392
	s_or_b32 s9, s8, s14
	v_readlane_b32 s48, v255, 16
	v_or_b32_e32 v116, s9, v125
	v_readlane_b32 s56, v255, 24
	v_readlane_b32 s57, v255, 25
	s_waitcnt lgkmcnt(5)
	v_mfma_f32_32x32x16_bf16 v[48:63], v[64:67], v[72:75], v[48:63]
	s_waitcnt lgkmcnt(0)
	s_barrier
	s_or_b32 s8, s8, 0x600
	v_readlane_b32 s49, v255, 17
	v_readlane_b32 s50, v255, 18
	v_readlane_b32 s51, v255, 19
	v_readlane_b32 s52, v255, 20
	s_waitcnt lgkmcnt(4)
	v_mfma_f32_32x32x16_bf16 v[32:47], v[64:67], v[76:79], v[32:47]
	v_lshl_add_u64 v[64:65], v[116:117], 2, s[56:57]
	v_add_u32_e32 v66, s9, v125
	v_mov_b32_e32 v67, v117
	v_lshl_add_u64 v[66:67], v[66:67], 2, s[56:57]
	v_readlane_b32 s53, v255, 21
	v_readlane_b32 s54, v255, 22
	v_readlane_b32 s55, v255, 23
	v_mfma_f32_32x32x16_bf16 v[16:31], v[68:71], v[72:75], v[16:31]
	v_readlane_b32 s58, v255, 26
	v_readlane_b32 s59, v255, 27
	v_readlane_b32 s60, v255, 28
	v_readlane_b32 s61, v255, 29
	v_readlane_b32 s62, v255, 30
	v_readlane_b32 s63, v255, 31
	v_mfma_f32_32x32x16_bf16 v[0:15], v[68:71], v[76:79], v[0:15]
	global_load_dword v70, v[64:65], off sc1
	global_load_dword v71, v[66:67], off offset:128 sc1
	v_add_u32_e32 v64, s30, v97
	v_ashrrev_i32_e32 v66, 7, v64
	v_or_b32_e32 v64, s8, v125
	v_ashrrev_i32_e32 v67, 31, v66
	v_or_b32_e32 v68, s8, v156
	v_lshlrev_b32_e32 v64, 8, v64
	s_waitcnt lgkmcnt(1)
	v_mfma_f32_32x32x16_bf16 v[48:63], v[80:83], v[88:91], v[48:63]
	v_lshlrev_b64 v[66:67], 19, v[66:67]
	v_lshlrev_b32_e32 v68, 8, v68
	v_and_b32_e32 v116, 0x7c000, v64
	v_lshl_add_u64 v[66:67], v[136:137], 0, v[66:67]
	v_mov_b32_e32 v65, v117
	v_and_b32_e32 v64, 0x7e000, v68
	v_lshl_add_u64 v[68:69], v[66:67], 0, v[116:117]
	s_waitcnt lgkmcnt(0)
	v_mfma_f32_32x32x16_bf16 v[32:47], v[80:83], v[92:95], v[32:47]
	v_lshlrev_b32_e32 v116, 1, v98
	v_lshl_add_u64 v[64:65], v[66:67], 0, v[64:65]
	v_lshl_add_u64 v[66:67], v[68:69], 0, v[116:117]
	v_lshl_add_u64 v[64:65], v[64:65], 0, v[116:117]
	s_mov_b64 s[8:9], 0
	s_waitcnt vmcnt(1)
	v_mul_f32_e32 v48, v48, v70
	s_waitcnt vmcnt(0)
	s_nop 3
	v_mul_f32_e32 v32, v32, v71
	v_mul_f32_e32 v49, v49, v70
	v_mul_f32_e32 v33, v33, v71
	v_mul_f32_e32 v50, v50, v70
	v_mul_f32_e32 v34, v34, v71
	v_mul_f32_e32 v51, v51, v70
	v_mul_f32_e32 v35, v35, v71
	v_mul_f32_e32 v52, v52, v70
	v_mul_f32_e32 v36, v36, v71
	v_mul_f32_e32 v53, v53, v70
	v_mul_f32_e32 v37, v37, v71
	v_mul_f32_e32 v54, v54, v70
	v_mul_f32_e32 v38, v38, v71
	v_mul_f32_e32 v55, v55, v70
	v_mul_f32_e32 v39, v39, v71
	v_mul_f32_e32 v56, v56, v70
	v_cvt_pk_bf16_f32 v48, v48, s0
	v_cvt_pk_bf16_f32 v32, v32, s0
	v_cvt_pk_bf16_f32 v49, v49, s0
	v_cvt_pk_bf16_f32 v33, v33, s0
	v_cvt_pk_bf16_f32 v50, v50, s0
	v_cvt_pk_bf16_f32 v34, v34, s0
	v_cvt_pk_bf16_f32 v51, v51, s0
	v_cvt_pk_bf16_f32 v35, v35, s0
	v_cvt_pk_bf16_f32 v52, v52, s0
	v_cvt_pk_bf16_f32 v36, v36, s0
	v_cvt_pk_bf16_f32 v53, v53, s0
	v_cvt_pk_bf16_f32 v37, v37, s0
	v_cvt_pk_bf16_f32 v54, v54, s0
	v_cvt_pk_bf16_f32 v38, v38, s0
	v_cvt_pk_bf16_f32 v55, v55, s0
	v_cvt_pk_bf16_f32 v39, v39, s0
	v_cvt_pk_bf16_f32 v56, v56, s0
	global_store_short v[66:67], v48, off
	global_store_short v[64:65], v32, off
	global_store_short v[66:67], v49, off offset:64
	global_store_short v[64:65], v33, off offset:64
	global_store_short v[66:67], v50, off offset:128
	global_store_short v[64:65], v34, off offset:128
	global_store_short v[66:67], v51, off offset:192
	global_store_short v[64:65], v35, off offset:192
	global_store_short v[66:67], v52, off offset:512
	global_store_short v[64:65], v36, off offset:512
	global_store_short v[66:67], v53, off offset:576
	global_store_short v[64:65], v37, off offset:576
	global_store_short v[66:67], v54, off offset:640
	global_store_short v[64:65], v38, off offset:640
	global_store_short v[66:67], v55, off offset:704
	global_store_short v[64:65], v39, off offset:704
	global_store_short v[66:67], v56, off offset:1024
	v_mul_f32_e32 v32, v40, v71
	v_cvt_pk_bf16_f32 v32, v32, s0
	global_store_short v[64:65], v32, off offset:1024
	v_mul_f32_e32 v32, v57, v70
	v_cvt_pk_bf16_f32 v32, v32, s0
	global_store_short v[66:67], v32, off offset:1088
	v_mul_f32_e32 v32, v41, v71
	v_cvt_pk_bf16_f32 v32, v32, s0
	global_store_short v[64:65], v32, off offset:1088
	v_mul_f32_e32 v32, v58, v70
	v_cvt_pk_bf16_f32 v32, v32, s0
	global_store_short v[66:67], v32, off offset:1152
	v_mul_f32_e32 v32, v42, v71
	v_cvt_pk_bf16_f32 v32, v32, s0
	global_store_short v[64:65], v32, off offset:1152
	v_mul_f32_e32 v32, v59, v70
	v_cvt_pk_bf16_f32 v32, v32, s0
	global_store_short v[66:67], v32, off offset:1216
	v_mul_f32_e32 v32, v43, v71
	v_cvt_pk_bf16_f32 v32, v32, s0
	global_store_short v[64:65], v32, off offset:1216
	v_mul_f32_e32 v32, v60, v70
	v_cvt_pk_bf16_f32 v32, v32, s0
	global_store_short v[66:67], v32, off offset:1536
	v_mul_f32_e32 v32, v44, v71
	v_cvt_pk_bf16_f32 v32, v32, s0
	global_store_short v[64:65], v32, off offset:1536
	v_mul_f32_e32 v32, v61, v70
	v_cvt_pk_bf16_f32 v32, v32, s0
	v_mfma_f32_32x32x16_bf16 v[16:31], v[84:87], v[88:91], v[16:31]
	global_store_short v[66:67], v32, off offset:1600
	v_mul_f32_e32 v32, v45, v71
	v_cvt_pk_bf16_f32 v32, v32, s0
	global_store_short v[64:65], v32, off offset:1600
	v_mul_f32_e32 v32, v62, v70
	v_cvt_pk_bf16_f32 v32, v32, s0
	global_store_short v[66:67], v32, off offset:1664
	v_mfma_f32_32x32x16_bf16 v[0:15], v[84:87], v[92:95], v[0:15]
	v_mul_f32_e32 v32, v46, v71
	v_cvt_pk_bf16_f32 v32, v32, s0
	global_store_short v[64:65], v32, off offset:1664
	v_mul_f32_e32 v32, v63, v70
	v_cvt_pk_bf16_f32 v32, v32, s0
	global_store_short v[66:67], v32, off offset:1728
	v_mul_f32_e32 v32, v47, v71
	v_mul_f32_e32 v16, v16, v70
	s_nop 3
	v_mul_f32_e32 v0, v0, v71
	v_cvt_pk_bf16_f32 v32, v32, s0
	v_cvt_pk_bf16_f32 v16, v16, s0
	v_cvt_pk_bf16_f32 v0, v0, s0
	global_store_short v[64:65], v32, off offset:1728
	global_store_short v[66:67], v16, off offset:2048
	global_store_short v[64:65], v0, off offset:2048
	v_mul_f32_e32 v0, v17, v70
	v_cvt_pk_bf16_f32 v0, v0, s0
	global_store_short v[66:67], v0, off offset:2112
	v_mul_f32_e32 v0, v1, v71
	v_cvt_pk_bf16_f32 v0, v0, s0
	global_store_short v[64:65], v0, off offset:2112
	v_mul_f32_e32 v0, v18, v70
	v_cvt_pk_bf16_f32 v0, v0, s0
	global_store_short v[66:67], v0, off offset:2176
	v_mul_f32_e32 v0, v2, v71
	v_cvt_pk_bf16_f32 v0, v0, s0
	global_store_short v[64:65], v0, off offset:2176
	v_mul_f32_e32 v0, v19, v70
	v_cvt_pk_bf16_f32 v0, v0, s0
	global_store_short v[66:67], v0, off offset:2240
	v_mul_f32_e32 v0, v3, v71
	v_cvt_pk_bf16_f32 v0, v0, s0
	global_store_short v[64:65], v0, off offset:2240
	v_mul_f32_e32 v0, v20, v70
	v_cvt_pk_bf16_f32 v0, v0, s0
	global_store_short v[66:67], v0, off offset:2560
	v_mul_f32_e32 v0, v4, v71
	v_cvt_pk_bf16_f32 v0, v0, s0
	global_store_short v[64:65], v0, off offset:2560
	v_mul_f32_e32 v0, v21, v70
	v_cvt_pk_bf16_f32 v0, v0, s0
	global_store_short v[66:67], v0, off offset:2624
	v_mul_f32_e32 v0, v5, v71
	v_cvt_pk_bf16_f32 v0, v0, s0
	global_store_short v[64:65], v0, off offset:2624
	v_mul_f32_e32 v0, v22, v70
	v_cvt_pk_bf16_f32 v0, v0, s0
	global_store_short v[66:67], v0, off offset:2688
	v_mul_f32_e32 v0, v6, v71
	v_cvt_pk_bf16_f32 v0, v0, s0
	global_store_short v[64:65], v0, off offset:2688
	v_mul_f32_e32 v0, v23, v70
	v_cvt_pk_bf16_f32 v0, v0, s0
	global_store_short v[66:67], v0, off offset:2752
	v_mul_f32_e32 v0, v7, v71
	v_cvt_pk_bf16_f32 v0, v0, s0
	global_store_short v[64:65], v0, off offset:2752
	v_mul_f32_e32 v0, v24, v70
	v_cvt_pk_bf16_f32 v0, v0, s0
	global_store_short v[66:67], v0, off offset:3072
	v_mul_f32_e32 v0, v8, v71
	v_cvt_pk_bf16_f32 v0, v0, s0
	global_store_short v[64:65], v0, off offset:3072
	v_mul_f32_e32 v0, v25, v70
	v_cvt_pk_bf16_f32 v0, v0, s0
	global_store_short v[66:67], v0, off offset:3136
	v_mul_f32_e32 v0, v9, v71
	v_cvt_pk_bf16_f32 v0, v0, s0
	global_store_short v[64:65], v0, off offset:3136
	v_mul_f32_e32 v0, v26, v70
	v_cvt_pk_bf16_f32 v0, v0, s0
	global_store_short v[66:67], v0, off offset:3200
	v_mul_f32_e32 v0, v10, v71
	v_cvt_pk_bf16_f32 v0, v0, s0
	global_store_short v[64:65], v0, off offset:3200
	v_mul_f32_e32 v0, v27, v70
	v_cvt_pk_bf16_f32 v0, v0, s0
	global_store_short v[66:67], v0, off offset:3264
	v_mul_f32_e32 v0, v11, v71
	v_cvt_pk_bf16_f32 v0, v0, s0
	global_store_short v[64:65], v0, off offset:3264
	v_mul_f32_e32 v0, v28, v70
	v_cvt_pk_bf16_f32 v0, v0, s0
	global_store_short v[66:67], v0, off offset:3584
	v_mul_f32_e32 v0, v12, v71
	v_cvt_pk_bf16_f32 v0, v0, s0
	global_store_short v[64:65], v0, off offset:3584
	v_mul_f32_e32 v0, v29, v70
	v_cvt_pk_bf16_f32 v0, v0, s0
	global_store_short v[66:67], v0, off offset:3648
	v_mul_f32_e32 v0, v13, v71
	v_cvt_pk_bf16_f32 v0, v0, s0
	global_store_short v[64:65], v0, off offset:3648
	v_mul_f32_e32 v0, v30, v70
	v_cvt_pk_bf16_f32 v0, v0, s0
	global_store_short v[66:67], v0, off offset:3712
	v_mul_f32_e32 v0, v14, v71
	v_cvt_pk_bf16_f32 v0, v0, s0
	global_store_short v[64:65], v0, off offset:3712
	v_mul_f32_e32 v0, v31, v70
	v_cvt_pk_bf16_f32 v0, v0, s0
	global_store_short v[66:67], v0, off offset:3776
	v_mul_f32_e32 v0, v15, v71
	v_cvt_pk_bf16_f32 v0, v0, s0
	global_store_short v[64:65], v0, off offset:3776
.LBB0_225:
	s_andn2_b64 vcc, exec, s[8:9]
	s_cbranch_vccnz .LBB0_229
	s_add_i32 s8, s67, 0xfffffe00
	s_lshr_b32 s30, s8, 4
	s_lshl_b32 s9, s67, 7
	s_lshl_b32 s8, s30, 8
	s_and_b32 s9, s9, 0x80
	s_or_b32 s8, s8, s9
	s_bfe_u32 s68, s67, 0x30001
	v_add_u32_e32 v147, s8, v157
	s_lshl_b64 s[8:9], s[30:31], 16
	s_add_u32 s10, s19, s8
	s_addc_u32 s11, s20, s9
	s_lshl_b32 s69, s67, 3
	s_and_b32 s69, s69, 64
	s_lshl_b32 s70, s69, 1
	s_add_u32 s70, s10, s70
	s_addc_u32 s71, s11, 0
	s_lshl_b32 s10, s30, 7
	v_or_b32_e32 v148, v147, v98
	s_or_b32 s30, s69, s10
	s_lshl_b64 s[10:11], s[30:31], 9
	v_ashrrev_i32_e32 v149, 31, v148
	s_add_u32 s72, s21, s10
	v_lshlrev_b64 v[0:1], 10, v[148:149]
	s_addc_u32 s73, s22, s11
	v_lshl_add_u64 v[0:1], s[36:37], 0, v[0:1]
	s_lshl_b32 s30, s68, 7
	v_lshl_add_u64 v[0:1], v[0:1], 0, s[30:31]
	v_lshlrev_b32_e32 v116, 1, v102
	v_lshl_add_u64 v[0:1], v[0:1], 0, v[116:117]
	global_load_dwordx4 v[76:79], v[0:1], off sc1
	global_load_dwordx4 v[72:75], v[0:1], off offset:32 sc1
	global_load_dwordx4 v[68:71], v[0:1], off offset:64 sc1
	global_load_dwordx4 v[64:67], v[0:1], off offset:96 sc1
	v_lshl_add_u64 v[0:1], s[70:71], 0, v[108:109]
	v_lshlrev_b32_e32 v116, 1, v106
	v_lshl_add_u64 v[0:1], v[0:1], 0, v[116:117]
	v_lshl_add_u64 v[4:5], s[72:73], 0, v[110:111]
	global_load_dwordx4 v[0:3], v[0:1], off sc1
	v_lshl_add_u64 v[4:5], v[4:5], 0, v[116:117]
	v_lshl_add_u64 v[8:9], s[70:71], 0, v[114:115]
	v_lshl_add_u64 v[12:13], s[72:73], 0, v[128:129]
	global_load_dwordx4 v[4:7], v[4:5], off sc1
	v_lshl_add_u64 v[8:9], v[8:9], 0, v[116:117]
	v_lshl_add_u64 v[12:13], v[12:13], 0, v[116:117]
	global_load_dwordx4 v[8:11], v[8:9], off sc1
	s_lshl_b32 s69, s67, 4
	global_load_dwordx4 v[12:15], v[12:13], off sc1
	s_and_b32 s69, s69, 0x80
	s_or_b32 s8, s8, s69
	v_mov_b32_e32 v155, 0
	s_mov_b32 s30, 0
	v_lshl_add_u64 v[150:151], v[140:141], 0, s[8:9]
	v_lshl_add_u64 v[152:153], v[142:143], 0, s[10:11]
	v_mov_b32_e32 v168, 0xf149f2ca
	v_mov_b32_e32 v16, 0
	v_mov_b32_e32 v17, v155
	v_mov_b32_e32 v18, v155
	v_mov_b32_e32 v19, v155
	v_mov_b32_e32 v20, v155
	v_mov_b32_e32 v21, v155
	v_mov_b32_e32 v22, v155
	v_mov_b32_e32 v23, v155
	v_mov_b32_e32 v24, v155
	v_mov_b32_e32 v25, v155
	v_mov_b32_e32 v26, v155
	v_mov_b32_e32 v27, v155
	v_mov_b32_e32 v28, v155
	v_mov_b32_e32 v29, v155
	v_mov_b32_e32 v30, v155
	v_mov_b32_e32 v31, v155
	s_waitcnt vmcnt(0)
	ds_write_b128 v113, v[0:3]
	v_add_u32_e32 v0, 0x2400, v159
	ds_write2_b64 v0, v[4:5], v[6:7] offset1:1
	ds_write_b128 v113, v[8:11] offset:4608
	v_add_u32_e32 v0, 0x3500, v159
	v_and_b32_e32 v1, 64, v213
	ds_write2_b64 v0, v[12:13], v[14:15] offset1:1
	v_xor_b32_e32 v0, 32, v213
	v_add_u32_e32 v1, 64, v1
	v_cmp_lt_i32_e32 vcc, v0, v1
	v_mov_b32_e32 v1, v155
	v_mov_b32_e32 v2, v155
	v_cndmask_b32_e32 v0, v213, v0, vcc
	v_lshlrev_b32_e32 v149, 2, v0
	v_mov_b32_e32 v0, 0
	v_mov_b32_e32 v3, v155
	v_mov_b32_e32 v4, v155
	v_mov_b32_e32 v5, v155
	v_mov_b32_e32 v6, v155
	v_mov_b32_e32 v7, v155
	v_mov_b32_e32 v8, v155
	v_mov_b32_e32 v9, v155
	v_mov_b32_e32 v10, v155
	v_mov_b32_e32 v11, v155
	v_mov_b32_e32 v12, v155
	v_mov_b32_e32 v13, v155
	v_mov_b32_e32 v14, v155
	v_mov_b32_e32 v15, v155
	s_waitcnt lgkmcnt(0)
	s_barrier
.LBB0_227:
	v_lshl_add_u64 v[32:33], v[150:151], 0, v[138:139]
	s_mov_b32 s9, 0x133d2000
	v_add_co_u32_e32 v34, vcc, s9, v32
	s_mov_b32 s9, 0x13bce000
	s_nop 0
	v_addc_co_u32_e32 v35, vcc, 0, v33, vcc
	global_load_dwordx4 v[80:83], v[34:35], off sc1
	v_lshl_add_u64 v[34:35], v[152:153], 0, v[138:139]
	v_add_co_u32_e32 v36, vcc, s9, v34
	s_mov_b32 s9, 0x133d4000
	s_nop 0
	v_addc_co_u32_e32 v37, vcc, 0, v35, vcc
	v_add_co_u32_e32 v32, vcc, s9, v32
	s_and_b32 s8, s30, 1
	s_nop 0
	v_addc_co_u32_e32 v33, vcc, 0, v33, vcc
	s_mov_b32 s9, 0x13bd2000
	global_load_dwordx4 v[88:91], v[32:33], off sc1
	v_add_co_u32_e32 v32, vcc, s9, v34
	s_mul_i32 s9, s8, 0x4600
	v_or_b32_e32 v170, s9, v163
	v_mov_b32_e32 v169, v155
	v_addc_co_u32_e32 v33, vcc, 0, v35, vcc
	v_add_u32_e32 v155, v170, v161
	global_load_dwordx4 v[84:87], v[36:37], off offset:128 sc1
	global_load_dwordx4 v[92:95], v[32:33], off offset:128 sc1
	ds_read_b128 v[32:35], v155
	ds_read_b128 v[36:39], v155 offset:32
	s_waitcnt lgkmcnt(1)
	v_mfma_f32_32x32x16_bf16 v[48:63], v[32:35], v[76:79], 0
	ds_read_b128 v[32:35], v155 offset:64
	ds_read_b128 v[172:175], v155 offset:4640
	v_mov_b32_e32 v154, v168
	s_xor_b32 s8, s8, 1
	s_mulk_i32 s8, 0x4600
	s_add_i32 s30, s30, 1
	v_lshl_add_u64 v[150:151], v[150:151], 0, s[28:29]
	s_waitcnt lgkmcnt(2)
	v_mfma_f32_32x32x16_bf16 v[48:63], v[36:39], v[72:75], v[48:63]
	v_lshl_add_u64 v[152:153], v[152:153], 0, s[24:25]
	s_cmp_lg_u32 s30, 3
	s_waitcnt lgkmcnt(1)
	v_mfma_f32_32x32x16_bf16 v[48:63], v[32:35], v[68:71], v[48:63]
	ds_read_b128 v[32:35], v155 offset:96
	s_waitcnt lgkmcnt(0)
	v_mfma_f32_32x32x16_bf16 v[48:63], v[32:35], v[64:67], v[48:63]
	ds_read_b128 v[32:35], v155 offset:4608
	s_waitcnt lgkmcnt(0)
	v_mfma_f32_32x32x16_bf16 v[32:47], v[32:35], v[76:79], 0
	s_nop 8
	v_max_f32_e32 v168, v48, v48
	v_mfma_f32_32x32x16_bf16 v[32:47], v[172:175], v[72:75], v[32:47]
	ds_read_b128 v[172:175], v155 offset:4672
	s_waitcnt lgkmcnt(0)
	v_mfma_f32_32x32x16_bf16 v[32:47], v[172:175], v[68:71], v[32:47]
	ds_read_b128 v[172:175], v155 offset:4704
	v_max_f32_e32 v155, v49, v49
	v_max_f32_e32 v155, v168, v155
	v_max3_f32 v155, v155, v50, v51
	v_max3_f32 v155, v155, v52, v53
	v_max3_f32 v155, v155, v54, v55
	v_max3_f32 v155, v155, v56, v57
	s_waitcnt lgkmcnt(0)
	v_mfma_f32_32x32x16_bf16 v[32:47], v[172:175], v[64:67], v[32:47]
	v_max3_f32 v155, v155, v58, v59
	v_max3_f32 v155, v155, v60, v61
	v_max3_f32 v155, v155, v62, v63
	s_nop 8
	v_max3_f32 v155, v155, v32, v33
	v_max3_f32 v155, v155, v34, v35
	v_max3_f32 v155, v155, v36, v37
	v_max3_f32 v155, v155, v38, v39
	v_max3_f32 v155, v155, v40, v41
	v_max3_f32 v155, v155, v42, v43
	v_max3_f32 v155, v155, v44, v45
	v_max3_f32 v155, v155, v46, v47
	ds_bpermute_b32 v168, v149, v155
	s_waitcnt lgkmcnt(0)
	v_max3_f32 v168, v154, v155, v168
	v_sub_f32_e32 v48, v48, v168
	v_exp_f32_e32 v171, v48
	v_sub_f32_e32 v49, v49, v168
	v_exp_f32_e32 v172, v49
	v_sub_f32_e32 v49, v50, v168
	v_exp_f32_e32 v173, v49
	v_sub_f32_e32 v49, v51, v168
	v_exp_f32_e32 v174, v49
	v_sub_f32_e32 v49, v52, v168
	v_add_f32_e32 v48, 0, v171
	v_exp_f32_e32 v175, v49
	v_sub_f32_e32 v49, v53, v168
	v_add_f32_e32 v48, v172, v48
	v_exp_f32_e32 v176, v49
	v_sub_f32_e32 v49, v54, v168
	v_add_f32_e32 v48, v173, v48
	v_exp_f32_e32 v177, v49
	v_sub_f32_e32 v49, v55, v168
	v_add_f32_e32 v48, v174, v48
	v_exp_f32_e32 v178, v49
	v_add_f32_e32 v48, v175, v48
	v_add_f32_e32 v48, v176, v48
	v_add_f32_e32 v48, v177, v48
	v_add_f32_e32 v49, v178, v48
	v_sub_f32_e32 v48, v56, v168
	v_exp_f32_e32 v48, v48
	v_sub_f32_e32 v56, v63, v168
	v_exp_f32_e32 v56, v56
	v_sub_f32_e32 v32, v32, v168
	v_add_f32_e32 v50, v48, v49
	v_sub_f32_e32 v49, v57, v168
	v_exp_f32_e32 v49, v49
	v_sub_f32_e32 v154, v154, v168
	v_exp_f32_e32 v154, v154
	v_add_f32_e32 v51, v49, v50
	v_sub_f32_e32 v50, v58, v168
	v_exp_f32_e32 v50, v50
	v_pk_mul_f32 v[30:31], v[30:31], v[154:155] op_sel_hi:[1,0]
	v_pk_mul_f32 v[28:29], v[28:29], v[154:155] op_sel_hi:[1,0]
	v_pk_mul_f32 v[26:27], v[26:27], v[154:155] op_sel_hi:[1,0]
	v_add_f32_e32 v52, v50, v51
	v_sub_f32_e32 v51, v59, v168
	v_exp_f32_e32 v51, v51
	v_pk_mul_f32 v[24:25], v[24:25], v[154:155] op_sel_hi:[1,0]
	v_pk_mul_f32 v[22:23], v[22:23], v[154:155] op_sel_hi:[1,0]
	v_pk_mul_f32 v[20:21], v[20:21], v[154:155] op_sel_hi:[1,0]
	v_add_f32_e32 v53, v51, v52
	v_sub_f32_e32 v52, v60, v168
	v_exp_f32_e32 v52, v52
	v_pk_mul_f32 v[18:19], v[18:19], v[154:155] op_sel_hi:[1,0]
	v_pk_mul_f32 v[16:17], v[16:17], v[154:155] op_sel_hi:[1,0]
	v_pk_mul_f32 v[14:15], v[14:15], v[154:155] op_sel_hi:[1,0]
	v_add_f32_e32 v54, v52, v53
	v_sub_f32_e32 v53, v61, v168
	v_exp_f32_e32 v53, v53
	v_pk_mul_f32 v[12:13], v[12:13], v[154:155] op_sel_hi:[1,0]
	v_pk_mul_f32 v[10:11], v[10:11], v[154:155] op_sel_hi:[1,0]
	v_pk_mul_f32 v[8:9], v[8:9], v[154:155] op_sel_hi:[1,0]
	v_add_f32_e32 v55, v53, v54
	v_sub_f32_e32 v54, v62, v168
	v_exp_f32_e32 v54, v54
	v_pk_mul_f32 v[6:7], v[6:7], v[154:155] op_sel_hi:[1,0]
	v_pk_mul_f32 v[4:5], v[4:5], v[154:155] op_sel_hi:[1,0]
	v_pk_mul_f32 v[2:3], v[2:3], v[154:155] op_sel_hi:[1,0]
	v_add_f32_e32 v55, v54, v55
	v_add_f32_e32 v62, v56, v55
	v_exp_f32_e32 v55, v32
	v_sub_f32_e32 v32, v33, v168
	v_exp_f32_e32 v57, v32
	v_sub_f32_e32 v32, v34, v168
	v_exp_f32_e32 v58, v32
	v_sub_f32_e32 v32, v35, v168
	v_exp_f32_e32 v59, v32
	v_sub_f32_e32 v32, v36, v168
	v_exp_f32_e32 v36, v32
	v_sub_f32_e32 v32, v37, v168
	v_exp_f32_e32 v37, v32
	v_sub_f32_e32 v32, v38, v168
	v_exp_f32_e32 v60, v32
	v_sub_f32_e32 v32, v39, v168
	v_exp_f32_e32 v61, v32
	v_sub_f32_e32 v32, v40, v168
	v_exp_f32_e32 v38, v32
	v_sub_f32_e32 v32, v41, v168
	v_exp_f32_e32 v39, v32
	v_sub_f32_e32 v32, v42, v168
	v_exp_f32_e32 v40, v32
	v_sub_f32_e32 v32, v43, v168
	v_exp_f32_e32 v41, v32
	v_sub_f32_e32 v32, v44, v168
	v_exp_f32_e32 v42, v32
	v_sub_f32_e32 v32, v45, v168
	v_exp_f32_e32 v43, v32
	v_sub_f32_e32 v32, v46, v168
	v_exp_f32_e32 v44, v32
	v_sub_f32_e32 v32, v47, v168
	v_exp_f32_e32 v45, v32
	v_add_f32_e32 v32, v55, v62
	v_add_f32_e32 v32, v57, v32
	v_add_f32_e32 v32, v58, v32
	v_add_f32_e32 v32, v59, v32
	v_add_f32_e32 v32, v36, v32
	v_add_f32_e32 v32, v37, v32
	v_add_f32_e32 v32, v60, v32
	v_add_f32_e32 v32, v61, v32
	v_add_f32_e32 v32, v38, v32
	v_add_f32_e32 v32, v39, v32
	v_add_f32_e32 v32, v40, v32
	v_add_f32_e32 v32, v41, v32
	v_add_f32_e32 v32, v42, v32
	v_lshlrev_b32_e32 v46, 1, v160
	v_add_f32_e32 v32, v43, v32
	v_add3_u32 v46, v170, v164, v46
	v_add_f32_e32 v32, v44, v32
	v_add_u32_e32 v62, 0x2000, v46
	v_pk_mul_f32 v[0:1], v[0:1], v[154:155] op_sel_hi:[1,0]
	v_add_f32_e32 v155, v45, v32
	v_cvt_pk_bf16_f32 v32, v171, v172
	v_cvt_pk_bf16_f32 v33, v173, v174
	v_cvt_pk_bf16_f32 v34, v175, v176
	v_cvt_pk_bf16_f32 v35, v177, v178
	ds_read2_b64 v[170:173], v62 offset0:128 offset1:130
	ds_read2_b64 v[174:177], v62 offset0:132 offset1:134
	v_add_u32_e32 v63, 0x3000, v46
	s_waitcnt lgkmcnt(1)
	v_mfma_f32_32x32x16_bf16 v[16:31], v[170:173], v[32:35], v[16:31]
	ds_read2_b64 v[170:173], v63 offset0:160 offset1:162
	v_fmac_f32_e32 v155, v169, v154
	s_waitcnt lgkmcnt(0)
	v_mfma_f32_32x32x16_bf16 v[0:15], v[170:173], v[32:35], v[0:15]
	v_cvt_pk_bf16_f32 v32, v48, v49
	ds_read2_b64 v[46:49], v63 offset0:164 offset1:166
	v_cvt_pk_bf16_f32 v33, v50, v51
	v_cvt_pk_bf16_f32 v34, v52, v53
	v_cvt_pk_bf16_f32 v35, v54, v56
	s_waitcnt lgkmcnt(0)
	s_nop 0
	v_mfma_f32_32x32x16_bf16 v[0:15], v[46:49], v[32:35], v[0:15]
	ds_read2_b64 v[46:49], v62 offset0:136 offset1:138
	v_mfma_f32_32x32x16_bf16 v[16:31], v[174:177], v[32:35], v[16:31]
	v_cvt_pk_bf16_f32 v32, v55, v57
	v_cvt_pk_bf16_f32 v33, v58, v59
	v_cvt_pk_bf16_f32 v34, v36, v37
	v_cvt_pk_bf16_f32 v35, v60, v61
	s_waitcnt lgkmcnt(0)
	s_nop 0
	v_mfma_f32_32x32x16_bf16 v[16:31], v[46:49], v[32:35], v[16:31]
	ds_read2_b64 v[46:49], v63 offset0:168 offset1:170
	s_waitcnt lgkmcnt(0)
	v_mfma_f32_32x32x16_bf16 v[0:15], v[46:49], v[32:35], v[0:15]
	v_cvt_pk_bf16_f32 v32, v38, v39
	ds_read2_b64 v[36:39], v62 offset0:140 offset1:142
	v_cvt_pk_bf16_f32 v33, v40, v41
	v_cvt_pk_bf16_f32 v34, v42, v43
	v_cvt_pk_bf16_f32 v35, v44, v45
	s_waitcnt lgkmcnt(0)
	s_nop 0
	v_mfma_f32_32x32x16_bf16 v[16:31], v[36:39], v[32:35], v[16:31]
	ds_read2_b64 v[36:39], v63 offset0:172 offset1:174
	s_waitcnt lgkmcnt(0)
	v_mfma_f32_32x32x16_bf16 v[0:15], v[36:39], v[32:35], v[0:15]
	v_add3_u32 v32, v105, s8, v116
	v_add_u32_e32 v33, v32, v158
	v_add_u32_e32 v34, 0x2400, v33
	s_waitcnt vmcnt(3)
	ds_write_b128 v32, v[80:83]
	s_waitcnt vmcnt(1)
	ds_write2_b64 v34, v[84:85], v[86:87] offset1:1
	ds_write_b128 v32, v[88:91] offset:4608
	v_add_u32_e32 v32, 0x3500, v33
	s_waitcnt vmcnt(0)
	ds_write2_b64 v32, v[92:93], v[94:95] offset1:1
	s_waitcnt lgkmcnt(0)
	s_barrier
	s_cbranch_scc1 .LBB0_227
	v_add_u32_e32 v80, v163, v161
	ds_read_b128 v[32:35], v80 offset:17920
	ds_read_b128 v[36:39], v80 offset:17952
	v_add_u32_e32 v82, 0x6800, v165
	v_add_u32_e32 v83, 0x6800, v166
	s_or_b32 s30, s68, s15
	s_waitcnt lgkmcnt(1)
	v_mfma_f32_32x32x16_bf16 v[48:63], v[32:35], v[76:79], 0
	ds_read_b128 v[32:35], v80 offset:17984
	v_readlane_b32 s48, v255, 16
	s_lshl_b64 s[8:9], s[30:31], 2
	v_readlane_b32 s50, v255, 18
	v_readlane_b32 s51, v255, 19
	s_add_u32 s8, s50, s8
	s_addc_u32 s9, s51, s9
	s_waitcnt lgkmcnt(1)
	v_mfma_f32_32x32x16_bf16 v[48:63], v[36:39], v[72:75], v[48:63]
	s_lshl_b32 s30, s68, 14
	v_readlane_b32 s49, v255, 17
	v_readlane_b32 s52, v255, 20
	v_readlane_b32 s53, v255, 21
	v_readlane_b32 s54, v255, 22
	v_readlane_b32 s55, v255, 23
	v_readlane_b32 s56, v255, 24
	s_waitcnt lgkmcnt(0)
	v_mfma_f32_32x32x16_bf16 v[48:63], v[32:35], v[68:71], v[48:63]
	ds_read_b128 v[32:35], v80 offset:18016
	v_readlane_b32 s57, v255, 25
	v_readlane_b32 s58, v255, 26
	v_readlane_b32 s59, v255, 27
	v_readlane_b32 s60, v255, 28
	v_readlane_b32 s61, v255, 29
	v_readlane_b32 s62, v255, 30
	v_readlane_b32 s63, v255, 31
	s_waitcnt lgkmcnt(0)
	v_mfma_f32_32x32x16_bf16 v[48:63], v[32:35], v[64:67], v[48:63]
	ds_read_b128 v[32:35], v80 offset:22528
	s_waitcnt lgkmcnt(0)
	v_mfma_f32_32x32x16_bf16 v[32:47], v[32:35], v[76:79], 0
	ds_read_b128 v[76:79], v80 offset:22560
	s_waitcnt lgkmcnt(0)
	v_mfma_f32_32x32x16_bf16 v[32:47], v[76:79], v[72:75], v[32:47]
	ds_read_b128 v[72:75], v80 offset:22592
	s_waitcnt lgkmcnt(0)
	v_mfma_f32_32x32x16_bf16 v[32:47], v[72:75], v[68:71], v[32:47]
	ds_read_b128 v[68:71], v80 offset:22624
	s_waitcnt lgkmcnt(0)
	v_mfma_f32_32x32x16_bf16 v[32:47], v[68:71], v[64:67], v[32:47]
	v_max_f32_e32 v64, v49, v49
	v_max_f32_e32 v65, v48, v48
	v_max_f32_e32 v64, v65, v64
	v_max3_f32 v64, v64, v50, v51
	v_max3_f32 v64, v64, v52, v53
	v_max3_f32 v64, v64, v54, v55
	v_max3_f32 v64, v64, v56, v57
	v_max3_f32 v64, v64, v58, v59
	v_max3_f32 v64, v64, v60, v61
	v_max3_f32 v64, v64, v62, v63
	s_nop 1
	v_max3_f32 v64, v64, v32, v33
	v_max3_f32 v64, v64, v34, v35
	v_max3_f32 v64, v64, v36, v37
	v_max3_f32 v64, v64, v38, v39
	v_max3_f32 v64, v64, v40, v41
	v_max3_f32 v64, v64, v42, v43
	v_max3_f32 v64, v64, v44, v45
	v_max3_f32 v64, v64, v46, v47
	ds_bpermute_b32 v65, v149, v64
	s_waitcnt lgkmcnt(0)
	v_max3_f32 v65, v168, v64, v65
	v_sub_f32_e32 v32, v32, v65
	v_exp_f32_e32 v66, v32
	v_sub_f32_e32 v32, v33, v65
	v_exp_f32_e32 v67, v32
	v_sub_f32_e32 v32, v34, v65
	v_exp_f32_e32 v68, v32
	v_sub_f32_e32 v32, v35, v65
	v_exp_f32_e32 v69, v32
	v_sub_f32_e32 v32, v36, v65
	v_exp_f32_e32 v70, v32
	v_sub_f32_e32 v32, v37, v65
	v_exp_f32_e32 v71, v32
	v_sub_f32_e32 v32, v38, v65
	v_exp_f32_e32 v72, v32
	v_sub_f32_e32 v32, v39, v65
	v_exp_f32_e32 v73, v32
	v_sub_f32_e32 v32, v40, v65
	v_exp_f32_e32 v74, v32
	v_sub_f32_e32 v32, v41, v65
	v_exp_f32_e32 v75, v32
	v_sub_f32_e32 v32, v42, v65
	v_sub_f32_e32 v64, v168, v65
	v_sub_f32_e32 v48, v48, v65
	v_sub_f32_e32 v49, v49, v65
	v_sub_f32_e32 v50, v50, v65
	v_sub_f32_e32 v51, v51, v65
	v_sub_f32_e32 v52, v52, v65
	v_sub_f32_e32 v53, v53, v65
	v_sub_f32_e32 v54, v54, v65
	v_sub_f32_e32 v55, v55, v65
	v_exp_f32_e32 v76, v32
	v_sub_f32_e32 v32, v43, v65
	v_exp_f32_e32 v64, v64
	v_exp_f32_e32 v48, v48
	v_exp_f32_e32 v49, v49
	v_exp_f32_e32 v50, v50
	v_exp_f32_e32 v51, v51
	v_exp_f32_e32 v52, v52
	v_exp_f32_e32 v53, v53
	v_exp_f32_e32 v54, v54
	v_exp_f32_e32 v55, v55
	v_exp_f32_e32 v77, v32
	v_sub_f32_e32 v32, v44, v65
	v_exp_f32_e32 v78, v32
	v_sub_f32_e32 v32, v45, v65
	ds_read2_b64 v[36:39], v82 offset0:64 offset1:66
	ds_read2_b64 v[40:43], v82 offset0:68 offset1:70
	v_exp_f32_e32 v79, v32
	v_sub_f32_e32 v32, v46, v65
	v_exp_f32_e32 v80, v32
	v_sub_f32_e32 v32, v47, v65
	v_exp_f32_e32 v81, v32
	v_pk_mul_f32 v[30:31], v[30:31], v[64:65] op_sel_hi:[1,0]
	v_pk_mul_f32 v[28:29], v[28:29], v[64:65] op_sel_hi:[1,0]
	v_pk_mul_f32 v[26:27], v[26:27], v[64:65] op_sel_hi:[1,0]
	v_pk_mul_f32 v[24:25], v[24:25], v[64:65] op_sel_hi:[1,0]
	v_pk_mul_f32 v[22:23], v[22:23], v[64:65] op_sel_hi:[1,0]
	v_pk_mul_f32 v[20:21], v[20:21], v[64:65] op_sel_hi:[1,0]
	v_pk_mul_f32 v[18:19], v[18:19], v[64:65] op_sel_hi:[1,0]
	v_pk_mul_f32 v[16:17], v[16:17], v[64:65] op_sel_hi:[1,0]
	v_cvt_pk_bf16_f32 v32, v48, v49
	v_cvt_pk_bf16_f32 v33, v50, v51
	v_cvt_pk_bf16_f32 v34, v52, v53
	v_cvt_pk_bf16_f32 v35, v54, v55
	v_sub_f32_e32 v56, v56, v65
	v_sub_f32_e32 v57, v57, v65
	s_waitcnt lgkmcnt(1)
	v_mfma_f32_32x32x16_bf16 v[16:31], v[36:39], v[32:35], v[16:31]
	v_sub_f32_e32 v58, v58, v65
	v_sub_f32_e32 v59, v59, v65
	v_sub_f32_e32 v60, v60, v65
	v_sub_f32_e32 v61, v61, v65
	v_sub_f32_e32 v62, v62, v65
	v_sub_f32_e32 v63, v63, v65
	v_exp_f32_e32 v56, v56
	v_exp_f32_e32 v57, v57
	v_exp_f32_e32 v58, v58
	v_exp_f32_e32 v59, v59
	v_exp_f32_e32 v60, v60
	v_exp_f32_e32 v61, v61
	v_exp_f32_e32 v62, v62
	v_exp_f32_e32 v63, v63
	ds_read2_b64 v[36:39], v83 offset0:64 offset1:66
	ds_read2_b64 v[44:47], v83 offset0:68 offset1:70
	v_pk_mul_f32 v[14:15], v[14:15], v[64:65] op_sel_hi:[1,0]
	v_pk_mul_f32 v[12:13], v[12:13], v[64:65] op_sel_hi:[1,0]
	v_pk_mul_f32 v[10:11], v[10:11], v[64:65] op_sel_hi:[1,0]
	v_pk_mul_f32 v[8:9], v[8:9], v[64:65] op_sel_hi:[1,0]
	v_pk_mul_f32 v[6:7], v[6:7], v[64:65] op_sel_hi:[1,0]
	v_pk_mul_f32 v[4:5], v[4:5], v[64:65] op_sel_hi:[1,0]
	v_pk_mul_f32 v[2:3], v[2:3], v[64:65] op_sel_hi:[1,0]
	v_pk_mul_f32 v[0:1], v[0:1], v[64:65] op_sel_hi:[1,0]
	s_waitcnt lgkmcnt(1)
	s_nop 0
	v_mfma_f32_32x32x16_bf16 v[0:15], v[36:39], v[32:35], v[0:15]
	v_cvt_pk_bf16_f32 v32, v56, v57
	v_cvt_pk_bf16_f32 v33, v58, v59
	v_cvt_pk_bf16_f32 v34, v60, v61
	v_cvt_pk_bf16_f32 v35, v62, v63
	ds_read2_b64 v[36:39], v82 offset0:72 offset1:74
	s_nop 0
	v_mfma_f32_32x32x16_bf16 v[16:31], v[40:43], v[32:35], v[16:31]
	s_waitcnt lgkmcnt(1)
	v_mfma_f32_32x32x16_bf16 v[0:15], v[44:47], v[32:35], v[0:15]
	v_cvt_pk_bf16_f32 v32, v66, v67
	v_cvt_pk_bf16_f32 v33, v68, v69
	v_cvt_pk_bf16_f32 v34, v70, v71
	v_cvt_pk_bf16_f32 v35, v72, v73
	s_waitcnt lgkmcnt(0)
	s_nop 0
	v_mfma_f32_32x32x16_bf16 v[16:31], v[36:39], v[32:35], v[16:31]
	ds_read2_b64 v[36:39], v83 offset0:72 offset1:74
	s_waitcnt lgkmcnt(0)
	v_mfma_f32_32x32x16_bf16 v[0:15], v[36:39], v[32:35], v[0:15]
	ds_read2_b64 v[36:39], v82 offset0:76 offset1:78
	v_cvt_pk_bf16_f32 v32, v74, v75
	v_cvt_pk_bf16_f32 v33, v76, v77
	v_cvt_pk_bf16_f32 v34, v78, v79
	v_cvt_pk_bf16_f32 v35, v80, v81
	s_waitcnt lgkmcnt(0)
	s_nop 0
	v_mfma_f32_32x32x16_bf16 v[16:31], v[36:39], v[32:35], v[16:31]
	ds_read2_b64 v[36:39], v83 offset0:76 offset1:78
	s_waitcnt lgkmcnt(0)
	s_barrier
	v_mfma_f32_32x32x16_bf16 v[0:15], v[36:39], v[32:35], v[0:15]
	v_add_f32_e32 v32, 0, v48
	v_add_f32_e32 v32, v49, v32
	v_add_f32_e32 v32, v50, v32
	v_add_f32_e32 v32, v51, v32
	v_add_f32_e32 v32, v52, v32
	v_add_f32_e32 v32, v53, v32
	v_add_f32_e32 v32, v54, v32
	v_add_f32_e32 v32, v55, v32
	v_add_f32_e32 v32, v56, v32
	v_add_f32_e32 v32, v57, v32
	v_add_f32_e32 v32, v58, v32
	v_add_f32_e32 v32, v59, v32
	v_add_f32_e32 v32, v60, v32
	v_add_f32_e32 v32, v61, v32
	v_add_f32_e32 v32, v62, v32
	v_add_f32_e32 v32, v63, v32
	v_add_f32_e32 v32, v66, v32
	v_add_f32_e32 v32, v67, v32
	v_add_f32_e32 v32, v68, v32
	v_add_f32_e32 v32, v69, v32
	v_add_f32_e32 v32, v70, v32
	v_add_f32_e32 v32, v71, v32
	v_add_f32_e32 v32, v72, v32
	v_add_f32_e32 v32, v73, v32
	v_add_f32_e32 v32, v74, v32
	v_add_f32_e32 v32, v75, v32
	v_add_f32_e32 v32, v76, v32
	v_add_f32_e32 v32, v77, v32
	v_add_f32_e32 v32, v78, v32
	v_add_f32_e32 v32, v79, v32
	v_add_f32_e32 v32, v80, v32
	v_add_f32_e32 v32, v81, v32
	v_fmac_f32_e32 v32, v155, v64
	ds_bpermute_b32 v33, v149, v32
	s_waitcnt lgkmcnt(0)
	v_add_f32_e32 v32, v32, v33
	global_load_dword v33, v117, s[8:9] sc1
	s_mov_b32 s8, 0x3fb8aa3b
	s_waitcnt vmcnt(0)
	v_mul_f32_e32 v34, 0x3fb8aa3b, v33
	v_max_f32_e32 v34, v65, v34
	v_sub_f32_e32 v35, v65, v34
	v_fma_f32 v33, v33, s8, -v34
	v_exp_f32_e32 v35, v35
	v_exp_f32_e32 v33, v33
	s_nop 0
	v_fmac_f32_e32 v33, v35, v32
	v_div_scale_f32 v32, s[8:9], v33, v33, v35
	v_rcp_f32_e32 v34, v32
	s_mov_b64 s[8:9], 0x1490e000
	v_fma_f32 v36, -v32, v34, 1.0
	v_fmac_f32_e32 v34, v36, v34
	v_div_scale_f32 v36, vcc, v35, v33, v35
	v_mul_f32_e32 v37, v36, v34
	v_fma_f32 v38, -v32, v37, v36
	v_fmac_f32_e32 v37, v38, v34
	v_fma_f32 v32, -v32, v37, v36
	v_div_fmas_f32 v32, v32, v34, v37
	v_ashrrev_i32_e32 v34, 7, v147
	v_div_fixup_f32 v32, v32, v33, v35
	v_ashrrev_i32_e32 v35, 31, v34
	v_lshlrev_b64 v[34:35], 19, v[34:35]
	v_lshl_add_u64 v[34:35], s[2:3], 0, v[34:35]
	v_lshlrev_b32_e32 v33, 6, v148
	v_lshl_add_u64 v[34:35], v[34:35], 0, s[30:31]
	v_and_b32_e32 v116, 0x1fc0, v33
	v_lshl_add_u64 v[34:35], v[34:35], 0, v[116:117]
	v_lshlrev_b32_e32 v116, 1, v122
	v_lshl_add_u64 v[34:35], v[34:35], 0, v[116:117]
	v_lshl_add_u64 v[36:37], v[34:35], 0, s[8:9]
	v_pk_mul_f32 v[16:17], v[16:17], v[32:33] op_sel_hi:[1,0]
	v_pk_mul_f32 v[18:19], v[18:19], v[32:33] op_sel_hi:[1,0]
	s_mov_b32 s8, 0x1490e000
	v_cvt_pk_bf16_f32 v16, v16, v17
	v_cvt_pk_bf16_f32 v17, v18, v19
	v_add_co_u32_e32 v18, vcc, s8, v34
	v_pk_mul_f32 v[0:1], v[0:1], v[32:33] op_sel_hi:[1,0]
	s_nop 0
	v_addc_co_u32_e32 v19, vcc, 0, v35, vcc
	v_pk_mul_f32 v[2:3], v[2:3], v[32:33] op_sel_hi:[1,0]
	s_mov_b32 s8, 0x14910000
	v_cvt_pk_bf16_f32 v0, v0, v1
	v_cvt_pk_bf16_f32 v1, v2, v3
	v_add_co_u32_e32 v2, vcc, s8, v34
	global_store_dwordx2 v[18:19], v[16:17], off
	s_nop 0
	v_addc_co_u32_e32 v3, vcc, 0, v35, vcc
	v_pk_mul_f32 v[16:17], v[20:21], v[32:33] op_sel_hi:[1,0]
	v_pk_mul_f32 v[18:19], v[22:23], v[32:33] op_sel_hi:[1,0]
	global_store_dwordx2 v[2:3], v[0:1], off
	v_pk_mul_f32 v[0:1], v[4:5], v[32:33] op_sel_hi:[1,0]
	v_pk_mul_f32 v[4:5], v[6:7], v[32:33] op_sel_hi:[1,0]
	v_cvt_pk_bf16_f32 v16, v16, v17
	v_cvt_pk_bf16_f32 v17, v18, v19
	v_cvt_pk_bf16_f32 v0, v0, v1
	v_cvt_pk_bf16_f32 v1, v4, v5
	global_store_dwordx2 v[36:37], v[16:17], off offset:16
	v_pk_mul_f32 v[16:17], v[24:25], v[32:33] op_sel_hi:[1,0]
	v_pk_mul_f32 v[18:19], v[26:27], v[32:33] op_sel_hi:[1,0]
	global_store_dwordx2 v[2:3], v[0:1], off offset:16
	v_pk_mul_f32 v[0:1], v[8:9], v[32:33] op_sel_hi:[1,0]
	v_pk_mul_f32 v[4:5], v[10:11], v[32:33] op_sel_hi:[1,0]
	v_cvt_pk_bf16_f32 v16, v16, v17
	v_cvt_pk_bf16_f32 v17, v18, v19
	v_cvt_pk_bf16_f32 v0, v0, v1
	v_cvt_pk_bf16_f32 v1, v4, v5
	global_store_dwordx2 v[36:37], v[16:17], off offset:32
	v_pk_mul_f32 v[16:17], v[28:29], v[32:33] op_sel_hi:[1,0]
	v_pk_mul_f32 v[18:19], v[30:31], v[32:33] op_sel_hi:[1,0]
	global_store_dwordx2 v[2:3], v[0:1], off offset:32
	v_pk_mul_f32 v[0:1], v[12:13], v[32:33] op_sel_hi:[1,0]
	v_pk_mul_f32 v[4:5], v[14:15], v[32:33] op_sel_hi:[1,0]
	v_cvt_pk_bf16_f32 v16, v16, v17
	v_cvt_pk_bf16_f32 v17, v18, v19
	v_cvt_pk_bf16_f32 v0, v0, v1
	v_cvt_pk_bf16_f32 v1, v4, v5
	global_store_dwordx2 v[36:37], v[16:17], off offset:48
	global_store_dwordx2 v[2:3], v[0:1], off offset:48

.LBB0_230:
	s_andn2_b64 vcc, exec, s[8:9]
	s_cbranch_vccnz .LBB0_234
	s_add_i32 s8, s67, 0xffffff00
	s_lshr_b32 s30, s8, 4
	s_lshl_b32 s9, s67, 7
	s_lshl_b32 s8, s30, 8
	s_and_b32 s9, s9, 0x80
	s_or_b32 s8, s8, s9
	s_bfe_u32 s68, s67, 0x30001
	v_add_u32_e32 v147, s8, v157
	s_lshl_b64 s[8:9], s[30:31], 16
	s_add_u32 s10, s23, s8
	s_addc_u32 s11, s34, s9
	s_lshl_b32 s69, s67, 3
	s_and_b32 s69, s69, 64
	s_lshl_b32 s70, s69, 1
	s_add_u32 s70, s10, s70
	s_addc_u32 s71, s11, 0
	s_lshl_b32 s10, s30, 7
	v_or_b32_e32 v148, v147, v98
	s_or_b32 s30, s69, s10
	s_lshl_b64 s[10:11], s[30:31], 9
	v_ashrrev_i32_e32 v149, 31, v148
	s_add_u32 s72, s35, s10
	v_lshlrev_b64 v[0:1], 10, v[148:149]
	s_addc_u32 s73, s40, s11
	v_lshl_add_u64 v[0:1], s[38:39], 0, v[0:1]
	s_lshl_b32 s30, s68, 7
	v_lshl_add_u64 v[0:1], v[0:1], 0, s[30:31]
	v_lshlrev_b32_e32 v116, 1, v102
	v_lshl_add_u64 v[0:1], v[0:1], 0, v[116:117]
	global_load_dwordx4 v[76:79], v[0:1], off sc1
	global_load_dwordx4 v[72:75], v[0:1], off offset:32 sc1
	global_load_dwordx4 v[68:71], v[0:1], off offset:64 sc1
	global_load_dwordx4 v[64:67], v[0:1], off offset:96 sc1
	v_lshl_add_u64 v[0:1], s[70:71], 0, v[108:109]
	v_lshlrev_b32_e32 v116, 1, v106
	v_lshl_add_u64 v[0:1], v[0:1], 0, v[116:117]
	v_lshl_add_u64 v[4:5], s[72:73], 0, v[110:111]
	global_load_dwordx4 v[0:3], v[0:1], off sc1
	v_lshl_add_u64 v[4:5], v[4:5], 0, v[116:117]
	v_lshl_add_u64 v[8:9], s[70:71], 0, v[114:115]
	v_lshl_add_u64 v[12:13], s[72:73], 0, v[128:129]
	global_load_dwordx4 v[4:7], v[4:5], off sc1
	v_lshl_add_u64 v[8:9], v[8:9], 0, v[116:117]
	v_lshl_add_u64 v[12:13], v[12:13], 0, v[116:117]
	global_load_dwordx4 v[8:11], v[8:9], off sc1
	s_lshl_b32 s69, s67, 4
	global_load_dwordx4 v[12:15], v[12:13], off sc1
	s_and_b32 s69, s69, 0x80
	s_or_b32 s8, s8, s69
	v_mov_b32_e32 v155, 0
	s_mov_b32 s30, 0
	v_lshl_add_u64 v[150:151], v[140:141], 0, s[8:9]
	v_lshl_add_u64 v[152:153], v[142:143], 0, s[10:11]
	v_mov_b32_e32 v168, 0xf149f2ca
	v_mov_b32_e32 v16, 0
	v_mov_b32_e32 v17, v155
	v_mov_b32_e32 v18, v155
	v_mov_b32_e32 v19, v155
	v_mov_b32_e32 v20, v155
	v_mov_b32_e32 v21, v155
	v_mov_b32_e32 v22, v155
	v_mov_b32_e32 v23, v155
	v_mov_b32_e32 v24, v155
	v_mov_b32_e32 v25, v155
	v_mov_b32_e32 v26, v155
	v_mov_b32_e32 v27, v155
	v_mov_b32_e32 v28, v155
	v_mov_b32_e32 v29, v155
	v_mov_b32_e32 v30, v155
	v_mov_b32_e32 v31, v155
	s_waitcnt vmcnt(0)
	ds_write_b128 v113, v[0:3]
	v_add_u32_e32 v0, 0x2400, v159
	ds_write2_b64 v0, v[4:5], v[6:7] offset1:1
	ds_write_b128 v113, v[8:11] offset:4608
	v_add_u32_e32 v0, 0x3500, v159
	v_and_b32_e32 v1, 64, v213
	ds_write2_b64 v0, v[12:13], v[14:15] offset1:1
	v_xor_b32_e32 v0, 32, v213
	v_add_u32_e32 v1, 64, v1
	v_cmp_lt_i32_e32 vcc, v0, v1
	v_mov_b32_e32 v1, v155
	v_mov_b32_e32 v2, v155
	v_cndmask_b32_e32 v0, v213, v0, vcc
	v_lshlrev_b32_e32 v149, 2, v0
	v_mov_b32_e32 v0, 0
	v_mov_b32_e32 v3, v155
	v_mov_b32_e32 v4, v155
	v_mov_b32_e32 v5, v155
	v_mov_b32_e32 v6, v155
	v_mov_b32_e32 v7, v155
	v_mov_b32_e32 v8, v155
	v_mov_b32_e32 v9, v155
	v_mov_b32_e32 v10, v155
	v_mov_b32_e32 v11, v155
	v_mov_b32_e32 v12, v155
	v_mov_b32_e32 v13, v155
	v_mov_b32_e32 v14, v155
	v_mov_b32_e32 v15, v155
	s_waitcnt lgkmcnt(0)
	s_barrier
.LBB0_232:
	v_lshl_add_u64 v[32:33], v[150:151], 0, v[138:139]
	s_mov_b32 s9, 0x132d2000
	v_add_co_u32_e32 v34, vcc, s9, v32
	s_mov_b32 s9, 0x13ace000
	s_nop 0
	v_addc_co_u32_e32 v35, vcc, 0, v33, vcc
	global_load_dwordx4 v[80:83], v[34:35], off sc1
	v_lshl_add_u64 v[34:35], v[152:153], 0, v[138:139]
	v_add_co_u32_e32 v36, vcc, s9, v34
	s_mov_b32 s9, 0x132d4000
	s_nop 0
	v_addc_co_u32_e32 v37, vcc, 0, v35, vcc
	v_add_co_u32_e32 v32, vcc, s9, v32
	s_and_b32 s8, s30, 1
	s_nop 0
	v_addc_co_u32_e32 v33, vcc, 0, v33, vcc
	s_mov_b32 s9, 0x13ad2000
	global_load_dwordx4 v[88:91], v[32:33], off sc1
	v_add_co_u32_e32 v32, vcc, s9, v34
	s_mul_i32 s9, s8, 0x4600
	v_or_b32_e32 v170, s9, v163
	v_mov_b32_e32 v169, v155
	v_addc_co_u32_e32 v33, vcc, 0, v35, vcc
	v_add_u32_e32 v155, v170, v161
	global_load_dwordx4 v[84:87], v[36:37], off offset:128 sc1
	global_load_dwordx4 v[92:95], v[32:33], off offset:128 sc1
	ds_read_b128 v[32:35], v155
	ds_read_b128 v[36:39], v155 offset:32
	s_waitcnt lgkmcnt(1)
	v_mfma_f32_32x32x16_bf16 v[48:63], v[32:35], v[76:79], 0
	ds_read_b128 v[32:35], v155 offset:64
	ds_read_b128 v[172:175], v155 offset:4640
	v_mov_b32_e32 v154, v168
	s_xor_b32 s8, s8, 1
	s_mulk_i32 s8, 0x4600
	s_add_i32 s30, s30, 1
	v_lshl_add_u64 v[150:151], v[150:151], 0, s[28:29]
	s_waitcnt lgkmcnt(2)
	v_mfma_f32_32x32x16_bf16 v[48:63], v[36:39], v[72:75], v[48:63]
	v_lshl_add_u64 v[152:153], v[152:153], 0, s[24:25]
	s_cmp_lg_u32 s30, 3
	s_waitcnt lgkmcnt(1)
	v_mfma_f32_32x32x16_bf16 v[48:63], v[32:35], v[68:71], v[48:63]
	ds_read_b128 v[32:35], v155 offset:96
	s_waitcnt lgkmcnt(0)
	v_mfma_f32_32x32x16_bf16 v[48:63], v[32:35], v[64:67], v[48:63]
	ds_read_b128 v[32:35], v155 offset:4608
	s_waitcnt lgkmcnt(0)
	v_mfma_f32_32x32x16_bf16 v[32:47], v[32:35], v[76:79], 0
	s_nop 8
	v_max_f32_e32 v168, v48, v48
	v_mfma_f32_32x32x16_bf16 v[32:47], v[172:175], v[72:75], v[32:47]
	ds_read_b128 v[172:175], v155 offset:4672
	s_waitcnt lgkmcnt(0)
	v_mfma_f32_32x32x16_bf16 v[32:47], v[172:175], v[68:71], v[32:47]
	ds_read_b128 v[172:175], v155 offset:4704
	v_max_f32_e32 v155, v49, v49
	v_max_f32_e32 v155, v168, v155
	v_max3_f32 v155, v155, v50, v51
	v_max3_f32 v155, v155, v52, v53
	v_max3_f32 v155, v155, v54, v55
	v_max3_f32 v155, v155, v56, v57
	s_waitcnt lgkmcnt(0)
	v_mfma_f32_32x32x16_bf16 v[32:47], v[172:175], v[64:67], v[32:47]
	v_max3_f32 v155, v155, v58, v59
	v_max3_f32 v155, v155, v60, v61
	v_max3_f32 v155, v155, v62, v63
	s_nop 8
	v_max3_f32 v155, v155, v32, v33
	v_max3_f32 v155, v155, v34, v35
	v_max3_f32 v155, v155, v36, v37
	v_max3_f32 v155, v155, v38, v39
	v_max3_f32 v155, v155, v40, v41
	v_max3_f32 v155, v155, v42, v43
	v_max3_f32 v155, v155, v44, v45
	v_max3_f32 v155, v155, v46, v47
	ds_bpermute_b32 v168, v149, v155
	s_waitcnt lgkmcnt(0)
	v_max3_f32 v168, v154, v155, v168
	v_sub_f32_e32 v48, v48, v168
	v_exp_f32_e32 v171, v48
	v_sub_f32_e32 v49, v49, v168
	v_exp_f32_e32 v172, v49
	v_sub_f32_e32 v49, v50, v168
	v_exp_f32_e32 v173, v49
	v_sub_f32_e32 v49, v51, v168
	v_exp_f32_e32 v174, v49
	v_sub_f32_e32 v49, v52, v168
	v_add_f32_e32 v48, 0, v171
	v_exp_f32_e32 v175, v49
	v_sub_f32_e32 v49, v53, v168
	v_add_f32_e32 v48, v172, v48
	v_exp_f32_e32 v176, v49
	v_sub_f32_e32 v49, v54, v168
	v_add_f32_e32 v48, v173, v48
	v_exp_f32_e32 v177, v49
	v_sub_f32_e32 v49, v55, v168
	v_add_f32_e32 v48, v174, v48
	v_exp_f32_e32 v178, v49
	v_add_f32_e32 v48, v175, v48
	v_add_f32_e32 v48, v176, v48
	v_add_f32_e32 v48, v177, v48
	v_add_f32_e32 v49, v178, v48
	v_sub_f32_e32 v48, v56, v168
	v_exp_f32_e32 v48, v48
	v_sub_f32_e32 v56, v63, v168
	v_exp_f32_e32 v56, v56
	v_sub_f32_e32 v32, v32, v168
	v_add_f32_e32 v50, v48, v49
	v_sub_f32_e32 v49, v57, v168
	v_exp_f32_e32 v49, v49
	v_sub_f32_e32 v154, v154, v168
	v_exp_f32_e32 v154, v154
	v_add_f32_e32 v51, v49, v50
	v_sub_f32_e32 v50, v58, v168
	v_exp_f32_e32 v50, v50
	v_pk_mul_f32 v[30:31], v[30:31], v[154:155] op_sel_hi:[1,0]
	v_pk_mul_f32 v[28:29], v[28:29], v[154:155] op_sel_hi:[1,0]
	v_pk_mul_f32 v[26:27], v[26:27], v[154:155] op_sel_hi:[1,0]
	v_add_f32_e32 v52, v50, v51
	v_sub_f32_e32 v51, v59, v168
	v_exp_f32_e32 v51, v51
	v_pk_mul_f32 v[24:25], v[24:25], v[154:155] op_sel_hi:[1,0]
	v_pk_mul_f32 v[22:23], v[22:23], v[154:155] op_sel_hi:[1,0]
	v_pk_mul_f32 v[20:21], v[20:21], v[154:155] op_sel_hi:[1,0]
	v_add_f32_e32 v53, v51, v52
	v_sub_f32_e32 v52, v60, v168
	v_exp_f32_e32 v52, v52
	v_pk_mul_f32 v[18:19], v[18:19], v[154:155] op_sel_hi:[1,0]
	v_pk_mul_f32 v[16:17], v[16:17], v[154:155] op_sel_hi:[1,0]
	v_pk_mul_f32 v[14:15], v[14:15], v[154:155] op_sel_hi:[1,0]
	v_add_f32_e32 v54, v52, v53
	v_sub_f32_e32 v53, v61, v168
	v_exp_f32_e32 v53, v53
	v_pk_mul_f32 v[12:13], v[12:13], v[154:155] op_sel_hi:[1,0]
	v_pk_mul_f32 v[10:11], v[10:11], v[154:155] op_sel_hi:[1,0]
	v_pk_mul_f32 v[8:9], v[8:9], v[154:155] op_sel_hi:[1,0]
	v_add_f32_e32 v55, v53, v54
	v_sub_f32_e32 v54, v62, v168
	v_exp_f32_e32 v54, v54
	v_pk_mul_f32 v[6:7], v[6:7], v[154:155] op_sel_hi:[1,0]
	v_pk_mul_f32 v[4:5], v[4:5], v[154:155] op_sel_hi:[1,0]
	v_pk_mul_f32 v[2:3], v[2:3], v[154:155] op_sel_hi:[1,0]
	v_add_f32_e32 v55, v54, v55
	v_add_f32_e32 v62, v56, v55
	v_exp_f32_e32 v55, v32
	v_sub_f32_e32 v32, v33, v168
	v_exp_f32_e32 v57, v32
	v_sub_f32_e32 v32, v34, v168
	v_exp_f32_e32 v58, v32
	v_sub_f32_e32 v32, v35, v168
	v_exp_f32_e32 v59, v32
	v_sub_f32_e32 v32, v36, v168
	v_exp_f32_e32 v36, v32
	v_sub_f32_e32 v32, v37, v168
	v_exp_f32_e32 v37, v32
	v_sub_f32_e32 v32, v38, v168
	v_exp_f32_e32 v60, v32
	v_sub_f32_e32 v32, v39, v168
	v_exp_f32_e32 v61, v32
	v_sub_f32_e32 v32, v40, v168
	v_exp_f32_e32 v38, v32
	v_sub_f32_e32 v32, v41, v168
	v_exp_f32_e32 v39, v32
	v_sub_f32_e32 v32, v42, v168
	v_exp_f32_e32 v40, v32
	v_sub_f32_e32 v32, v43, v168
	v_exp_f32_e32 v41, v32
	v_sub_f32_e32 v32, v44, v168
	v_exp_f32_e32 v42, v32
	v_sub_f32_e32 v32, v45, v168
	v_exp_f32_e32 v43, v32
	v_sub_f32_e32 v32, v46, v168
	v_exp_f32_e32 v44, v32
	v_sub_f32_e32 v32, v47, v168
	v_exp_f32_e32 v45, v32
	v_add_f32_e32 v32, v55, v62
	v_add_f32_e32 v32, v57, v32
	v_add_f32_e32 v32, v58, v32
	v_add_f32_e32 v32, v59, v32
	v_add_f32_e32 v32, v36, v32
	v_add_f32_e32 v32, v37, v32
	v_add_f32_e32 v32, v60, v32
	v_add_f32_e32 v32, v61, v32
	v_add_f32_e32 v32, v38, v32
	v_add_f32_e32 v32, v39, v32
	v_add_f32_e32 v32, v40, v32
	v_add_f32_e32 v32, v41, v32
	v_add_f32_e32 v32, v42, v32
	v_lshlrev_b32_e32 v46, 1, v160
	v_add_f32_e32 v32, v43, v32
	v_add3_u32 v46, v170, v164, v46
	v_add_f32_e32 v32, v44, v32
	v_add_u32_e32 v62, 0x2000, v46
	v_pk_mul_f32 v[0:1], v[0:1], v[154:155] op_sel_hi:[1,0]
	v_add_f32_e32 v155, v45, v32
	v_cvt_pk_bf16_f32 v32, v171, v172
	v_cvt_pk_bf16_f32 v33, v173, v174
	v_cvt_pk_bf16_f32 v34, v175, v176
	v_cvt_pk_bf16_f32 v35, v177, v178
	ds_read2_b64 v[170:173], v62 offset0:128 offset1:130
	ds_read2_b64 v[174:177], v62 offset0:132 offset1:134
	v_add_u32_e32 v63, 0x3000, v46
	s_waitcnt lgkmcnt(1)
	v_mfma_f32_32x32x16_bf16 v[16:31], v[170:173], v[32:35], v[16:31]
	ds_read2_b64 v[170:173], v63 offset0:160 offset1:162
	v_fmac_f32_e32 v155, v169, v154
	s_waitcnt lgkmcnt(0)
	v_mfma_f32_32x32x16_bf16 v[0:15], v[170:173], v[32:35], v[0:15]
	v_cvt_pk_bf16_f32 v32, v48, v49
	ds_read2_b64 v[46:49], v63 offset0:164 offset1:166
	v_cvt_pk_bf16_f32 v33, v50, v51
	v_cvt_pk_bf16_f32 v34, v52, v53
	v_cvt_pk_bf16_f32 v35, v54, v56
	s_waitcnt lgkmcnt(0)
	s_nop 0
	v_mfma_f32_32x32x16_bf16 v[0:15], v[46:49], v[32:35], v[0:15]
	ds_read2_b64 v[46:49], v62 offset0:136 offset1:138
	v_mfma_f32_32x32x16_bf16 v[16:31], v[174:177], v[32:35], v[16:31]
	v_cvt_pk_bf16_f32 v32, v55, v57
	v_cvt_pk_bf16_f32 v33, v58, v59
	v_cvt_pk_bf16_f32 v34, v36, v37
	v_cvt_pk_bf16_f32 v35, v60, v61
	s_waitcnt lgkmcnt(0)
	s_nop 0
	v_mfma_f32_32x32x16_bf16 v[16:31], v[46:49], v[32:35], v[16:31]
	ds_read2_b64 v[46:49], v63 offset0:168 offset1:170
	s_waitcnt lgkmcnt(0)
	v_mfma_f32_32x32x16_bf16 v[0:15], v[46:49], v[32:35], v[0:15]
	v_cvt_pk_bf16_f32 v32, v38, v39
	ds_read2_b64 v[36:39], v62 offset0:140 offset1:142
	v_cvt_pk_bf16_f32 v33, v40, v41
	v_cvt_pk_bf16_f32 v34, v42, v43
	v_cvt_pk_bf16_f32 v35, v44, v45
	s_waitcnt lgkmcnt(0)
	s_nop 0
	v_mfma_f32_32x32x16_bf16 v[16:31], v[36:39], v[32:35], v[16:31]
	ds_read2_b64 v[36:39], v63 offset0:172 offset1:174
	s_waitcnt lgkmcnt(0)
	v_mfma_f32_32x32x16_bf16 v[0:15], v[36:39], v[32:35], v[0:15]
	v_add3_u32 v32, v105, s8, v116
	v_add_u32_e32 v33, v32, v158
	v_add_u32_e32 v34, 0x2400, v33
	s_waitcnt vmcnt(3)
	ds_write_b128 v32, v[80:83]
	s_waitcnt vmcnt(1)
	ds_write2_b64 v34, v[84:85], v[86:87] offset1:1
	ds_write_b128 v32, v[88:91] offset:4608
	v_add_u32_e32 v32, 0x3500, v33
	s_waitcnt vmcnt(0)
	ds_write2_b64 v32, v[92:93], v[94:95] offset1:1
	s_waitcnt lgkmcnt(0)
	s_barrier
	s_cbranch_scc1 .LBB0_232
	v_add_u32_e32 v80, v163, v161
	ds_read_b128 v[32:35], v80 offset:17920
	ds_read_b128 v[36:39], v80 offset:17952
	v_add_u32_e32 v82, 0x6800, v166
	s_lshl_b32 s30, s68, 14
	s_waitcnt lgkmcnt(1)
	v_mfma_f32_32x32x16_bf16 v[48:63], v[32:35], v[76:79], 0
	ds_read_b128 v[32:35], v80 offset:17984
	s_waitcnt lgkmcnt(1)
	v_mfma_f32_32x32x16_bf16 v[48:63], v[36:39], v[72:75], v[48:63]
	s_waitcnt lgkmcnt(0)
	v_mfma_f32_32x32x16_bf16 v[48:63], v[32:35], v[68:71], v[48:63]
	ds_read_b128 v[32:35], v80 offset:18016
	s_waitcnt lgkmcnt(0)
	v_mfma_f32_32x32x16_bf16 v[48:63], v[32:35], v[64:67], v[48:63]
	ds_read_b128 v[32:35], v80 offset:22528
	s_waitcnt lgkmcnt(0)
	v_mfma_f32_32x32x16_bf16 v[32:47], v[32:35], v[76:79], 0
	ds_read_b128 v[76:79], v80 offset:22560
	s_waitcnt lgkmcnt(0)
	v_mfma_f32_32x32x16_bf16 v[32:47], v[76:79], v[72:75], v[32:47]
	ds_read_b128 v[72:75], v80 offset:22592
	s_waitcnt lgkmcnt(0)
	v_mfma_f32_32x32x16_bf16 v[32:47], v[72:75], v[68:71], v[32:47]
	ds_read_b128 v[68:71], v80 offset:22624
	s_waitcnt lgkmcnt(0)
	v_mfma_f32_32x32x16_bf16 v[32:47], v[68:71], v[64:67], v[32:47]
	v_max_f32_e32 v64, v49, v49
	v_max_f32_e32 v65, v48, v48
	v_max_f32_e32 v64, v65, v64
	v_max3_f32 v64, v64, v50, v51
	v_max3_f32 v64, v64, v52, v53
	v_max3_f32 v64, v64, v54, v55
	v_max3_f32 v64, v64, v56, v57
	v_max3_f32 v64, v64, v58, v59
	v_max3_f32 v64, v64, v60, v61
	v_max3_f32 v64, v64, v62, v63
	s_nop 1
	v_max3_f32 v64, v64, v32, v33
	v_max3_f32 v64, v64, v34, v35
	v_max3_f32 v64, v64, v36, v37
	v_max3_f32 v64, v64, v38, v39
	v_max3_f32 v64, v64, v40, v41
	v_max3_f32 v64, v64, v42, v43
	v_max3_f32 v64, v64, v44, v45
	v_max3_f32 v64, v64, v46, v47
	ds_bpermute_b32 v65, v149, v64
	s_waitcnt lgkmcnt(0)
	v_max3_f32 v65, v168, v64, v65
	v_sub_f32_e32 v64, v168, v65
	v_exp_f32_e32 v64, v64
	v_sub_f32_e32 v48, v48, v65
	v_sub_f32_e32 v49, v49, v65
	v_exp_f32_e32 v48, v48
	v_exp_f32_e32 v49, v49
	v_sub_f32_e32 v50, v50, v65
	v_exp_f32_e32 v50, v50
	v_sub_f32_e32 v51, v51, v65
	v_sub_f32_e32 v52, v52, v65
	v_sub_f32_e32 v53, v53, v65
	v_sub_f32_e32 v54, v54, v65
	v_sub_f32_e32 v55, v55, v65
	v_exp_f32_e32 v51, v51
	v_exp_f32_e32 v52, v52
	v_exp_f32_e32 v53, v53
	v_exp_f32_e32 v54, v54
	v_exp_f32_e32 v55, v55
	v_sub_f32_e32 v56, v56, v65
	v_sub_f32_e32 v57, v57, v65
	v_sub_f32_e32 v58, v58, v65
	v_sub_f32_e32 v59, v59, v65
	v_sub_f32_e32 v60, v60, v65
	v_sub_f32_e32 v61, v61, v65
	v_sub_f32_e32 v62, v62, v65
	v_sub_f32_e32 v63, v63, v65
	v_sub_f32_e32 v32, v32, v65
	v_sub_f32_e32 v33, v33, v65
	v_sub_f32_e32 v34, v34, v65
	v_sub_f32_e32 v35, v35, v65
	v_sub_f32_e32 v36, v36, v65
	v_sub_f32_e32 v37, v37, v65
	v_sub_f32_e32 v38, v38, v65
	v_sub_f32_e32 v39, v39, v65
	v_sub_f32_e32 v40, v40, v65
	v_sub_f32_e32 v41, v41, v65
	v_sub_f32_e32 v42, v42, v65
	v_sub_f32_e32 v43, v43, v65
	v_sub_f32_e32 v44, v44, v65
	v_sub_f32_e32 v45, v45, v65
	v_sub_f32_e32 v46, v46, v65
	v_sub_f32_e32 v47, v47, v65
	v_pk_mul_f32 v[30:31], v[30:31], v[64:65] op_sel_hi:[1,0]
	v_pk_mul_f32 v[28:29], v[28:29], v[64:65] op_sel_hi:[1,0]
	v_pk_mul_f32 v[26:27], v[26:27], v[64:65] op_sel_hi:[1,0]
	v_pk_mul_f32 v[24:25], v[24:25], v[64:65] op_sel_hi:[1,0]
	v_pk_mul_f32 v[22:23], v[22:23], v[64:65] op_sel_hi:[1,0]
	v_pk_mul_f32 v[20:21], v[20:21], v[64:65] op_sel_hi:[1,0]
	v_pk_mul_f32 v[18:19], v[18:19], v[64:65] op_sel_hi:[1,0]
	v_pk_mul_f32 v[16:17], v[16:17], v[64:65] op_sel_hi:[1,0]
	v_pk_mul_f32 v[14:15], v[14:15], v[64:65] op_sel_hi:[1,0]
	v_pk_mul_f32 v[12:13], v[12:13], v[64:65] op_sel_hi:[1,0]
	v_pk_mul_f32 v[10:11], v[10:11], v[64:65] op_sel_hi:[1,0]
	v_pk_mul_f32 v[8:9], v[8:9], v[64:65] op_sel_hi:[1,0]
	v_pk_mul_f32 v[6:7], v[6:7], v[64:65] op_sel_hi:[1,0]
	v_pk_mul_f32 v[4:5], v[4:5], v[64:65] op_sel_hi:[1,0]
	v_pk_mul_f32 v[2:3], v[2:3], v[64:65] op_sel_hi:[1,0]
	v_pk_mul_f32 v[0:1], v[0:1], v[64:65] op_sel_hi:[1,0]
	v_add_u32_e32 v65, 0x6800, v165
	v_cvt_pk_bf16_f32 v66, v48, v49
	ds_read2_b64 v[70:73], v65 offset0:64 offset1:66
	ds_read2_b64 v[74:77], v65 offset0:68 offset1:70
	v_add_f32_e32 v48, 0, v48
	v_add_f32_e32 v48, v49, v48
	v_add_f32_e32 v48, v50, v48
	v_cvt_pk_bf16_f32 v67, v50, v51
	v_cvt_pk_bf16_f32 v68, v52, v53
	v_cvt_pk_bf16_f32 v69, v54, v55
	v_add_f32_e32 v48, v51, v48
	v_exp_f32_e32 v56, v56
	s_waitcnt lgkmcnt(1)
	v_mfma_f32_32x32x16_bf16 v[16:31], v[70:73], v[66:69], v[16:31]
	ds_read2_b64 v[70:73], v82 offset0:64 offset1:66
	ds_read2_b64 v[78:81], v82 offset0:68 offset1:70
	v_add_f32_e32 v48, v52, v48
	v_exp_f32_e32 v57, v57
	v_add_f32_e32 v48, v53, v48
	v_exp_f32_e32 v58, v58
	v_add_f32_e32 v48, v54, v48
	v_exp_f32_e32 v59, v59
	v_add_f32_e32 v48, v55, v48
	v_exp_f32_e32 v60, v60
	v_exp_f32_e32 v61, v61
	v_exp_f32_e32 v62, v62
	v_exp_f32_e32 v63, v63
	s_waitcnt lgkmcnt(1)
	v_mfma_f32_32x32x16_bf16 v[0:15], v[70:73], v[66:69], v[0:15]
	v_add_f32_e32 v48, v56, v48
	v_add_f32_e32 v48, v57, v48
	v_add_f32_e32 v48, v58, v48
	v_add_f32_e32 v48, v59, v48
	v_exp_f32_e32 v32, v32
	v_exp_f32_e32 v33, v33
	v_cvt_pk_bf16_f32 v66, v56, v57
	v_cvt_pk_bf16_f32 v67, v58, v59
	v_cvt_pk_bf16_f32 v68, v60, v61
	v_cvt_pk_bf16_f32 v69, v62, v63
	ds_read2_b64 v[70:73], v65 offset0:72 offset1:74
	v_add_f32_e32 v48, v60, v48
	v_mfma_f32_32x32x16_bf16 v[16:31], v[74:77], v[66:69], v[16:31]
	v_add_f32_e32 v48, v61, v48
	v_exp_f32_e32 v34, v34
	v_add_f32_e32 v48, v62, v48
	v_exp_f32_e32 v35, v35
	v_add_f32_e32 v48, v63, v48
	v_exp_f32_e32 v36, v36
	v_exp_f32_e32 v37, v37
	v_exp_f32_e32 v38, v38
	v_exp_f32_e32 v39, v39
	s_waitcnt lgkmcnt(1)
	v_mfma_f32_32x32x16_bf16 v[0:15], v[78:81], v[66:69], v[0:15]
	v_cvt_pk_bf16_f32 v66, v32, v33
	v_add_f32_e32 v32, v32, v48
	v_add_f32_e32 v32, v33, v32
	v_add_f32_e32 v32, v34, v32
	v_add_f32_e32 v32, v35, v32
	v_exp_f32_e32 v40, v40
	v_cvt_pk_bf16_f32 v67, v34, v35
	v_cvt_pk_bf16_f32 v68, v36, v37
	v_cvt_pk_bf16_f32 v69, v38, v39
	v_add_f32_e32 v32, v36, v32
	v_exp_f32_e32 v41, v41
	s_waitcnt lgkmcnt(0)
	v_mfma_f32_32x32x16_bf16 v[16:31], v[70:73], v[66:69], v[16:31]
	ds_read2_b64 v[70:73], v82 offset0:72 offset1:74
	v_add_f32_e32 v32, v37, v32
	v_exp_f32_e32 v42, v42
	v_add_f32_e32 v32, v38, v32
	v_exp_f32_e32 v43, v43
	v_add_f32_e32 v32, v39, v32
	v_exp_f32_e32 v44, v44
	v_add_f32_e32 v32, v40, v32
	v_exp_f32_e32 v45, v45
	v_add_f32_e32 v32, v41, v32
	v_exp_f32_e32 v46, v46
	v_add_f32_e32 v32, v42, v32
	v_exp_f32_e32 v47, v47
	v_add_f32_e32 v32, v43, v32
	v_add_f32_e32 v32, v44, v32
	v_add_f32_e32 v32, v45, v32
	s_waitcnt lgkmcnt(0)
	v_mfma_f32_32x32x16_bf16 v[0:15], v[70:73], v[66:69], v[0:15]
	ds_read2_b64 v[70:73], v65 offset0:76 offset1:78
	v_add_f32_e32 v32, v46, v32
	v_add_f32_e32 v32, v47, v32
	v_fmac_f32_e32 v32, v155, v64
	ds_bpermute_b32 v33, v149, v32
	v_cvt_pk_bf16_f32 v66, v40, v41
	v_cvt_pk_bf16_f32 v67, v42, v43
	v_cvt_pk_bf16_f32 v68, v44, v45
	v_cvt_pk_bf16_f32 v69, v46, v47
	s_waitcnt lgkmcnt(0)
	v_add_f32_e32 v32, v32, v33
	v_div_scale_f32 v33, s[8:9], v32, v32, 1.0
	v_mfma_f32_32x32x16_bf16 v[16:31], v[70:73], v[66:69], v[16:31]
	ds_read2_b64 v[70:73], v82 offset0:76 offset1:78
	v_rcp_f32_e32 v34, v33
	s_movk_i32 s8, 0x2000
	s_waitcnt lgkmcnt(0)
	s_barrier
	v_fma_f32 v35, -v33, v34, 1.0
	v_fmac_f32_e32 v34, v35, v34
	v_div_scale_f32 v35, vcc, 1.0, v32, 1.0
	v_mul_f32_e32 v36, v35, v34
	v_fma_f32 v37, -v33, v36, v35
	v_mfma_f32_32x32x16_bf16 v[0:15], v[70:73], v[66:69], v[0:15]
	v_fmac_f32_e32 v36, v37, v34
	v_fma_f32 v33, -v33, v36, v35
	v_div_fmas_f32 v33, v33, v34, v36
	v_ashrrev_i32_e32 v34, 7, v147
	v_ashrrev_i32_e32 v35, 31, v34
	v_lshlrev_b64 v[34:35], 19, v[34:35]
	v_div_fixup_f32 v32, v33, v32, 1.0
	v_lshl_add_u64 v[34:35], s[0:1], 0, v[34:35]
	v_lshlrev_b32_e32 v33, 6, v148
	v_lshl_add_u64 v[34:35], v[34:35], 0, s[30:31]
	v_and_b32_e32 v116, 0x1fc0, v33
	v_lshl_add_u64 v[34:35], v[34:35], 0, v[116:117]
	v_lshlrev_b32_e32 v116, 1, v122
	v_lshl_add_u64 v[34:35], v[34:35], 0, v[116:117]
	v_pk_mul_f32 v[0:1], v[0:1], v[32:33] op_sel_hi:[1,0]
	v_pk_mul_f32 v[2:3], v[2:3], v[32:33] op_sel_hi:[1,0]
	v_pk_mul_f32 v[16:17], v[16:17], v[32:33] op_sel_hi:[1,0]
	v_pk_mul_f32 v[18:19], v[18:19], v[32:33] op_sel_hi:[1,0]
	v_cvt_pk_bf16_f32 v0, v0, v1
	v_cvt_pk_bf16_f32 v1, v2, v3
	v_add_co_u32_e32 v2, vcc, s8, v34
	v_cvt_pk_bf16_f32 v16, v16, v17
	v_cvt_pk_bf16_f32 v17, v18, v19
	v_addc_co_u32_e32 v3, vcc, 0, v35, vcc
	global_store_dwordx2 v[34:35], v[16:17], off
	v_pk_mul_f32 v[16:17], v[20:21], v[32:33] op_sel_hi:[1,0]
	v_pk_mul_f32 v[18:19], v[22:23], v[32:33] op_sel_hi:[1,0]
	global_store_dwordx2 v[2:3], v[0:1], off
	v_pk_mul_f32 v[0:1], v[4:5], v[32:33] op_sel_hi:[1,0]
	v_pk_mul_f32 v[4:5], v[6:7], v[32:33] op_sel_hi:[1,0]
	v_cvt_pk_bf16_f32 v16, v16, v17
	v_cvt_pk_bf16_f32 v17, v18, v19
	v_cvt_pk_bf16_f32 v0, v0, v1
	v_cvt_pk_bf16_f32 v1, v4, v5
	global_store_dwordx2 v[34:35], v[16:17], off offset:16
	v_pk_mul_f32 v[16:17], v[24:25], v[32:33] op_sel_hi:[1,0]
	v_pk_mul_f32 v[18:19], v[26:27], v[32:33] op_sel_hi:[1,0]
	global_store_dwordx2 v[2:3], v[0:1], off offset:16
	v_pk_mul_f32 v[0:1], v[8:9], v[32:33] op_sel_hi:[1,0]
	v_pk_mul_f32 v[4:5], v[10:11], v[32:33] op_sel_hi:[1,0]
	v_cvt_pk_bf16_f32 v16, v16, v17
	v_cvt_pk_bf16_f32 v17, v18, v19
	v_cvt_pk_bf16_f32 v0, v0, v1
	v_cvt_pk_bf16_f32 v1, v4, v5
	global_store_dwordx2 v[34:35], v[16:17], off offset:32
	v_pk_mul_f32 v[16:17], v[28:29], v[32:33] op_sel_hi:[1,0]
	v_pk_mul_f32 v[18:19], v[30:31], v[32:33] op_sel_hi:[1,0]
	global_store_dwordx2 v[2:3], v[0:1], off offset:32
	v_pk_mul_f32 v[0:1], v[12:13], v[32:33] op_sel_hi:[1,0]
	v_pk_mul_f32 v[4:5], v[14:15], v[32:33] op_sel_hi:[1,0]
	v_cvt_pk_bf16_f32 v16, v16, v17
	v_cvt_pk_bf16_f32 v17, v18, v19
	v_cvt_pk_bf16_f32 v0, v0, v1
	v_cvt_pk_bf16_f32 v1, v4, v5
	global_store_dwordx2 v[34:35], v[16:17], off offset:48
	global_store_dwordx2 v[2:3], v[0:1], off offset:48

.LBB0_235:
	s_andn2_b64 vcc, exec, s[8:9]
	s_cbranch_vccnz .LBB0_248
	s_add_i32 s8, s67, 0xffffff80
	s_lshr_b32 s8, s8, 6
	s_lshl_b32 s11, s67, 7
	s_lshl_b32 s9, s8, 10
	s_and_b32 s69, s11, 0x380
	s_add_i32 s11, s8, s16
	s_or_b32 s9, s9, s69
	s_mul_i32 s30, s11, 0x600
	s_bfe_u32 s10, s67, 0x30003
	v_add_u32_e32 v147, s9, v162
	s_lshl_b64 s[8:9], s[30:31], 8
	s_add_u32 s8, s41, s8
	s_addc_u32 s9, s42, s9
	s_lshl_b32 s30, s67, 1
	s_and_b32 s30, s30, 64
	s_lshl_b32 s68, s30, 1
	s_add_u32 s8, s8, s68
	s_addc_u32 s9, s9, 0
	s_lshl_b32 s11, s11, 7
	v_or_b32_e32 v148, v147, v98
	s_or_b32 s11, s11, s30
	s_mul_hi_i32 s30, s11, 0xc00
	s_mulk_i32 s11, 0xc00
	v_ashrrev_i32_e32 v149, 31, v148
	s_add_u32 s70, s43, s11
	v_lshlrev_b64 v[0:1], 10, v[148:149]
	s_addc_u32 s71, s80, s30
	v_lshl_add_u64 v[0:1], s[36:37], 0, v[0:1]
	s_lshl_b32 s30, s10, 7
	v_lshl_add_u64 v[0:1], v[0:1], 0, s[30:31]
	v_lshlrev_b32_e32 v116, 1, v102
	v_lshl_add_u64 v[0:1], v[0:1], 0, v[116:117]
	v_lshl_add_u64 v[2:3], s[8:9], 0, v[108:109]
	v_lshlrev_b32_e32 v116, 1, v106
	v_lshl_add_u64 v[4:5], s[70:71], 0, v[130:131]
	v_lshl_add_u64 v[2:3], v[2:3], 0, v[116:117]
	v_lshl_add_u64 v[150:151], v[4:5], 0, v[116:117]
	v_lshl_add_u64 v[4:5], s[8:9], 0, v[114:115]
	global_load_dwordx4 v[80:83], v[150:151], off sc1
	v_lshl_add_u64 v[4:5], v[4:5], 0, v[116:117]
	global_load_dwordx4 v[84:87], v[2:3], off sc1
	global_load_dwordx4 v[88:91], v[4:5], off sc1
	v_lshl_add_u64 v[2:3], s[70:71], 0, v[132:133]
	v_lshl_add_u64 v[152:153], v[2:3], 0, v[116:117]
	global_load_dwordx4 v[92:95], v[152:153], off sc1
	global_load_dwordx4 v[64:67], v[0:1], off sc1
	global_load_dwordx4 v[68:71], v[0:1], off offset:32 sc1
	global_load_dwordx4 v[72:75], v[0:1], off offset:64 sc1
	global_load_dwordx4 v[76:79], v[0:1], off offset:96 sc1
	v_and_b32_e32 v2, 64, v213
	v_add_u32_e32 v168, 64, v2
	v_mov_b32_e32 v2, 0x80
	v_sub_u32_e64 v2, s69, v2 clamp
	s_min_u32 s30, s69, 0x300
	v_readfirstlane_b32 s11, v2
	s_addk_i32 s30, 0x100
	s_lshr_b32 s11, s11, 6
	s_lshr_b32 s30, s30, 6
	s_sub_i32 s68, s30, s11
	v_xor_b32_e32 v149, 32, v213
	s_add_i32 s68, s68, 8
	s_cmp_eq_u32 s68, 0
	v_cmp_lt_i32_e32 vcc, v149, v168
	v_add_u32_e32 v0, 0x2400, v159
	v_add_u32_e32 v1, 0x3500, v159
	s_waitcnt vmcnt(0)
	ds_write_b128 v113, v[84:87]
	ds_write2_b64 v0, v[80:81], v[82:83] offset1:1
	ds_write_b128 v113, v[88:91] offset:4608
	ds_write2_b64 v1, v[92:93], v[94:95] offset1:1
	s_waitcnt lgkmcnt(0)
	s_barrier
	s_cbranch_scc1 .LBB0_246
	v_lshl_add_u64 v[154:155], s[8:9], 0, v[116:117]
	v_cndmask_b32_e32 v0, v213, v149, vcc
	s_min_u32 s8, s69, 0x80
	v_mov_b32_e32 v171, 0
	v_lshlrev_b32_e32 v169, 2, v0
	v_add_u32_e32 v170, s8, v167
	s_mov_b32 s70, 0
	v_mov_b32_e32 v173, 0xf149f2ca
	v_mov_b32_e32 v0, 0
	v_mov_b32_e32 v1, v171
	v_mov_b32_e32 v2, v171
	v_mov_b32_e32 v3, v171
	v_mov_b32_e32 v4, v171
	v_mov_b32_e32 v5, v171
	v_mov_b32_e32 v6, v171
	v_mov_b32_e32 v7, v171
	v_mov_b32_e32 v8, v171
	v_mov_b32_e32 v9, v171
	v_mov_b32_e32 v10, v171
	v_mov_b32_e32 v11, v171
	v_mov_b32_e32 v12, v171
	v_mov_b32_e32 v13, v171
	v_mov_b32_e32 v14, v171
	v_mov_b32_e32 v15, v171
	v_mov_b32_e32 v16, 0
	v_mov_b32_e32 v17, v171
	v_mov_b32_e32 v18, v171
	v_mov_b32_e32 v19, v171
	v_mov_b32_e32 v20, v171
	v_mov_b32_e32 v21, v171
	v_mov_b32_e32 v22, v171
	v_mov_b32_e32 v23, v171
	v_mov_b32_e32 v24, v171
	v_mov_b32_e32 v25, v171
	v_mov_b32_e32 v26, v171
	v_mov_b32_e32 v27, v171
	v_mov_b32_e32 v28, v171
	v_mov_b32_e32 v29, v171
	v_mov_b32_e32 v30, v171
	v_mov_b32_e32 v31, v171
.LBB0_238:
	s_add_i32 s69, s70, 1
	s_cmp_lt_i32 s69, s68
	s_cselect_b64 s[8:9], -1, 0
	s_cmp_ge_i32 s69, s68
	s_cbranch_scc1 .LBB0_240
	s_cmp_gt_u32 s70, 6
	s_cselect_b32 s30, s11, 0
	s_add_i32 s30, s30, s70
	s_lshl_b32 s30, s30, 6
	s_add_i32 s30, s30, 64
	v_add_u32_e32 v32, s30, v104
	v_ashrrev_i32_e32 v33, 31, v32
	v_lshlrev_b64 v[32:33], 8, v[32:33]
	v_lshl_add_u64 v[32:33], v[154:155], 0, v[32:33]
	s_lshl_b64 s[72:73], s[30:31], 1
	v_lshl_add_u64 v[34:35], v[150:151], 0, s[72:73]
	global_load_dwordx4 v[84:87], v[32:33], off sc1
	global_load_dwordx4 v[80:83], v[34:35], off sc1
	v_add_u32_e32 v32, s30, v112
	v_ashrrev_i32_e32 v33, 31, v32
	v_lshlrev_b64 v[32:33], 8, v[32:33]
	v_lshl_add_u64 v[32:33], v[154:155], 0, v[32:33]
	v_lshl_add_u64 v[34:35], v[152:153], 0, s[72:73]
	global_load_dwordx4 v[88:91], v[32:33], off sc1
	global_load_dwordx4 v[92:95], v[34:35], off sc1

.LBB0_247:
	v_cmp_lt_i32_e32 vcc, v149, v168
	s_or_b32 s30, s10, s15
	v_readlane_b32 s48, v255, 16
	v_cndmask_b32_e32 v33, v213, v149, vcc
	v_lshlrev_b32_e32 v33, 2, v33
	ds_bpermute_b32 v33, v33, v32
	s_lshl_b64 s[8:9], s[30:31], 2
	v_readlane_b32 s50, v255, 18
	v_readlane_b32 s51, v255, 19
	s_add_u32 s8, s50, s8
	s_addc_u32 s9, s51, s9
	s_waitcnt lgkmcnt(0)
	v_add_f32_e32 v32, v32, v33
	global_load_dword v33, v117, s[8:9] sc1
	v_max_f32_e32 v35, v172, v172
	s_mov_b32 s8, 0x3fb8aa3b
	s_lshl_b32 s30, s10, 14
	v_readlane_b32 s49, v255, 17
	v_readlane_b32 s52, v255, 20
	v_readlane_b32 s53, v255, 21
	v_readlane_b32 s54, v255, 22
	v_readlane_b32 s55, v255, 23
	v_readlane_b32 s56, v255, 24
	v_readlane_b32 s57, v255, 25
	v_readlane_b32 s58, v255, 26
	v_readlane_b32 s59, v255, 27
	v_readlane_b32 s60, v255, 28
	v_readlane_b32 s61, v255, 29
	v_readlane_b32 s62, v255, 30
	v_readlane_b32 s63, v255, 31
	s_waitcnt vmcnt(0)
	v_mul_f32_e32 v34, 0x3fb8aa3b, v33
	v_max_f32_e32 v34, v35, v34
	v_sub_f32_e32 v35, v172, v34
	v_fma_f32 v33, v33, s8, -v34
	v_exp_f32_e32 v35, v35
	v_exp_f32_e32 v33, v33
	s_nop 0
	v_fmac_f32_e32 v33, v32, v35
	v_div_scale_f32 v32, s[8:9], v33, v33, v35
	v_rcp_f32_e32 v34, v32
	s_mov_b64 s[8:9], 0x1490e000
	v_fma_f32 v36, -v32, v34, 1.0
	v_fmac_f32_e32 v34, v36, v34
	v_div_scale_f32 v36, vcc, v35, v33, v35
	v_mul_f32_e32 v37, v36, v34
	v_fma_f32 v38, -v32, v37, v36
	v_fmac_f32_e32 v37, v38, v34
	v_fma_f32 v32, -v32, v37, v36
	v_div_fmas_f32 v32, v32, v34, v37
	v_ashrrev_i32_e32 v34, 7, v147
	v_div_fixup_f32 v32, v32, v33, v35
	v_ashrrev_i32_e32 v35, 31, v34
	v_lshlrev_b64 v[34:35], 19, v[34:35]
	v_lshl_add_u64 v[34:35], s[2:3], 0, v[34:35]
	v_lshlrev_b32_e32 v33, 6, v148
	v_lshl_add_u64 v[34:35], v[34:35], 0, s[30:31]
	v_and_b32_e32 v116, 0x1fc0, v33
	v_lshl_add_u64 v[34:35], v[34:35], 0, v[116:117]
	v_lshlrev_b32_e32 v116, 1, v122
	v_lshl_add_u64 v[34:35], v[34:35], 0, v[116:117]
	v_lshl_add_u64 v[36:37], v[34:35], 0, s[8:9]
	v_pk_mul_f32 v[16:17], v[16:17], v[32:33] op_sel_hi:[1,0]
	v_pk_mul_f32 v[18:19], v[18:19], v[32:33] op_sel_hi:[1,0]
	s_mov_b32 s8, 0x1490e000
	v_cvt_pk_bf16_f32 v16, v16, v17
	v_cvt_pk_bf16_f32 v17, v18, v19
	v_add_co_u32_e32 v18, vcc, s8, v34
	v_pk_mul_f32 v[0:1], v[0:1], v[32:33] op_sel_hi:[1,0]
	s_nop 0
	v_addc_co_u32_e32 v19, vcc, 0, v35, vcc
	v_pk_mul_f32 v[2:3], v[2:3], v[32:33] op_sel_hi:[1,0]
	s_mov_b32 s8, 0x14910000
	v_cvt_pk_bf16_f32 v0, v0, v1
	v_cvt_pk_bf16_f32 v1, v2, v3
	v_add_co_u32_e32 v2, vcc, s8, v34
	global_store_dwordx2 v[18:19], v[16:17], off
	s_nop 0
	v_addc_co_u32_e32 v3, vcc, 0, v35, vcc
	v_pk_mul_f32 v[16:17], v[20:21], v[32:33] op_sel_hi:[1,0]
	v_pk_mul_f32 v[18:19], v[22:23], v[32:33] op_sel_hi:[1,0]
	global_store_dwordx2 v[2:3], v[0:1], off
	v_pk_mul_f32 v[0:1], v[4:5], v[32:33] op_sel_hi:[1,0]
	v_pk_mul_f32 v[4:5], v[6:7], v[32:33] op_sel_hi:[1,0]
	v_cvt_pk_bf16_f32 v16, v16, v17
	v_cvt_pk_bf16_f32 v17, v18, v19
	v_cvt_pk_bf16_f32 v0, v0, v1
	v_cvt_pk_bf16_f32 v1, v4, v5
	global_store_dwordx2 v[36:37], v[16:17], off offset:16
	v_pk_mul_f32 v[16:17], v[24:25], v[32:33] op_sel_hi:[1,0]
	v_pk_mul_f32 v[18:19], v[26:27], v[32:33] op_sel_hi:[1,0]
	global_store_dwordx2 v[2:3], v[0:1], off offset:16
	v_pk_mul_f32 v[0:1], v[8:9], v[32:33] op_sel_hi:[1,0]
	v_pk_mul_f32 v[4:5], v[10:11], v[32:33] op_sel_hi:[1,0]
	v_cvt_pk_bf16_f32 v16, v16, v17
	v_cvt_pk_bf16_f32 v17, v18, v19
	v_cvt_pk_bf16_f32 v0, v0, v1
	v_cvt_pk_bf16_f32 v1, v4, v5
	global_store_dwordx2 v[36:37], v[16:17], off offset:32
	v_pk_mul_f32 v[16:17], v[28:29], v[32:33] op_sel_hi:[1,0]
	v_pk_mul_f32 v[18:19], v[30:31], v[32:33] op_sel_hi:[1,0]
	global_store_dwordx2 v[2:3], v[0:1], off offset:32
	v_pk_mul_f32 v[0:1], v[12:13], v[32:33] op_sel_hi:[1,0]
	v_pk_mul_f32 v[4:5], v[14:15], v[32:33] op_sel_hi:[1,0]
	v_cvt_pk_bf16_f32 v16, v16, v17
	v_cvt_pk_bf16_f32 v17, v18, v19
	v_cvt_pk_bf16_f32 v0, v0, v1
	v_cvt_pk_bf16_f32 v1, v4, v5
	global_store_dwordx2 v[36:37], v[16:17], off offset:48
	global_store_dwordx2 v[2:3], v[0:1], off offset:48

.LBB0_249:
	s_ashr_i32 s8, s67, 6
	s_lshl_b32 s11, s67, 7
	s_lshl_b32 s9, s8, 10
	s_and_b32 s11, s11, 0x380
	s_or_b32 s9, s9, s11
	s_add_i32 s11, s8, s16
	s_mul_i32 s8, s11, 0x600
	v_add_u32_e32 v147, s9, v162
	s_ashr_i32 s9, s8, 31
	s_bfe_u32 s10, s67, 0x30003
	s_lshl_b64 s[8:9], s[8:9], 8
	s_add_u32 s30, s81, s8
	s_addc_u32 s69, s64, s9
	s_lshl_b32 s68, s67, 1
	s_and_b32 s70, s68, 64
	s_lshl_b32 s68, s70, 1
	s_add_u32 s68, s30, s68
	s_addc_u32 s69, s69, 0
	s_lshl_b32 s11, s11, 7
	v_or_b32_e32 v148, v147, v98
	s_or_b32 s72, s70, s11
	s_mul_i32 s30, s72, 0xc00
	v_ashrrev_i32_e32 v149, 31, v148
	s_mul_hi_i32 s11, s72, 0xc00
	s_add_u32 s70, s65, s30
	v_lshlrev_b64 v[0:1], 10, v[148:149]
	s_addc_u32 s71, s66, s11
	v_lshl_add_u64 v[0:1], s[38:39], 0, v[0:1]
	s_lshl_b32 s30, s10, 7
	v_lshl_add_u64 v[0:1], v[0:1], 0, s[30:31]
	v_lshlrev_b32_e32 v116, 1, v102
	v_lshl_add_u64 v[0:1], v[0:1], 0, v[116:117]
	global_load_dwordx4 v[76:79], v[0:1], off sc1
	global_load_dwordx4 v[72:75], v[0:1], off offset:32 sc1
	global_load_dwordx4 v[68:71], v[0:1], off offset:64 sc1
	global_load_dwordx4 v[64:67], v[0:1], off offset:96 sc1
	v_lshl_add_u64 v[0:1], s[68:69], 0, v[108:109]
	v_lshlrev_b32_e32 v116, 1, v106
	v_lshl_add_u64 v[0:1], v[0:1], 0, v[116:117]
	v_lshl_add_u64 v[4:5], s[70:71], 0, v[130:131]
	global_load_dwordx4 v[0:3], v[0:1], off sc1
	v_lshl_add_u64 v[4:5], v[4:5], 0, v[116:117]
	v_lshl_add_u64 v[8:9], s[68:69], 0, v[114:115]
	v_lshl_add_u64 v[12:13], s[70:71], 0, v[132:133]
	global_load_dwordx4 v[4:7], v[4:5], off sc1
	v_lshl_add_u64 v[8:9], v[8:9], 0, v[116:117]
	v_lshl_add_u64 v[12:13], v[12:13], 0, v[116:117]
	global_load_dwordx4 v[8:11], v[8:9], off sc1
	s_lshl_b32 s30, s67, 2
	global_load_dwordx4 v[12:15], v[12:13], off sc1
	s_and_b32 s30, s30, 0x80
	s_or_b32 s8, s8, s30
	v_mov_b32_e32 v155, 0
	s_mov_b32 s11, 0
	v_lshl_add_u64 v[150:151], v[140:141], 0, s[8:9]
	v_mov_b32_e32 v168, 0xf149f2ca
	v_mov_b32_e32 v16, 0
	v_mov_b32_e32 v17, v155
	v_mov_b32_e32 v18, v155
	v_mov_b32_e32 v19, v155
	v_mov_b32_e32 v20, v155
	v_mov_b32_e32 v21, v155
	v_mov_b32_e32 v22, v155
	v_mov_b32_e32 v23, v155
	v_mov_b32_e32 v24, v155
	v_mov_b32_e32 v25, v155
	v_mov_b32_e32 v26, v155
	v_mov_b32_e32 v27, v155
	v_mov_b32_e32 v28, v155
	v_mov_b32_e32 v29, v155
	v_mov_b32_e32 v30, v155
	v_mov_b32_e32 v31, v155
	s_waitcnt vmcnt(0)
	ds_write_b128 v113, v[0:3]
	v_add_u32_e32 v0, 0x2400, v159
	ds_write2_b64 v0, v[4:5], v[6:7] offset1:1
	ds_write_b128 v113, v[8:11] offset:4608
	v_add_u32_e32 v0, 0x3500, v159
	v_and_b32_e32 v1, 64, v213
	ds_write2_b64 v0, v[12:13], v[14:15] offset1:1
	v_xor_b32_e32 v0, 32, v213
	v_add_u32_e32 v1, 64, v1
	v_cmp_lt_i32_e32 vcc, v0, v1
	v_mov_b32_e32 v1, v155
	v_mov_b32_e32 v2, v155
	v_cndmask_b32_e32 v0, v213, v0, vcc
	v_lshlrev_b32_e32 v149, 2, v0
	v_mov_b32_e32 v0, 0xc00
	v_mad_i64_i32 v[152:153], s[8:9], s72, v0, v[144:145]
	v_mov_b32_e32 v0, 0
	v_mov_b32_e32 v3, v155
	v_mov_b32_e32 v4, v155
	v_mov_b32_e32 v5, v155
	v_mov_b32_e32 v6, v155
	v_mov_b32_e32 v7, v155
	v_mov_b32_e32 v8, v155
	v_mov_b32_e32 v9, v155
	v_mov_b32_e32 v10, v155
	v_mov_b32_e32 v11, v155
	v_mov_b32_e32 v12, v155
	v_mov_b32_e32 v13, v155
	v_mov_b32_e32 v14, v155
	v_mov_b32_e32 v15, v155
	s_waitcnt lgkmcnt(0)
	s_barrier
.LBB0_250:
	v_lshl_add_u64 v[32:33], v[150:151], 0, v[138:139]
	s_mov_b32 s9, 0x134d2000
	v_add_co_u32_e32 v34, vcc, s9, v32
	s_mov_b32 s9, 0x13cce000
	s_nop 0
	v_addc_co_u32_e32 v35, vcc, 0, v33, vcc
	global_load_dwordx4 v[80:83], v[34:35], off sc1
	v_lshl_add_u64 v[34:35], v[152:153], 0, v[138:139]
	v_add_co_u32_e32 v36, vcc, s9, v34
	s_mov_b32 s9, 0x134d4000
	s_nop 0
	v_addc_co_u32_e32 v37, vcc, 0, v35, vcc
	v_add_co_u32_e32 v32, vcc, s9, v32
	s_and_b32 s8, s11, 1
	s_nop 0
	v_addc_co_u32_e32 v33, vcc, 0, v33, vcc
	s_mov_b32 s9, 0x13ce6000
	global_load_dwordx4 v[88:91], v[32:33], off sc1
	v_add_co_u32_e32 v32, vcc, s9, v34
	s_mul_i32 s9, s8, 0x4600
	v_or_b32_e32 v170, s9, v163
	v_mov_b32_e32 v169, v155
	v_addc_co_u32_e32 v33, vcc, 0, v35, vcc
	v_add_u32_e32 v155, v170, v161
	global_load_dwordx4 v[84:87], v[36:37], off offset:128 sc1
	global_load_dwordx4 v[92:95], v[32:33], off offset:128 sc1
	ds_read_b128 v[32:35], v155
	ds_read_b128 v[36:39], v155 offset:32
	s_waitcnt lgkmcnt(1)
	v_mfma_f32_32x32x16_bf16 v[48:63], v[32:35], v[76:79], 0
	ds_read_b128 v[32:35], v155 offset:64
	ds_read_b128 v[172:175], v155 offset:4640
	v_mov_b32_e32 v154, v168
	s_xor_b32 s8, s8, 1
	s_mulk_i32 s8, 0x4600
	s_add_i32 s11, s11, 1
	v_lshl_add_u64 v[150:151], v[150:151], 0, s[28:29]
	s_waitcnt lgkmcnt(2)
	v_mfma_f32_32x32x16_bf16 v[48:63], v[36:39], v[72:75], v[48:63]
	v_lshl_add_u64 v[152:153], v[152:153], 0, s[24:25]
	s_cmp_lg_u32 s11, 23
	s_waitcnt lgkmcnt(1)
	v_mfma_f32_32x32x16_bf16 v[48:63], v[32:35], v[68:71], v[48:63]
	ds_read_b128 v[32:35], v155 offset:96
	s_waitcnt lgkmcnt(0)
	v_mfma_f32_32x32x16_bf16 v[48:63], v[32:35], v[64:67], v[48:63]
	ds_read_b128 v[32:35], v155 offset:4608
	s_waitcnt lgkmcnt(0)
	v_mfma_f32_32x32x16_bf16 v[32:47], v[32:35], v[76:79], 0
	s_nop 8
	v_max_f32_e32 v168, v48, v48
	v_mfma_f32_32x32x16_bf16 v[32:47], v[172:175], v[72:75], v[32:47]
	ds_read_b128 v[172:175], v155 offset:4672
	s_waitcnt lgkmcnt(0)
	v_mfma_f32_32x32x16_bf16 v[32:47], v[172:175], v[68:71], v[32:47]
	ds_read_b128 v[172:175], v155 offset:4704
	v_max_f32_e32 v155, v49, v49
	v_max_f32_e32 v155, v168, v155
	v_max3_f32 v155, v155, v50, v51
	v_max3_f32 v155, v155, v52, v53
	v_max3_f32 v155, v155, v54, v55
	v_max3_f32 v155, v155, v56, v57
	s_waitcnt lgkmcnt(0)
	v_mfma_f32_32x32x16_bf16 v[32:47], v[172:175], v[64:67], v[32:47]
	v_max3_f32 v155, v155, v58, v59
	v_max3_f32 v155, v155, v60, v61
	v_max3_f32 v155, v155, v62, v63
	s_nop 8
	v_max3_f32 v155, v155, v32, v33
	v_max3_f32 v155, v155, v34, v35
	v_max3_f32 v155, v155, v36, v37
	v_max3_f32 v155, v155, v38, v39
	v_max3_f32 v155, v155, v40, v41
	v_max3_f32 v155, v155, v42, v43
	v_max3_f32 v155, v155, v44, v45
	v_max3_f32 v155, v155, v46, v47
	ds_bpermute_b32 v168, v149, v155
	s_waitcnt lgkmcnt(0)
	v_max3_f32 v168, v154, v155, v168
	v_sub_f32_e32 v48, v48, v168
	v_exp_f32_e32 v171, v48
	v_sub_f32_e32 v49, v49, v168
	v_exp_f32_e32 v172, v49
	v_sub_f32_e32 v49, v50, v168
	v_exp_f32_e32 v173, v49
	v_sub_f32_e32 v49, v51, v168
	v_exp_f32_e32 v174, v49
	v_sub_f32_e32 v49, v52, v168
	v_add_f32_e32 v48, 0, v171
	v_exp_f32_e32 v175, v49
	v_sub_f32_e32 v49, v53, v168
	v_add_f32_e32 v48, v172, v48
	v_exp_f32_e32 v176, v49
	v_sub_f32_e32 v49, v54, v168
	v_add_f32_e32 v48, v173, v48
	v_exp_f32_e32 v177, v49
	v_sub_f32_e32 v49, v55, v168
	v_add_f32_e32 v48, v174, v48
	v_exp_f32_e32 v178, v49
	v_add_f32_e32 v48, v175, v48
	v_add_f32_e32 v48, v176, v48
	v_add_f32_e32 v48, v177, v48
	v_add_f32_e32 v49, v178, v48
	v_sub_f32_e32 v48, v56, v168
	v_exp_f32_e32 v48, v48
	v_sub_f32_e32 v56, v63, v168
	v_exp_f32_e32 v56, v56
	v_sub_f32_e32 v32, v32, v168
	v_add_f32_e32 v50, v48, v49
	v_sub_f32_e32 v49, v57, v168
	v_exp_f32_e32 v49, v49
	v_sub_f32_e32 v154, v154, v168
	v_exp_f32_e32 v154, v154
	v_add_f32_e32 v51, v49, v50
	v_sub_f32_e32 v50, v58, v168
	v_exp_f32_e32 v50, v50
	v_pk_mul_f32 v[30:31], v[30:31], v[154:155] op_sel_hi:[1,0]
	v_pk_mul_f32 v[28:29], v[28:29], v[154:155] op_sel_hi:[1,0]
	v_pk_mul_f32 v[26:27], v[26:27], v[154:155] op_sel_hi:[1,0]
	v_add_f32_e32 v52, v50, v51
	v_sub_f32_e32 v51, v59, v168
	v_exp_f32_e32 v51, v51
	v_pk_mul_f32 v[24:25], v[24:25], v[154:155] op_sel_hi:[1,0]
	v_pk_mul_f32 v[22:23], v[22:23], v[154:155] op_sel_hi:[1,0]
	v_pk_mul_f32 v[20:21], v[20:21], v[154:155] op_sel_hi:[1,0]
	v_add_f32_e32 v53, v51, v52
	v_sub_f32_e32 v52, v60, v168
	v_exp_f32_e32 v52, v52
	v_pk_mul_f32 v[18:19], v[18:19], v[154:155] op_sel_hi:[1,0]
	v_pk_mul_f32 v[16:17], v[16:17], v[154:155] op_sel_hi:[1,0]
	v_pk_mul_f32 v[14:15], v[14:15], v[154:155] op_sel_hi:[1,0]
	v_add_f32_e32 v54, v52, v53
	v_sub_f32_e32 v53, v61, v168
	v_exp_f32_e32 v53, v53
	v_pk_mul_f32 v[12:13], v[12:13], v[154:155] op_sel_hi:[1,0]
	v_pk_mul_f32 v[10:11], v[10:11], v[154:155] op_sel_hi:[1,0]
	v_pk_mul_f32 v[8:9], v[8:9], v[154:155] op_sel_hi:[1,0]
	v_add_f32_e32 v55, v53, v54
	v_sub_f32_e32 v54, v62, v168
	v_exp_f32_e32 v54, v54
	v_pk_mul_f32 v[6:7], v[6:7], v[154:155] op_sel_hi:[1,0]
	v_pk_mul_f32 v[4:5], v[4:5], v[154:155] op_sel_hi:[1,0]
	v_pk_mul_f32 v[2:3], v[2:3], v[154:155] op_sel_hi:[1,0]
	v_add_f32_e32 v55, v54, v55
	v_add_f32_e32 v62, v56, v55
	v_exp_f32_e32 v55, v32
	v_sub_f32_e32 v32, v33, v168
	v_exp_f32_e32 v57, v32
	v_sub_f32_e32 v32, v34, v168
	v_exp_f32_e32 v58, v32
	v_sub_f32_e32 v32, v35, v168
	v_exp_f32_e32 v59, v32
	v_sub_f32_e32 v32, v36, v168
	v_exp_f32_e32 v36, v32
	v_sub_f32_e32 v32, v37, v168
	v_exp_f32_e32 v37, v32
	v_sub_f32_e32 v32, v38, v168
	v_exp_f32_e32 v60, v32
	v_sub_f32_e32 v32, v39, v168
	v_exp_f32_e32 v61, v32
	v_sub_f32_e32 v32, v40, v168
	v_exp_f32_e32 v38, v32
	v_sub_f32_e32 v32, v41, v168
	v_exp_f32_e32 v39, v32
	v_sub_f32_e32 v32, v42, v168
	v_exp_f32_e32 v40, v32
	v_sub_f32_e32 v32, v43, v168
	v_exp_f32_e32 v41, v32
	v_sub_f32_e32 v32, v44, v168
	v_exp_f32_e32 v42, v32
	v_sub_f32_e32 v32, v45, v168
	v_exp_f32_e32 v43, v32
	v_sub_f32_e32 v32, v46, v168
	v_exp_f32_e32 v44, v32
	v_sub_f32_e32 v32, v47, v168
	v_exp_f32_e32 v45, v32
	v_add_f32_e32 v32, v55, v62
	v_add_f32_e32 v32, v57, v32
	v_add_f32_e32 v32, v58, v32
	v_add_f32_e32 v32, v59, v32
	v_add_f32_e32 v32, v36, v32
	v_add_f32_e32 v32, v37, v32
	v_add_f32_e32 v32, v60, v32
	v_add_f32_e32 v32, v61, v32
	v_add_f32_e32 v32, v38, v32
	v_add_f32_e32 v32, v39, v32
	v_add_f32_e32 v32, v40, v32
	v_add_f32_e32 v32, v41, v32
	v_add_f32_e32 v32, v42, v32
	v_lshlrev_b32_e32 v46, 1, v160
	v_add_f32_e32 v32, v43, v32
	v_add3_u32 v46, v170, v164, v46
	v_add_f32_e32 v32, v44, v32
	v_add_u32_e32 v62, 0x2000, v46
	v_pk_mul_f32 v[0:1], v[0:1], v[154:155] op_sel_hi:[1,0]
	v_add_f32_e32 v155, v45, v32
	v_cvt_pk_bf16_f32 v32, v171, v172
	v_cvt_pk_bf16_f32 v33, v173, v174
	v_cvt_pk_bf16_f32 v34, v175, v176
	v_cvt_pk_bf16_f32 v35, v177, v178
	ds_read2_b64 v[170:173], v62 offset0:128 offset1:130
	ds_read2_b64 v[174:177], v62 offset0:132 offset1:134
	v_add_u32_e32 v63, 0x3000, v46
	s_waitcnt lgkmcnt(1)
	v_mfma_f32_32x32x16_bf16 v[16:31], v[170:173], v[32:35], v[16:31]
	ds_read2_b64 v[170:173], v63 offset0:160 offset1:162
	v_fmac_f32_e32 v155, v169, v154
	s_waitcnt lgkmcnt(0)
	v_mfma_f32_32x32x16_bf16 v[0:15], v[170:173], v[32:35], v[0:15]
	v_cvt_pk_bf16_f32 v32, v48, v49
	ds_read2_b64 v[46:49], v63 offset0:164 offset1:166
	v_cvt_pk_bf16_f32 v33, v50, v51
	v_cvt_pk_bf16_f32 v34, v52, v53
	v_cvt_pk_bf16_f32 v35, v54, v56
	s_waitcnt lgkmcnt(0)
	s_nop 0
	v_mfma_f32_32x32x16_bf16 v[0:15], v[46:49], v[32:35], v[0:15]
	ds_read2_b64 v[46:49], v62 offset0:136 offset1:138
	v_mfma_f32_32x32x16_bf16 v[16:31], v[174:177], v[32:35], v[16:31]
	v_cvt_pk_bf16_f32 v32, v55, v57
	v_cvt_pk_bf16_f32 v33, v58, v59
	v_cvt_pk_bf16_f32 v34, v36, v37
	v_cvt_pk_bf16_f32 v35, v60, v61
	s_waitcnt lgkmcnt(0)
	s_nop 0
	v_mfma_f32_32x32x16_bf16 v[16:31], v[46:49], v[32:35], v[16:31]
	ds_read2_b64 v[46:49], v63 offset0:168 offset1:170
	s_waitcnt lgkmcnt(0)
	v_mfma_f32_32x32x16_bf16 v[0:15], v[46:49], v[32:35], v[0:15]
	v_cvt_pk_bf16_f32 v32, v38, v39
	ds_read2_b64 v[36:39], v62 offset0:140 offset1:142
	v_cvt_pk_bf16_f32 v33, v40, v41
	v_cvt_pk_bf16_f32 v34, v42, v43
	v_cvt_pk_bf16_f32 v35, v44, v45
	s_waitcnt lgkmcnt(0)
	s_nop 0
	v_mfma_f32_32x32x16_bf16 v[16:31], v[36:39], v[32:35], v[16:31]
	ds_read2_b64 v[36:39], v63 offset0:172 offset1:174
	s_waitcnt lgkmcnt(0)
	v_mfma_f32_32x32x16_bf16 v[0:15], v[36:39], v[32:35], v[0:15]
	v_add3_u32 v32, v105, s8, v116
	v_add_u32_e32 v33, v32, v158
	v_add_u32_e32 v34, 0x2400, v33
	s_waitcnt vmcnt(3)
	ds_write_b128 v32, v[80:83]
	s_waitcnt vmcnt(1)
	ds_write2_b64 v34, v[84:85], v[86:87] offset1:1
	ds_write_b128 v32, v[88:91] offset:4608
	v_add_u32_e32 v32, 0x3500, v33
	s_waitcnt vmcnt(0)
	ds_write2_b64 v32, v[92:93], v[94:95] offset1:1
	s_waitcnt lgkmcnt(0)
	s_barrier
	s_cbranch_scc1 .LBB0_250
	v_add_u32_e32 v80, v163, v161
	ds_read_b128 v[32:35], v80 offset:17920
	ds_read_b128 v[36:39], v80 offset:17952
	v_add_u32_e32 v82, 0x6800, v166
	s_lshl_b32 s30, s10, 14
	s_waitcnt lgkmcnt(1)
	v_mfma_f32_32x32x16_bf16 v[48:63], v[32:35], v[76:79], 0
	ds_read_b128 v[32:35], v80 offset:17984
	s_waitcnt lgkmcnt(1)
	v_mfma_f32_32x32x16_bf16 v[48:63], v[36:39], v[72:75], v[48:63]
	s_waitcnt lgkmcnt(0)
	v_mfma_f32_32x32x16_bf16 v[48:63], v[32:35], v[68:71], v[48:63]
	ds_read_b128 v[32:35], v80 offset:18016
	s_waitcnt lgkmcnt(0)
	v_mfma_f32_32x32x16_bf16 v[48:63], v[32:35], v[64:67], v[48:63]
	ds_read_b128 v[32:35], v80 offset:22528
	s_waitcnt lgkmcnt(0)
	v_mfma_f32_32x32x16_bf16 v[32:47], v[32:35], v[76:79], 0
	ds_read_b128 v[76:79], v80 offset:22560
	s_waitcnt lgkmcnt(0)
	v_mfma_f32_32x32x16_bf16 v[32:47], v[76:79], v[72:75], v[32:47]
	ds_read_b128 v[72:75], v80 offset:22592
	s_waitcnt lgkmcnt(0)
	v_mfma_f32_32x32x16_bf16 v[32:47], v[72:75], v[68:71], v[32:47]
	ds_read_b128 v[68:71], v80 offset:22624
	s_waitcnt lgkmcnt(0)
	v_mfma_f32_32x32x16_bf16 v[32:47], v[68:71], v[64:67], v[32:47]
	v_max_f32_e32 v64, v49, v49
	v_max_f32_e32 v65, v48, v48
	v_max_f32_e32 v64, v65, v64
	v_max3_f32 v64, v64, v50, v51
	v_max3_f32 v64, v64, v52, v53
	v_max3_f32 v64, v64, v54, v55
	v_max3_f32 v64, v64, v56, v57
	v_max3_f32 v64, v64, v58, v59
	v_max3_f32 v64, v64, v60, v61
	v_max3_f32 v64, v64, v62, v63
	s_nop 1
	v_max3_f32 v64, v64, v32, v33
	v_max3_f32 v64, v64, v34, v35
	v_max3_f32 v64, v64, v36, v37
	v_max3_f32 v64, v64, v38, v39
	v_max3_f32 v64, v64, v40, v41
	v_max3_f32 v64, v64, v42, v43
	v_max3_f32 v64, v64, v44, v45
	v_max3_f32 v64, v64, v46, v47
	ds_bpermute_b32 v65, v149, v64
	s_waitcnt lgkmcnt(0)
	v_max3_f32 v65, v168, v64, v65
	v_sub_f32_e32 v64, v168, v65
	v_exp_f32_e32 v64, v64
	v_sub_f32_e32 v48, v48, v65
	v_sub_f32_e32 v49, v49, v65
	v_exp_f32_e32 v48, v48
	v_exp_f32_e32 v49, v49
	v_sub_f32_e32 v50, v50, v65
	v_exp_f32_e32 v50, v50
	v_sub_f32_e32 v51, v51, v65
	v_sub_f32_e32 v52, v52, v65
	v_sub_f32_e32 v53, v53, v65
	v_sub_f32_e32 v54, v54, v65
	v_sub_f32_e32 v55, v55, v65
	v_exp_f32_e32 v51, v51
	v_exp_f32_e32 v52, v52
	v_exp_f32_e32 v53, v53
	v_exp_f32_e32 v54, v54
	v_exp_f32_e32 v55, v55
	v_sub_f32_e32 v56, v56, v65
	v_sub_f32_e32 v57, v57, v65
	v_sub_f32_e32 v58, v58, v65
	v_sub_f32_e32 v59, v59, v65
	v_sub_f32_e32 v60, v60, v65
	v_sub_f32_e32 v61, v61, v65
	v_sub_f32_e32 v62, v62, v65
	v_sub_f32_e32 v63, v63, v65
	v_sub_f32_e32 v32, v32, v65
	v_sub_f32_e32 v33, v33, v65
	v_sub_f32_e32 v34, v34, v65
	v_sub_f32_e32 v35, v35, v65
	v_sub_f32_e32 v36, v36, v65
	v_sub_f32_e32 v37, v37, v65
	v_sub_f32_e32 v38, v38, v65
	v_sub_f32_e32 v39, v39, v65
	v_sub_f32_e32 v40, v40, v65
	v_sub_f32_e32 v41, v41, v65
	v_sub_f32_e32 v42, v42, v65
	v_sub_f32_e32 v43, v43, v65
	v_sub_f32_e32 v44, v44, v65
	v_sub_f32_e32 v45, v45, v65
	v_sub_f32_e32 v46, v46, v65
	v_sub_f32_e32 v47, v47, v65
	v_pk_mul_f32 v[30:31], v[30:31], v[64:65] op_sel_hi:[1,0]
	v_pk_mul_f32 v[28:29], v[28:29], v[64:65] op_sel_hi:[1,0]
	v_pk_mul_f32 v[26:27], v[26:27], v[64:65] op_sel_hi:[1,0]
	v_pk_mul_f32 v[24:25], v[24:25], v[64:65] op_sel_hi:[1,0]
	v_pk_mul_f32 v[22:23], v[22:23], v[64:65] op_sel_hi:[1,0]
	v_pk_mul_f32 v[20:21], v[20:21], v[64:65] op_sel_hi:[1,0]
	v_pk_mul_f32 v[18:19], v[18:19], v[64:65] op_sel_hi:[1,0]
	v_pk_mul_f32 v[16:17], v[16:17], v[64:65] op_sel_hi:[1,0]
	v_pk_mul_f32 v[14:15], v[14:15], v[64:65] op_sel_hi:[1,0]
	v_pk_mul_f32 v[12:13], v[12:13], v[64:65] op_sel_hi:[1,0]
	v_pk_mul_f32 v[10:11], v[10:11], v[64:65] op_sel_hi:[1,0]
	v_pk_mul_f32 v[8:9], v[8:9], v[64:65] op_sel_hi:[1,0]
	v_pk_mul_f32 v[6:7], v[6:7], v[64:65] op_sel_hi:[1,0]
	v_pk_mul_f32 v[4:5], v[4:5], v[64:65] op_sel_hi:[1,0]
	v_pk_mul_f32 v[2:3], v[2:3], v[64:65] op_sel_hi:[1,0]
	v_pk_mul_f32 v[0:1], v[0:1], v[64:65] op_sel_hi:[1,0]
	v_add_u32_e32 v65, 0x6800, v165
	v_cvt_pk_bf16_f32 v66, v48, v49
	ds_read2_b64 v[70:73], v65 offset0:64 offset1:66
	ds_read2_b64 v[74:77], v65 offset0:68 offset1:70
	v_add_f32_e32 v48, 0, v48
	v_add_f32_e32 v48, v49, v48
	v_add_f32_e32 v48, v50, v48
	v_cvt_pk_bf16_f32 v67, v50, v51
	v_cvt_pk_bf16_f32 v68, v52, v53
	v_cvt_pk_bf16_f32 v69, v54, v55
	v_add_f32_e32 v48, v51, v48
	v_exp_f32_e32 v56, v56
	s_waitcnt lgkmcnt(1)
	v_mfma_f32_32x32x16_bf16 v[16:31], v[70:73], v[66:69], v[16:31]
	ds_read2_b64 v[70:73], v82 offset0:64 offset1:66
	ds_read2_b64 v[78:81], v82 offset0:68 offset1:70
	v_add_f32_e32 v48, v52, v48
	v_exp_f32_e32 v57, v57
	v_add_f32_e32 v48, v53, v48
	v_exp_f32_e32 v58, v58
	v_add_f32_e32 v48, v54, v48
	v_exp_f32_e32 v59, v59
	v_add_f32_e32 v48, v55, v48
	v_exp_f32_e32 v60, v60
	v_exp_f32_e32 v61, v61
	v_exp_f32_e32 v62, v62
	v_exp_f32_e32 v63, v63
	s_waitcnt lgkmcnt(1)
	v_mfma_f32_32x32x16_bf16 v[0:15], v[70:73], v[66:69], v[0:15]
	v_add_f32_e32 v48, v56, v48
	v_add_f32_e32 v48, v57, v48
	v_add_f32_e32 v48, v58, v48
	v_add_f32_e32 v48, v59, v48
	v_exp_f32_e32 v32, v32
	v_exp_f32_e32 v33, v33
	v_cvt_pk_bf16_f32 v66, v56, v57
	v_cvt_pk_bf16_f32 v67, v58, v59
	v_cvt_pk_bf16_f32 v68, v60, v61
	v_cvt_pk_bf16_f32 v69, v62, v63
	ds_read2_b64 v[70:73], v65 offset0:72 offset1:74
	v_add_f32_e32 v48, v60, v48
	v_mfma_f32_32x32x16_bf16 v[16:31], v[74:77], v[66:69], v[16:31]
	v_add_f32_e32 v48, v61, v48
	v_exp_f32_e32 v34, v34
	v_add_f32_e32 v48, v62, v48
	v_exp_f32_e32 v35, v35
	v_add_f32_e32 v48, v63, v48
	v_exp_f32_e32 v36, v36
	v_exp_f32_e32 v37, v37
	v_exp_f32_e32 v38, v38
	v_exp_f32_e32 v39, v39
	s_waitcnt lgkmcnt(1)
	v_mfma_f32_32x32x16_bf16 v[0:15], v[78:81], v[66:69], v[0:15]
	v_cvt_pk_bf16_f32 v66, v32, v33
	v_add_f32_e32 v32, v32, v48
	v_add_f32_e32 v32, v33, v32
	v_add_f32_e32 v32, v34, v32
	v_add_f32_e32 v32, v35, v32
	v_exp_f32_e32 v40, v40
	v_cvt_pk_bf16_f32 v67, v34, v35
	v_cvt_pk_bf16_f32 v68, v36, v37
	v_cvt_pk_bf16_f32 v69, v38, v39
	v_add_f32_e32 v32, v36, v32
	v_exp_f32_e32 v41, v41
	s_waitcnt lgkmcnt(0)
	v_mfma_f32_32x32x16_bf16 v[16:31], v[70:73], v[66:69], v[16:31]
	ds_read2_b64 v[70:73], v82 offset0:72 offset1:74
	v_add_f32_e32 v32, v37, v32
	v_exp_f32_e32 v42, v42
	v_add_f32_e32 v32, v38, v32
	v_exp_f32_e32 v43, v43
	v_add_f32_e32 v32, v39, v32
	v_exp_f32_e32 v44, v44
	v_add_f32_e32 v32, v40, v32
	v_exp_f32_e32 v45, v45
	v_add_f32_e32 v32, v41, v32
	v_exp_f32_e32 v46, v46
	v_add_f32_e32 v32, v42, v32
	v_exp_f32_e32 v47, v47
	v_add_f32_e32 v32, v43, v32
	v_add_f32_e32 v32, v44, v32
	v_add_f32_e32 v32, v45, v32
	s_waitcnt lgkmcnt(0)
	v_mfma_f32_32x32x16_bf16 v[0:15], v[70:73], v[66:69], v[0:15]
	ds_read2_b64 v[70:73], v65 offset0:76 offset1:78
	v_add_f32_e32 v32, v46, v32
	v_add_f32_e32 v32, v47, v32
	v_fmac_f32_e32 v32, v155, v64
	ds_bpermute_b32 v33, v149, v32
	v_cvt_pk_bf16_f32 v66, v40, v41
	v_cvt_pk_bf16_f32 v67, v42, v43
	v_cvt_pk_bf16_f32 v68, v44, v45
	v_cvt_pk_bf16_f32 v69, v46, v47
	s_waitcnt lgkmcnt(0)
	v_add_f32_e32 v32, v32, v33
	v_div_scale_f32 v33, s[8:9], v32, v32, 1.0
	v_mfma_f32_32x32x16_bf16 v[16:31], v[70:73], v[66:69], v[16:31]
	ds_read2_b64 v[70:73], v82 offset0:76 offset1:78
	v_rcp_f32_e32 v34, v33
	s_movk_i32 s8, 0x2000
	s_waitcnt lgkmcnt(0)
	s_barrier
	v_fma_f32 v35, -v33, v34, 1.0
	v_fmac_f32_e32 v34, v35, v34
	v_div_scale_f32 v35, vcc, 1.0, v32, 1.0
	v_mul_f32_e32 v36, v35, v34
	v_fma_f32 v37, -v33, v36, v35
	v_mfma_f32_32x32x16_bf16 v[0:15], v[70:73], v[66:69], v[0:15]
	v_fmac_f32_e32 v36, v37, v34
	v_fma_f32 v33, -v33, v36, v35
	v_div_fmas_f32 v33, v33, v34, v36
	v_ashrrev_i32_e32 v34, 7, v147
	v_ashrrev_i32_e32 v35, 31, v34
	v_lshlrev_b64 v[34:35], 19, v[34:35]
	v_div_fixup_f32 v32, v33, v32, 1.0
	v_lshl_add_u64 v[34:35], s[0:1], 0, v[34:35]
	v_lshlrev_b32_e32 v33, 6, v148
	v_lshl_add_u64 v[34:35], v[34:35], 0, s[30:31]
	v_and_b32_e32 v116, 0x1fc0, v33
	v_lshl_add_u64 v[34:35], v[34:35], 0, v[116:117]
	v_lshlrev_b32_e32 v116, 1, v122
	v_lshl_add_u64 v[34:35], v[34:35], 0, v[116:117]
	v_pk_mul_f32 v[0:1], v[0:1], v[32:33] op_sel_hi:[1,0]
	v_pk_mul_f32 v[2:3], v[2:3], v[32:33] op_sel_hi:[1,0]
	v_pk_mul_f32 v[16:17], v[16:17], v[32:33] op_sel_hi:[1,0]
	v_pk_mul_f32 v[18:19], v[18:19], v[32:33] op_sel_hi:[1,0]
	v_cvt_pk_bf16_f32 v0, v0, v1
	v_cvt_pk_bf16_f32 v1, v2, v3
	v_add_co_u32_e32 v2, vcc, s8, v34
	v_cvt_pk_bf16_f32 v16, v16, v17
	v_cvt_pk_bf16_f32 v17, v18, v19
	v_addc_co_u32_e32 v3, vcc, 0, v35, vcc
	global_store_dwordx2 v[34:35], v[16:17], off
	v_pk_mul_f32 v[16:17], v[20:21], v[32:33] op_sel_hi:[1,0]
	v_pk_mul_f32 v[18:19], v[22:23], v[32:33] op_sel_hi:[1,0]
	global_store_dwordx2 v[2:3], v[0:1], off
	v_pk_mul_f32 v[0:1], v[4:5], v[32:33] op_sel_hi:[1,0]
	v_pk_mul_f32 v[4:5], v[6:7], v[32:33] op_sel_hi:[1,0]
	v_cvt_pk_bf16_f32 v16, v16, v17
	v_cvt_pk_bf16_f32 v17, v18, v19
	v_cvt_pk_bf16_f32 v0, v0, v1
	v_cvt_pk_bf16_f32 v1, v4, v5
	global_store_dwordx2 v[34:35], v[16:17], off offset:16
	v_pk_mul_f32 v[16:17], v[24:25], v[32:33] op_sel_hi:[1,0]
	v_pk_mul_f32 v[18:19], v[26:27], v[32:33] op_sel_hi:[1,0]
	global_store_dwordx2 v[2:3], v[0:1], off offset:16
	v_pk_mul_f32 v[0:1], v[8:9], v[32:33] op_sel_hi:[1,0]
	v_pk_mul_f32 v[4:5], v[10:11], v[32:33] op_sel_hi:[1,0]
	v_cvt_pk_bf16_f32 v16, v16, v17
	v_cvt_pk_bf16_f32 v17, v18, v19
	v_cvt_pk_bf16_f32 v0, v0, v1
	v_cvt_pk_bf16_f32 v1, v4, v5
	global_store_dwordx2 v[34:35], v[16:17], off offset:32
	v_pk_mul_f32 v[16:17], v[28:29], v[32:33] op_sel_hi:[1,0]
	v_pk_mul_f32 v[18:19], v[30:31], v[32:33] op_sel_hi:[1,0]
	global_store_dwordx2 v[2:3], v[0:1], off offset:32
	v_pk_mul_f32 v[0:1], v[12:13], v[32:33] op_sel_hi:[1,0]
	v_pk_mul_f32 v[4:5], v[14:15], v[32:33] op_sel_hi:[1,0]
	v_cvt_pk_bf16_f32 v16, v16, v17
	v_cvt_pk_bf16_f32 v17, v18, v19
	v_cvt_pk_bf16_f32 v0, v0, v1
	v_cvt_pk_bf16_f32 v1, v4, v5
	global_store_dwordx2 v[34:35], v[16:17], off offset:48
	global_store_dwordx2 v[2:3], v[0:1], off offset:48
	s_branch .LBB0_218

.Lgq_skip2:
	s_movk_i32 s13, 0x600
	s_xor_b64 s[16:17], s[16:17], -1
	s_waitcnt lgkmcnt(0)
	v_cmp_gt_u32_e64 s[42:43], s13, v103
	s_movk_i32 s13, 0x5ff
	v_cmp_lt_u32_e64 s[40:41], s13, v103
	s_and_saveexec_b64 s[18:19], s[42:43]
	s_mov_b32 s13, 0xaaab
	v_mul_u32_u24_sdwa v1, v103, s13 dst_sel:DWORD dst_unused:UNUSED_PAD src0_sel:WORD_0 src1_sel:DWORD
	v_lshrrev_b32_e32 v1, 21, v1
	v_mul_lo_u16_e32 v2, 48, v1
	v_sub_u16_e32 v2, v103, v2
	v_lshlrev_b16_e32 v1, 7, v1
	v_lshlrev_b16_e32 v97, 7, v2
	v_add_u16_e32 v102, 0xe00, v1
	s_or_b64 exec, exec, s[18:19]
	s_mov_b32 s13, 0xaaab
	v_mul_u32_u24_sdwa v1, v0, s13 dst_sel:DWORD dst_unused:UNUSED_PAD src0_sel:WORD_0 src1_sel:DWORD
	v_lshrrev_b32_e32 v1, 21, v1
	v_mul_lo_u16_e32 v2, 48, v1
	v_sub_u16_e32 v0, v0, v2
	v_lshlrev_b16_e32 v92, 7, v0
	v_mov_b32_e32 v73, 0x358637bd
	s_and_saveexec_b64 s[18:19], s[38:39]
	s_cbranch_execz .LBB0_267
	v_lshlrev_b32_e32 v116, 2, v92
	v_lshl_add_u64 v[2:3], v[84:85], 0, v[116:117]
	global_load_dword v2, v[2:3], off sc1
	s_waitcnt vmcnt(0)
	v_cvt_f32_u32_e32 v2, v2
	v_fmamk_f32 v73, v2, 0x36800000, v212
.LBB0_267:
	s_or_b64 exec, exec, s[18:19]
	v_and_b32_e32 v93, 0xffff, v1
	v_mov_b32_e32 v1, 0xe00
	v_lshl_add_u32 v4, v93, 7, v1
	v_add_u32_e32 v1, 0xfffff000, v92
	v_lshrrev_b32_e32 v1, 10, v1
	v_add_u32_e32 v1, 1, v1
	v_cmp_lt_u16_e32 vcc, 31, v0
	s_mul_i32 s13, s12, 3
	v_mov_b64_e32 v[2:3], s[10:11]
	v_cndmask_b32_e32 v1, 0, v1, vcc
	v_add_u32_e32 v1, s13, v1
	s_mov_b32 s13, 0xd000
	v_mad_u64_u32 v[2:3], s[18:19], v1, s13, v[2:3]
	v_lshlrev_b32_e32 v116, 2, v4
	v_lshl_add_u64 v[2:3], v[2:3], 0, v[116:117]
	v_mov_b32_e32 v89, v117
	v_lshl_add_u64 v[2:3], v[2:3], 0, v[88:89]
	v_mov_b32_e32 v91, v117
	v_lshl_add_u64 v[2:3], v[2:3], 0, v[90:91]
	global_load_dword v89, v[2:3], off sc1
	global_load_dword v91, v[2:3], off offset:128 sc1
	global_load_dword v200, v[2:3], off offset:512 sc1
	global_load_dword v201, v[2:3], off offset:640 sc1
	v_mov_b32_e32 v1, s31
	v_lshlrev_b64 v[0:1], 18, v[0:1]
	v_lshlrev_b32_e32 v116, 11, v4
	v_lshl_add_u64 v[64:65], v[80:81], 0, v[0:1]
	v_lshl_add_u64 v[66:67], v[82:83], 0, v[116:117]
	s_mov_b64 s[18:19], -1
	s_andn2_b64 vcc, exec, s[16:17]
	v_add_u32_e32 v79, 0x400, v94
	v_add_u32_e32 v78, 0x2000, v94
	v_add_u32_e32 v77, 0x2400, v94
	v_add_u32_e32 v76, 0x4000, v94
	v_add_u32_e32 v75, 0x4400, v94
	v_add_u32_e32 v74, 0x6000, v94
	v_add_u32_e32 v72, 0x6400, v94
	v_add_u32_e32 v71, 0x8000, v94
	v_add_u32_e32 v70, 0x8400, v94
	v_add_u32_e32 v69, 0xa000, v94
	v_add_u32_e32 v68, 0xa400, v94
	s_cbranch_vccnz .LBB0_269
	v_readfirstlane_b32 s13, v94
	s_mov_b32 m0, s13
	s_mov_b64 s[16:17], 0x400
	v_readfirstlane_b32 s13, v79
	global_load_lds_dwordx4 v[64:65], off sc1
	v_lshl_add_u64 v[0:1], v[64:65], 0, s[16:17]
	s_mov_b32 m0, s13
	v_readfirstlane_b32 s13, v78
	global_load_lds_dwordx4 v[0:1], off sc1
	s_mov_b32 m0, s13
	v_readfirstlane_b32 s13, v77
	global_load_lds_dwordx4 v[66:67], off sc1
	v_lshl_add_u64 v[0:1], v[66:67], 0, s[16:17]
	s_mov_b32 m0, s13
	v_readfirstlane_b32 s13, v76
	global_load_lds_dwordx4 v[0:1], off sc1
	v_lshl_add_u64 v[0:1], v[64:65], 0, s[44:45]
	s_mov_b32 m0, s13
	v_readfirstlane_b32 s13, v75
	global_load_lds_dwordx4 v[0:1], off sc1
	v_lshl_add_u64 v[0:1], v[64:65], 0, s[66:67]
	s_mov_b32 m0, s13
	v_readfirstlane_b32 s13, v74
	global_load_lds_dwordx4 v[0:1], off sc1
	v_lshl_add_u64 v[0:1], v[66:67], 0, s[44:45]
	s_mov_b32 m0, s13
	v_readfirstlane_b32 s13, v72
	global_load_lds_dwordx4 v[0:1], off sc1
	v_lshl_add_u64 v[0:1], v[66:67], 0, s[66:67]
	s_mov_b32 m0, s13
	v_readfirstlane_b32 s13, v71
	global_load_lds_dwordx4 v[0:1], off sc1
	v_lshl_add_u64 v[0:1], v[64:65], 0, s[28:29]
	s_mov_b32 m0, s13
	s_mov_b64 s[16:17], 0x4400
	v_readfirstlane_b32 s13, v70
	global_load_lds_dwordx4 v[0:1], off sc1
	v_lshl_add_u64 v[0:1], v[64:65], 0, s[16:17]
	s_mov_b32 m0, s13
	v_readfirstlane_b32 s13, v69
	global_load_lds_dwordx4 v[0:1], off sc1
	v_lshl_add_u64 v[0:1], v[66:67], 0, s[28:29]
	s_mov_b32 m0, s13
	v_readfirstlane_b32 s13, v68
	global_load_lds_dwordx4 v[0:1], off sc1
	v_lshl_add_u64 v[0:1], v[66:67], 0, s[16:17]
	s_mov_b32 m0, s13
	s_mov_b64 s[18:19], 0
	global_load_lds_dwordx4 v[0:1], off sc1
	s_waitcnt vmcnt(8)

.Lgt_pair:
	s_mov_b32 s62, 1
	v_add_u32_e32 v116, v95, v99
	v_add_u32_e32 v119, v98, v99
	v_add_u32_e32 v122, v95, v100
	v_add_u32_e32 v125, v98, v100
	v_add_u32_e32 v243, 0x4000, v119
	v_add_u32_e32 v248, 0x4000, v125
	v_readfirstlane_b32 s50, v94
	s_mov_b64 s[72:73], 0x40000
	s_mov_b64 s[86:87], 0x4000
	s_add_u32 s51, s50, 0x4000
	s_add_u32 s52, s50, 0x8000
	s_add_u32 s53, s50, 0x2000
	s_add_u32 s54, s50, 0x6000
	s_add_u32 s55, s50, 0xa000
	s_add_u32 s56, s50, 0xc000
	s_add_u32 s57, s50, 0xe000
	s_add_u32 s58, s50, 0x12000
	v_lshl_add_u64 v[78:79], v[66:67], 0, s[72:73]
	s_mov_b32 m0, s56
	s_nop 0
	global_load_lds_dwordx4 v[78:79], off sc1
	global_load_lds_dwordx4 v[78:79], off offset:1024 sc1
	v_lshl_add_u64 v[78:79], v[78:79], 0, s[44:45]
	s_mov_b32 m0, s57
	s_nop 0
	global_load_lds_dwordx4 v[78:79], off sc1
	global_load_lds_dwordx4 v[78:79], off offset:1024 sc1
	v_lshl_add_u64 v[78:79], v[78:79], 0, s[44:45]
	s_mov_b32 m0, s58
	s_nop 0
	global_load_lds_dwordx4 v[78:79], off sc1
	global_load_lds_dwordx4 v[78:79], off offset:1024 sc1
	v_lshl_add_u64 v[64:65], v[64:65], 0, s[86:87]
	v_lshl_add_u64 v[66:67], v[66:67], 0, s[86:87]
	s_waitcnt vmcnt(4)
	s_waitcnt lgkmcnt(0)
	s_barrier
	ds_read_b128 v[104:107], v116
	ds_read_b128 v[112:115], v119 offset:8192
	ds_read_b128 v[128:131], v119 offset:10240
	ds_read_b128 v[132:135], v119 offset:49152
	ds_read_b128 v[204:207], v119 offset:51200
	ds_read_b128 v[108:111], v116 offset:2048
	ds_read_b128 v[208:211], v122
	ds_read_b128 v[244:247], v125 offset:8192
	ds_read_b128 v[250:253], v125 offset:10240
	ds_read_b128 v[68:71], v125 offset:49152
	ds_read_b128 v[214:217], v122 offset:2048
	ds_read_b128 v[74:77], v125 offset:51200
	s_waitcnt lgkmcnt(6)
	v_mfma_f32_32x32x16_bf16 v[48:63], v[104:107], v[112:115], 0
	v_mfma_f32_32x32x16_bf16 v[32:47], v[104:107], v[128:131], 0
	v_mfma_f32_32x32x16_bf16 v[136:151], v[104:107], v[132:135], 0
	v_mfma_f32_32x32x16_bf16 v[152:167], v[104:107], v[204:207], 0
	v_mfma_f32_32x32x16_bf16 v[16:31], v[108:111], v[112:115], 0
	v_mfma_f32_32x32x16_bf16 v[0:15], v[108:111], v[128:131], 0
	v_mfma_f32_32x32x16_bf16 v[168:183], v[108:111], v[132:135], 0
	v_mfma_f32_32x32x16_bf16 v[184:199], v[108:111], v[204:207], 0
	s_waitcnt vmcnt(2)
	s_waitcnt lgkmcnt(0)
	s_barrier
	ds_read_b128 v[104:107], v116 offset:16384
	ds_read_b128 v[112:115], v119 offset:24576
	v_mfma_f32_32x32x16_bf16 v[48:63], v[208:211], v[244:247], v[48:63]
	ds_read_b128 v[128:131], v119 offset:26624
	ds_read_b128 v[132:135], v243 offset:40960
	v_mfma_f32_32x32x16_bf16 v[32:47], v[208:211], v[250:253], v[32:47]
	ds_read_b128 v[204:207], v243 offset:43008
	ds_read_b128 v[108:111], v116 offset:18432
	v_mfma_f32_32x32x16_bf16 v[136:151], v[208:211], v[68:71], v[136:151]
	v_mfma_f32_32x32x16_bf16 v[152:167], v[208:211], v[74:77], v[152:167]
	ds_read_b128 v[208:211], v122 offset:16384
	v_mfma_f32_32x32x16_bf16 v[16:31], v[214:217], v[244:247], v[16:31]
	ds_read_b128 v[244:247], v125 offset:24576
	v_mfma_f32_32x32x16_bf16 v[0:15], v[214:217], v[250:253], v[0:15]
	ds_read_b128 v[250:253], v125 offset:26624
	v_mfma_f32_32x32x16_bf16 v[168:183], v[214:217], v[68:71], v[168:183]
	ds_read_b128 v[68:71], v248 offset:40960
	v_mfma_f32_32x32x16_bf16 v[184:199], v[214:217], v[74:77], v[184:199]
	ds_read_b128 v[214:217], v122 offset:18432
	ds_read_b128 v[74:77], v248 offset:43008
	s_waitcnt lgkmcnt(6)
	v_mfma_f32_32x32x16_bf16 v[48:63], v[104:107], v[112:115], v[48:63]
	s_mov_b32 m0, s50
	v_lshl_add_u64 v[64:65], v[64:65], 0, s[44:45]
	global_load_lds_dwordx4 v[64:65], off sc1
	v_mfma_f32_32x32x16_bf16 v[32:47], v[104:107], v[128:131], v[32:47]
	global_load_lds_dwordx4 v[64:65], off offset:1024 sc1
	v_mfma_f32_32x32x16_bf16 v[136:151], v[104:107], v[132:135], v[136:151]
	s_mov_b32 m0, s53
	v_lshl_add_u64 v[66:67], v[66:67], 0, s[44:45]
	global_load_lds_dwordx4 v[66:67], off sc1
	v_mfma_f32_32x32x16_bf16 v[152:167], v[104:107], v[204:207], v[152:167]
	global_load_lds_dwordx4 v[66:67], off offset:1024 sc1
	v_mfma_f32_32x32x16_bf16 v[16:31], v[108:111], v[112:115], v[16:31]
	s_mov_b32 m0, s56
	v_lshl_add_u64 v[78:79], v[66:67], 0, s[72:73]
	global_load_lds_dwordx4 v[78:79], off sc1
	v_mfma_f32_32x32x16_bf16 v[0:15], v[108:111], v[128:131], v[0:15]
	global_load_lds_dwordx4 v[78:79], off offset:1024 sc1
	v_mfma_f32_32x32x16_bf16 v[168:183], v[108:111], v[132:135], v[168:183]
	v_mfma_f32_32x32x16_bf16 v[184:199], v[108:111], v[204:207], v[184:199]
	s_waitcnt vmcnt(6)
	s_waitcnt lgkmcnt(0)
	s_barrier
	ds_read_b128 v[104:107], v116 offset:32768
	ds_read_b128 v[112:115], v119 offset:40960
	v_mfma_f32_32x32x16_bf16 v[48:63], v[208:211], v[244:247], v[48:63]
	ds_read_b128 v[128:131], v119 offset:43008
	ds_read_b128 v[132:135], v243 offset:57344
	v_mfma_f32_32x32x16_bf16 v[32:47], v[208:211], v[250:253], v[32:47]
	ds_read_b128 v[204:207], v243 offset:59392
	ds_read_b128 v[108:111], v116 offset:34816
	v_mfma_f32_32x32x16_bf16 v[136:151], v[208:211], v[68:71], v[136:151]
	v_mfma_f32_32x32x16_bf16 v[152:167], v[208:211], v[74:77], v[152:167]
	ds_read_b128 v[208:211], v122 offset:32768
	v_mfma_f32_32x32x16_bf16 v[16:31], v[214:217], v[244:247], v[16:31]
	ds_read_b128 v[244:247], v125 offset:40960
	v_mfma_f32_32x32x16_bf16 v[0:15], v[214:217], v[250:253], v[0:15]
	ds_read_b128 v[250:253], v125 offset:43008
	v_mfma_f32_32x32x16_bf16 v[168:183], v[214:217], v[68:71], v[168:183]
	ds_read_b128 v[68:71], v248 offset:57344
	v_mfma_f32_32x32x16_bf16 v[184:199], v[214:217], v[74:77], v[184:199]
	ds_read_b128 v[214:217], v122 offset:34816
	ds_read_b128 v[74:77], v248 offset:59392
	s_waitcnt lgkmcnt(6)
	v_mfma_f32_32x32x16_bf16 v[48:63], v[104:107], v[112:115], v[48:63]
	s_mov_b32 m0, s51
	v_lshl_add_u64 v[64:65], v[64:65], 0, s[44:45]
	global_load_lds_dwordx4 v[64:65], off sc1
	v_mfma_f32_32x32x16_bf16 v[32:47], v[104:107], v[128:131], v[32:47]
	global_load_lds_dwordx4 v[64:65], off offset:1024 sc1
	v_mfma_f32_32x32x16_bf16 v[136:151], v[104:107], v[132:135], v[136:151]
	s_mov_b32 m0, s54
	v_lshl_add_u64 v[66:67], v[66:67], 0, s[44:45]
	global_load_lds_dwordx4 v[66:67], off sc1
	v_mfma_f32_32x32x16_bf16 v[152:167], v[104:107], v[204:207], v[152:167]
	global_load_lds_dwordx4 v[66:67], off offset:1024 sc1
	v_mfma_f32_32x32x16_bf16 v[16:31], v[108:111], v[112:115], v[16:31]
	s_mov_b32 m0, s57
	v_lshl_add_u64 v[78:79], v[66:67], 0, s[72:73]
	global_load_lds_dwordx4 v[78:79], off sc1
	v_mfma_f32_32x32x16_bf16 v[0:15], v[108:111], v[128:131], v[0:15]
	global_load_lds_dwordx4 v[78:79], off offset:1024 sc1
	v_mfma_f32_32x32x16_bf16 v[168:183], v[108:111], v[132:135], v[168:183]
	v_mfma_f32_32x32x16_bf16 v[184:199], v[108:111], v[204:207], v[184:199]
	s_waitcnt vmcnt(6)
	s_waitcnt lgkmcnt(0)
	s_barrier
	ds_read_b128 v[104:107], v116
	ds_read_b128 v[112:115], v119 offset:8192
	v_mfma_f32_32x32x16_bf16 v[48:63], v[208:211], v[244:247], v[48:63]
	ds_read_b128 v[128:131], v119 offset:10240
	ds_read_b128 v[132:135], v119 offset:49152
	v_mfma_f32_32x32x16_bf16 v[32:47], v[208:211], v[250:253], v[32:47]
	ds_read_b128 v[204:207], v119 offset:51200
	ds_read_b128 v[108:111], v116 offset:2048
	v_mfma_f32_32x32x16_bf16 v[136:151], v[208:211], v[68:71], v[136:151]
	v_mfma_f32_32x32x16_bf16 v[152:167], v[208:211], v[74:77], v[152:167]
	ds_read_b128 v[208:211], v122
	v_mfma_f32_32x32x16_bf16 v[16:31], v[214:217], v[244:247], v[16:31]
	ds_read_b128 v[244:247], v125 offset:8192
	v_mfma_f32_32x32x16_bf16 v[0:15], v[214:217], v[250:253], v[0:15]
	ds_read_b128 v[250:253], v125 offset:10240
	v_mfma_f32_32x32x16_bf16 v[168:183], v[214:217], v[68:71], v[168:183]
	ds_read_b128 v[68:71], v125 offset:49152
	v_mfma_f32_32x32x16_bf16 v[184:199], v[214:217], v[74:77], v[184:199]
	ds_read_b128 v[214:217], v122 offset:2048
	ds_read_b128 v[74:77], v125 offset:51200
	s_waitcnt lgkmcnt(6)
	v_mfma_f32_32x32x16_bf16 v[48:63], v[104:107], v[112:115], v[48:63]
	s_mov_b32 m0, s52
	v_lshl_add_u64 v[64:65], v[64:65], 0, s[44:45]
	global_load_lds_dwordx4 v[64:65], off sc1
	v_mfma_f32_32x32x16_bf16 v[32:47], v[104:107], v[128:131], v[32:47]
	global_load_lds_dwordx4 v[64:65], off offset:1024 sc1
	v_mfma_f32_32x32x16_bf16 v[136:151], v[104:107], v[132:135], v[136:151]
	s_mov_b32 m0, s55
	v_lshl_add_u64 v[66:67], v[66:67], 0, s[44:45]
	global_load_lds_dwordx4 v[66:67], off sc1
	v_mfma_f32_32x32x16_bf16 v[152:167], v[104:107], v[204:207], v[152:167]
	global_load_lds_dwordx4 v[66:67], off offset:1024 sc1
	v_mfma_f32_32x32x16_bf16 v[16:31], v[108:111], v[112:115], v[16:31]
	s_mov_b32 m0, s58
	v_lshl_add_u64 v[78:79], v[66:67], 0, s[72:73]
	global_load_lds_dwordx4 v[78:79], off sc1
	v_mfma_f32_32x32x16_bf16 v[0:15], v[108:111], v[128:131], v[0:15]
	global_load_lds_dwordx4 v[78:79], off offset:1024 sc1
	v_mfma_f32_32x32x16_bf16 v[168:183], v[108:111], v[132:135], v[168:183]
	v_mfma_f32_32x32x16_bf16 v[184:199], v[108:111], v[204:207], v[184:199]
	s_waitcnt vmcnt(6)
	s_waitcnt lgkmcnt(0)
	s_barrier
	ds_read_b128 v[104:107], v116 offset:16384
	ds_read_b128 v[112:115], v119 offset:24576
	v_mfma_f32_32x32x16_bf16 v[48:63], v[208:211], v[244:247], v[48:63]
	ds_read_b128 v[128:131], v119 offset:26624
	ds_read_b128 v[132:135], v243 offset:40960
	v_mfma_f32_32x32x16_bf16 v[32:47], v[208:211], v[250:253], v[32:47]
	ds_read_b128 v[204:207], v243 offset:43008
	ds_read_b128 v[108:111], v116 offset:18432
	v_mfma_f32_32x32x16_bf16 v[136:151], v[208:211], v[68:71], v[136:151]
	v_mfma_f32_32x32x16_bf16 v[152:167], v[208:211], v[74:77], v[152:167]
	ds_read_b128 v[208:211], v122 offset:16384
	v_mfma_f32_32x32x16_bf16 v[16:31], v[214:217], v[244:247], v[16:31]
	ds_read_b128 v[244:247], v125 offset:24576
	v_mfma_f32_32x32x16_bf16 v[0:15], v[214:217], v[250:253], v[0:15]
	ds_read_b128 v[250:253], v125 offset:26624
	v_mfma_f32_32x32x16_bf16 v[168:183], v[214:217], v[68:71], v[168:183]
	ds_read_b128 v[68:71], v248 offset:40960
	v_mfma_f32_32x32x16_bf16 v[184:199], v[214:217], v[74:77], v[184:199]
	ds_read_b128 v[214:217], v122 offset:18432
	ds_read_b128 v[74:77], v248 offset:43008
	s_waitcnt lgkmcnt(6)
	v_mfma_f32_32x32x16_bf16 v[48:63], v[104:107], v[112:115], v[48:63]
	s_mov_b32 m0, s50
	v_lshl_add_u64 v[64:65], v[64:65], 0, s[44:45]
	global_load_lds_dwordx4 v[64:65], off sc1
	v_mfma_f32_32x32x16_bf16 v[32:47], v[104:107], v[128:131], v[32:47]
	global_load_lds_dwordx4 v[64:65], off offset:1024 sc1
	v_mfma_f32_32x32x16_bf16 v[136:151], v[104:107], v[132:135], v[136:151]
	s_mov_b32 m0, s53
	v_lshl_add_u64 v[66:67], v[66:67], 0, s[44:45]
	global_load_lds_dwordx4 v[66:67], off sc1
	v_mfma_f32_32x32x16_bf16 v[152:167], v[104:107], v[204:207], v[152:167]
	global_load_lds_dwordx4 v[66:67], off offset:1024 sc1
	v_mfma_f32_32x32x16_bf16 v[16:31], v[108:111], v[112:115], v[16:31]
	s_mov_b32 m0, s56
	v_lshl_add_u64 v[78:79], v[66:67], 0, s[72:73]
	global_load_lds_dwordx4 v[78:79], off sc1
	v_mfma_f32_32x32x16_bf16 v[0:15], v[108:111], v[128:131], v[0:15]
	global_load_lds_dwordx4 v[78:79], off offset:1024 sc1
	v_mfma_f32_32x32x16_bf16 v[168:183], v[108:111], v[132:135], v[168:183]
	v_mfma_f32_32x32x16_bf16 v[184:199], v[108:111], v[204:207], v[184:199]
	s_waitcnt vmcnt(6)
	s_waitcnt lgkmcnt(0)
	s_barrier
	ds_read_b128 v[104:107], v116 offset:32768
	ds_read_b128 v[112:115], v119 offset:40960
	v_mfma_f32_32x32x16_bf16 v[48:63], v[208:211], v[244:247], v[48:63]
	ds_read_b128 v[128:131], v119 offset:43008
	ds_read_b128 v[132:135], v243 offset:57344
	v_mfma_f32_32x32x16_bf16 v[32:47], v[208:211], v[250:253], v[32:47]
	ds_read_b128 v[204:207], v243 offset:59392
	ds_read_b128 v[108:111], v116 offset:34816
	v_mfma_f32_32x32x16_bf16 v[136:151], v[208:211], v[68:71], v[136:151]
	v_mfma_f32_32x32x16_bf16 v[152:167], v[208:211], v[74:77], v[152:167]
	ds_read_b128 v[208:211], v122 offset:32768
	v_mfma_f32_32x32x16_bf16 v[16:31], v[214:217], v[244:247], v[16:31]
	ds_read_b128 v[244:247], v125 offset:40960
	v_mfma_f32_32x32x16_bf16 v[0:15], v[214:217], v[250:253], v[0:15]
	ds_read_b128 v[250:253], v125 offset:43008
	v_mfma_f32_32x32x16_bf16 v[168:183], v[214:217], v[68:71], v[168:183]
	ds_read_b128 v[68:71], v248 offset:57344
	v_mfma_f32_32x32x16_bf16 v[184:199], v[214:217], v[74:77], v[184:199]
	ds_read_b128 v[214:217], v122 offset:34816
	ds_read_b128 v[74:77], v248 offset:59392
	s_waitcnt lgkmcnt(6)
	v_mfma_f32_32x32x16_bf16 v[48:63], v[104:107], v[112:115], v[48:63]
	s_mov_b32 m0, s51
	v_lshl_add_u64 v[64:65], v[64:65], 0, s[44:45]
	global_load_lds_dwordx4 v[64:65], off sc1
	v_mfma_f32_32x32x16_bf16 v[32:47], v[104:107], v[128:131], v[32:47]
	global_load_lds_dwordx4 v[64:65], off offset:1024 sc1
	v_mfma_f32_32x32x16_bf16 v[136:151], v[104:107], v[132:135], v[136:151]
	s_mov_b32 m0, s54
	v_lshl_add_u64 v[66:67], v[66:67], 0, s[44:45]
	global_load_lds_dwordx4 v[66:67], off sc1
	v_mfma_f32_32x32x16_bf16 v[152:167], v[104:107], v[204:207], v[152:167]
	global_load_lds_dwordx4 v[66:67], off offset:1024 sc1
	v_mfma_f32_32x32x16_bf16 v[16:31], v[108:111], v[112:115], v[16:31]
	s_mov_b32 m0, s57
	v_lshl_add_u64 v[78:79], v[66:67], 0, s[72:73]
	global_load_lds_dwordx4 v[78:79], off sc1
	v_mfma_f32_32x32x16_bf16 v[0:15], v[108:111], v[128:131], v[0:15]
	global_load_lds_dwordx4 v[78:79], off offset:1024 sc1
	v_mfma_f32_32x32x16_bf16 v[168:183], v[108:111], v[132:135], v[168:183]
	v_mfma_f32_32x32x16_bf16 v[184:199], v[108:111], v[204:207], v[184:199]
	s_waitcnt vmcnt(6)
	s_waitcnt lgkmcnt(0)
	s_barrier
	ds_read_b128 v[104:107], v116
	ds_read_b128 v[112:115], v119 offset:8192
	v_mfma_f32_32x32x16_bf16 v[48:63], v[208:211], v[244:247], v[48:63]
	ds_read_b128 v[128:131], v119 offset:10240
	ds_read_b128 v[132:135], v119 offset:49152
	v_mfma_f32_32x32x16_bf16 v[32:47], v[208:211], v[250:253], v[32:47]
	ds_read_b128 v[204:207], v119 offset:51200
	ds_read_b128 v[108:111], v116 offset:2048
	v_mfma_f32_32x32x16_bf16 v[136:151], v[208:211], v[68:71], v[136:151]
	v_mfma_f32_32x32x16_bf16 v[152:167], v[208:211], v[74:77], v[152:167]
	ds_read_b128 v[208:211], v122
	v_mfma_f32_32x32x16_bf16 v[16:31], v[214:217], v[244:247], v[16:31]
	ds_read_b128 v[244:247], v125 offset:8192
	v_mfma_f32_32x32x16_bf16 v[0:15], v[214:217], v[250:253], v[0:15]
	ds_read_b128 v[250:253], v125 offset:10240
	v_mfma_f32_32x32x16_bf16 v[168:183], v[214:217], v[68:71], v[168:183]
	ds_read_b128 v[68:71], v125 offset:49152
	v_mfma_f32_32x32x16_bf16 v[184:199], v[214:217], v[74:77], v[184:199]
	ds_read_b128 v[214:217], v122 offset:2048
	ds_read_b128 v[74:77], v125 offset:51200
	s_waitcnt lgkmcnt(6)
	v_mfma_f32_32x32x16_bf16 v[48:63], v[104:107], v[112:115], v[48:63]
	s_mov_b32 m0, s52
	v_lshl_add_u64 v[64:65], v[64:65], 0, s[44:45]
	global_load_lds_dwordx4 v[64:65], off sc1
	v_mfma_f32_32x32x16_bf16 v[32:47], v[104:107], v[128:131], v[32:47]
	global_load_lds_dwordx4 v[64:65], off offset:1024 sc1
	v_mfma_f32_32x32x16_bf16 v[136:151], v[104:107], v[132:135], v[136:151]
	s_mov_b32 m0, s55
	v_lshl_add_u64 v[66:67], v[66:67], 0, s[44:45]
	global_load_lds_dwordx4 v[66:67], off sc1
	v_mfma_f32_32x32x16_bf16 v[152:167], v[104:107], v[204:207], v[152:167]
	global_load_lds_dwordx4 v[66:67], off offset:1024 sc1
	v_mfma_f32_32x32x16_bf16 v[16:31], v[108:111], v[112:115], v[16:31]
	s_mov_b32 m0, s58
	v_lshl_add_u64 v[78:79], v[66:67], 0, s[72:73]
	global_load_lds_dwordx4 v[78:79], off sc1
	v_mfma_f32_32x32x16_bf16 v[0:15], v[108:111], v[128:131], v[0:15]
	global_load_lds_dwordx4 v[78:79], off offset:1024 sc1
	v_mfma_f32_32x32x16_bf16 v[168:183], v[108:111], v[132:135], v[168:183]
	v_mfma_f32_32x32x16_bf16 v[184:199], v[108:111], v[204:207], v[184:199]
	s_waitcnt vmcnt(6)
	s_waitcnt lgkmcnt(0)
	s_barrier
	ds_read_b128 v[104:107], v116 offset:16384
	ds_read_b128 v[112:115], v119 offset:24576
	v_mfma_f32_32x32x16_bf16 v[48:63], v[208:211], v[244:247], v[48:63]
	ds_read_b128 v[128:131], v119 offset:26624
	ds_read_b128 v[132:135], v243 offset:40960
	v_mfma_f32_32x32x16_bf16 v[32:47], v[208:211], v[250:253], v[32:47]
	ds_read_b128 v[204:207], v243 offset:43008
	ds_read_b128 v[108:111], v116 offset:18432
	v_mfma_f32_32x32x16_bf16 v[136:151], v[208:211], v[68:71], v[136:151]
	v_mfma_f32_32x32x16_bf16 v[152:167], v[208:211], v[74:77], v[152:167]
	ds_read_b128 v[208:211], v122 offset:16384
	v_mfma_f32_32x32x16_bf16 v[16:31], v[214:217], v[244:247], v[16:31]
	ds_read_b128 v[244:247], v125 offset:24576
	v_mfma_f32_32x32x16_bf16 v[0:15], v[214:217], v[250:253], v[0:15]
	ds_read_b128 v[250:253], v125 offset:26624
	v_mfma_f32_32x32x16_bf16 v[168:183], v[214:217], v[68:71], v[168:183]
	ds_read_b128 v[68:71], v248 offset:40960
	v_mfma_f32_32x32x16_bf16 v[184:199], v[214:217], v[74:77], v[184:199]
	ds_read_b128 v[214:217], v122 offset:18432
	ds_read_b128 v[74:77], v248 offset:43008
	s_waitcnt lgkmcnt(6)
	v_mfma_f32_32x32x16_bf16 v[48:63], v[104:107], v[112:115], v[48:63]
	s_mov_b32 m0, s50
	v_lshl_add_u64 v[64:65], v[64:65], 0, s[44:45]
	global_load_lds_dwordx4 v[64:65], off sc1
	v_mfma_f32_32x32x16_bf16 v[32:47], v[104:107], v[128:131], v[32:47]
	global_load_lds_dwordx4 v[64:65], off offset:1024 sc1
	v_mfma_f32_32x32x16_bf16 v[136:151], v[104:107], v[132:135], v[136:151]
	s_mov_b32 m0, s53
	v_lshl_add_u64 v[66:67], v[66:67], 0, s[44:45]
	global_load_lds_dwordx4 v[66:67], off sc1
	v_mfma_f32_32x32x16_bf16 v[152:167], v[104:107], v[204:207], v[152:167]
	global_load_lds_dwordx4 v[66:67], off offset:1024 sc1
	v_mfma_f32_32x32x16_bf16 v[16:31], v[108:111], v[112:115], v[16:31]
	s_mov_b32 m0, s56
	v_lshl_add_u64 v[78:79], v[66:67], 0, s[72:73]
	global_load_lds_dwordx4 v[78:79], off sc1
	v_mfma_f32_32x32x16_bf16 v[0:15], v[108:111], v[128:131], v[0:15]
	global_load_lds_dwordx4 v[78:79], off offset:1024 sc1
	v_mfma_f32_32x32x16_bf16 v[168:183], v[108:111], v[132:135], v[168:183]
	v_mfma_f32_32x32x16_bf16 v[184:199], v[108:111], v[204:207], v[184:199]
	s_waitcnt vmcnt(6)
	s_waitcnt lgkmcnt(0)
	s_barrier
	ds_read_b128 v[104:107], v116 offset:32768
	ds_read_b128 v[112:115], v119 offset:40960
	v_mfma_f32_32x32x16_bf16 v[48:63], v[208:211], v[244:247], v[48:63]
	ds_read_b128 v[128:131], v119 offset:43008
	ds_read_b128 v[132:135], v243 offset:57344
	v_mfma_f32_32x32x16_bf16 v[32:47], v[208:211], v[250:253], v[32:47]
	ds_read_b128 v[204:207], v243 offset:59392
	ds_read_b128 v[108:111], v116 offset:34816
	v_mfma_f32_32x32x16_bf16 v[136:151], v[208:211], v[68:71], v[136:151]
	v_mfma_f32_32x32x16_bf16 v[152:167], v[208:211], v[74:77], v[152:167]
	ds_read_b128 v[208:211], v122 offset:32768
	v_mfma_f32_32x32x16_bf16 v[16:31], v[214:217], v[244:247], v[16:31]
	ds_read_b128 v[244:247], v125 offset:40960
	v_mfma_f32_32x32x16_bf16 v[0:15], v[214:217], v[250:253], v[0:15]
	ds_read_b128 v[250:253], v125 offset:43008
	v_mfma_f32_32x32x16_bf16 v[168:183], v[214:217], v[68:71], v[168:183]
	ds_read_b128 v[68:71], v248 offset:57344
	v_mfma_f32_32x32x16_bf16 v[184:199], v[214:217], v[74:77], v[184:199]
	ds_read_b128 v[214:217], v122 offset:34816
	ds_read_b128 v[74:77], v248 offset:59392
	s_waitcnt lgkmcnt(6)
	v_mfma_f32_32x32x16_bf16 v[48:63], v[104:107], v[112:115], v[48:63]
	s_mov_b32 m0, s51
	v_lshl_add_u64 v[64:65], v[64:65], 0, s[44:45]
	global_load_lds_dwordx4 v[64:65], off sc1
	v_mfma_f32_32x32x16_bf16 v[32:47], v[104:107], v[128:131], v[32:47]
	global_load_lds_dwordx4 v[64:65], off offset:1024 sc1
	v_mfma_f32_32x32x16_bf16 v[136:151], v[104:107], v[132:135], v[136:151]
	s_mov_b32 m0, s54
	v_lshl_add_u64 v[66:67], v[66:67], 0, s[44:45]
	global_load_lds_dwordx4 v[66:67], off sc1
	v_mfma_f32_32x32x16_bf16 v[152:167], v[104:107], v[204:207], v[152:167]
	global_load_lds_dwordx4 v[66:67], off offset:1024 sc1
	v_mfma_f32_32x32x16_bf16 v[16:31], v[108:111], v[112:115], v[16:31]
	s_mov_b32 m0, s57
	v_lshl_add_u64 v[78:79], v[66:67], 0, s[72:73]
	global_load_lds_dwordx4 v[78:79], off sc1
	v_mfma_f32_32x32x16_bf16 v[0:15], v[108:111], v[128:131], v[0:15]
	global_load_lds_dwordx4 v[78:79], off offset:1024 sc1
	v_mfma_f32_32x32x16_bf16 v[168:183], v[108:111], v[132:135], v[168:183]
	v_mfma_f32_32x32x16_bf16 v[184:199], v[108:111], v[204:207], v[184:199]
	s_waitcnt vmcnt(6)
	s_waitcnt lgkmcnt(0)
	s_barrier
	ds_read_b128 v[104:107], v116
	ds_read_b128 v[112:115], v119 offset:8192
	v_mfma_f32_32x32x16_bf16 v[48:63], v[208:211], v[244:247], v[48:63]
	ds_read_b128 v[128:131], v119 offset:10240
	ds_read_b128 v[132:135], v119 offset:49152
	v_mfma_f32_32x32x16_bf16 v[32:47], v[208:211], v[250:253], v[32:47]
	ds_read_b128 v[204:207], v119 offset:51200
	ds_read_b128 v[108:111], v116 offset:2048
	v_mfma_f32_32x32x16_bf16 v[136:151], v[208:211], v[68:71], v[136:151]
	v_mfma_f32_32x32x16_bf16 v[152:167], v[208:211], v[74:77], v[152:167]
	ds_read_b128 v[208:211], v122
	v_mfma_f32_32x32x16_bf16 v[16:31], v[214:217], v[244:247], v[16:31]
	ds_read_b128 v[244:247], v125 offset:8192
	v_mfma_f32_32x32x16_bf16 v[0:15], v[214:217], v[250:253], v[0:15]
	ds_read_b128 v[250:253], v125 offset:10240
	v_mfma_f32_32x32x16_bf16 v[168:183], v[214:217], v[68:71], v[168:183]
	ds_read_b128 v[68:71], v125 offset:49152
	v_mfma_f32_32x32x16_bf16 v[184:199], v[214:217], v[74:77], v[184:199]
	ds_read_b128 v[214:217], v122 offset:2048
	ds_read_b128 v[74:77], v125 offset:51200
	s_waitcnt lgkmcnt(6)
	v_mfma_f32_32x32x16_bf16 v[48:63], v[104:107], v[112:115], v[48:63]
	s_mov_b32 m0, s52
	v_lshl_add_u64 v[64:65], v[64:65], 0, s[44:45]
	global_load_lds_dwordx4 v[64:65], off sc1
	v_mfma_f32_32x32x16_bf16 v[32:47], v[104:107], v[128:131], v[32:47]
	global_load_lds_dwordx4 v[64:65], off offset:1024 sc1
	v_mfma_f32_32x32x16_bf16 v[136:151], v[104:107], v[132:135], v[136:151]
	s_mov_b32 m0, s55
	v_lshl_add_u64 v[66:67], v[66:67], 0, s[44:45]
	global_load_lds_dwordx4 v[66:67], off sc1
	v_mfma_f32_32x32x16_bf16 v[152:167], v[104:107], v[204:207], v[152:167]
	global_load_lds_dwordx4 v[66:67], off offset:1024 sc1
	v_mfma_f32_32x32x16_bf16 v[16:31], v[108:111], v[112:115], v[16:31]
	s_mov_b32 m0, s58
	v_lshl_add_u64 v[78:79], v[66:67], 0, s[72:73]
	global_load_lds_dwordx4 v[78:79], off sc1
	v_mfma_f32_32x32x16_bf16 v[0:15], v[108:111], v[128:131], v[0:15]
	global_load_lds_dwordx4 v[78:79], off offset:1024 sc1
	v_mfma_f32_32x32x16_bf16 v[168:183], v[108:111], v[132:135], v[168:183]
	v_mfma_f32_32x32x16_bf16 v[184:199], v[108:111], v[204:207], v[184:199]
	s_waitcnt vmcnt(6)
	s_waitcnt lgkmcnt(0)
	s_barrier
	ds_read_b128 v[104:107], v116 offset:16384
	ds_read_b128 v[112:115], v119 offset:24576
	v_mfma_f32_32x32x16_bf16 v[48:63], v[208:211], v[244:247], v[48:63]
	ds_read_b128 v[128:131], v119 offset:26624
	ds_read_b128 v[132:135], v243 offset:40960
	v_mfma_f32_32x32x16_bf16 v[32:47], v[208:211], v[250:253], v[32:47]
	ds_read_b128 v[204:207], v243 offset:43008
	ds_read_b128 v[108:111], v116 offset:18432
	v_mfma_f32_32x32x16_bf16 v[136:151], v[208:211], v[68:71], v[136:151]
	v_mfma_f32_32x32x16_bf16 v[152:167], v[208:211], v[74:77], v[152:167]
	ds_read_b128 v[208:211], v122 offset:16384
	v_mfma_f32_32x32x16_bf16 v[16:31], v[214:217], v[244:247], v[16:31]
	ds_read_b128 v[244:247], v125 offset:24576
	v_mfma_f32_32x32x16_bf16 v[0:15], v[214:217], v[250:253], v[0:15]
	ds_read_b128 v[250:253], v125 offset:26624
	v_mfma_f32_32x32x16_bf16 v[168:183], v[214:217], v[68:71], v[168:183]
	ds_read_b128 v[68:71], v248 offset:40960
	v_mfma_f32_32x32x16_bf16 v[184:199], v[214:217], v[74:77], v[184:199]
	ds_read_b128 v[214:217], v122 offset:18432
	ds_read_b128 v[74:77], v248 offset:43008
	s_waitcnt lgkmcnt(6)
	v_mfma_f32_32x32x16_bf16 v[48:63], v[104:107], v[112:115], v[48:63]
	s_mov_b32 m0, s50
	v_lshl_add_u64 v[64:65], v[64:65], 0, s[44:45]
	global_load_lds_dwordx4 v[64:65], off sc1
	v_mfma_f32_32x32x16_bf16 v[32:47], v[104:107], v[128:131], v[32:47]
	global_load_lds_dwordx4 v[64:65], off offset:1024 sc1
	v_mfma_f32_32x32x16_bf16 v[136:151], v[104:107], v[132:135], v[136:151]
	s_mov_b32 m0, s53
	v_lshl_add_u64 v[66:67], v[66:67], 0, s[44:45]
	global_load_lds_dwordx4 v[66:67], off sc1
	v_mfma_f32_32x32x16_bf16 v[152:167], v[104:107], v[204:207], v[152:167]
	global_load_lds_dwordx4 v[66:67], off offset:1024 sc1
	v_mfma_f32_32x32x16_bf16 v[16:31], v[108:111], v[112:115], v[16:31]
	s_mov_b32 m0, s56
	v_lshl_add_u64 v[78:79], v[66:67], 0, s[72:73]
	global_load_lds_dwordx4 v[78:79], off sc1
	v_mfma_f32_32x32x16_bf16 v[0:15], v[108:111], v[128:131], v[0:15]
	global_load_lds_dwordx4 v[78:79], off offset:1024 sc1
	v_mfma_f32_32x32x16_bf16 v[168:183], v[108:111], v[132:135], v[168:183]
	v_mfma_f32_32x32x16_bf16 v[184:199], v[108:111], v[204:207], v[184:199]
	s_waitcnt vmcnt(6)
	s_waitcnt lgkmcnt(0)
	s_barrier
	ds_read_b128 v[104:107], v116 offset:32768
	ds_read_b128 v[112:115], v119 offset:40960
	v_mfma_f32_32x32x16_bf16 v[48:63], v[208:211], v[244:247], v[48:63]
	ds_read_b128 v[128:131], v119 offset:43008
	ds_read_b128 v[132:135], v243 offset:57344
	v_mfma_f32_32x32x16_bf16 v[32:47], v[208:211], v[250:253], v[32:47]
	ds_read_b128 v[204:207], v243 offset:59392
	ds_read_b128 v[108:111], v116 offset:34816
	v_mfma_f32_32x32x16_bf16 v[136:151], v[208:211], v[68:71], v[136:151]
	v_mfma_f32_32x32x16_bf16 v[152:167], v[208:211], v[74:77], v[152:167]
	ds_read_b128 v[208:211], v122 offset:32768
	v_mfma_f32_32x32x16_bf16 v[16:31], v[214:217], v[244:247], v[16:31]
	ds_read_b128 v[244:247], v125 offset:40960
	v_mfma_f32_32x32x16_bf16 v[0:15], v[214:217], v[250:253], v[0:15]
	ds_read_b128 v[250:253], v125 offset:43008
	v_mfma_f32_32x32x16_bf16 v[168:183], v[214:217], v[68:71], v[168:183]
	ds_read_b128 v[68:71], v248 offset:57344
	v_mfma_f32_32x32x16_bf16 v[184:199], v[214:217], v[74:77], v[184:199]
	ds_read_b128 v[214:217], v122 offset:34816
	ds_read_b128 v[74:77], v248 offset:59392
	s_waitcnt lgkmcnt(6)
	v_mfma_f32_32x32x16_bf16 v[48:63], v[104:107], v[112:115], v[48:63]
	s_mov_b32 m0, s51
	v_lshl_add_u64 v[64:65], v[64:65], 0, s[44:45]
	global_load_lds_dwordx4 v[64:65], off sc1
	v_mfma_f32_32x32x16_bf16 v[32:47], v[104:107], v[128:131], v[32:47]
	global_load_lds_dwordx4 v[64:65], off offset:1024 sc1
	v_mfma_f32_32x32x16_bf16 v[136:151], v[104:107], v[132:135], v[136:151]
	s_mov_b32 m0, s54
	v_lshl_add_u64 v[66:67], v[66:67], 0, s[44:45]
	global_load_lds_dwordx4 v[66:67], off sc1
	v_mfma_f32_32x32x16_bf16 v[152:167], v[104:107], v[204:207], v[152:167]
	global_load_lds_dwordx4 v[66:67], off offset:1024 sc1
	v_mfma_f32_32x32x16_bf16 v[16:31], v[108:111], v[112:115], v[16:31]
	s_mov_b32 m0, s57
	v_lshl_add_u64 v[78:79], v[66:67], 0, s[72:73]
	global_load_lds_dwordx4 v[78:79], off sc1
	v_mfma_f32_32x32x16_bf16 v[0:15], v[108:111], v[128:131], v[0:15]
	global_load_lds_dwordx4 v[78:79], off offset:1024 sc1
	v_mfma_f32_32x32x16_bf16 v[168:183], v[108:111], v[132:135], v[168:183]
	v_mfma_f32_32x32x16_bf16 v[184:199], v[108:111], v[204:207], v[184:199]
	s_waitcnt vmcnt(6)
	s_waitcnt lgkmcnt(0)
	s_barrier
	ds_read_b128 v[104:107], v116
	ds_read_b128 v[112:115], v119 offset:8192
	v_mfma_f32_32x32x16_bf16 v[48:63], v[208:211], v[244:247], v[48:63]
	ds_read_b128 v[128:131], v119 offset:10240
	ds_read_b128 v[132:135], v119 offset:49152
	v_mfma_f32_32x32x16_bf16 v[32:47], v[208:211], v[250:253], v[32:47]
	ds_read_b128 v[204:207], v119 offset:51200
	ds_read_b128 v[108:111], v116 offset:2048
	v_mfma_f32_32x32x16_bf16 v[136:151], v[208:211], v[68:71], v[136:151]
	v_mfma_f32_32x32x16_bf16 v[152:167], v[208:211], v[74:77], v[152:167]
	ds_read_b128 v[208:211], v122
	v_mfma_f32_32x32x16_bf16 v[16:31], v[214:217], v[244:247], v[16:31]
	ds_read_b128 v[244:247], v125 offset:8192
	v_mfma_f32_32x32x16_bf16 v[0:15], v[214:217], v[250:253], v[0:15]
	ds_read_b128 v[250:253], v125 offset:10240
	v_mfma_f32_32x32x16_bf16 v[168:183], v[214:217], v[68:71], v[168:183]
	ds_read_b128 v[68:71], v125 offset:49152
	v_mfma_f32_32x32x16_bf16 v[184:199], v[214:217], v[74:77], v[184:199]
	ds_read_b128 v[214:217], v122 offset:2048
	ds_read_b128 v[74:77], v125 offset:51200
	s_waitcnt lgkmcnt(6)
	v_mfma_f32_32x32x16_bf16 v[48:63], v[104:107], v[112:115], v[48:63]
	s_mov_b32 m0, s52
	v_lshl_add_u64 v[64:65], v[64:65], 0, s[44:45]
	global_load_lds_dwordx4 v[64:65], off sc1
	v_mfma_f32_32x32x16_bf16 v[32:47], v[104:107], v[128:131], v[32:47]
	global_load_lds_dwordx4 v[64:65], off offset:1024 sc1
	v_mfma_f32_32x32x16_bf16 v[136:151], v[104:107], v[132:135], v[136:151]
	s_mov_b32 m0, s55
	v_lshl_add_u64 v[66:67], v[66:67], 0, s[44:45]
	global_load_lds_dwordx4 v[66:67], off sc1
	v_mfma_f32_32x32x16_bf16 v[152:167], v[104:107], v[204:207], v[152:167]
	global_load_lds_dwordx4 v[66:67], off offset:1024 sc1
	v_mfma_f32_32x32x16_bf16 v[16:31], v[108:111], v[112:115], v[16:31]
	s_mov_b32 m0, s58
	v_lshl_add_u64 v[78:79], v[66:67], 0, s[72:73]
	global_load_lds_dwordx4 v[78:79], off sc1
	v_mfma_f32_32x32x16_bf16 v[0:15], v[108:111], v[128:131], v[0:15]
	global_load_lds_dwordx4 v[78:79], off offset:1024 sc1
	v_mfma_f32_32x32x16_bf16 v[168:183], v[108:111], v[132:135], v[168:183]
	v_mfma_f32_32x32x16_bf16 v[184:199], v[108:111], v[204:207], v[184:199]
	s_waitcnt vmcnt(6)
	s_waitcnt lgkmcnt(0)
	s_barrier
	ds_read_b128 v[104:107], v116 offset:16384
	ds_read_b128 v[112:115], v119 offset:24576
	v_mfma_f32_32x32x16_bf16 v[48:63], v[208:211], v[244:247], v[48:63]
	ds_read_b128 v[128:131], v119 offset:26624
	ds_read_b128 v[132:135], v243 offset:40960
	v_mfma_f32_32x32x16_bf16 v[32:47], v[208:211], v[250:253], v[32:47]
	ds_read_b128 v[204:207], v243 offset:43008
	ds_read_b128 v[108:111], v116 offset:18432
	v_mfma_f32_32x32x16_bf16 v[136:151], v[208:211], v[68:71], v[136:151]
	v_mfma_f32_32x32x16_bf16 v[152:167], v[208:211], v[74:77], v[152:167]
	ds_read_b128 v[208:211], v122 offset:16384
	v_mfma_f32_32x32x16_bf16 v[16:31], v[214:217], v[244:247], v[16:31]
	ds_read_b128 v[244:247], v125 offset:24576
	v_mfma_f32_32x32x16_bf16 v[0:15], v[214:217], v[250:253], v[0:15]
	ds_read_b128 v[250:253], v125 offset:26624
	v_mfma_f32_32x32x16_bf16 v[168:183], v[214:217], v[68:71], v[168:183]
	ds_read_b128 v[68:71], v248 offset:40960
	v_mfma_f32_32x32x16_bf16 v[184:199], v[214:217], v[74:77], v[184:199]
	ds_read_b128 v[214:217], v122 offset:18432
	ds_read_b128 v[74:77], v248 offset:43008
	s_waitcnt lgkmcnt(6)
	v_mfma_f32_32x32x16_bf16 v[48:63], v[104:107], v[112:115], v[48:63]
	s_mov_b32 m0, s50
	v_lshl_add_u64 v[64:65], v[64:65], 0, s[44:45]
	global_load_lds_dwordx4 v[64:65], off sc1
	v_mfma_f32_32x32x16_bf16 v[32:47], v[104:107], v[128:131], v[32:47]
	global_load_lds_dwordx4 v[64:65], off offset:1024 sc1
	v_mfma_f32_32x32x16_bf16 v[136:151], v[104:107], v[132:135], v[136:151]
	s_mov_b32 m0, s53
	v_lshl_add_u64 v[66:67], v[66:67], 0, s[44:45]
	global_load_lds_dwordx4 v[66:67], off sc1
	v_mfma_f32_32x32x16_bf16 v[152:167], v[104:107], v[204:207], v[152:167]
	global_load_lds_dwordx4 v[66:67], off offset:1024 sc1
	v_mfma_f32_32x32x16_bf16 v[16:31], v[108:111], v[112:115], v[16:31]
	s_mov_b32 m0, s56
	v_lshl_add_u64 v[78:79], v[66:67], 0, s[72:73]
	global_load_lds_dwordx4 v[78:79], off sc1
	v_mfma_f32_32x32x16_bf16 v[0:15], v[108:111], v[128:131], v[0:15]
	global_load_lds_dwordx4 v[78:79], off offset:1024 sc1
	v_mfma_f32_32x32x16_bf16 v[168:183], v[108:111], v[132:135], v[168:183]
	v_mfma_f32_32x32x16_bf16 v[184:199], v[108:111], v[204:207], v[184:199]
	s_waitcnt vmcnt(6)
	s_waitcnt lgkmcnt(0)
	s_barrier
	ds_read_b128 v[104:107], v116 offset:32768
	ds_read_b128 v[112:115], v119 offset:40960
	v_mfma_f32_32x32x16_bf16 v[48:63], v[208:211], v[244:247], v[48:63]
	ds_read_b128 v[128:131], v119 offset:43008
	ds_read_b128 v[132:135], v243 offset:57344
	v_mfma_f32_32x32x16_bf16 v[32:47], v[208:211], v[250:253], v[32:47]
	ds_read_b128 v[204:207], v243 offset:59392
	ds_read_b128 v[108:111], v116 offset:34816
	v_mfma_f32_32x32x16_bf16 v[136:151], v[208:211], v[68:71], v[136:151]
	v_mfma_f32_32x32x16_bf16 v[152:167], v[208:211], v[74:77], v[152:167]
	ds_read_b128 v[208:211], v122 offset:32768
	v_mfma_f32_32x32x16_bf16 v[16:31], v[214:217], v[244:247], v[16:31]
	ds_read_b128 v[244:247], v125 offset:40960
	v_mfma_f32_32x32x16_bf16 v[0:15], v[214:217], v[250:253], v[0:15]
	ds_read_b128 v[250:253], v125 offset:43008
	v_mfma_f32_32x32x16_bf16 v[168:183], v[214:217], v[68:71], v[168:183]
	ds_read_b128 v[68:71], v248 offset:57344
	v_mfma_f32_32x32x16_bf16 v[184:199], v[214:217], v[74:77], v[184:199]
	ds_read_b128 v[214:217], v122 offset:34816
	ds_read_b128 v[74:77], v248 offset:59392
	s_waitcnt lgkmcnt(6)
	v_mfma_f32_32x32x16_bf16 v[48:63], v[104:107], v[112:115], v[48:63]
	s_mov_b32 m0, s51
	v_lshl_add_u64 v[64:65], v[64:65], 0, s[44:45]
	global_load_lds_dwordx4 v[64:65], off sc1
	v_mfma_f32_32x32x16_bf16 v[32:47], v[104:107], v[128:131], v[32:47]
	global_load_lds_dwordx4 v[64:65], off offset:1024 sc1
	v_mfma_f32_32x32x16_bf16 v[136:151], v[104:107], v[132:135], v[136:151]
	s_mov_b32 m0, s54
	v_lshl_add_u64 v[66:67], v[66:67], 0, s[44:45]
	global_load_lds_dwordx4 v[66:67], off sc1
	v_mfma_f32_32x32x16_bf16 v[152:167], v[104:107], v[204:207], v[152:167]
	global_load_lds_dwordx4 v[66:67], off offset:1024 sc1
	v_mfma_f32_32x32x16_bf16 v[16:31], v[108:111], v[112:115], v[16:31]
	s_mov_b32 m0, s57
	v_lshl_add_u64 v[78:79], v[66:67], 0, s[72:73]
	global_load_lds_dwordx4 v[78:79], off sc1
	v_mfma_f32_32x32x16_bf16 v[0:15], v[108:111], v[128:131], v[0:15]
	global_load_lds_dwordx4 v[78:79], off offset:1024 sc1
	v_mfma_f32_32x32x16_bf16 v[168:183], v[108:111], v[132:135], v[168:183]
	v_mfma_f32_32x32x16_bf16 v[184:199], v[108:111], v[204:207], v[184:199]
	s_waitcnt vmcnt(6)
	s_waitcnt lgkmcnt(0)
	s_barrier
	ds_read_b128 v[104:107], v116
	ds_read_b128 v[112:115], v119 offset:8192
	v_mfma_f32_32x32x16_bf16 v[48:63], v[208:211], v[244:247], v[48:63]
	ds_read_b128 v[128:131], v119 offset:10240
	ds_read_b128 v[132:135], v119 offset:49152
	v_mfma_f32_32x32x16_bf16 v[32:47], v[208:211], v[250:253], v[32:47]
	ds_read_b128 v[204:207], v119 offset:51200
	ds_read_b128 v[108:111], v116 offset:2048
	v_mfma_f32_32x32x16_bf16 v[136:151], v[208:211], v[68:71], v[136:151]
	v_mfma_f32_32x32x16_bf16 v[152:167], v[208:211], v[74:77], v[152:167]
	ds_read_b128 v[208:211], v122
	v_mfma_f32_32x32x16_bf16 v[16:31], v[214:217], v[244:247], v[16:31]
	ds_read_b128 v[244:247], v125 offset:8192
	v_mfma_f32_32x32x16_bf16 v[0:15], v[214:217], v[250:253], v[0:15]
	ds_read_b128 v[250:253], v125 offset:10240
	v_mfma_f32_32x32x16_bf16 v[168:183], v[214:217], v[68:71], v[168:183]
	ds_read_b128 v[68:71], v125 offset:49152
	v_mfma_f32_32x32x16_bf16 v[184:199], v[214:217], v[74:77], v[184:199]
	ds_read_b128 v[214:217], v122 offset:2048
	ds_read_b128 v[74:77], v125 offset:51200
	s_waitcnt lgkmcnt(6)
	v_mfma_f32_32x32x16_bf16 v[48:63], v[104:107], v[112:115], v[48:63]
	s_mov_b32 m0, s52
	v_lshl_add_u64 v[64:65], v[64:65], 0, s[44:45]
	global_load_lds_dwordx4 v[64:65], off sc1
	v_mfma_f32_32x32x16_bf16 v[32:47], v[104:107], v[128:131], v[32:47]
	global_load_lds_dwordx4 v[64:65], off offset:1024 sc1
	v_mfma_f32_32x32x16_bf16 v[136:151], v[104:107], v[132:135], v[136:151]
	s_mov_b32 m0, s55
	v_lshl_add_u64 v[66:67], v[66:67], 0, s[44:45]
	global_load_lds_dwordx4 v[66:67], off sc1
	v_mfma_f32_32x32x16_bf16 v[152:167], v[104:107], v[204:207], v[152:167]
	global_load_lds_dwordx4 v[66:67], off offset:1024 sc1
	v_mfma_f32_32x32x16_bf16 v[16:31], v[108:111], v[112:115], v[16:31]
	s_mov_b32 m0, s58
	v_lshl_add_u64 v[78:79], v[66:67], 0, s[72:73]
	global_load_lds_dwordx4 v[78:79], off sc1
	v_mfma_f32_32x32x16_bf16 v[0:15], v[108:111], v[128:131], v[0:15]
	global_load_lds_dwordx4 v[78:79], off offset:1024 sc1
	v_mfma_f32_32x32x16_bf16 v[168:183], v[108:111], v[132:135], v[168:183]
	v_mfma_f32_32x32x16_bf16 v[184:199], v[108:111], v[204:207], v[184:199]
	s_waitcnt vmcnt(6)
	s_waitcnt lgkmcnt(0)
	s_barrier
	ds_read_b128 v[104:107], v116 offset:16384
	ds_read_b128 v[112:115], v119 offset:24576
	v_mfma_f32_32x32x16_bf16 v[48:63], v[208:211], v[244:247], v[48:63]
	ds_read_b128 v[128:131], v119 offset:26624
	ds_read_b128 v[132:135], v243 offset:40960
	v_mfma_f32_32x32x16_bf16 v[32:47], v[208:211], v[250:253], v[32:47]
	ds_read_b128 v[204:207], v243 offset:43008
	ds_read_b128 v[108:111], v116 offset:18432
	v_mfma_f32_32x32x16_bf16 v[136:151], v[208:211], v[68:71], v[136:151]
	v_mfma_f32_32x32x16_bf16 v[152:167], v[208:211], v[74:77], v[152:167]
	ds_read_b128 v[208:211], v122 offset:16384
	v_mfma_f32_32x32x16_bf16 v[16:31], v[214:217], v[244:247], v[16:31]
	ds_read_b128 v[244:247], v125 offset:24576
	v_mfma_f32_32x32x16_bf16 v[0:15], v[214:217], v[250:253], v[0:15]
	ds_read_b128 v[250:253], v125 offset:26624
	v_mfma_f32_32x32x16_bf16 v[168:183], v[214:217], v[68:71], v[168:183]
	ds_read_b128 v[68:71], v248 offset:40960
	v_mfma_f32_32x32x16_bf16 v[184:199], v[214:217], v[74:77], v[184:199]
	ds_read_b128 v[214:217], v122 offset:18432
	ds_read_b128 v[74:77], v248 offset:43008
	s_waitcnt lgkmcnt(6)
	v_mfma_f32_32x32x16_bf16 v[48:63], v[104:107], v[112:115], v[48:63]
	s_mov_b32 m0, s50
	v_lshl_add_u64 v[64:65], v[64:65], 0, s[44:45]
	global_load_lds_dwordx4 v[64:65], off sc1
	v_mfma_f32_32x32x16_bf16 v[32:47], v[104:107], v[128:131], v[32:47]
	global_load_lds_dwordx4 v[64:65], off offset:1024 sc1
	v_mfma_f32_32x32x16_bf16 v[136:151], v[104:107], v[132:135], v[136:151]
	s_mov_b32 m0, s53
	v_lshl_add_u64 v[66:67], v[66:67], 0, s[44:45]
	global_load_lds_dwordx4 v[66:67], off sc1
	v_mfma_f32_32x32x16_bf16 v[152:167], v[104:107], v[204:207], v[152:167]
	global_load_lds_dwordx4 v[66:67], off offset:1024 sc1
	v_mfma_f32_32x32x16_bf16 v[16:31], v[108:111], v[112:115], v[16:31]
	s_mov_b32 m0, s56
	v_lshl_add_u64 v[78:79], v[66:67], 0, s[72:73]
	global_load_lds_dwordx4 v[78:79], off sc1
	v_mfma_f32_32x32x16_bf16 v[0:15], v[108:111], v[128:131], v[0:15]
	global_load_lds_dwordx4 v[78:79], off offset:1024 sc1
	v_mfma_f32_32x32x16_bf16 v[168:183], v[108:111], v[132:135], v[168:183]
	v_mfma_f32_32x32x16_bf16 v[184:199], v[108:111], v[204:207], v[184:199]
	s_waitcnt vmcnt(6)
	s_waitcnt lgkmcnt(0)
	s_barrier
	ds_read_b128 v[104:107], v116 offset:32768
	ds_read_b128 v[112:115], v119 offset:40960
	v_mfma_f32_32x32x16_bf16 v[48:63], v[208:211], v[244:247], v[48:63]
	ds_read_b128 v[128:131], v119 offset:43008
	ds_read_b128 v[132:135], v243 offset:57344
	v_mfma_f32_32x32x16_bf16 v[32:47], v[208:211], v[250:253], v[32:47]
	ds_read_b128 v[204:207], v243 offset:59392
	ds_read_b128 v[108:111], v116 offset:34816
	v_mfma_f32_32x32x16_bf16 v[136:151], v[208:211], v[68:71], v[136:151]
	v_mfma_f32_32x32x16_bf16 v[152:167], v[208:211], v[74:77], v[152:167]
	ds_read_b128 v[208:211], v122 offset:32768
	v_mfma_f32_32x32x16_bf16 v[16:31], v[214:217], v[244:247], v[16:31]
	ds_read_b128 v[244:247], v125 offset:40960
	v_mfma_f32_32x32x16_bf16 v[0:15], v[214:217], v[250:253], v[0:15]
	ds_read_b128 v[250:253], v125 offset:43008
	v_mfma_f32_32x32x16_bf16 v[168:183], v[214:217], v[68:71], v[168:183]
	ds_read_b128 v[68:71], v248 offset:57344
	v_mfma_f32_32x32x16_bf16 v[184:199], v[214:217], v[74:77], v[184:199]
	ds_read_b128 v[214:217], v122 offset:34816
	ds_read_b128 v[74:77], v248 offset:59392
	s_waitcnt lgkmcnt(6)
	v_mfma_f32_32x32x16_bf16 v[48:63], v[104:107], v[112:115], v[48:63]
	s_mov_b32 m0, s51
	v_lshl_add_u64 v[64:65], v[64:65], 0, s[44:45]
	global_load_lds_dwordx4 v[64:65], off sc1
	v_mfma_f32_32x32x16_bf16 v[32:47], v[104:107], v[128:131], v[32:47]
	global_load_lds_dwordx4 v[64:65], off offset:1024 sc1
	v_mfma_f32_32x32x16_bf16 v[136:151], v[104:107], v[132:135], v[136:151]
	s_mov_b32 m0, s54
	v_lshl_add_u64 v[66:67], v[66:67], 0, s[44:45]
	global_load_lds_dwordx4 v[66:67], off sc1
	v_mfma_f32_32x32x16_bf16 v[152:167], v[104:107], v[204:207], v[152:167]
	global_load_lds_dwordx4 v[66:67], off offset:1024 sc1
	v_mfma_f32_32x32x16_bf16 v[16:31], v[108:111], v[112:115], v[16:31]
	s_mov_b32 m0, s57
	v_lshl_add_u64 v[78:79], v[66:67], 0, s[72:73]
	global_load_lds_dwordx4 v[78:79], off sc1
	v_mfma_f32_32x32x16_bf16 v[0:15], v[108:111], v[128:131], v[0:15]
	global_load_lds_dwordx4 v[78:79], off offset:1024 sc1
	v_mfma_f32_32x32x16_bf16 v[168:183], v[108:111], v[132:135], v[168:183]
	v_mfma_f32_32x32x16_bf16 v[184:199], v[108:111], v[204:207], v[184:199]
	s_waitcnt vmcnt(6)
	s_waitcnt lgkmcnt(0)
	s_barrier
	ds_read_b128 v[104:107], v116
	ds_read_b128 v[112:115], v119 offset:8192
	v_mfma_f32_32x32x16_bf16 v[48:63], v[208:211], v[244:247], v[48:63]
	ds_read_b128 v[128:131], v119 offset:10240
	ds_read_b128 v[132:135], v119 offset:49152
	v_mfma_f32_32x32x16_bf16 v[32:47], v[208:211], v[250:253], v[32:47]
	ds_read_b128 v[204:207], v119 offset:51200
	ds_read_b128 v[108:111], v116 offset:2048
	v_mfma_f32_32x32x16_bf16 v[136:151], v[208:211], v[68:71], v[136:151]
	v_mfma_f32_32x32x16_bf16 v[152:167], v[208:211], v[74:77], v[152:167]
	ds_read_b128 v[208:211], v122
	v_mfma_f32_32x32x16_bf16 v[16:31], v[214:217], v[244:247], v[16:31]
	ds_read_b128 v[244:247], v125 offset:8192
	v_mfma_f32_32x32x16_bf16 v[0:15], v[214:217], v[250:253], v[0:15]
	ds_read_b128 v[250:253], v125 offset:10240
	v_mfma_f32_32x32x16_bf16 v[168:183], v[214:217], v[68:71], v[168:183]
	ds_read_b128 v[68:71], v125 offset:49152
	v_mfma_f32_32x32x16_bf16 v[184:199], v[214:217], v[74:77], v[184:199]
	ds_read_b128 v[214:217], v122 offset:2048
	ds_read_b128 v[74:77], v125 offset:51200
	s_waitcnt lgkmcnt(6)
	v_mfma_f32_32x32x16_bf16 v[48:63], v[104:107], v[112:115], v[48:63]
	s_mov_b32 m0, s52
	v_lshl_add_u64 v[64:65], v[64:65], 0, s[44:45]
	global_load_lds_dwordx4 v[64:65], off sc1
	v_mfma_f32_32x32x16_bf16 v[32:47], v[104:107], v[128:131], v[32:47]
	global_load_lds_dwordx4 v[64:65], off offset:1024 sc1
	v_mfma_f32_32x32x16_bf16 v[136:151], v[104:107], v[132:135], v[136:151]
	s_mov_b32 m0, s55
	v_lshl_add_u64 v[66:67], v[66:67], 0, s[44:45]
	global_load_lds_dwordx4 v[66:67], off sc1
	v_mfma_f32_32x32x16_bf16 v[152:167], v[104:107], v[204:207], v[152:167]
	global_load_lds_dwordx4 v[66:67], off offset:1024 sc1
	v_mfma_f32_32x32x16_bf16 v[16:31], v[108:111], v[112:115], v[16:31]
	s_mov_b32 m0, s58
	v_lshl_add_u64 v[78:79], v[66:67], 0, s[72:73]
	global_load_lds_dwordx4 v[78:79], off sc1
	v_mfma_f32_32x32x16_bf16 v[0:15], v[108:111], v[128:131], v[0:15]
	global_load_lds_dwordx4 v[78:79], off offset:1024 sc1
	v_mfma_f32_32x32x16_bf16 v[168:183], v[108:111], v[132:135], v[168:183]
	v_mfma_f32_32x32x16_bf16 v[184:199], v[108:111], v[204:207], v[184:199]
	s_waitcnt vmcnt(6)
	s_waitcnt lgkmcnt(0)
	s_barrier
	ds_read_b128 v[104:107], v116 offset:16384
	ds_read_b128 v[112:115], v119 offset:24576
	v_mfma_f32_32x32x16_bf16 v[48:63], v[208:211], v[244:247], v[48:63]
	ds_read_b128 v[128:131], v119 offset:26624
	ds_read_b128 v[132:135], v243 offset:40960
	v_mfma_f32_32x32x16_bf16 v[32:47], v[208:211], v[250:253], v[32:47]
	ds_read_b128 v[204:207], v243 offset:43008
	ds_read_b128 v[108:111], v116 offset:18432
	v_mfma_f32_32x32x16_bf16 v[136:151], v[208:211], v[68:71], v[136:151]
	v_mfma_f32_32x32x16_bf16 v[152:167], v[208:211], v[74:77], v[152:167]
	ds_read_b128 v[208:211], v122 offset:16384
	v_mfma_f32_32x32x16_bf16 v[16:31], v[214:217], v[244:247], v[16:31]
	ds_read_b128 v[244:247], v125 offset:24576
	v_mfma_f32_32x32x16_bf16 v[0:15], v[214:217], v[250:253], v[0:15]
	ds_read_b128 v[250:253], v125 offset:26624
	v_mfma_f32_32x32x16_bf16 v[168:183], v[214:217], v[68:71], v[168:183]
	ds_read_b128 v[68:71], v248 offset:40960
	v_mfma_f32_32x32x16_bf16 v[184:199], v[214:217], v[74:77], v[184:199]
	ds_read_b128 v[214:217], v122 offset:18432
	ds_read_b128 v[74:77], v248 offset:43008
	s_waitcnt lgkmcnt(6)
	v_mfma_f32_32x32x16_bf16 v[48:63], v[104:107], v[112:115], v[48:63]
	s_mov_b32 m0, s50
	v_lshl_add_u64 v[64:65], v[64:65], 0, s[44:45]
	global_load_lds_dwordx4 v[64:65], off sc1
	v_mfma_f32_32x32x16_bf16 v[32:47], v[104:107], v[128:131], v[32:47]
	global_load_lds_dwordx4 v[64:65], off offset:1024 sc1
	v_mfma_f32_32x32x16_bf16 v[136:151], v[104:107], v[132:135], v[136:151]
	s_mov_b32 m0, s53
	v_lshl_add_u64 v[66:67], v[66:67], 0, s[44:45]
	global_load_lds_dwordx4 v[66:67], off sc1
	v_mfma_f32_32x32x16_bf16 v[152:167], v[104:107], v[204:207], v[152:167]
	global_load_lds_dwordx4 v[66:67], off offset:1024 sc1
	v_mfma_f32_32x32x16_bf16 v[16:31], v[108:111], v[112:115], v[16:31]
	s_mov_b32 m0, s56
	v_lshl_add_u64 v[78:79], v[66:67], 0, s[72:73]
	global_load_lds_dwordx4 v[78:79], off sc1
	v_mfma_f32_32x32x16_bf16 v[0:15], v[108:111], v[128:131], v[0:15]
	global_load_lds_dwordx4 v[78:79], off offset:1024 sc1
	v_mfma_f32_32x32x16_bf16 v[168:183], v[108:111], v[132:135], v[168:183]
	v_mfma_f32_32x32x16_bf16 v[184:199], v[108:111], v[204:207], v[184:199]
	s_waitcnt vmcnt(6)
	s_waitcnt lgkmcnt(0)
	s_barrier
	ds_read_b128 v[104:107], v116 offset:32768
	ds_read_b128 v[112:115], v119 offset:40960
	v_mfma_f32_32x32x16_bf16 v[48:63], v[208:211], v[244:247], v[48:63]
	ds_read_b128 v[128:131], v119 offset:43008
	ds_read_b128 v[132:135], v243 offset:57344
	v_mfma_f32_32x32x16_bf16 v[32:47], v[208:211], v[250:253], v[32:47]
	ds_read_b128 v[204:207], v243 offset:59392
	ds_read_b128 v[108:111], v116 offset:34816
	v_mfma_f32_32x32x16_bf16 v[136:151], v[208:211], v[68:71], v[136:151]
	v_mfma_f32_32x32x16_bf16 v[152:167], v[208:211], v[74:77], v[152:167]
	ds_read_b128 v[208:211], v122 offset:32768
	v_mfma_f32_32x32x16_bf16 v[16:31], v[214:217], v[244:247], v[16:31]
	ds_read_b128 v[244:247], v125 offset:40960
	v_mfma_f32_32x32x16_bf16 v[0:15], v[214:217], v[250:253], v[0:15]
	ds_read_b128 v[250:253], v125 offset:43008
	v_mfma_f32_32x32x16_bf16 v[168:183], v[214:217], v[68:71], v[168:183]
	ds_read_b128 v[68:71], v248 offset:57344
	v_mfma_f32_32x32x16_bf16 v[184:199], v[214:217], v[74:77], v[184:199]
	ds_read_b128 v[214:217], v122 offset:34816
	ds_read_b128 v[74:77], v248 offset:59392
	s_waitcnt lgkmcnt(6)
	v_mfma_f32_32x32x16_bf16 v[48:63], v[104:107], v[112:115], v[48:63]
	s_mov_b32 m0, s51
	v_lshl_add_u64 v[64:65], v[64:65], 0, s[44:45]
	global_load_lds_dwordx4 v[64:65], off sc1
	v_mfma_f32_32x32x16_bf16 v[32:47], v[104:107], v[128:131], v[32:47]
	global_load_lds_dwordx4 v[64:65], off offset:1024 sc1
	v_mfma_f32_32x32x16_bf16 v[136:151], v[104:107], v[132:135], v[136:151]
	s_mov_b32 m0, s54
	v_lshl_add_u64 v[66:67], v[66:67], 0, s[44:45]
	global_load_lds_dwordx4 v[66:67], off sc1
	v_mfma_f32_32x32x16_bf16 v[152:167], v[104:107], v[204:207], v[152:167]
	global_load_lds_dwordx4 v[66:67], off offset:1024 sc1
	v_mfma_f32_32x32x16_bf16 v[16:31], v[108:111], v[112:115], v[16:31]
	s_mov_b32 m0, s57
	v_lshl_add_u64 v[78:79], v[66:67], 0, s[72:73]
	global_load_lds_dwordx4 v[78:79], off sc1
	v_mfma_f32_32x32x16_bf16 v[0:15], v[108:111], v[128:131], v[0:15]
	global_load_lds_dwordx4 v[78:79], off offset:1024 sc1
	v_mfma_f32_32x32x16_bf16 v[168:183], v[108:111], v[132:135], v[168:183]
	v_mfma_f32_32x32x16_bf16 v[184:199], v[108:111], v[204:207], v[184:199]
	s_waitcnt vmcnt(6)
	s_waitcnt lgkmcnt(0)
	s_barrier
	ds_read_b128 v[104:107], v116
	ds_read_b128 v[112:115], v119 offset:8192
	v_mfma_f32_32x32x16_bf16 v[48:63], v[208:211], v[244:247], v[48:63]
	ds_read_b128 v[128:131], v119 offset:10240
	ds_read_b128 v[132:135], v119 offset:49152
	v_mfma_f32_32x32x16_bf16 v[32:47], v[208:211], v[250:253], v[32:47]
	ds_read_b128 v[204:207], v119 offset:51200
	ds_read_b128 v[108:111], v116 offset:2048
	v_mfma_f32_32x32x16_bf16 v[136:151], v[208:211], v[68:71], v[136:151]
	v_mfma_f32_32x32x16_bf16 v[152:167], v[208:211], v[74:77], v[152:167]
	ds_read_b128 v[208:211], v122
	v_mfma_f32_32x32x16_bf16 v[16:31], v[214:217], v[244:247], v[16:31]
	ds_read_b128 v[244:247], v125 offset:8192
	v_mfma_f32_32x32x16_bf16 v[0:15], v[214:217], v[250:253], v[0:15]
	ds_read_b128 v[250:253], v125 offset:10240
	v_mfma_f32_32x32x16_bf16 v[168:183], v[214:217], v[68:71], v[168:183]
	ds_read_b128 v[68:71], v125 offset:49152
	v_mfma_f32_32x32x16_bf16 v[184:199], v[214:217], v[74:77], v[184:199]
	ds_read_b128 v[214:217], v122 offset:2048
	ds_read_b128 v[74:77], v125 offset:51200
	s_waitcnt lgkmcnt(6)
	v_mfma_f32_32x32x16_bf16 v[48:63], v[104:107], v[112:115], v[48:63]
	s_mov_b32 m0, s52
	v_lshl_add_u64 v[64:65], v[64:65], 0, s[44:45]
	global_load_lds_dwordx4 v[64:65], off sc1
	v_mfma_f32_32x32x16_bf16 v[32:47], v[104:107], v[128:131], v[32:47]
	global_load_lds_dwordx4 v[64:65], off offset:1024 sc1
	v_mfma_f32_32x32x16_bf16 v[136:151], v[104:107], v[132:135], v[136:151]
	s_mov_b32 m0, s55
	v_lshl_add_u64 v[66:67], v[66:67], 0, s[44:45]
	global_load_lds_dwordx4 v[66:67], off sc1
	v_mfma_f32_32x32x16_bf16 v[152:167], v[104:107], v[204:207], v[152:167]
	global_load_lds_dwordx4 v[66:67], off offset:1024 sc1
	v_mfma_f32_32x32x16_bf16 v[16:31], v[108:111], v[112:115], v[16:31]
	s_mov_b32 m0, s58
	v_lshl_add_u64 v[78:79], v[66:67], 0, s[72:73]
	global_load_lds_dwordx4 v[78:79], off sc1
	v_mfma_f32_32x32x16_bf16 v[0:15], v[108:111], v[128:131], v[0:15]
	global_load_lds_dwordx4 v[78:79], off offset:1024 sc1
	v_mfma_f32_32x32x16_bf16 v[168:183], v[108:111], v[132:135], v[168:183]
	v_mfma_f32_32x32x16_bf16 v[184:199], v[108:111], v[204:207], v[184:199]
	s_waitcnt vmcnt(6)
	s_waitcnt lgkmcnt(0)
	s_barrier
	ds_read_b128 v[104:107], v116 offset:16384
	ds_read_b128 v[112:115], v119 offset:24576
	v_mfma_f32_32x32x16_bf16 v[48:63], v[208:211], v[244:247], v[48:63]
	ds_read_b128 v[128:131], v119 offset:26624
	ds_read_b128 v[132:135], v243 offset:40960
	v_mfma_f32_32x32x16_bf16 v[32:47], v[208:211], v[250:253], v[32:47]
	ds_read_b128 v[204:207], v243 offset:43008
	ds_read_b128 v[108:111], v116 offset:18432
	v_mfma_f32_32x32x16_bf16 v[136:151], v[208:211], v[68:71], v[136:151]
	v_mfma_f32_32x32x16_bf16 v[152:167], v[208:211], v[74:77], v[152:167]
	ds_read_b128 v[208:211], v122 offset:16384
	v_mfma_f32_32x32x16_bf16 v[16:31], v[214:217], v[244:247], v[16:31]
	ds_read_b128 v[244:247], v125 offset:24576
	v_mfma_f32_32x32x16_bf16 v[0:15], v[214:217], v[250:253], v[0:15]
	ds_read_b128 v[250:253], v125 offset:26624
	v_mfma_f32_32x32x16_bf16 v[168:183], v[214:217], v[68:71], v[168:183]
	ds_read_b128 v[68:71], v248 offset:40960
	v_mfma_f32_32x32x16_bf16 v[184:199], v[214:217], v[74:77], v[184:199]
	ds_read_b128 v[214:217], v122 offset:18432
	ds_read_b128 v[74:77], v248 offset:43008
	s_waitcnt lgkmcnt(6)
	v_mfma_f32_32x32x16_bf16 v[48:63], v[104:107], v[112:115], v[48:63]
	s_mov_b32 m0, s50
	v_lshl_add_u64 v[64:65], v[64:65], 0, s[44:45]
	global_load_lds_dwordx4 v[64:65], off sc1
	v_mfma_f32_32x32x16_bf16 v[32:47], v[104:107], v[128:131], v[32:47]
	global_load_lds_dwordx4 v[64:65], off offset:1024 sc1
	v_mfma_f32_32x32x16_bf16 v[136:151], v[104:107], v[132:135], v[136:151]
	s_mov_b32 m0, s53
	v_lshl_add_u64 v[66:67], v[66:67], 0, s[44:45]
	global_load_lds_dwordx4 v[66:67], off sc1
	v_mfma_f32_32x32x16_bf16 v[152:167], v[104:107], v[204:207], v[152:167]
	global_load_lds_dwordx4 v[66:67], off offset:1024 sc1
	v_mfma_f32_32x32x16_bf16 v[16:31], v[108:111], v[112:115], v[16:31]
	s_mov_b32 m0, s56
	v_lshl_add_u64 v[78:79], v[66:67], 0, s[72:73]
	global_load_lds_dwordx4 v[78:79], off sc1
	v_mfma_f32_32x32x16_bf16 v[0:15], v[108:111], v[128:131], v[0:15]
	global_load_lds_dwordx4 v[78:79], off offset:1024 sc1
	v_mfma_f32_32x32x16_bf16 v[168:183], v[108:111], v[132:135], v[168:183]
	v_mfma_f32_32x32x16_bf16 v[184:199], v[108:111], v[204:207], v[184:199]
	s_waitcnt vmcnt(6)
	s_waitcnt lgkmcnt(0)
	s_barrier
	ds_read_b128 v[104:107], v116 offset:32768
	ds_read_b128 v[112:115], v119 offset:40960
	v_mfma_f32_32x32x16_bf16 v[48:63], v[208:211], v[244:247], v[48:63]
	ds_read_b128 v[128:131], v119 offset:43008
	ds_read_b128 v[132:135], v243 offset:57344
	v_mfma_f32_32x32x16_bf16 v[32:47], v[208:211], v[250:253], v[32:47]
	ds_read_b128 v[204:207], v243 offset:59392
	ds_read_b128 v[108:111], v116 offset:34816
	v_mfma_f32_32x32x16_bf16 v[136:151], v[208:211], v[68:71], v[136:151]
	v_mfma_f32_32x32x16_bf16 v[152:167], v[208:211], v[74:77], v[152:167]
	ds_read_b128 v[208:211], v122 offset:32768
	v_mfma_f32_32x32x16_bf16 v[16:31], v[214:217], v[244:247], v[16:31]
	ds_read_b128 v[244:247], v125 offset:40960
	v_mfma_f32_32x32x16_bf16 v[0:15], v[214:217], v[250:253], v[0:15]
	ds_read_b128 v[250:253], v125 offset:43008
	v_mfma_f32_32x32x16_bf16 v[168:183], v[214:217], v[68:71], v[168:183]
	ds_read_b128 v[68:71], v248 offset:57344
	v_mfma_f32_32x32x16_bf16 v[184:199], v[214:217], v[74:77], v[184:199]
	ds_read_b128 v[214:217], v122 offset:34816
	ds_read_b128 v[74:77], v248 offset:59392
	s_waitcnt lgkmcnt(6)
	v_mfma_f32_32x32x16_bf16 v[48:63], v[104:107], v[112:115], v[48:63]
	s_mov_b32 m0, s51
	v_lshl_add_u64 v[64:65], v[64:65], 0, s[44:45]
	global_load_lds_dwordx4 v[64:65], off sc1
	v_mfma_f32_32x32x16_bf16 v[32:47], v[104:107], v[128:131], v[32:47]
	global_load_lds_dwordx4 v[64:65], off offset:1024 sc1
	v_mfma_f32_32x32x16_bf16 v[136:151], v[104:107], v[132:135], v[136:151]
	s_mov_b32 m0, s54
	v_lshl_add_u64 v[66:67], v[66:67], 0, s[44:45]
	global_load_lds_dwordx4 v[66:67], off sc1
	v_mfma_f32_32x32x16_bf16 v[152:167], v[104:107], v[204:207], v[152:167]
	global_load_lds_dwordx4 v[66:67], off offset:1024 sc1
	v_mfma_f32_32x32x16_bf16 v[16:31], v[108:111], v[112:115], v[16:31]
	s_mov_b32 m0, s57
	v_lshl_add_u64 v[78:79], v[66:67], 0, s[72:73]
	global_load_lds_dwordx4 v[78:79], off sc1
	v_mfma_f32_32x32x16_bf16 v[0:15], v[108:111], v[128:131], v[0:15]
	global_load_lds_dwordx4 v[78:79], off offset:1024 sc1
	v_mfma_f32_32x32x16_bf16 v[168:183], v[108:111], v[132:135], v[168:183]
	v_mfma_f32_32x32x16_bf16 v[184:199], v[108:111], v[204:207], v[184:199]
	s_waitcnt vmcnt(6)
	s_waitcnt lgkmcnt(0)
	s_barrier
	ds_read_b128 v[104:107], v116
	ds_read_b128 v[112:115], v119 offset:8192
	v_mfma_f32_32x32x16_bf16 v[48:63], v[208:211], v[244:247], v[48:63]
	ds_read_b128 v[128:131], v119 offset:10240
	ds_read_b128 v[132:135], v119 offset:49152
	v_mfma_f32_32x32x16_bf16 v[32:47], v[208:211], v[250:253], v[32:47]
	ds_read_b128 v[204:207], v119 offset:51200
	ds_read_b128 v[108:111], v116 offset:2048
	v_mfma_f32_32x32x16_bf16 v[136:151], v[208:211], v[68:71], v[136:151]
	v_mfma_f32_32x32x16_bf16 v[152:167], v[208:211], v[74:77], v[152:167]
	ds_read_b128 v[208:211], v122
	v_mfma_f32_32x32x16_bf16 v[16:31], v[214:217], v[244:247], v[16:31]
	ds_read_b128 v[244:247], v125 offset:8192
	v_mfma_f32_32x32x16_bf16 v[0:15], v[214:217], v[250:253], v[0:15]
	ds_read_b128 v[250:253], v125 offset:10240
	v_mfma_f32_32x32x16_bf16 v[168:183], v[214:217], v[68:71], v[168:183]
	ds_read_b128 v[68:71], v125 offset:49152
	v_mfma_f32_32x32x16_bf16 v[184:199], v[214:217], v[74:77], v[184:199]
	ds_read_b128 v[214:217], v122 offset:2048
	ds_read_b128 v[74:77], v125 offset:51200
	s_waitcnt lgkmcnt(6)
	v_mfma_f32_32x32x16_bf16 v[48:63], v[104:107], v[112:115], v[48:63]
	s_mov_b32 m0, s52
	v_lshl_add_u64 v[64:65], v[64:65], 0, s[44:45]
	global_load_lds_dwordx4 v[64:65], off sc1
	v_mfma_f32_32x32x16_bf16 v[32:47], v[104:107], v[128:131], v[32:47]
	global_load_lds_dwordx4 v[64:65], off offset:1024 sc1
	v_mfma_f32_32x32x16_bf16 v[136:151], v[104:107], v[132:135], v[136:151]
	s_mov_b32 m0, s55
	v_lshl_add_u64 v[66:67], v[66:67], 0, s[44:45]
	global_load_lds_dwordx4 v[66:67], off sc1
	v_mfma_f32_32x32x16_bf16 v[152:167], v[104:107], v[204:207], v[152:167]
	global_load_lds_dwordx4 v[66:67], off offset:1024 sc1
	v_mfma_f32_32x32x16_bf16 v[16:31], v[108:111], v[112:115], v[16:31]
	s_mov_b32 m0, s58
	v_lshl_add_u64 v[78:79], v[66:67], 0, s[72:73]
	global_load_lds_dwordx4 v[78:79], off sc1
	v_mfma_f32_32x32x16_bf16 v[0:15], v[108:111], v[128:131], v[0:15]
	global_load_lds_dwordx4 v[78:79], off offset:1024 sc1
	v_mfma_f32_32x32x16_bf16 v[168:183], v[108:111], v[132:135], v[168:183]
	v_mfma_f32_32x32x16_bf16 v[184:199], v[108:111], v[204:207], v[184:199]
	s_waitcnt vmcnt(6)
	s_waitcnt lgkmcnt(0)
	s_barrier
	ds_read_b128 v[104:107], v116 offset:16384
	ds_read_b128 v[112:115], v119 offset:24576
	v_mfma_f32_32x32x16_bf16 v[48:63], v[208:211], v[244:247], v[48:63]
	ds_read_b128 v[128:131], v119 offset:26624
	ds_read_b128 v[132:135], v243 offset:40960
	v_mfma_f32_32x32x16_bf16 v[32:47], v[208:211], v[250:253], v[32:47]
	ds_read_b128 v[204:207], v243 offset:43008
	ds_read_b128 v[108:111], v116 offset:18432
	v_mfma_f32_32x32x16_bf16 v[136:151], v[208:211], v[68:71], v[136:151]
	v_mfma_f32_32x32x16_bf16 v[152:167], v[208:211], v[74:77], v[152:167]
	ds_read_b128 v[208:211], v122 offset:16384
	v_mfma_f32_32x32x16_bf16 v[16:31], v[214:217], v[244:247], v[16:31]
	ds_read_b128 v[244:247], v125 offset:24576
	v_mfma_f32_32x32x16_bf16 v[0:15], v[214:217], v[250:253], v[0:15]
	ds_read_b128 v[250:253], v125 offset:26624
	v_mfma_f32_32x32x16_bf16 v[168:183], v[214:217], v[68:71], v[168:183]
	ds_read_b128 v[68:71], v248 offset:40960
	v_mfma_f32_32x32x16_bf16 v[184:199], v[214:217], v[74:77], v[184:199]
	ds_read_b128 v[214:217], v122 offset:18432
	ds_read_b128 v[74:77], v248 offset:43008
	s_waitcnt lgkmcnt(6)
	v_mfma_f32_32x32x16_bf16 v[48:63], v[104:107], v[112:115], v[48:63]
	s_mov_b32 m0, s50
	v_lshl_add_u64 v[64:65], v[64:65], 0, s[44:45]
	global_load_lds_dwordx4 v[64:65], off sc1
	v_mfma_f32_32x32x16_bf16 v[32:47], v[104:107], v[128:131], v[32:47]
	global_load_lds_dwordx4 v[64:65], off offset:1024 sc1
	v_mfma_f32_32x32x16_bf16 v[136:151], v[104:107], v[132:135], v[136:151]
	s_mov_b32 m0, s53
	v_lshl_add_u64 v[66:67], v[66:67], 0, s[44:45]
	global_load_lds_dwordx4 v[66:67], off sc1
	v_mfma_f32_32x32x16_bf16 v[152:167], v[104:107], v[204:207], v[152:167]
	global_load_lds_dwordx4 v[66:67], off offset:1024 sc1
	v_mfma_f32_32x32x16_bf16 v[16:31], v[108:111], v[112:115], v[16:31]
	s_mov_b32 m0, s56
	v_lshl_add_u64 v[78:79], v[66:67], 0, s[72:73]
	global_load_lds_dwordx4 v[78:79], off sc1
	v_mfma_f32_32x32x16_bf16 v[0:15], v[108:111], v[128:131], v[0:15]
	global_load_lds_dwordx4 v[78:79], off offset:1024 sc1
	v_mfma_f32_32x32x16_bf16 v[168:183], v[108:111], v[132:135], v[168:183]
	v_mfma_f32_32x32x16_bf16 v[184:199], v[108:111], v[204:207], v[184:199]
	s_waitcnt vmcnt(6)
	s_waitcnt lgkmcnt(0)
	s_barrier
	ds_read_b128 v[104:107], v116 offset:32768
	ds_read_b128 v[112:115], v119 offset:40960
	v_mfma_f32_32x32x16_bf16 v[48:63], v[208:211], v[244:247], v[48:63]
	ds_read_b128 v[128:131], v119 offset:43008
	ds_read_b128 v[132:135], v243 offset:57344
	v_mfma_f32_32x32x16_bf16 v[32:47], v[208:211], v[250:253], v[32:47]
	ds_read_b128 v[204:207], v243 offset:59392
	ds_read_b128 v[108:111], v116 offset:34816
	v_mfma_f32_32x32x16_bf16 v[136:151], v[208:211], v[68:71], v[136:151]
	v_mfma_f32_32x32x16_bf16 v[152:167], v[208:211], v[74:77], v[152:167]
	ds_read_b128 v[208:211], v122 offset:32768
	v_mfma_f32_32x32x16_bf16 v[16:31], v[214:217], v[244:247], v[16:31]
	ds_read_b128 v[244:247], v125 offset:40960
	v_mfma_f32_32x32x16_bf16 v[0:15], v[214:217], v[250:253], v[0:15]
	ds_read_b128 v[250:253], v125 offset:43008
	v_mfma_f32_32x32x16_bf16 v[168:183], v[214:217], v[68:71], v[168:183]
	ds_read_b128 v[68:71], v248 offset:57344
	v_mfma_f32_32x32x16_bf16 v[184:199], v[214:217], v[74:77], v[184:199]
	ds_read_b128 v[214:217], v122 offset:34816
	ds_read_b128 v[74:77], v248 offset:59392
	s_waitcnt lgkmcnt(6)
	v_mfma_f32_32x32x16_bf16 v[48:63], v[104:107], v[112:115], v[48:63]
	s_mov_b32 m0, s51
	v_lshl_add_u64 v[64:65], v[64:65], 0, s[44:45]
	global_load_lds_dwordx4 v[64:65], off sc1
	v_mfma_f32_32x32x16_bf16 v[32:47], v[104:107], v[128:131], v[32:47]
	global_load_lds_dwordx4 v[64:65], off offset:1024 sc1
	v_mfma_f32_32x32x16_bf16 v[136:151], v[104:107], v[132:135], v[136:151]
	s_mov_b32 m0, s54
	v_lshl_add_u64 v[66:67], v[66:67], 0, s[44:45]
	global_load_lds_dwordx4 v[66:67], off sc1
	v_mfma_f32_32x32x16_bf16 v[152:167], v[104:107], v[204:207], v[152:167]
	global_load_lds_dwordx4 v[66:67], off offset:1024 sc1
	v_mfma_f32_32x32x16_bf16 v[16:31], v[108:111], v[112:115], v[16:31]
	s_mov_b32 m0, s57
	v_lshl_add_u64 v[78:79], v[66:67], 0, s[72:73]
	global_load_lds_dwordx4 v[78:79], off sc1
	v_mfma_f32_32x32x16_bf16 v[0:15], v[108:111], v[128:131], v[0:15]
	global_load_lds_dwordx4 v[78:79], off offset:1024 sc1
	v_mfma_f32_32x32x16_bf16 v[168:183], v[108:111], v[132:135], v[168:183]
	v_mfma_f32_32x32x16_bf16 v[184:199], v[108:111], v[204:207], v[184:199]
	s_waitcnt vmcnt(6)
	s_waitcnt lgkmcnt(0)
	s_barrier
	ds_read_b128 v[104:107], v116
	ds_read_b128 v[112:115], v119 offset:8192
	v_mfma_f32_32x32x16_bf16 v[48:63], v[208:211], v[244:247], v[48:63]
	ds_read_b128 v[128:131], v119 offset:10240
	ds_read_b128 v[132:135], v119 offset:49152
	v_mfma_f32_32x32x16_bf16 v[32:47], v[208:211], v[250:253], v[32:47]
	ds_read_b128 v[204:207], v119 offset:51200
	ds_read_b128 v[108:111], v116 offset:2048
	v_mfma_f32_32x32x16_bf16 v[136:151], v[208:211], v[68:71], v[136:151]
	v_mfma_f32_32x32x16_bf16 v[152:167], v[208:211], v[74:77], v[152:167]
	ds_read_b128 v[208:211], v122
	v_mfma_f32_32x32x16_bf16 v[16:31], v[214:217], v[244:247], v[16:31]
	ds_read_b128 v[244:247], v125 offset:8192
	v_mfma_f32_32x32x16_bf16 v[0:15], v[214:217], v[250:253], v[0:15]
	ds_read_b128 v[250:253], v125 offset:10240
	v_mfma_f32_32x32x16_bf16 v[168:183], v[214:217], v[68:71], v[168:183]
	ds_read_b128 v[68:71], v125 offset:49152
	v_mfma_f32_32x32x16_bf16 v[184:199], v[214:217], v[74:77], v[184:199]
	ds_read_b128 v[214:217], v122 offset:2048
	ds_read_b128 v[74:77], v125 offset:51200
	s_waitcnt lgkmcnt(6)
	v_mfma_f32_32x32x16_bf16 v[48:63], v[104:107], v[112:115], v[48:63]
	s_mov_b32 m0, s52
	v_lshl_add_u64 v[64:65], v[64:65], 0, s[44:45]
	global_load_lds_dwordx4 v[64:65], off sc1
	v_mfma_f32_32x32x16_bf16 v[32:47], v[104:107], v[128:131], v[32:47]
	global_load_lds_dwordx4 v[64:65], off offset:1024 sc1
	v_mfma_f32_32x32x16_bf16 v[136:151], v[104:107], v[132:135], v[136:151]
	s_mov_b32 m0, s55
	v_lshl_add_u64 v[66:67], v[66:67], 0, s[44:45]
	global_load_lds_dwordx4 v[66:67], off sc1
	v_mfma_f32_32x32x16_bf16 v[152:167], v[104:107], v[204:207], v[152:167]
	global_load_lds_dwordx4 v[66:67], off offset:1024 sc1
	v_mfma_f32_32x32x16_bf16 v[16:31], v[108:111], v[112:115], v[16:31]
	s_mov_b32 m0, s58
	v_lshl_add_u64 v[78:79], v[66:67], 0, s[72:73]
	global_load_lds_dwordx4 v[78:79], off sc1
	v_mfma_f32_32x32x16_bf16 v[0:15], v[108:111], v[128:131], v[0:15]
	global_load_lds_dwordx4 v[78:79], off offset:1024 sc1
	v_mfma_f32_32x32x16_bf16 v[168:183], v[108:111], v[132:135], v[168:183]
	v_mfma_f32_32x32x16_bf16 v[184:199], v[108:111], v[204:207], v[184:199]
	s_waitcnt vmcnt(6)
	s_waitcnt lgkmcnt(0)
	s_barrier
	ds_read_b128 v[104:107], v116 offset:16384
	ds_read_b128 v[112:115], v119 offset:24576
	v_mfma_f32_32x32x16_bf16 v[48:63], v[208:211], v[244:247], v[48:63]
	ds_read_b128 v[128:131], v119 offset:26624
	ds_read_b128 v[132:135], v243 offset:40960
	v_mfma_f32_32x32x16_bf16 v[32:47], v[208:211], v[250:253], v[32:47]
	ds_read_b128 v[204:207], v243 offset:43008
	ds_read_b128 v[108:111], v116 offset:18432
	v_mfma_f32_32x32x16_bf16 v[136:151], v[208:211], v[68:71], v[136:151]
	v_mfma_f32_32x32x16_bf16 v[152:167], v[208:211], v[74:77], v[152:167]
	ds_read_b128 v[208:211], v122 offset:16384
	v_mfma_f32_32x32x16_bf16 v[16:31], v[214:217], v[244:247], v[16:31]
	ds_read_b128 v[244:247], v125 offset:24576
	v_mfma_f32_32x32x16_bf16 v[0:15], v[214:217], v[250:253], v[0:15]
	ds_read_b128 v[250:253], v125 offset:26624
	v_mfma_f32_32x32x16_bf16 v[168:183], v[214:217], v[68:71], v[168:183]
	ds_read_b128 v[68:71], v248 offset:40960
	v_mfma_f32_32x32x16_bf16 v[184:199], v[214:217], v[74:77], v[184:199]
	ds_read_b128 v[214:217], v122 offset:18432
	ds_read_b128 v[74:77], v248 offset:43008
	s_waitcnt lgkmcnt(6)
	v_mfma_f32_32x32x16_bf16 v[48:63], v[104:107], v[112:115], v[48:63]
	s_mov_b32 m0, s50
	v_lshl_add_u64 v[64:65], v[64:65], 0, s[44:45]
	global_load_lds_dwordx4 v[64:65], off sc1
	v_mfma_f32_32x32x16_bf16 v[32:47], v[104:107], v[128:131], v[32:47]
	global_load_lds_dwordx4 v[64:65], off offset:1024 sc1
	v_mfma_f32_32x32x16_bf16 v[136:151], v[104:107], v[132:135], v[136:151]
	s_mov_b32 m0, s53
	v_lshl_add_u64 v[66:67], v[66:67], 0, s[44:45]
	global_load_lds_dwordx4 v[66:67], off sc1
	v_mfma_f32_32x32x16_bf16 v[152:167], v[104:107], v[204:207], v[152:167]
	global_load_lds_dwordx4 v[66:67], off offset:1024 sc1
	v_mfma_f32_32x32x16_bf16 v[16:31], v[108:111], v[112:115], v[16:31]
	s_mov_b32 m0, s56
	v_lshl_add_u64 v[78:79], v[66:67], 0, s[72:73]
	global_load_lds_dwordx4 v[78:79], off sc1
	v_mfma_f32_32x32x16_bf16 v[0:15], v[108:111], v[128:131], v[0:15]
	global_load_lds_dwordx4 v[78:79], off offset:1024 sc1
	v_mfma_f32_32x32x16_bf16 v[168:183], v[108:111], v[132:135], v[168:183]
	v_mfma_f32_32x32x16_bf16 v[184:199], v[108:111], v[204:207], v[184:199]
	s_waitcnt vmcnt(6)
	s_waitcnt lgkmcnt(0)
	s_barrier
	ds_read_b128 v[104:107], v116 offset:32768
	ds_read_b128 v[112:115], v119 offset:40960
	v_mfma_f32_32x32x16_bf16 v[48:63], v[208:211], v[244:247], v[48:63]
	ds_read_b128 v[128:131], v119 offset:43008
	ds_read_b128 v[132:135], v243 offset:57344
	v_mfma_f32_32x32x16_bf16 v[32:47], v[208:211], v[250:253], v[32:47]
	ds_read_b128 v[204:207], v243 offset:59392
	ds_read_b128 v[108:111], v116 offset:34816
	v_mfma_f32_32x32x16_bf16 v[136:151], v[208:211], v[68:71], v[136:151]
	v_mfma_f32_32x32x16_bf16 v[152:167], v[208:211], v[74:77], v[152:167]
	ds_read_b128 v[208:211], v122 offset:32768
	v_mfma_f32_32x32x16_bf16 v[16:31], v[214:217], v[244:247], v[16:31]
	ds_read_b128 v[244:247], v125 offset:40960
	v_mfma_f32_32x32x16_bf16 v[0:15], v[214:217], v[250:253], v[0:15]
	ds_read_b128 v[250:253], v125 offset:43008
	v_mfma_f32_32x32x16_bf16 v[168:183], v[214:217], v[68:71], v[168:183]
	ds_read_b128 v[68:71], v248 offset:57344
	v_mfma_f32_32x32x16_bf16 v[184:199], v[214:217], v[74:77], v[184:199]
	ds_read_b128 v[214:217], v122 offset:34816
	ds_read_b128 v[74:77], v248 offset:59392
	s_waitcnt lgkmcnt(6)
	v_mfma_f32_32x32x16_bf16 v[48:63], v[104:107], v[112:115], v[48:63]
	s_mov_b32 m0, s51
	v_lshl_add_u64 v[64:65], v[64:65], 0, s[44:45]
	global_load_lds_dwordx4 v[64:65], off sc1
	v_mfma_f32_32x32x16_bf16 v[32:47], v[104:107], v[128:131], v[32:47]
	global_load_lds_dwordx4 v[64:65], off offset:1024 sc1
	v_mfma_f32_32x32x16_bf16 v[136:151], v[104:107], v[132:135], v[136:151]
	s_mov_b32 m0, s54
	v_lshl_add_u64 v[66:67], v[66:67], 0, s[44:45]
	global_load_lds_dwordx4 v[66:67], off sc1
	v_mfma_f32_32x32x16_bf16 v[152:167], v[104:107], v[204:207], v[152:167]
	global_load_lds_dwordx4 v[66:67], off offset:1024 sc1
	v_mfma_f32_32x32x16_bf16 v[16:31], v[108:111], v[112:115], v[16:31]
	s_mov_b32 m0, s57
	v_lshl_add_u64 v[78:79], v[66:67], 0, s[72:73]
	global_load_lds_dwordx4 v[78:79], off sc1
	v_mfma_f32_32x32x16_bf16 v[0:15], v[108:111], v[128:131], v[0:15]
	global_load_lds_dwordx4 v[78:79], off offset:1024 sc1
	v_mfma_f32_32x32x16_bf16 v[168:183], v[108:111], v[132:135], v[168:183]
	v_mfma_f32_32x32x16_bf16 v[184:199], v[108:111], v[204:207], v[184:199]
	s_waitcnt vmcnt(6)
	s_waitcnt lgkmcnt(0)
	s_barrier
	ds_read_b128 v[104:107], v116
	ds_read_b128 v[112:115], v119 offset:8192
	v_mfma_f32_32x32x16_bf16 v[48:63], v[208:211], v[244:247], v[48:63]
	ds_read_b128 v[128:131], v119 offset:10240
	ds_read_b128 v[132:135], v119 offset:49152
	v_mfma_f32_32x32x16_bf16 v[32:47], v[208:211], v[250:253], v[32:47]
	ds_read_b128 v[204:207], v119 offset:51200
	ds_read_b128 v[108:111], v116 offset:2048
	v_mfma_f32_32x32x16_bf16 v[136:151], v[208:211], v[68:71], v[136:151]
	v_mfma_f32_32x32x16_bf16 v[152:167], v[208:211], v[74:77], v[152:167]
	ds_read_b128 v[208:211], v122
	v_mfma_f32_32x32x16_bf16 v[16:31], v[214:217], v[244:247], v[16:31]
	ds_read_b128 v[244:247], v125 offset:8192
	v_mfma_f32_32x32x16_bf16 v[0:15], v[214:217], v[250:253], v[0:15]
	ds_read_b128 v[250:253], v125 offset:10240
	v_mfma_f32_32x32x16_bf16 v[168:183], v[214:217], v[68:71], v[168:183]
	ds_read_b128 v[68:71], v125 offset:49152
	v_mfma_f32_32x32x16_bf16 v[184:199], v[214:217], v[74:77], v[184:199]
	ds_read_b128 v[214:217], v122 offset:2048
	ds_read_b128 v[74:77], v125 offset:51200
	s_waitcnt lgkmcnt(6)
	v_mfma_f32_32x32x16_bf16 v[48:63], v[104:107], v[112:115], v[48:63]
	v_mfma_f32_32x32x16_bf16 v[32:47], v[104:107], v[128:131], v[32:47]
	v_mfma_f32_32x32x16_bf16 v[136:151], v[104:107], v[132:135], v[136:151]
	v_mfma_f32_32x32x16_bf16 v[152:167], v[104:107], v[204:207], v[152:167]
	v_mfma_f32_32x32x16_bf16 v[16:31], v[108:111], v[112:115], v[16:31]
	v_mfma_f32_32x32x16_bf16 v[0:15], v[108:111], v[128:131], v[0:15]
	v_mfma_f32_32x32x16_bf16 v[168:183], v[108:111], v[132:135], v[168:183]
	v_mfma_f32_32x32x16_bf16 v[184:199], v[108:111], v[204:207], v[184:199]
	s_waitcnt vmcnt(0)
	s_waitcnt lgkmcnt(0)
	s_barrier
	ds_read_b128 v[104:107], v116 offset:16384
	ds_read_b128 v[112:115], v119 offset:24576
	v_mfma_f32_32x32x16_bf16 v[48:63], v[208:211], v[244:247], v[48:63]
	ds_read_b128 v[128:131], v119 offset:26624
	ds_read_b128 v[132:135], v243 offset:40960
	v_mfma_f32_32x32x16_bf16 v[32:47], v[208:211], v[250:253], v[32:47]
	ds_read_b128 v[204:207], v243 offset:43008
	ds_read_b128 v[108:111], v116 offset:18432
	v_mfma_f32_32x32x16_bf16 v[136:151], v[208:211], v[68:71], v[136:151]
	v_mfma_f32_32x32x16_bf16 v[152:167], v[208:211], v[74:77], v[152:167]
	ds_read_b128 v[208:211], v122 offset:16384
	v_mfma_f32_32x32x16_bf16 v[16:31], v[214:217], v[244:247], v[16:31]
	ds_read_b128 v[244:247], v125 offset:24576
	v_mfma_f32_32x32x16_bf16 v[0:15], v[214:217], v[250:253], v[0:15]
	ds_read_b128 v[250:253], v125 offset:26624
	v_mfma_f32_32x32x16_bf16 v[168:183], v[214:217], v[68:71], v[168:183]
	ds_read_b128 v[68:71], v248 offset:40960
	v_mfma_f32_32x32x16_bf16 v[184:199], v[214:217], v[74:77], v[184:199]
	ds_read_b128 v[214:217], v122 offset:18432
	ds_read_b128 v[74:77], v248 offset:43008
	s_waitcnt lgkmcnt(6)
	v_mfma_f32_32x32x16_bf16 v[48:63], v[104:107], v[112:115], v[48:63]
	v_mfma_f32_32x32x16_bf16 v[32:47], v[104:107], v[128:131], v[32:47]
	v_mfma_f32_32x32x16_bf16 v[136:151], v[104:107], v[132:135], v[136:151]
	v_mfma_f32_32x32x16_bf16 v[152:167], v[104:107], v[204:207], v[152:167]
	v_mfma_f32_32x32x16_bf16 v[16:31], v[108:111], v[112:115], v[16:31]
	v_mfma_f32_32x32x16_bf16 v[0:15], v[108:111], v[128:131], v[0:15]
	v_mfma_f32_32x32x16_bf16 v[168:183], v[108:111], v[132:135], v[168:183]
	v_mfma_f32_32x32x16_bf16 v[184:199], v[108:111], v[204:207], v[184:199]
	s_waitcnt lgkmcnt(0)
	v_mfma_f32_32x32x16_bf16 v[48:63], v[208:211], v[244:247], v[48:63]
	v_mfma_f32_32x32x16_bf16 v[32:47], v[208:211], v[250:253], v[32:47]
	v_mfma_f32_32x32x16_bf16 v[136:151], v[208:211], v[68:71], v[136:151]
	v_mfma_f32_32x32x16_bf16 v[152:167], v[208:211], v[74:77], v[152:167]
	v_mfma_f32_32x32x16_bf16 v[16:31], v[214:217], v[244:247], v[16:31]
	v_mfma_f32_32x32x16_bf16 v[0:15], v[214:217], v[250:253], v[0:15]
	v_mfma_f32_32x32x16_bf16 v[168:183], v[214:217], v[68:71], v[168:183]
	v_mfma_f32_32x32x16_bf16 v[184:199], v[214:217], v[74:77], v[184:199]
	v_add_u32_e32 v79, 0x400, v94
	v_add_u32_e32 v78, 0x2000, v94
	v_add_u32_e32 v77, 0x2400, v94
	v_add_u32_e32 v76, 0x4000, v94
	v_add_u32_e32 v75, 0x4400, v94
	v_add_u32_e32 v74, 0x6000, v94
	v_add_u32_e32 v71, 0x8000, v94
	v_add_u32_e32 v70, 0x8400, v94
	v_add_u32_e32 v69, 0xa000, v94
	v_add_u32_e32 v68, 0xa400, v94
	s_branch .Lgt_post

.Lgt_single:
	v_add_u32_e32 v104, v95, v99
	v_add_u32_e32 v105, v98, v99
	v_add_u32_e32 v106, v95, v100
	v_add_u32_e32 v107, v98, v100
	v_readfirstlane_b32 s52, v94
	s_mov_b64 s[50:51], 0x4000
	s_add_u32 s53, s52, 0x4000
	s_add_u32 s54, s52, 0x8000
	s_add_u32 s55, s52, 0xc000
	s_add_u32 s56, s52, 0x2000
	s_add_u32 s57, s52, 0x6000
	s_add_u32 s58, s52, 0xa000
	s_add_u32 s59, s52, 0xe000
	v_lshl_add_u64 v[64:65], v[64:65], 0, s[50:51]
	v_lshl_add_u64 v[66:67], v[66:67], 0, s[50:51]
	s_waitcnt lgkmcnt(0)
	s_barrier
	ds_read_b128 v[128:131], v104
	ds_read_b128 v[136:139], v105 offset:8192
	ds_read_b128 v[140:143], v105 offset:10240
	ds_read_b128 v[132:135], v104 offset:2048
	ds_read_b128 v[144:147], v106
	ds_read_b128 v[152:155], v107 offset:8192
	ds_read_b128 v[156:159], v107 offset:10240
	ds_read_b128 v[148:151], v106 offset:2048
	s_mov_b32 m0, s55
	v_lshl_add_u64 v[64:65], v[64:65], 0, s[44:45]
	global_load_lds_dwordx4 v[64:65], off sc1
	global_load_lds_dwordx4 v[64:65], off offset:1024 sc1
	s_mov_b32 m0, s59
	v_lshl_add_u64 v[66:67], v[66:67], 0, s[44:45]
	global_load_lds_dwordx4 v[66:67], off sc1
	global_load_lds_dwordx4 v[66:67], off offset:1024 sc1
	s_waitcnt vmcnt(8)
	s_waitcnt lgkmcnt(0)
	s_barrier
	ds_read_b128 v[160:163], v104 offset:16384
	ds_read_b128 v[168:171], v105 offset:24576
	v_mfma_f32_32x32x16_bf16 v[48:63], v[128:131], v[136:139], 0
	ds_read_b128 v[172:175], v105 offset:26624
	ds_read_b128 v[164:167], v104 offset:18432
	v_mfma_f32_32x32x16_bf16 v[32:47], v[128:131], v[140:143], 0
	ds_read_b128 v[176:179], v106 offset:16384
	ds_read_b128 v[188:191], v107 offset:24576
	v_mfma_f32_32x32x16_bf16 v[16:31], v[132:135], v[136:139], 0
	ds_read_b128 v[192:195], v107 offset:26624
	ds_read_b128 v[184:187], v106 offset:18432
	v_mfma_f32_32x32x16_bf16 v[0:15], v[132:135], v[140:143], 0
	s_mov_b32 m0, s52
	v_lshl_add_u64 v[64:65], v[64:65], 0, s[44:45]
	global_load_lds_dwordx4 v[64:65], off sc1
	v_mfma_f32_32x32x16_bf16 v[48:63], v[144:147], v[152:155], v[48:63]
	global_load_lds_dwordx4 v[64:65], off offset:1024 sc1
	v_mfma_f32_32x32x16_bf16 v[32:47], v[144:147], v[156:159], v[32:47]
	s_mov_b32 m0, s56
	v_lshl_add_u64 v[66:67], v[66:67], 0, s[44:45]
	global_load_lds_dwordx4 v[66:67], off sc1
	v_mfma_f32_32x32x16_bf16 v[16:31], v[148:151], v[152:155], v[16:31]
	global_load_lds_dwordx4 v[66:67], off offset:1024 sc1
	v_mfma_f32_32x32x16_bf16 v[0:15], v[148:151], v[156:159], v[0:15]
	s_waitcnt vmcnt(8)
	s_waitcnt lgkmcnt(0)
	s_barrier
	ds_read_b128 v[128:131], v104 offset:32768
	ds_read_b128 v[136:139], v105 offset:40960
	v_mfma_f32_32x32x16_bf16 v[48:63], v[160:163], v[168:171], v[48:63]
	ds_read_b128 v[140:143], v105 offset:43008
	ds_read_b128 v[132:135], v104 offset:34816
	v_mfma_f32_32x32x16_bf16 v[32:47], v[160:163], v[172:175], v[32:47]
	ds_read_b128 v[144:147], v106 offset:32768
	ds_read_b128 v[152:155], v107 offset:40960
	v_mfma_f32_32x32x16_bf16 v[16:31], v[164:167], v[168:171], v[16:31]
	ds_read_b128 v[156:159], v107 offset:43008
	ds_read_b128 v[148:151], v106 offset:34816
	v_mfma_f32_32x32x16_bf16 v[0:15], v[164:167], v[172:175], v[0:15]
	s_mov_b32 m0, s53
	v_lshl_add_u64 v[64:65], v[64:65], 0, s[44:45]
	global_load_lds_dwordx4 v[64:65], off sc1
	v_mfma_f32_32x32x16_bf16 v[48:63], v[176:179], v[188:191], v[48:63]
	global_load_lds_dwordx4 v[64:65], off offset:1024 sc1
	v_mfma_f32_32x32x16_bf16 v[32:47], v[176:179], v[192:195], v[32:47]
	s_mov_b32 m0, s57
	v_lshl_add_u64 v[66:67], v[66:67], 0, s[44:45]
	global_load_lds_dwordx4 v[66:67], off sc1
	v_mfma_f32_32x32x16_bf16 v[16:31], v[184:187], v[188:191], v[16:31]
	global_load_lds_dwordx4 v[66:67], off offset:1024 sc1
	v_mfma_f32_32x32x16_bf16 v[0:15], v[184:187], v[192:195], v[0:15]
	s_waitcnt vmcnt(8)
	s_waitcnt lgkmcnt(0)
	s_barrier
	ds_read_b128 v[160:163], v104 offset:49152
	ds_read_b128 v[168:171], v105 offset:57344
	v_mfma_f32_32x32x16_bf16 v[48:63], v[128:131], v[136:139], v[48:63]
	ds_read_b128 v[172:175], v105 offset:59392
	ds_read_b128 v[164:167], v104 offset:51200
	v_mfma_f32_32x32x16_bf16 v[32:47], v[128:131], v[140:143], v[32:47]
	ds_read_b128 v[176:179], v106 offset:49152
	ds_read_b128 v[188:191], v107 offset:57344
	v_mfma_f32_32x32x16_bf16 v[16:31], v[132:135], v[136:139], v[16:31]
	ds_read_b128 v[192:195], v107 offset:59392
	ds_read_b128 v[184:187], v106 offset:51200
	v_mfma_f32_32x32x16_bf16 v[0:15], v[132:135], v[140:143], v[0:15]
	s_mov_b32 m0, s54
	v_lshl_add_u64 v[64:65], v[64:65], 0, s[44:45]
	global_load_lds_dwordx4 v[64:65], off sc1
	v_mfma_f32_32x32x16_bf16 v[48:63], v[144:147], v[152:155], v[48:63]
	global_load_lds_dwordx4 v[64:65], off offset:1024 sc1
	v_mfma_f32_32x32x16_bf16 v[32:47], v[144:147], v[156:159], v[32:47]
	s_mov_b32 m0, s58
	v_lshl_add_u64 v[66:67], v[66:67], 0, s[44:45]
	global_load_lds_dwordx4 v[66:67], off sc1
	v_mfma_f32_32x32x16_bf16 v[16:31], v[148:151], v[152:155], v[16:31]
	global_load_lds_dwordx4 v[66:67], off offset:1024 sc1
	v_mfma_f32_32x32x16_bf16 v[0:15], v[148:151], v[156:159], v[0:15]
	s_waitcnt vmcnt(8)
	s_waitcnt lgkmcnt(0)
	s_barrier
	ds_read_b128 v[128:131], v104
	ds_read_b128 v[136:139], v105 offset:8192
	v_mfma_f32_32x32x16_bf16 v[48:63], v[160:163], v[168:171], v[48:63]
	ds_read_b128 v[140:143], v105 offset:10240
	ds_read_b128 v[132:135], v104 offset:2048
	v_mfma_f32_32x32x16_bf16 v[32:47], v[160:163], v[172:175], v[32:47]
	ds_read_b128 v[144:147], v106
	ds_read_b128 v[152:155], v107 offset:8192
	v_mfma_f32_32x32x16_bf16 v[16:31], v[164:167], v[168:171], v[16:31]
	ds_read_b128 v[156:159], v107 offset:10240
	ds_read_b128 v[148:151], v106 offset:2048
	v_mfma_f32_32x32x16_bf16 v[0:15], v[164:167], v[172:175], v[0:15]
	s_mov_b32 m0, s55
	v_lshl_add_u64 v[64:65], v[64:65], 0, s[44:45]
	global_load_lds_dwordx4 v[64:65], off sc1
	v_mfma_f32_32x32x16_bf16 v[48:63], v[176:179], v[188:191], v[48:63]
	global_load_lds_dwordx4 v[64:65], off offset:1024 sc1
	v_mfma_f32_32x32x16_bf16 v[32:47], v[176:179], v[192:195], v[32:47]
	s_mov_b32 m0, s59
	v_lshl_add_u64 v[66:67], v[66:67], 0, s[44:45]
	global_load_lds_dwordx4 v[66:67], off sc1
	v_mfma_f32_32x32x16_bf16 v[16:31], v[184:187], v[188:191], v[16:31]
	global_load_lds_dwordx4 v[66:67], off offset:1024 sc1
	v_mfma_f32_32x32x16_bf16 v[0:15], v[184:187], v[192:195], v[0:15]
	s_waitcnt vmcnt(8)
	s_waitcnt lgkmcnt(0)
	s_barrier
	ds_read_b128 v[160:163], v104 offset:16384
	ds_read_b128 v[168:171], v105 offset:24576
	v_mfma_f32_32x32x16_bf16 v[48:63], v[128:131], v[136:139], v[48:63]
	ds_read_b128 v[172:175], v105 offset:26624
	ds_read_b128 v[164:167], v104 offset:18432
	v_mfma_f32_32x32x16_bf16 v[32:47], v[128:131], v[140:143], v[32:47]
	ds_read_b128 v[176:179], v106 offset:16384
	ds_read_b128 v[188:191], v107 offset:24576
	v_mfma_f32_32x32x16_bf16 v[16:31], v[132:135], v[136:139], v[16:31]
	ds_read_b128 v[192:195], v107 offset:26624
	ds_read_b128 v[184:187], v106 offset:18432
	v_mfma_f32_32x32x16_bf16 v[0:15], v[132:135], v[140:143], v[0:15]
	s_mov_b32 m0, s52
	v_lshl_add_u64 v[64:65], v[64:65], 0, s[44:45]
	global_load_lds_dwordx4 v[64:65], off sc1
	v_mfma_f32_32x32x16_bf16 v[48:63], v[144:147], v[152:155], v[48:63]
	global_load_lds_dwordx4 v[64:65], off offset:1024 sc1
	v_mfma_f32_32x32x16_bf16 v[32:47], v[144:147], v[156:159], v[32:47]
	s_mov_b32 m0, s56
	v_lshl_add_u64 v[66:67], v[66:67], 0, s[44:45]
	global_load_lds_dwordx4 v[66:67], off sc1
	v_mfma_f32_32x32x16_bf16 v[16:31], v[148:151], v[152:155], v[16:31]
	global_load_lds_dwordx4 v[66:67], off offset:1024 sc1
	v_mfma_f32_32x32x16_bf16 v[0:15], v[148:151], v[156:159], v[0:15]
	s_waitcnt vmcnt(8)
	s_waitcnt lgkmcnt(0)
	s_barrier
	ds_read_b128 v[128:131], v104 offset:32768
	ds_read_b128 v[136:139], v105 offset:40960
	v_mfma_f32_32x32x16_bf16 v[48:63], v[160:163], v[168:171], v[48:63]
	ds_read_b128 v[140:143], v105 offset:43008
	ds_read_b128 v[132:135], v104 offset:34816
	v_mfma_f32_32x32x16_bf16 v[32:47], v[160:163], v[172:175], v[32:47]
	ds_read_b128 v[144:147], v106 offset:32768
	ds_read_b128 v[152:155], v107 offset:40960
	v_mfma_f32_32x32x16_bf16 v[16:31], v[164:167], v[168:171], v[16:31]
	ds_read_b128 v[156:159], v107 offset:43008
	ds_read_b128 v[148:151], v106 offset:34816
	v_mfma_f32_32x32x16_bf16 v[0:15], v[164:167], v[172:175], v[0:15]
	s_mov_b32 m0, s53
	v_lshl_add_u64 v[64:65], v[64:65], 0, s[44:45]
	global_load_lds_dwordx4 v[64:65], off sc1
	v_mfma_f32_32x32x16_bf16 v[48:63], v[176:179], v[188:191], v[48:63]
	global_load_lds_dwordx4 v[64:65], off offset:1024 sc1
	v_mfma_f32_32x32x16_bf16 v[32:47], v[176:179], v[192:195], v[32:47]
	s_mov_b32 m0, s57
	v_lshl_add_u64 v[66:67], v[66:67], 0, s[44:45]
	global_load_lds_dwordx4 v[66:67], off sc1
	v_mfma_f32_32x32x16_bf16 v[16:31], v[184:187], v[188:191], v[16:31]
	global_load_lds_dwordx4 v[66:67], off offset:1024 sc1
	v_mfma_f32_32x32x16_bf16 v[0:15], v[184:187], v[192:195], v[0:15]
	s_waitcnt vmcnt(8)
	s_waitcnt lgkmcnt(0)
	s_barrier
	ds_read_b128 v[160:163], v104 offset:49152
	ds_read_b128 v[168:171], v105 offset:57344
	v_mfma_f32_32x32x16_bf16 v[48:63], v[128:131], v[136:139], v[48:63]
	ds_read_b128 v[172:175], v105 offset:59392
	ds_read_b128 v[164:167], v104 offset:51200
	v_mfma_f32_32x32x16_bf16 v[32:47], v[128:131], v[140:143], v[32:47]
	ds_read_b128 v[176:179], v106 offset:49152
	ds_read_b128 v[188:191], v107 offset:57344
	v_mfma_f32_32x32x16_bf16 v[16:31], v[132:135], v[136:139], v[16:31]
	ds_read_b128 v[192:195], v107 offset:59392
	ds_read_b128 v[184:187], v106 offset:51200
	v_mfma_f32_32x32x16_bf16 v[0:15], v[132:135], v[140:143], v[0:15]
	s_mov_b32 m0, s54
	v_lshl_add_u64 v[64:65], v[64:65], 0, s[44:45]
	global_load_lds_dwordx4 v[64:65], off sc1
	v_mfma_f32_32x32x16_bf16 v[48:63], v[144:147], v[152:155], v[48:63]
	global_load_lds_dwordx4 v[64:65], off offset:1024 sc1
	v_mfma_f32_32x32x16_bf16 v[32:47], v[144:147], v[156:159], v[32:47]
	s_mov_b32 m0, s58
	v_lshl_add_u64 v[66:67], v[66:67], 0, s[44:45]
	global_load_lds_dwordx4 v[66:67], off sc1
	v_mfma_f32_32x32x16_bf16 v[16:31], v[148:151], v[152:155], v[16:31]
	global_load_lds_dwordx4 v[66:67], off offset:1024 sc1
	v_mfma_f32_32x32x16_bf16 v[0:15], v[148:151], v[156:159], v[0:15]
	s_waitcnt vmcnt(8)
	s_waitcnt lgkmcnt(0)
	s_barrier
	ds_read_b128 v[128:131], v104
	ds_read_b128 v[136:139], v105 offset:8192
	v_mfma_f32_32x32x16_bf16 v[48:63], v[160:163], v[168:171], v[48:63]
	ds_read_b128 v[140:143], v105 offset:10240
	ds_read_b128 v[132:135], v104 offset:2048
	v_mfma_f32_32x32x16_bf16 v[32:47], v[160:163], v[172:175], v[32:47]
	ds_read_b128 v[144:147], v106
	ds_read_b128 v[152:155], v107 offset:8192
	v_mfma_f32_32x32x16_bf16 v[16:31], v[164:167], v[168:171], v[16:31]
	ds_read_b128 v[156:159], v107 offset:10240
	ds_read_b128 v[148:151], v106 offset:2048
	v_mfma_f32_32x32x16_bf16 v[0:15], v[164:167], v[172:175], v[0:15]
	s_mov_b32 m0, s55
	v_lshl_add_u64 v[64:65], v[64:65], 0, s[44:45]
	global_load_lds_dwordx4 v[64:65], off sc1
	v_mfma_f32_32x32x16_bf16 v[48:63], v[176:179], v[188:191], v[48:63]
	global_load_lds_dwordx4 v[64:65], off offset:1024 sc1
	v_mfma_f32_32x32x16_bf16 v[32:47], v[176:179], v[192:195], v[32:47]
	s_mov_b32 m0, s59
	v_lshl_add_u64 v[66:67], v[66:67], 0, s[44:45]
	global_load_lds_dwordx4 v[66:67], off sc1
	v_mfma_f32_32x32x16_bf16 v[16:31], v[184:187], v[188:191], v[16:31]
	global_load_lds_dwordx4 v[66:67], off offset:1024 sc1
	v_mfma_f32_32x32x16_bf16 v[0:15], v[184:187], v[192:195], v[0:15]
	s_waitcnt vmcnt(8)
	s_waitcnt lgkmcnt(0)
	s_barrier
	ds_read_b128 v[160:163], v104 offset:16384
	ds_read_b128 v[168:171], v105 offset:24576
	v_mfma_f32_32x32x16_bf16 v[48:63], v[128:131], v[136:139], v[48:63]
	ds_read_b128 v[172:175], v105 offset:26624
	ds_read_b128 v[164:167], v104 offset:18432
	v_mfma_f32_32x32x16_bf16 v[32:47], v[128:131], v[140:143], v[32:47]
	ds_read_b128 v[176:179], v106 offset:16384
	ds_read_b128 v[188:191], v107 offset:24576
	v_mfma_f32_32x32x16_bf16 v[16:31], v[132:135], v[136:139], v[16:31]
	ds_read_b128 v[192:195], v107 offset:26624
	ds_read_b128 v[184:187], v106 offset:18432
	v_mfma_f32_32x32x16_bf16 v[0:15], v[132:135], v[140:143], v[0:15]
	s_mov_b32 m0, s52
	v_lshl_add_u64 v[64:65], v[64:65], 0, s[44:45]
	global_load_lds_dwordx4 v[64:65], off sc1
	v_mfma_f32_32x32x16_bf16 v[48:63], v[144:147], v[152:155], v[48:63]
	global_load_lds_dwordx4 v[64:65], off offset:1024 sc1
	v_mfma_f32_32x32x16_bf16 v[32:47], v[144:147], v[156:159], v[32:47]
	s_mov_b32 m0, s56
	v_lshl_add_u64 v[66:67], v[66:67], 0, s[44:45]
	global_load_lds_dwordx4 v[66:67], off sc1
	v_mfma_f32_32x32x16_bf16 v[16:31], v[148:151], v[152:155], v[16:31]
	global_load_lds_dwordx4 v[66:67], off offset:1024 sc1
	v_mfma_f32_32x32x16_bf16 v[0:15], v[148:151], v[156:159], v[0:15]
	s_waitcnt vmcnt(8)
	s_waitcnt lgkmcnt(0)
	s_barrier
	ds_read_b128 v[128:131], v104 offset:32768
	ds_read_b128 v[136:139], v105 offset:40960
	v_mfma_f32_32x32x16_bf16 v[48:63], v[160:163], v[168:171], v[48:63]
	ds_read_b128 v[140:143], v105 offset:43008
	ds_read_b128 v[132:135], v104 offset:34816
	v_mfma_f32_32x32x16_bf16 v[32:47], v[160:163], v[172:175], v[32:47]
	ds_read_b128 v[144:147], v106 offset:32768
	ds_read_b128 v[152:155], v107 offset:40960
	v_mfma_f32_32x32x16_bf16 v[16:31], v[164:167], v[168:171], v[16:31]
	ds_read_b128 v[156:159], v107 offset:43008
	ds_read_b128 v[148:151], v106 offset:34816
	v_mfma_f32_32x32x16_bf16 v[0:15], v[164:167], v[172:175], v[0:15]
	s_mov_b32 m0, s53
	v_lshl_add_u64 v[64:65], v[64:65], 0, s[44:45]
	global_load_lds_dwordx4 v[64:65], off sc1
	v_mfma_f32_32x32x16_bf16 v[48:63], v[176:179], v[188:191], v[48:63]
	global_load_lds_dwordx4 v[64:65], off offset:1024 sc1
	v_mfma_f32_32x32x16_bf16 v[32:47], v[176:179], v[192:195], v[32:47]
	s_mov_b32 m0, s57
	v_lshl_add_u64 v[66:67], v[66:67], 0, s[44:45]
	global_load_lds_dwordx4 v[66:67], off sc1
	v_mfma_f32_32x32x16_bf16 v[16:31], v[184:187], v[188:191], v[16:31]
	global_load_lds_dwordx4 v[66:67], off offset:1024 sc1
	v_mfma_f32_32x32x16_bf16 v[0:15], v[184:187], v[192:195], v[0:15]
	s_waitcnt vmcnt(8)
	s_waitcnt lgkmcnt(0)
	s_barrier
	ds_read_b128 v[160:163], v104 offset:49152
	ds_read_b128 v[168:171], v105 offset:57344
	v_mfma_f32_32x32x16_bf16 v[48:63], v[128:131], v[136:139], v[48:63]
	ds_read_b128 v[172:175], v105 offset:59392
	ds_read_b128 v[164:167], v104 offset:51200
	v_mfma_f32_32x32x16_bf16 v[32:47], v[128:131], v[140:143], v[32:47]
	ds_read_b128 v[176:179], v106 offset:49152
	ds_read_b128 v[188:191], v107 offset:57344
	v_mfma_f32_32x32x16_bf16 v[16:31], v[132:135], v[136:139], v[16:31]
	ds_read_b128 v[192:195], v107 offset:59392
	ds_read_b128 v[184:187], v106 offset:51200
	v_mfma_f32_32x32x16_bf16 v[0:15], v[132:135], v[140:143], v[0:15]
	s_mov_b32 m0, s54
	v_lshl_add_u64 v[64:65], v[64:65], 0, s[44:45]
	global_load_lds_dwordx4 v[64:65], off sc1
	v_mfma_f32_32x32x16_bf16 v[48:63], v[144:147], v[152:155], v[48:63]
	global_load_lds_dwordx4 v[64:65], off offset:1024 sc1
	v_mfma_f32_32x32x16_bf16 v[32:47], v[144:147], v[156:159], v[32:47]
	s_mov_b32 m0, s58
	v_lshl_add_u64 v[66:67], v[66:67], 0, s[44:45]
	global_load_lds_dwordx4 v[66:67], off sc1
	v_mfma_f32_32x32x16_bf16 v[16:31], v[148:151], v[152:155], v[16:31]
	global_load_lds_dwordx4 v[66:67], off offset:1024 sc1
	v_mfma_f32_32x32x16_bf16 v[0:15], v[148:151], v[156:159], v[0:15]
	s_waitcnt vmcnt(8)
	s_waitcnt lgkmcnt(0)
	s_barrier
	ds_read_b128 v[128:131], v104
	ds_read_b128 v[136:139], v105 offset:8192
	v_mfma_f32_32x32x16_bf16 v[48:63], v[160:163], v[168:171], v[48:63]
	ds_read_b128 v[140:143], v105 offset:10240
	ds_read_b128 v[132:135], v104 offset:2048
	v_mfma_f32_32x32x16_bf16 v[32:47], v[160:163], v[172:175], v[32:47]
	ds_read_b128 v[144:147], v106
	ds_read_b128 v[152:155], v107 offset:8192
	v_mfma_f32_32x32x16_bf16 v[16:31], v[164:167], v[168:171], v[16:31]
	ds_read_b128 v[156:159], v107 offset:10240
	ds_read_b128 v[148:151], v106 offset:2048
	v_mfma_f32_32x32x16_bf16 v[0:15], v[164:167], v[172:175], v[0:15]
	s_mov_b32 m0, s55
	v_lshl_add_u64 v[64:65], v[64:65], 0, s[44:45]
	global_load_lds_dwordx4 v[64:65], off sc1
	v_mfma_f32_32x32x16_bf16 v[48:63], v[176:179], v[188:191], v[48:63]
	global_load_lds_dwordx4 v[64:65], off offset:1024 sc1
	v_mfma_f32_32x32x16_bf16 v[32:47], v[176:179], v[192:195], v[32:47]
	s_mov_b32 m0, s59
	v_lshl_add_u64 v[66:67], v[66:67], 0, s[44:45]
	global_load_lds_dwordx4 v[66:67], off sc1
	v_mfma_f32_32x32x16_bf16 v[16:31], v[184:187], v[188:191], v[16:31]
	global_load_lds_dwordx4 v[66:67], off offset:1024 sc1
	v_mfma_f32_32x32x16_bf16 v[0:15], v[184:187], v[192:195], v[0:15]
	s_waitcnt vmcnt(8)
	s_waitcnt lgkmcnt(0)
	s_barrier
	ds_read_b128 v[160:163], v104 offset:16384
	ds_read_b128 v[168:171], v105 offset:24576
	v_mfma_f32_32x32x16_bf16 v[48:63], v[128:131], v[136:139], v[48:63]
	ds_read_b128 v[172:175], v105 offset:26624
	ds_read_b128 v[164:167], v104 offset:18432
	v_mfma_f32_32x32x16_bf16 v[32:47], v[128:131], v[140:143], v[32:47]
	ds_read_b128 v[176:179], v106 offset:16384
	ds_read_b128 v[188:191], v107 offset:24576
	v_mfma_f32_32x32x16_bf16 v[16:31], v[132:135], v[136:139], v[16:31]
	ds_read_b128 v[192:195], v107 offset:26624
	ds_read_b128 v[184:187], v106 offset:18432
	v_mfma_f32_32x32x16_bf16 v[0:15], v[132:135], v[140:143], v[0:15]
	s_mov_b32 m0, s52
	v_lshl_add_u64 v[64:65], v[64:65], 0, s[44:45]
	global_load_lds_dwordx4 v[64:65], off sc1
	v_mfma_f32_32x32x16_bf16 v[48:63], v[144:147], v[152:155], v[48:63]
	global_load_lds_dwordx4 v[64:65], off offset:1024 sc1
	v_mfma_f32_32x32x16_bf16 v[32:47], v[144:147], v[156:159], v[32:47]
	s_mov_b32 m0, s56
	v_lshl_add_u64 v[66:67], v[66:67], 0, s[44:45]
	global_load_lds_dwordx4 v[66:67], off sc1
	v_mfma_f32_32x32x16_bf16 v[16:31], v[148:151], v[152:155], v[16:31]
	global_load_lds_dwordx4 v[66:67], off offset:1024 sc1
	v_mfma_f32_32x32x16_bf16 v[0:15], v[148:151], v[156:159], v[0:15]
	s_waitcnt vmcnt(8)
	s_waitcnt lgkmcnt(0)
	s_barrier
	ds_read_b128 v[128:131], v104 offset:32768
	ds_read_b128 v[136:139], v105 offset:40960
	v_mfma_f32_32x32x16_bf16 v[48:63], v[160:163], v[168:171], v[48:63]
	ds_read_b128 v[140:143], v105 offset:43008
	ds_read_b128 v[132:135], v104 offset:34816
	v_mfma_f32_32x32x16_bf16 v[32:47], v[160:163], v[172:175], v[32:47]
	ds_read_b128 v[144:147], v106 offset:32768
	ds_read_b128 v[152:155], v107 offset:40960
	v_mfma_f32_32x32x16_bf16 v[16:31], v[164:167], v[168:171], v[16:31]
	ds_read_b128 v[156:159], v107 offset:43008
	ds_read_b128 v[148:151], v106 offset:34816
	v_mfma_f32_32x32x16_bf16 v[0:15], v[164:167], v[172:175], v[0:15]
	s_mov_b32 m0, s53
	v_lshl_add_u64 v[64:65], v[64:65], 0, s[44:45]
	global_load_lds_dwordx4 v[64:65], off sc1
	v_mfma_f32_32x32x16_bf16 v[48:63], v[176:179], v[188:191], v[48:63]
	global_load_lds_dwordx4 v[64:65], off offset:1024 sc1
	v_mfma_f32_32x32x16_bf16 v[32:47], v[176:179], v[192:195], v[32:47]
	s_mov_b32 m0, s57
	v_lshl_add_u64 v[66:67], v[66:67], 0, s[44:45]
	global_load_lds_dwordx4 v[66:67], off sc1
	v_mfma_f32_32x32x16_bf16 v[16:31], v[184:187], v[188:191], v[16:31]
	global_load_lds_dwordx4 v[66:67], off offset:1024 sc1
	v_mfma_f32_32x32x16_bf16 v[0:15], v[184:187], v[192:195], v[0:15]
	s_waitcnt vmcnt(8)
	s_waitcnt lgkmcnt(0)
	s_barrier
	ds_read_b128 v[160:163], v104 offset:49152
	ds_read_b128 v[168:171], v105 offset:57344
	v_mfma_f32_32x32x16_bf16 v[48:63], v[128:131], v[136:139], v[48:63]
	ds_read_b128 v[172:175], v105 offset:59392
	ds_read_b128 v[164:167], v104 offset:51200
	v_mfma_f32_32x32x16_bf16 v[32:47], v[128:131], v[140:143], v[32:47]
	ds_read_b128 v[176:179], v106 offset:49152
	ds_read_b128 v[188:191], v107 offset:57344
	v_mfma_f32_32x32x16_bf16 v[16:31], v[132:135], v[136:139], v[16:31]
	ds_read_b128 v[192:195], v107 offset:59392
	ds_read_b128 v[184:187], v106 offset:51200
	v_mfma_f32_32x32x16_bf16 v[0:15], v[132:135], v[140:143], v[0:15]
	s_mov_b32 m0, s54
	v_lshl_add_u64 v[64:65], v[64:65], 0, s[44:45]
	global_load_lds_dwordx4 v[64:65], off sc1
	v_mfma_f32_32x32x16_bf16 v[48:63], v[144:147], v[152:155], v[48:63]
	global_load_lds_dwordx4 v[64:65], off offset:1024 sc1
	v_mfma_f32_32x32x16_bf16 v[32:47], v[144:147], v[156:159], v[32:47]
	s_mov_b32 m0, s58
	v_lshl_add_u64 v[66:67], v[66:67], 0, s[44:45]
	global_load_lds_dwordx4 v[66:67], off sc1
	v_mfma_f32_32x32x16_bf16 v[16:31], v[148:151], v[152:155], v[16:31]
	global_load_lds_dwordx4 v[66:67], off offset:1024 sc1
	v_mfma_f32_32x32x16_bf16 v[0:15], v[148:151], v[156:159], v[0:15]
	s_waitcnt vmcnt(8)
	s_waitcnt lgkmcnt(0)
	s_barrier
	ds_read_b128 v[128:131], v104
	ds_read_b128 v[136:139], v105 offset:8192
	v_mfma_f32_32x32x16_bf16 v[48:63], v[160:163], v[168:171], v[48:63]
	ds_read_b128 v[140:143], v105 offset:10240
	ds_read_b128 v[132:135], v104 offset:2048
	v_mfma_f32_32x32x16_bf16 v[32:47], v[160:163], v[172:175], v[32:47]
	ds_read_b128 v[144:147], v106
	ds_read_b128 v[152:155], v107 offset:8192
	v_mfma_f32_32x32x16_bf16 v[16:31], v[164:167], v[168:171], v[16:31]
	ds_read_b128 v[156:159], v107 offset:10240
	ds_read_b128 v[148:151], v106 offset:2048
	v_mfma_f32_32x32x16_bf16 v[0:15], v[164:167], v[172:175], v[0:15]
	s_mov_b32 m0, s55
	v_lshl_add_u64 v[64:65], v[64:65], 0, s[44:45]
	global_load_lds_dwordx4 v[64:65], off sc1
	v_mfma_f32_32x32x16_bf16 v[48:63], v[176:179], v[188:191], v[48:63]
	global_load_lds_dwordx4 v[64:65], off offset:1024 sc1
	v_mfma_f32_32x32x16_bf16 v[32:47], v[176:179], v[192:195], v[32:47]
	s_mov_b32 m0, s59
	v_lshl_add_u64 v[66:67], v[66:67], 0, s[44:45]
	global_load_lds_dwordx4 v[66:67], off sc1
	v_mfma_f32_32x32x16_bf16 v[16:31], v[184:187], v[188:191], v[16:31]
	global_load_lds_dwordx4 v[66:67], off offset:1024 sc1
	v_mfma_f32_32x32x16_bf16 v[0:15], v[184:187], v[192:195], v[0:15]
	s_waitcnt vmcnt(8)
	s_waitcnt lgkmcnt(0)
	s_barrier
	ds_read_b128 v[160:163], v104 offset:16384
	ds_read_b128 v[168:171], v105 offset:24576
	v_mfma_f32_32x32x16_bf16 v[48:63], v[128:131], v[136:139], v[48:63]
	ds_read_b128 v[172:175], v105 offset:26624
	ds_read_b128 v[164:167], v104 offset:18432
	v_mfma_f32_32x32x16_bf16 v[32:47], v[128:131], v[140:143], v[32:47]
	ds_read_b128 v[176:179], v106 offset:16384
	ds_read_b128 v[188:191], v107 offset:24576
	v_mfma_f32_32x32x16_bf16 v[16:31], v[132:135], v[136:139], v[16:31]
	ds_read_b128 v[192:195], v107 offset:26624
	ds_read_b128 v[184:187], v106 offset:18432
	v_mfma_f32_32x32x16_bf16 v[0:15], v[132:135], v[140:143], v[0:15]
	s_mov_b32 m0, s52
	v_lshl_add_u64 v[64:65], v[64:65], 0, s[44:45]
	global_load_lds_dwordx4 v[64:65], off sc1
	v_mfma_f32_32x32x16_bf16 v[48:63], v[144:147], v[152:155], v[48:63]
	global_load_lds_dwordx4 v[64:65], off offset:1024 sc1
	v_mfma_f32_32x32x16_bf16 v[32:47], v[144:147], v[156:159], v[32:47]
	s_mov_b32 m0, s56
	v_lshl_add_u64 v[66:67], v[66:67], 0, s[44:45]
	global_load_lds_dwordx4 v[66:67], off sc1
	v_mfma_f32_32x32x16_bf16 v[16:31], v[148:151], v[152:155], v[16:31]
	global_load_lds_dwordx4 v[66:67], off offset:1024 sc1
	v_mfma_f32_32x32x16_bf16 v[0:15], v[148:151], v[156:159], v[0:15]
	s_waitcnt vmcnt(8)
	s_waitcnt lgkmcnt(0)
	s_barrier
	ds_read_b128 v[128:131], v104 offset:32768
	ds_read_b128 v[136:139], v105 offset:40960
	v_mfma_f32_32x32x16_bf16 v[48:63], v[160:163], v[168:171], v[48:63]
	ds_read_b128 v[140:143], v105 offset:43008
	ds_read_b128 v[132:135], v104 offset:34816
	v_mfma_f32_32x32x16_bf16 v[32:47], v[160:163], v[172:175], v[32:47]
	ds_read_b128 v[144:147], v106 offset:32768
	ds_read_b128 v[152:155], v107 offset:40960
	v_mfma_f32_32x32x16_bf16 v[16:31], v[164:167], v[168:171], v[16:31]
	ds_read_b128 v[156:159], v107 offset:43008
	ds_read_b128 v[148:151], v106 offset:34816
	v_mfma_f32_32x32x16_bf16 v[0:15], v[164:167], v[172:175], v[0:15]
	s_mov_b32 m0, s53
	v_lshl_add_u64 v[64:65], v[64:65], 0, s[44:45]
	global_load_lds_dwordx4 v[64:65], off sc1
	v_mfma_f32_32x32x16_bf16 v[48:63], v[176:179], v[188:191], v[48:63]
	global_load_lds_dwordx4 v[64:65], off offset:1024 sc1
	v_mfma_f32_32x32x16_bf16 v[32:47], v[176:179], v[192:195], v[32:47]
	s_mov_b32 m0, s57
	v_lshl_add_u64 v[66:67], v[66:67], 0, s[44:45]
	global_load_lds_dwordx4 v[66:67], off sc1
	v_mfma_f32_32x32x16_bf16 v[16:31], v[184:187], v[188:191], v[16:31]
	global_load_lds_dwordx4 v[66:67], off offset:1024 sc1
	v_mfma_f32_32x32x16_bf16 v[0:15], v[184:187], v[192:195], v[0:15]
	s_waitcnt vmcnt(8)
	s_waitcnt lgkmcnt(0)
	s_barrier
	ds_read_b128 v[160:163], v104 offset:49152
	ds_read_b128 v[168:171], v105 offset:57344
	v_mfma_f32_32x32x16_bf16 v[48:63], v[128:131], v[136:139], v[48:63]
	ds_read_b128 v[172:175], v105 offset:59392
	ds_read_b128 v[164:167], v104 offset:51200
	v_mfma_f32_32x32x16_bf16 v[32:47], v[128:131], v[140:143], v[32:47]
	ds_read_b128 v[176:179], v106 offset:49152
	ds_read_b128 v[188:191], v107 offset:57344
	v_mfma_f32_32x32x16_bf16 v[16:31], v[132:135], v[136:139], v[16:31]
	ds_read_b128 v[192:195], v107 offset:59392
	ds_read_b128 v[184:187], v106 offset:51200
	v_mfma_f32_32x32x16_bf16 v[0:15], v[132:135], v[140:143], v[0:15]
	s_mov_b32 m0, s54
	v_lshl_add_u64 v[64:65], v[64:65], 0, s[44:45]
	global_load_lds_dwordx4 v[64:65], off sc1
	v_mfma_f32_32x32x16_bf16 v[48:63], v[144:147], v[152:155], v[48:63]
	global_load_lds_dwordx4 v[64:65], off offset:1024 sc1
	v_mfma_f32_32x32x16_bf16 v[32:47], v[144:147], v[156:159], v[32:47]
	s_mov_b32 m0, s58
	v_lshl_add_u64 v[66:67], v[66:67], 0, s[44:45]
	global_load_lds_dwordx4 v[66:67], off sc1
	v_mfma_f32_32x32x16_bf16 v[16:31], v[148:151], v[152:155], v[16:31]
	global_load_lds_dwordx4 v[66:67], off offset:1024 sc1
	v_mfma_f32_32x32x16_bf16 v[0:15], v[148:151], v[156:159], v[0:15]
	s_waitcnt vmcnt(8)
	s_waitcnt lgkmcnt(0)
	s_barrier
	ds_read_b128 v[128:131], v104
	ds_read_b128 v[136:139], v105 offset:8192
	v_mfma_f32_32x32x16_bf16 v[48:63], v[160:163], v[168:171], v[48:63]
	ds_read_b128 v[140:143], v105 offset:10240
	ds_read_b128 v[132:135], v104 offset:2048
	v_mfma_f32_32x32x16_bf16 v[32:47], v[160:163], v[172:175], v[32:47]
	ds_read_b128 v[144:147], v106
	ds_read_b128 v[152:155], v107 offset:8192
	v_mfma_f32_32x32x16_bf16 v[16:31], v[164:167], v[168:171], v[16:31]
	ds_read_b128 v[156:159], v107 offset:10240
	ds_read_b128 v[148:151], v106 offset:2048
	v_mfma_f32_32x32x16_bf16 v[0:15], v[164:167], v[172:175], v[0:15]
	s_mov_b32 m0, s55
	v_lshl_add_u64 v[64:65], v[64:65], 0, s[44:45]
	global_load_lds_dwordx4 v[64:65], off sc1
	v_mfma_f32_32x32x16_bf16 v[48:63], v[176:179], v[188:191], v[48:63]
	global_load_lds_dwordx4 v[64:65], off offset:1024 sc1
	v_mfma_f32_32x32x16_bf16 v[32:47], v[176:179], v[192:195], v[32:47]
	s_mov_b32 m0, s59
	v_lshl_add_u64 v[66:67], v[66:67], 0, s[44:45]
	global_load_lds_dwordx4 v[66:67], off sc1
	v_mfma_f32_32x32x16_bf16 v[16:31], v[184:187], v[188:191], v[16:31]
	global_load_lds_dwordx4 v[66:67], off offset:1024 sc1
	v_mfma_f32_32x32x16_bf16 v[0:15], v[184:187], v[192:195], v[0:15]
	s_waitcnt vmcnt(8)
	s_waitcnt lgkmcnt(0)
	s_barrier
	ds_read_b128 v[160:163], v104 offset:16384
	ds_read_b128 v[168:171], v105 offset:24576
	v_mfma_f32_32x32x16_bf16 v[48:63], v[128:131], v[136:139], v[48:63]
	ds_read_b128 v[172:175], v105 offset:26624
	ds_read_b128 v[164:167], v104 offset:18432
	v_mfma_f32_32x32x16_bf16 v[32:47], v[128:131], v[140:143], v[32:47]
	ds_read_b128 v[176:179], v106 offset:16384
	ds_read_b128 v[188:191], v107 offset:24576
	v_mfma_f32_32x32x16_bf16 v[16:31], v[132:135], v[136:139], v[16:31]
	ds_read_b128 v[192:195], v107 offset:26624
	ds_read_b128 v[184:187], v106 offset:18432
	v_mfma_f32_32x32x16_bf16 v[0:15], v[132:135], v[140:143], v[0:15]
	s_mov_b32 m0, s52
	v_lshl_add_u64 v[64:65], v[64:65], 0, s[44:45]
	global_load_lds_dwordx4 v[64:65], off sc1
	v_mfma_f32_32x32x16_bf16 v[48:63], v[144:147], v[152:155], v[48:63]
	global_load_lds_dwordx4 v[64:65], off offset:1024 sc1
	v_mfma_f32_32x32x16_bf16 v[32:47], v[144:147], v[156:159], v[32:47]
	s_mov_b32 m0, s56
	v_lshl_add_u64 v[66:67], v[66:67], 0, s[44:45]
	global_load_lds_dwordx4 v[66:67], off sc1
	v_mfma_f32_32x32x16_bf16 v[16:31], v[148:151], v[152:155], v[16:31]
	global_load_lds_dwordx4 v[66:67], off offset:1024 sc1
	v_mfma_f32_32x32x16_bf16 v[0:15], v[148:151], v[156:159], v[0:15]
	s_waitcnt vmcnt(8)
	s_waitcnt lgkmcnt(0)
	s_barrier
	ds_read_b128 v[128:131], v104 offset:32768
	ds_read_b128 v[136:139], v105 offset:40960
	v_mfma_f32_32x32x16_bf16 v[48:63], v[160:163], v[168:171], v[48:63]
	ds_read_b128 v[140:143], v105 offset:43008
	ds_read_b128 v[132:135], v104 offset:34816
	v_mfma_f32_32x32x16_bf16 v[32:47], v[160:163], v[172:175], v[32:47]
	ds_read_b128 v[144:147], v106 offset:32768
	ds_read_b128 v[152:155], v107 offset:40960
	v_mfma_f32_32x32x16_bf16 v[16:31], v[164:167], v[168:171], v[16:31]
	ds_read_b128 v[156:159], v107 offset:43008
	ds_read_b128 v[148:151], v106 offset:34816
	v_mfma_f32_32x32x16_bf16 v[0:15], v[164:167], v[172:175], v[0:15]
	s_mov_b32 m0, s53
	v_lshl_add_u64 v[64:65], v[64:65], 0, s[44:45]
	global_load_lds_dwordx4 v[64:65], off sc1
	v_mfma_f32_32x32x16_bf16 v[48:63], v[176:179], v[188:191], v[48:63]
	global_load_lds_dwordx4 v[64:65], off offset:1024 sc1
	v_mfma_f32_32x32x16_bf16 v[32:47], v[176:179], v[192:195], v[32:47]
	s_mov_b32 m0, s57
	v_lshl_add_u64 v[66:67], v[66:67], 0, s[44:45]
	global_load_lds_dwordx4 v[66:67], off sc1
	v_mfma_f32_32x32x16_bf16 v[16:31], v[184:187], v[188:191], v[16:31]
	global_load_lds_dwordx4 v[66:67], off offset:1024 sc1
	v_mfma_f32_32x32x16_bf16 v[0:15], v[184:187], v[192:195], v[0:15]
	s_waitcnt vmcnt(8)
	s_waitcnt lgkmcnt(0)
	s_barrier
	ds_read_b128 v[160:163], v104 offset:49152
	ds_read_b128 v[168:171], v105 offset:57344
	v_mfma_f32_32x32x16_bf16 v[48:63], v[128:131], v[136:139], v[48:63]
	ds_read_b128 v[172:175], v105 offset:59392
	ds_read_b128 v[164:167], v104 offset:51200
	v_mfma_f32_32x32x16_bf16 v[32:47], v[128:131], v[140:143], v[32:47]
	ds_read_b128 v[176:179], v106 offset:49152
	ds_read_b128 v[188:191], v107 offset:57344
	v_mfma_f32_32x32x16_bf16 v[16:31], v[132:135], v[136:139], v[16:31]
	ds_read_b128 v[192:195], v107 offset:59392
	ds_read_b128 v[184:187], v106 offset:51200
	v_mfma_f32_32x32x16_bf16 v[0:15], v[132:135], v[140:143], v[0:15]
	s_mov_b32 m0, s54
	v_lshl_add_u64 v[64:65], v[64:65], 0, s[44:45]
	global_load_lds_dwordx4 v[64:65], off sc1
	v_mfma_f32_32x32x16_bf16 v[48:63], v[144:147], v[152:155], v[48:63]
	global_load_lds_dwordx4 v[64:65], off offset:1024 sc1
	v_mfma_f32_32x32x16_bf16 v[32:47], v[144:147], v[156:159], v[32:47]
	s_mov_b32 m0, s58
	v_lshl_add_u64 v[66:67], v[66:67], 0, s[44:45]
	global_load_lds_dwordx4 v[66:67], off sc1
	v_mfma_f32_32x32x16_bf16 v[16:31], v[148:151], v[152:155], v[16:31]
	global_load_lds_dwordx4 v[66:67], off offset:1024 sc1
	v_mfma_f32_32x32x16_bf16 v[0:15], v[148:151], v[156:159], v[0:15]
	s_waitcnt vmcnt(8)
	s_waitcnt lgkmcnt(0)
	s_barrier
	ds_read_b128 v[128:131], v104
	ds_read_b128 v[136:139], v105 offset:8192
	v_mfma_f32_32x32x16_bf16 v[48:63], v[160:163], v[168:171], v[48:63]
	ds_read_b128 v[140:143], v105 offset:10240
	ds_read_b128 v[132:135], v104 offset:2048
	v_mfma_f32_32x32x16_bf16 v[32:47], v[160:163], v[172:175], v[32:47]
	ds_read_b128 v[144:147], v106
	ds_read_b128 v[152:155], v107 offset:8192
	v_mfma_f32_32x32x16_bf16 v[16:31], v[164:167], v[168:171], v[16:31]
	ds_read_b128 v[156:159], v107 offset:10240
	ds_read_b128 v[148:151], v106 offset:2048
	v_mfma_f32_32x32x16_bf16 v[0:15], v[164:167], v[172:175], v[0:15]
	s_mov_b32 m0, s55
	v_lshl_add_u64 v[64:65], v[64:65], 0, s[44:45]
	global_load_lds_dwordx4 v[64:65], off sc1
	v_mfma_f32_32x32x16_bf16 v[48:63], v[176:179], v[188:191], v[48:63]
	global_load_lds_dwordx4 v[64:65], off offset:1024 sc1
	v_mfma_f32_32x32x16_bf16 v[32:47], v[176:179], v[192:195], v[32:47]
	s_mov_b32 m0, s59
	v_lshl_add_u64 v[66:67], v[66:67], 0, s[44:45]
	global_load_lds_dwordx4 v[66:67], off sc1
	v_mfma_f32_32x32x16_bf16 v[16:31], v[184:187], v[188:191], v[16:31]
	global_load_lds_dwordx4 v[66:67], off offset:1024 sc1
	v_mfma_f32_32x32x16_bf16 v[0:15], v[184:187], v[192:195], v[0:15]
	s_waitcnt vmcnt(8)
	s_waitcnt lgkmcnt(0)
	s_barrier
	ds_read_b128 v[160:163], v104 offset:16384
	ds_read_b128 v[168:171], v105 offset:24576
	v_mfma_f32_32x32x16_bf16 v[48:63], v[128:131], v[136:139], v[48:63]
	ds_read_b128 v[172:175], v105 offset:26624
	ds_read_b128 v[164:167], v104 offset:18432
	v_mfma_f32_32x32x16_bf16 v[32:47], v[128:131], v[140:143], v[32:47]
	ds_read_b128 v[176:179], v106 offset:16384
	ds_read_b128 v[188:191], v107 offset:24576
	v_mfma_f32_32x32x16_bf16 v[16:31], v[132:135], v[136:139], v[16:31]
	ds_read_b128 v[192:195], v107 offset:26624
	ds_read_b128 v[184:187], v106 offset:18432
	v_mfma_f32_32x32x16_bf16 v[0:15], v[132:135], v[140:143], v[0:15]
	s_mov_b32 m0, s52
	v_lshl_add_u64 v[64:65], v[64:65], 0, s[44:45]
	global_load_lds_dwordx4 v[64:65], off sc1
	v_mfma_f32_32x32x16_bf16 v[48:63], v[144:147], v[152:155], v[48:63]
	global_load_lds_dwordx4 v[64:65], off offset:1024 sc1
	v_mfma_f32_32x32x16_bf16 v[32:47], v[144:147], v[156:159], v[32:47]
	s_mov_b32 m0, s56
	v_lshl_add_u64 v[66:67], v[66:67], 0, s[44:45]
	global_load_lds_dwordx4 v[66:67], off sc1
	v_mfma_f32_32x32x16_bf16 v[16:31], v[148:151], v[152:155], v[16:31]
	global_load_lds_dwordx4 v[66:67], off offset:1024 sc1
	v_mfma_f32_32x32x16_bf16 v[0:15], v[148:151], v[156:159], v[0:15]
	s_waitcnt vmcnt(8)
	s_waitcnt lgkmcnt(0)
	s_barrier
	ds_read_b128 v[128:131], v104 offset:32768
	ds_read_b128 v[136:139], v105 offset:40960
	v_mfma_f32_32x32x16_bf16 v[48:63], v[160:163], v[168:171], v[48:63]
	ds_read_b128 v[140:143], v105 offset:43008
	ds_read_b128 v[132:135], v104 offset:34816
	v_mfma_f32_32x32x16_bf16 v[32:47], v[160:163], v[172:175], v[32:47]
	ds_read_b128 v[144:147], v106 offset:32768
	ds_read_b128 v[152:155], v107 offset:40960
	v_mfma_f32_32x32x16_bf16 v[16:31], v[164:167], v[168:171], v[16:31]
	ds_read_b128 v[156:159], v107 offset:43008
	ds_read_b128 v[148:151], v106 offset:34816
	v_mfma_f32_32x32x16_bf16 v[0:15], v[164:167], v[172:175], v[0:15]
	s_mov_b32 m0, s53
	v_lshl_add_u64 v[64:65], v[64:65], 0, s[44:45]
	global_load_lds_dwordx4 v[64:65], off sc1
	v_mfma_f32_32x32x16_bf16 v[48:63], v[176:179], v[188:191], v[48:63]
	global_load_lds_dwordx4 v[64:65], off offset:1024 sc1
	v_mfma_f32_32x32x16_bf16 v[32:47], v[176:179], v[192:195], v[32:47]
	s_mov_b32 m0, s57
	v_lshl_add_u64 v[66:67], v[66:67], 0, s[44:45]
	global_load_lds_dwordx4 v[66:67], off sc1
	v_mfma_f32_32x32x16_bf16 v[16:31], v[184:187], v[188:191], v[16:31]
	global_load_lds_dwordx4 v[66:67], off offset:1024 sc1
	v_mfma_f32_32x32x16_bf16 v[0:15], v[184:187], v[192:195], v[0:15]
	s_waitcnt vmcnt(8)
	s_waitcnt lgkmcnt(0)
	s_barrier
	ds_read_b128 v[160:163], v104 offset:49152
	ds_read_b128 v[168:171], v105 offset:57344
	v_mfma_f32_32x32x16_bf16 v[48:63], v[128:131], v[136:139], v[48:63]
	ds_read_b128 v[172:175], v105 offset:59392
	ds_read_b128 v[164:167], v104 offset:51200
	v_mfma_f32_32x32x16_bf16 v[32:47], v[128:131], v[140:143], v[32:47]
	ds_read_b128 v[176:179], v106 offset:49152
	ds_read_b128 v[188:191], v107 offset:57344
	v_mfma_f32_32x32x16_bf16 v[16:31], v[132:135], v[136:139], v[16:31]
	ds_read_b128 v[192:195], v107 offset:59392
	ds_read_b128 v[184:187], v106 offset:51200
	v_mfma_f32_32x32x16_bf16 v[0:15], v[132:135], v[140:143], v[0:15]
	s_mov_b32 m0, s54
	v_lshl_add_u64 v[64:65], v[64:65], 0, s[44:45]
	global_load_lds_dwordx4 v[64:65], off sc1
	v_mfma_f32_32x32x16_bf16 v[48:63], v[144:147], v[152:155], v[48:63]
	global_load_lds_dwordx4 v[64:65], off offset:1024 sc1
	v_mfma_f32_32x32x16_bf16 v[32:47], v[144:147], v[156:159], v[32:47]
	s_mov_b32 m0, s58
	v_lshl_add_u64 v[66:67], v[66:67], 0, s[44:45]
	global_load_lds_dwordx4 v[66:67], off sc1
	v_mfma_f32_32x32x16_bf16 v[16:31], v[148:151], v[152:155], v[16:31]
	global_load_lds_dwordx4 v[66:67], off offset:1024 sc1
	v_mfma_f32_32x32x16_bf16 v[0:15], v[148:151], v[156:159], v[0:15]
	s_waitcnt vmcnt(8)
	s_waitcnt lgkmcnt(0)
	s_barrier
	ds_read_b128 v[128:131], v104
	ds_read_b128 v[136:139], v105 offset:8192
	v_mfma_f32_32x32x16_bf16 v[48:63], v[160:163], v[168:171], v[48:63]
	ds_read_b128 v[140:143], v105 offset:10240
	ds_read_b128 v[132:135], v104 offset:2048
	v_mfma_f32_32x32x16_bf16 v[32:47], v[160:163], v[172:175], v[32:47]
	ds_read_b128 v[144:147], v106
	ds_read_b128 v[152:155], v107 offset:8192
	v_mfma_f32_32x32x16_bf16 v[16:31], v[164:167], v[168:171], v[16:31]
	ds_read_b128 v[156:159], v107 offset:10240
	ds_read_b128 v[148:151], v106 offset:2048
	v_mfma_f32_32x32x16_bf16 v[0:15], v[164:167], v[172:175], v[0:15]
	s_mov_b32 m0, s55
	v_lshl_add_u64 v[64:65], v[64:65], 0, s[44:45]
	global_load_lds_dwordx4 v[64:65], off sc1
	v_mfma_f32_32x32x16_bf16 v[48:63], v[176:179], v[188:191], v[48:63]
	global_load_lds_dwordx4 v[64:65], off offset:1024 sc1
	v_mfma_f32_32x32x16_bf16 v[32:47], v[176:179], v[192:195], v[32:47]
	s_mov_b32 m0, s59
	v_lshl_add_u64 v[66:67], v[66:67], 0, s[44:45]
	global_load_lds_dwordx4 v[66:67], off sc1
	v_mfma_f32_32x32x16_bf16 v[16:31], v[184:187], v[188:191], v[16:31]
	global_load_lds_dwordx4 v[66:67], off offset:1024 sc1
	v_mfma_f32_32x32x16_bf16 v[0:15], v[184:187], v[192:195], v[0:15]
	s_waitcnt vmcnt(8)
	s_waitcnt lgkmcnt(0)
	s_barrier
	ds_read_b128 v[160:163], v104 offset:16384
	ds_read_b128 v[168:171], v105 offset:24576
	v_mfma_f32_32x32x16_bf16 v[48:63], v[128:131], v[136:139], v[48:63]
	ds_read_b128 v[172:175], v105 offset:26624
	ds_read_b128 v[164:167], v104 offset:18432
	v_mfma_f32_32x32x16_bf16 v[32:47], v[128:131], v[140:143], v[32:47]
	ds_read_b128 v[176:179], v106 offset:16384
	ds_read_b128 v[188:191], v107 offset:24576
	v_mfma_f32_32x32x16_bf16 v[16:31], v[132:135], v[136:139], v[16:31]
	ds_read_b128 v[192:195], v107 offset:26624
	ds_read_b128 v[184:187], v106 offset:18432
	v_mfma_f32_32x32x16_bf16 v[0:15], v[132:135], v[140:143], v[0:15]
	v_mfma_f32_32x32x16_bf16 v[48:63], v[144:147], v[152:155], v[48:63]
	v_mfma_f32_32x32x16_bf16 v[32:47], v[144:147], v[156:159], v[32:47]
	v_mfma_f32_32x32x16_bf16 v[16:31], v[148:151], v[152:155], v[16:31]
	v_mfma_f32_32x32x16_bf16 v[0:15], v[148:151], v[156:159], v[0:15]
	s_waitcnt vmcnt(4)
	s_waitcnt lgkmcnt(0)
	s_barrier
	ds_read_b128 v[128:131], v104 offset:32768
	ds_read_b128 v[136:139], v105 offset:40960
	v_mfma_f32_32x32x16_bf16 v[48:63], v[160:163], v[168:171], v[48:63]
	ds_read_b128 v[140:143], v105 offset:43008
	ds_read_b128 v[132:135], v104 offset:34816
	v_mfma_f32_32x32x16_bf16 v[32:47], v[160:163], v[172:175], v[32:47]
	ds_read_b128 v[144:147], v106 offset:32768
	ds_read_b128 v[152:155], v107 offset:40960
	v_mfma_f32_32x32x16_bf16 v[16:31], v[164:167], v[168:171], v[16:31]
	ds_read_b128 v[156:159], v107 offset:43008
	ds_read_b128 v[148:151], v106 offset:34816
	v_mfma_f32_32x32x16_bf16 v[0:15], v[164:167], v[172:175], v[0:15]
	v_mfma_f32_32x32x16_bf16 v[48:63], v[176:179], v[188:191], v[48:63]
	v_mfma_f32_32x32x16_bf16 v[32:47], v[176:179], v[192:195], v[32:47]
	v_mfma_f32_32x32x16_bf16 v[16:31], v[184:187], v[188:191], v[16:31]
	v_mfma_f32_32x32x16_bf16 v[0:15], v[184:187], v[192:195], v[0:15]
	s_waitcnt vmcnt(0)
	s_waitcnt lgkmcnt(0)
	s_barrier
	ds_read_b128 v[160:163], v104 offset:49152
	ds_read_b128 v[168:171], v105 offset:57344
	v_mfma_f32_32x32x16_bf16 v[48:63], v[128:131], v[136:139], v[48:63]
	ds_read_b128 v[172:175], v105 offset:59392
	ds_read_b128 v[164:167], v104 offset:51200
	v_mfma_f32_32x32x16_bf16 v[32:47], v[128:131], v[140:143], v[32:47]
	ds_read_b128 v[176:179], v106 offset:49152
	ds_read_b128 v[188:191], v107 offset:57344
	v_mfma_f32_32x32x16_bf16 v[16:31], v[132:135], v[136:139], v[16:31]
	ds_read_b128 v[192:195], v107 offset:59392
	ds_read_b128 v[184:187], v106 offset:51200
	v_mfma_f32_32x32x16_bf16 v[0:15], v[132:135], v[140:143], v[0:15]
	v_mfma_f32_32x32x16_bf16 v[48:63], v[144:147], v[152:155], v[48:63]
	v_mfma_f32_32x32x16_bf16 v[32:47], v[144:147], v[156:159], v[32:47]
	v_mfma_f32_32x32x16_bf16 v[16:31], v[148:151], v[152:155], v[16:31]
	v_mfma_f32_32x32x16_bf16 v[0:15], v[148:151], v[156:159], v[0:15]
	s_waitcnt lgkmcnt(0)
	v_mfma_f32_32x32x16_bf16 v[48:63], v[160:163], v[168:171], v[48:63]
	v_mfma_f32_32x32x16_bf16 v[32:47], v[160:163], v[172:175], v[32:47]
	v_mfma_f32_32x32x16_bf16 v[16:31], v[164:167], v[168:171], v[16:31]
	v_mfma_f32_32x32x16_bf16 v[0:15], v[164:167], v[172:175], v[0:15]
	v_mfma_f32_32x32x16_bf16 v[48:63], v[176:179], v[188:191], v[48:63]
	v_mfma_f32_32x32x16_bf16 v[32:47], v[176:179], v[192:195], v[32:47]
	v_mfma_f32_32x32x16_bf16 v[16:31], v[184:187], v[188:191], v[16:31]
	v_mfma_f32_32x32x16_bf16 v[0:15], v[184:187], v[192:195], v[0:15]

.LBB0_273:
	s_or_b64 exec, exec, s[16:17]
	s_waitcnt lgkmcnt(0)
	s_barrier
	s_and_saveexec_b64 s[16:17], s[42:43]
	s_cbranch_execz .LBB0_258
	v_ashrrev_i32_e32 v64, 7, v97
	v_ashrrev_i32_e32 v65, 31, v64
	v_lshlrev_b64 v[64:65], 18, v[64:65]
	v_ashrrev_i32_e32 v66, 7, v102
	v_readfirstlane_b32 s13, v94
	v_lshl_add_u64 v[64:65], v[80:81], 0, v[64:65]
	v_ashrrev_i32_e32 v67, 31, v66
	s_mov_b64 s[18:19], 0x400
	s_mov_b32 m0, s13
	v_readfirstlane_b32 s13, v79
	v_lshlrev_b64 v[66:67], 18, v[66:67]
	v_lshl_add_u64 v[104:105], v[64:65], 0, s[18:19]
	global_load_lds_dwordx4 v[64:65], off sc1
	s_mov_b32 m0, s13
	v_readfirstlane_b32 s13, v78
	v_lshl_add_u64 v[66:67], v[82:83], 0, v[66:67]
	global_load_lds_dwordx4 v[104:105], off sc1
	s_mov_b32 m0, s13
	v_readfirstlane_b32 s13, v77
	global_load_lds_dwordx4 v[66:67], off sc1
	v_lshl_add_u64 v[78:79], v[66:67], 0, s[18:19]
	s_mov_b32 m0, s13
	v_readfirstlane_b32 s13, v76
	global_load_lds_dwordx4 v[78:79], off sc1
	v_lshl_add_u64 v[78:79], v[64:65], 0, s[44:45]
	s_mov_b32 m0, s13
	v_readfirstlane_b32 s13, v75
	global_load_lds_dwordx4 v[78:79], off sc1
	v_lshl_add_u64 v[76:77], v[64:65], 0, s[66:67]
	s_mov_b32 m0, s13
	v_readfirstlane_b32 s13, v74
	global_load_lds_dwordx4 v[76:77], off sc1
	v_lshl_add_u64 v[76:77], v[66:67], 0, s[44:45]
	s_mov_b32 m0, s13
	v_readfirstlane_b32 s13, v72
	global_load_lds_dwordx4 v[76:77], off sc1
	v_lshl_add_u64 v[74:75], v[66:67], 0, s[66:67]
	s_mov_b32 m0, s13
	v_readfirstlane_b32 s13, v71
	global_load_lds_dwordx4 v[74:75], off sc1
	v_lshl_add_u64 v[72:73], v[64:65], 0, s[28:29]
	s_mov_b32 m0, s13
	s_mov_b64 s[18:19], 0x4400
	v_readfirstlane_b32 s13, v70
	global_load_lds_dwordx4 v[72:73], off sc1
	v_lshl_add_u64 v[64:65], v[64:65], 0, s[18:19]
	s_mov_b32 m0, s13
	v_readfirstlane_b32 s13, v69
	global_load_lds_dwordx4 v[64:65], off sc1
	v_lshl_add_u64 v[64:65], v[66:67], 0, s[28:29]
	s_mov_b32 m0, s13
	v_readfirstlane_b32 s13, v68
	global_load_lds_dwordx4 v[64:65], off sc1
	v_lshl_add_u64 v[64:65], v[66:67], 0, s[18:19]
	s_mov_b32 m0, s13
	s_nop 0
	global_load_lds_dwordx4 v[64:65], off sc1
	s_branch .LBB0_258

.LBB0_290:
	s_xor_b64 s[16:17], s[16:17], -1
	s_xor_b64 s[0:1], s[14:15], -1
	v_mov_b32_e32 v121, 0x358637bd
	s_and_saveexec_b64 s[18:19], s[36:37]
	s_cbranch_execz .LBB0_292
	s_ashr_i32 s11, s10, 31
	v_lshl_add_u64 v[0:1], s[10:11], 2, v[92:93]
	global_load_dword v0, v[0:1], off sc1
	s_waitcnt vmcnt(0)
	v_cvt_f32_u32_e32 v0, v0
	v_fmamk_f32 v121, v0, 0x36800000, v212
.LBB0_292:
	s_or_b64 exec, exec, s[18:19]
	s_add_i32 s9, s10, 0xfffff000
	s_lshr_b32 s9, s9, 10
	s_add_i32 s9, s9, 1
	s_cmpk_gt_i32 s10, 0xfff
	s_cselect_b32 s9, s9, 0
	s_mul_i32 s11, s12, 3
	s_add_i32 s9, s9, s11
	s_mul_hi_u32 s11, s9, 0xd000
	s_mul_i32 s9, s9, 0xd000
	s_add_u32 s49, s30, s9
	s_addc_u32 s11, s34, s11
	s_ashr_i32 s9, s8, 31
	s_lshl_b64 s[18:19], s[8:9], 2
	s_add_u32 s18, s49, s18
	s_addc_u32 s19, s11, s19
	v_lshl_add_u64 v[0:1], s[18:19], 0, v[116:117]
	v_mov_b32_e32 v95, v117
	v_lshl_add_u64 v[0:1], v[0:1], 0, v[94:95]
	global_load_dword v112, v[0:1], off sc1
	global_load_dword v95, v[0:1], off offset:128 sc1
	global_load_dword v243, v[0:1], off offset:512 sc1
	global_load_dword v248, v[0:1], off offset:640 sc1
	s_ashr_i32 s18, s10, 7
	s_ashr_i32 s19, s18, 31
	s_lshl_b64 s[18:19], s[18:19], 18
	v_lshl_add_u64 v[96:97], v[64:65], 0, s[18:19]
	s_ashr_i32 s18, s8, 7
	s_ashr_i32 s19, s18, 31
	s_lshl_b64 s[18:19], s[18:19], 18
	v_lshl_add_u64 v[98:99], v[66:67], 0, s[18:19]
	s_mov_b64 s[18:19], -1
	s_andn2_b64 vcc, exec, s[16:17]
	v_add_u32_e32 v132, 0x400, v100
	v_add_u32_e32 v131, 0x2000, v100
	v_add_u32_e32 v130, 0x2400, v100
	v_add_u32_e32 v129, 0x4000, v100
	v_add_u32_e32 v128, 0x4400, v100
	v_add_u32_e32 v125, 0x6000, v100
	v_add_u32_e32 v122, 0x6400, v100
	v_add_u32_e32 v119, 0x8000, v100
	v_add_u32_e32 v115, 0x8400, v100
	v_add_u32_e32 v114, 0xa000, v100
	v_add_u32_e32 v113, 0xa400, v100
	s_cbranch_vccnz .LBB0_294
	v_readfirstlane_b32 s11, v100
	s_mov_b32 m0, s11
	s_mov_b64 s[16:17], 0x400
	v_readfirstlane_b32 s11, v132
	global_load_lds_dwordx4 v[96:97], off sc1
	v_lshl_add_u64 v[0:1], v[96:97], 0, s[16:17]
	s_mov_b32 m0, s11
	v_readfirstlane_b32 s11, v131
	global_load_lds_dwordx4 v[0:1], off sc1
	s_mov_b32 m0, s11
	v_readfirstlane_b32 s11, v130
	global_load_lds_dwordx4 v[98:99], off sc1
	v_lshl_add_u64 v[0:1], v[98:99], 0, s[16:17]
	s_mov_b32 m0, s11
	v_readfirstlane_b32 s11, v129
	global_load_lds_dwordx4 v[0:1], off sc1
	v_lshl_add_u64 v[0:1], v[96:97], 0, s[44:45]
	s_mov_b32 m0, s11
	v_readfirstlane_b32 s11, v128
	global_load_lds_dwordx4 v[0:1], off sc1
	v_lshl_add_u64 v[0:1], v[96:97], 0, s[66:67]
	s_mov_b32 m0, s11
	v_readfirstlane_b32 s11, v125
	global_load_lds_dwordx4 v[0:1], off sc1
	v_lshl_add_u64 v[0:1], v[98:99], 0, s[44:45]
	s_mov_b32 m0, s11
	v_readfirstlane_b32 s11, v122
	global_load_lds_dwordx4 v[0:1], off sc1
	v_lshl_add_u64 v[0:1], v[98:99], 0, s[66:67]
	s_mov_b32 m0, s11
	v_readfirstlane_b32 s11, v119
	global_load_lds_dwordx4 v[0:1], off sc1
	v_lshl_add_u64 v[0:1], v[96:97], 0, s[28:29]
	s_mov_b32 m0, s11
	s_mov_b64 s[16:17], 0x4400
	v_readfirstlane_b32 s11, v115
	global_load_lds_dwordx4 v[0:1], off sc1
	v_lshl_add_u64 v[0:1], v[96:97], 0, s[16:17]
	s_mov_b32 m0, s11
	v_readfirstlane_b32 s11, v114
	global_load_lds_dwordx4 v[0:1], off sc1
	v_lshl_add_u64 v[0:1], v[98:99], 0, s[28:29]
	s_mov_b32 m0, s11
	v_readfirstlane_b32 s11, v113
	global_load_lds_dwordx4 v[0:1], off sc1
	v_lshl_add_u64 v[0:1], v[98:99], 0, s[16:17]
	s_mov_b32 m0, s11
	s_mov_b64 s[18:19], 0
	global_load_lds_dwordx4 v[0:1], off sc1
	s_waitcnt vmcnt(8)

.Lin_pair:
	s_mov_b32 s63, 1
	s_mov_b32 s62, 1
	v_add_u32_e32 v113, v101, v103
	v_add_u32_e32 v119, v102, v103
	v_add_u32_e32 v122, v101, v104
	v_add_u32_e32 v125, v102, v104
	v_add_u32_e32 v132, 0x4000, v119
	v_add_u32_e32 v133, 0x4000, v125
	v_readfirstlane_b32 s50, v100
	s_mov_b64 s[72:73], 0x40000
	s_mov_b64 s[86:87], 0x4000
	s_add_u32 s51, s50, 0x4000
	s_add_u32 s52, s50, 0x8000
	s_add_u32 s53, s50, 0x2000
	s_add_u32 s54, s50, 0x6000
	s_add_u32 s55, s50, 0xa000
	s_add_u32 s56, s50, 0xc000
	s_add_u32 s57, s50, 0xe000
	s_add_u32 s58, s50, 0x12000
	v_lshl_add_u64 v[114:115], v[98:99], 0, s[72:73]
	s_mov_b32 m0, s56
	s_nop 0
	global_load_lds_dwordx4 v[114:115], off sc1
	global_load_lds_dwordx4 v[114:115], off offset:1024 sc1
	v_lshl_add_u64 v[114:115], v[114:115], 0, s[44:45]
	s_mov_b32 m0, s57
	s_nop 0
	global_load_lds_dwordx4 v[114:115], off sc1
	global_load_lds_dwordx4 v[114:115], off offset:1024 sc1
	v_lshl_add_u64 v[114:115], v[114:115], 0, s[44:45]
	s_mov_b32 m0, s58
	s_nop 0
	global_load_lds_dwordx4 v[114:115], off sc1
	global_load_lds_dwordx4 v[114:115], off offset:1024 sc1
	v_lshl_add_u64 v[96:97], v[96:97], 0, s[86:87]
	v_lshl_add_u64 v[98:99], v[98:99], 0, s[86:87]
	s_waitcnt vmcnt(4)
	s_waitcnt lgkmcnt(0)
	s_barrier
	ds_read_b128 v[134:137], v113
	ds_read_b128 v[142:145], v119 offset:8192
	ds_read_b128 v[146:149], v119 offset:10240
	ds_read_b128 v[150:153], v119 offset:49152
	ds_read_b128 v[154:157], v119 offset:51200
	ds_read_b128 v[138:141], v113 offset:2048
	ds_read_b128 v[158:161], v122
	ds_read_b128 v[166:169], v125 offset:8192
	ds_read_b128 v[244:247], v125 offset:10240
	ds_read_b128 v[250:253], v125 offset:49152
	ds_read_b128 v[162:165], v122 offset:2048
	ds_read_b128 v[128:131], v125 offset:51200
	s_waitcnt lgkmcnt(6)
	v_mfma_f32_32x32x16_bf16 v[32:47], v[134:137], v[142:145], 0
	v_mfma_f32_32x32x16_bf16 v[48:63], v[134:137], v[146:149], 0
	v_mfma_f32_32x32x16_bf16 v[170:185], v[134:137], v[150:153], 0
	v_mfma_f32_32x32x16_bf16 v[186:201], v[134:137], v[154:157], 0
	v_mfma_f32_32x32x16_bf16 v[16:31], v[138:141], v[142:145], 0
	v_mfma_f32_32x32x16_bf16 v[0:15], v[138:141], v[146:149], 0
	v_mfma_f32_32x32x16_bf16 v[202:217], v[138:141], v[150:153], 0
	v_mfma_f32_32x32x16_bf16 v[226:241], v[138:141], v[154:157], 0
	s_waitcnt vmcnt(2)
	s_waitcnt lgkmcnt(0)
	s_barrier
	ds_read_b128 v[134:137], v113 offset:16384
	ds_read_b128 v[142:145], v119 offset:24576
	v_mfma_f32_32x32x16_bf16 v[32:47], v[158:161], v[166:169], v[32:47]
	ds_read_b128 v[146:149], v119 offset:26624
	ds_read_b128 v[150:153], v132 offset:40960
	v_mfma_f32_32x32x16_bf16 v[48:63], v[158:161], v[244:247], v[48:63]
	ds_read_b128 v[154:157], v132 offset:43008
	ds_read_b128 v[138:141], v113 offset:18432
	v_mfma_f32_32x32x16_bf16 v[170:185], v[158:161], v[250:253], v[170:185]
	v_mfma_f32_32x32x16_bf16 v[186:201], v[158:161], v[128:131], v[186:201]
	ds_read_b128 v[158:161], v122 offset:16384
	v_mfma_f32_32x32x16_bf16 v[16:31], v[162:165], v[166:169], v[16:31]
	ds_read_b128 v[166:169], v125 offset:24576
	v_mfma_f32_32x32x16_bf16 v[0:15], v[162:165], v[244:247], v[0:15]
	ds_read_b128 v[244:247], v125 offset:26624
	v_mfma_f32_32x32x16_bf16 v[202:217], v[162:165], v[250:253], v[202:217]
	ds_read_b128 v[250:253], v133 offset:40960
	v_mfma_f32_32x32x16_bf16 v[226:241], v[162:165], v[128:131], v[226:241]
	ds_read_b128 v[162:165], v122 offset:18432
	ds_read_b128 v[128:131], v133 offset:43008
	s_waitcnt lgkmcnt(6)
	v_mfma_f32_32x32x16_bf16 v[32:47], v[134:137], v[142:145], v[32:47]
	s_mov_b32 m0, s50
	v_lshl_add_u64 v[96:97], v[96:97], 0, s[44:45]
	global_load_lds_dwordx4 v[96:97], off sc1
	v_mfma_f32_32x32x16_bf16 v[48:63], v[134:137], v[146:149], v[48:63]
	global_load_lds_dwordx4 v[96:97], off offset:1024 sc1
	v_mfma_f32_32x32x16_bf16 v[170:185], v[134:137], v[150:153], v[170:185]
	s_mov_b32 m0, s53
	v_lshl_add_u64 v[98:99], v[98:99], 0, s[44:45]
	global_load_lds_dwordx4 v[98:99], off sc1
	v_mfma_f32_32x32x16_bf16 v[186:201], v[134:137], v[154:157], v[186:201]
	global_load_lds_dwordx4 v[98:99], off offset:1024 sc1
	v_mfma_f32_32x32x16_bf16 v[16:31], v[138:141], v[142:145], v[16:31]
	s_mov_b32 m0, s56
	v_lshl_add_u64 v[114:115], v[98:99], 0, s[72:73]
	global_load_lds_dwordx4 v[114:115], off sc1
	v_mfma_f32_32x32x16_bf16 v[0:15], v[138:141], v[146:149], v[0:15]
	global_load_lds_dwordx4 v[114:115], off offset:1024 sc1
	v_mfma_f32_32x32x16_bf16 v[202:217], v[138:141], v[150:153], v[202:217]
	v_mfma_f32_32x32x16_bf16 v[226:241], v[138:141], v[154:157], v[226:241]
	s_waitcnt vmcnt(6)
	s_waitcnt lgkmcnt(0)
	s_barrier
	ds_read_b128 v[134:137], v113 offset:32768
	ds_read_b128 v[142:145], v119 offset:40960
	v_mfma_f32_32x32x16_bf16 v[32:47], v[158:161], v[166:169], v[32:47]
	ds_read_b128 v[146:149], v119 offset:43008
	ds_read_b128 v[150:153], v132 offset:57344
	v_mfma_f32_32x32x16_bf16 v[48:63], v[158:161], v[244:247], v[48:63]
	ds_read_b128 v[154:157], v132 offset:59392
	ds_read_b128 v[138:141], v113 offset:34816
	v_mfma_f32_32x32x16_bf16 v[170:185], v[158:161], v[250:253], v[170:185]
	v_mfma_f32_32x32x16_bf16 v[186:201], v[158:161], v[128:131], v[186:201]
	ds_read_b128 v[158:161], v122 offset:32768
	v_mfma_f32_32x32x16_bf16 v[16:31], v[162:165], v[166:169], v[16:31]
	ds_read_b128 v[166:169], v125 offset:40960
	v_mfma_f32_32x32x16_bf16 v[0:15], v[162:165], v[244:247], v[0:15]
	ds_read_b128 v[244:247], v125 offset:43008
	v_mfma_f32_32x32x16_bf16 v[202:217], v[162:165], v[250:253], v[202:217]
	ds_read_b128 v[250:253], v133 offset:57344
	v_mfma_f32_32x32x16_bf16 v[226:241], v[162:165], v[128:131], v[226:241]
	ds_read_b128 v[162:165], v122 offset:34816
	ds_read_b128 v[128:131], v133 offset:59392
	s_waitcnt lgkmcnt(6)
	v_mfma_f32_32x32x16_bf16 v[32:47], v[134:137], v[142:145], v[32:47]
	s_mov_b32 m0, s51
	v_lshl_add_u64 v[96:97], v[96:97], 0, s[44:45]
	global_load_lds_dwordx4 v[96:97], off sc1
	v_mfma_f32_32x32x16_bf16 v[48:63], v[134:137], v[146:149], v[48:63]
	global_load_lds_dwordx4 v[96:97], off offset:1024 sc1
	v_mfma_f32_32x32x16_bf16 v[170:185], v[134:137], v[150:153], v[170:185]
	s_mov_b32 m0, s54
	v_lshl_add_u64 v[98:99], v[98:99], 0, s[44:45]
	global_load_lds_dwordx4 v[98:99], off sc1
	v_mfma_f32_32x32x16_bf16 v[186:201], v[134:137], v[154:157], v[186:201]
	global_load_lds_dwordx4 v[98:99], off offset:1024 sc1
	v_mfma_f32_32x32x16_bf16 v[16:31], v[138:141], v[142:145], v[16:31]
	s_mov_b32 m0, s57
	v_lshl_add_u64 v[114:115], v[98:99], 0, s[72:73]
	global_load_lds_dwordx4 v[114:115], off sc1
	v_mfma_f32_32x32x16_bf16 v[0:15], v[138:141], v[146:149], v[0:15]
	global_load_lds_dwordx4 v[114:115], off offset:1024 sc1
	v_mfma_f32_32x32x16_bf16 v[202:217], v[138:141], v[150:153], v[202:217]
	v_mfma_f32_32x32x16_bf16 v[226:241], v[138:141], v[154:157], v[226:241]
	s_waitcnt vmcnt(6)
	s_waitcnt lgkmcnt(0)
	s_barrier
	ds_read_b128 v[134:137], v113
	ds_read_b128 v[142:145], v119 offset:8192
	v_mfma_f32_32x32x16_bf16 v[32:47], v[158:161], v[166:169], v[32:47]
	ds_read_b128 v[146:149], v119 offset:10240
	ds_read_b128 v[150:153], v119 offset:49152
	v_mfma_f32_32x32x16_bf16 v[48:63], v[158:161], v[244:247], v[48:63]
	ds_read_b128 v[154:157], v119 offset:51200
	ds_read_b128 v[138:141], v113 offset:2048
	v_mfma_f32_32x32x16_bf16 v[170:185], v[158:161], v[250:253], v[170:185]
	v_mfma_f32_32x32x16_bf16 v[186:201], v[158:161], v[128:131], v[186:201]
	ds_read_b128 v[158:161], v122
	v_mfma_f32_32x32x16_bf16 v[16:31], v[162:165], v[166:169], v[16:31]
	ds_read_b128 v[166:169], v125 offset:8192
	v_mfma_f32_32x32x16_bf16 v[0:15], v[162:165], v[244:247], v[0:15]
	ds_read_b128 v[244:247], v125 offset:10240
	v_mfma_f32_32x32x16_bf16 v[202:217], v[162:165], v[250:253], v[202:217]
	ds_read_b128 v[250:253], v125 offset:49152
	v_mfma_f32_32x32x16_bf16 v[226:241], v[162:165], v[128:131], v[226:241]
	ds_read_b128 v[162:165], v122 offset:2048
	ds_read_b128 v[128:131], v125 offset:51200
	s_waitcnt lgkmcnt(6)
	v_mfma_f32_32x32x16_bf16 v[32:47], v[134:137], v[142:145], v[32:47]
	s_mov_b32 m0, s52
	v_lshl_add_u64 v[96:97], v[96:97], 0, s[44:45]
	global_load_lds_dwordx4 v[96:97], off sc1
	v_mfma_f32_32x32x16_bf16 v[48:63], v[134:137], v[146:149], v[48:63]
	global_load_lds_dwordx4 v[96:97], off offset:1024 sc1
	v_mfma_f32_32x32x16_bf16 v[170:185], v[134:137], v[150:153], v[170:185]
	s_mov_b32 m0, s55
	v_lshl_add_u64 v[98:99], v[98:99], 0, s[44:45]
	global_load_lds_dwordx4 v[98:99], off sc1
	v_mfma_f32_32x32x16_bf16 v[186:201], v[134:137], v[154:157], v[186:201]
	global_load_lds_dwordx4 v[98:99], off offset:1024 sc1
	v_mfma_f32_32x32x16_bf16 v[16:31], v[138:141], v[142:145], v[16:31]
	s_mov_b32 m0, s58
	v_lshl_add_u64 v[114:115], v[98:99], 0, s[72:73]
	global_load_lds_dwordx4 v[114:115], off sc1
	v_mfma_f32_32x32x16_bf16 v[0:15], v[138:141], v[146:149], v[0:15]
	global_load_lds_dwordx4 v[114:115], off offset:1024 sc1
	v_mfma_f32_32x32x16_bf16 v[202:217], v[138:141], v[150:153], v[202:217]
	v_mfma_f32_32x32x16_bf16 v[226:241], v[138:141], v[154:157], v[226:241]
	s_waitcnt vmcnt(6)
	s_waitcnt lgkmcnt(0)
	s_barrier
	ds_read_b128 v[134:137], v113 offset:16384
	ds_read_b128 v[142:145], v119 offset:24576
	v_mfma_f32_32x32x16_bf16 v[32:47], v[158:161], v[166:169], v[32:47]
	ds_read_b128 v[146:149], v119 offset:26624
	ds_read_b128 v[150:153], v132 offset:40960
	v_mfma_f32_32x32x16_bf16 v[48:63], v[158:161], v[244:247], v[48:63]
	ds_read_b128 v[154:157], v132 offset:43008
	ds_read_b128 v[138:141], v113 offset:18432
	v_mfma_f32_32x32x16_bf16 v[170:185], v[158:161], v[250:253], v[170:185]
	v_mfma_f32_32x32x16_bf16 v[186:201], v[158:161], v[128:131], v[186:201]
	ds_read_b128 v[158:161], v122 offset:16384
	v_mfma_f32_32x32x16_bf16 v[16:31], v[162:165], v[166:169], v[16:31]
	ds_read_b128 v[166:169], v125 offset:24576
	v_mfma_f32_32x32x16_bf16 v[0:15], v[162:165], v[244:247], v[0:15]
	ds_read_b128 v[244:247], v125 offset:26624
	v_mfma_f32_32x32x16_bf16 v[202:217], v[162:165], v[250:253], v[202:217]
	ds_read_b128 v[250:253], v133 offset:40960
	v_mfma_f32_32x32x16_bf16 v[226:241], v[162:165], v[128:131], v[226:241]
	ds_read_b128 v[162:165], v122 offset:18432
	ds_read_b128 v[128:131], v133 offset:43008
	s_waitcnt lgkmcnt(6)
	v_mfma_f32_32x32x16_bf16 v[32:47], v[134:137], v[142:145], v[32:47]
	s_mov_b32 m0, s50
	v_lshl_add_u64 v[96:97], v[96:97], 0, s[44:45]
	global_load_lds_dwordx4 v[96:97], off sc1
	v_mfma_f32_32x32x16_bf16 v[48:63], v[134:137], v[146:149], v[48:63]
	global_load_lds_dwordx4 v[96:97], off offset:1024 sc1
	v_mfma_f32_32x32x16_bf16 v[170:185], v[134:137], v[150:153], v[170:185]
	s_mov_b32 m0, s53
	v_lshl_add_u64 v[98:99], v[98:99], 0, s[44:45]
	global_load_lds_dwordx4 v[98:99], off sc1
	v_mfma_f32_32x32x16_bf16 v[186:201], v[134:137], v[154:157], v[186:201]
	global_load_lds_dwordx4 v[98:99], off offset:1024 sc1
	v_mfma_f32_32x32x16_bf16 v[16:31], v[138:141], v[142:145], v[16:31]
	s_mov_b32 m0, s56
	v_lshl_add_u64 v[114:115], v[98:99], 0, s[72:73]
	global_load_lds_dwordx4 v[114:115], off sc1
	v_mfma_f32_32x32x16_bf16 v[0:15], v[138:141], v[146:149], v[0:15]
	global_load_lds_dwordx4 v[114:115], off offset:1024 sc1
	v_mfma_f32_32x32x16_bf16 v[202:217], v[138:141], v[150:153], v[202:217]
	v_mfma_f32_32x32x16_bf16 v[226:241], v[138:141], v[154:157], v[226:241]
	s_waitcnt vmcnt(6)
	s_waitcnt lgkmcnt(0)
	s_barrier
	ds_read_b128 v[134:137], v113 offset:32768
	ds_read_b128 v[142:145], v119 offset:40960
	v_mfma_f32_32x32x16_bf16 v[32:47], v[158:161], v[166:169], v[32:47]
	ds_read_b128 v[146:149], v119 offset:43008
	ds_read_b128 v[150:153], v132 offset:57344
	v_mfma_f32_32x32x16_bf16 v[48:63], v[158:161], v[244:247], v[48:63]
	ds_read_b128 v[154:157], v132 offset:59392
	ds_read_b128 v[138:141], v113 offset:34816
	v_mfma_f32_32x32x16_bf16 v[170:185], v[158:161], v[250:253], v[170:185]
	v_mfma_f32_32x32x16_bf16 v[186:201], v[158:161], v[128:131], v[186:201]
	ds_read_b128 v[158:161], v122 offset:32768
	v_mfma_f32_32x32x16_bf16 v[16:31], v[162:165], v[166:169], v[16:31]
	ds_read_b128 v[166:169], v125 offset:40960
	v_mfma_f32_32x32x16_bf16 v[0:15], v[162:165], v[244:247], v[0:15]
	ds_read_b128 v[244:247], v125 offset:43008
	v_mfma_f32_32x32x16_bf16 v[202:217], v[162:165], v[250:253], v[202:217]
	ds_read_b128 v[250:253], v133 offset:57344
	v_mfma_f32_32x32x16_bf16 v[226:241], v[162:165], v[128:131], v[226:241]
	ds_read_b128 v[162:165], v122 offset:34816
	ds_read_b128 v[128:131], v133 offset:59392
	s_waitcnt lgkmcnt(6)
	v_mfma_f32_32x32x16_bf16 v[32:47], v[134:137], v[142:145], v[32:47]
	s_mov_b32 m0, s51
	v_lshl_add_u64 v[96:97], v[96:97], 0, s[44:45]
	global_load_lds_dwordx4 v[96:97], off sc1
	v_mfma_f32_32x32x16_bf16 v[48:63], v[134:137], v[146:149], v[48:63]
	global_load_lds_dwordx4 v[96:97], off offset:1024 sc1
	v_mfma_f32_32x32x16_bf16 v[170:185], v[134:137], v[150:153], v[170:185]
	s_mov_b32 m0, s54
	v_lshl_add_u64 v[98:99], v[98:99], 0, s[44:45]
	global_load_lds_dwordx4 v[98:99], off sc1
	v_mfma_f32_32x32x16_bf16 v[186:201], v[134:137], v[154:157], v[186:201]
	global_load_lds_dwordx4 v[98:99], off offset:1024 sc1
	v_mfma_f32_32x32x16_bf16 v[16:31], v[138:141], v[142:145], v[16:31]
	s_mov_b32 m0, s57
	v_lshl_add_u64 v[114:115], v[98:99], 0, s[72:73]
	global_load_lds_dwordx4 v[114:115], off sc1
	v_mfma_f32_32x32x16_bf16 v[0:15], v[138:141], v[146:149], v[0:15]
	global_load_lds_dwordx4 v[114:115], off offset:1024 sc1
	v_mfma_f32_32x32x16_bf16 v[202:217], v[138:141], v[150:153], v[202:217]
	v_mfma_f32_32x32x16_bf16 v[226:241], v[138:141], v[154:157], v[226:241]
	s_waitcnt vmcnt(6)
	s_waitcnt lgkmcnt(0)
	s_barrier
	ds_read_b128 v[134:137], v113
	ds_read_b128 v[142:145], v119 offset:8192
	v_mfma_f32_32x32x16_bf16 v[32:47], v[158:161], v[166:169], v[32:47]
	ds_read_b128 v[146:149], v119 offset:10240
	ds_read_b128 v[150:153], v119 offset:49152
	v_mfma_f32_32x32x16_bf16 v[48:63], v[158:161], v[244:247], v[48:63]
	ds_read_b128 v[154:157], v119 offset:51200
	ds_read_b128 v[138:141], v113 offset:2048
	v_mfma_f32_32x32x16_bf16 v[170:185], v[158:161], v[250:253], v[170:185]
	v_mfma_f32_32x32x16_bf16 v[186:201], v[158:161], v[128:131], v[186:201]
	ds_read_b128 v[158:161], v122
	v_mfma_f32_32x32x16_bf16 v[16:31], v[162:165], v[166:169], v[16:31]
	ds_read_b128 v[166:169], v125 offset:8192
	v_mfma_f32_32x32x16_bf16 v[0:15], v[162:165], v[244:247], v[0:15]
	ds_read_b128 v[244:247], v125 offset:10240
	v_mfma_f32_32x32x16_bf16 v[202:217], v[162:165], v[250:253], v[202:217]
	ds_read_b128 v[250:253], v125 offset:49152
	v_mfma_f32_32x32x16_bf16 v[226:241], v[162:165], v[128:131], v[226:241]
	ds_read_b128 v[162:165], v122 offset:2048
	ds_read_b128 v[128:131], v125 offset:51200
	s_waitcnt lgkmcnt(6)
	v_mfma_f32_32x32x16_bf16 v[32:47], v[134:137], v[142:145], v[32:47]
	s_mov_b32 m0, s52
	v_lshl_add_u64 v[96:97], v[96:97], 0, s[44:45]
	global_load_lds_dwordx4 v[96:97], off sc1
	v_mfma_f32_32x32x16_bf16 v[48:63], v[134:137], v[146:149], v[48:63]
	global_load_lds_dwordx4 v[96:97], off offset:1024 sc1
	v_mfma_f32_32x32x16_bf16 v[170:185], v[134:137], v[150:153], v[170:185]
	s_mov_b32 m0, s55
	v_lshl_add_u64 v[98:99], v[98:99], 0, s[44:45]
	global_load_lds_dwordx4 v[98:99], off sc1
	v_mfma_f32_32x32x16_bf16 v[186:201], v[134:137], v[154:157], v[186:201]
	global_load_lds_dwordx4 v[98:99], off offset:1024 sc1
	v_mfma_f32_32x32x16_bf16 v[16:31], v[138:141], v[142:145], v[16:31]
	s_mov_b32 m0, s58
	v_lshl_add_u64 v[114:115], v[98:99], 0, s[72:73]
	global_load_lds_dwordx4 v[114:115], off sc1
	v_mfma_f32_32x32x16_bf16 v[0:15], v[138:141], v[146:149], v[0:15]
	global_load_lds_dwordx4 v[114:115], off offset:1024 sc1
	v_mfma_f32_32x32x16_bf16 v[202:217], v[138:141], v[150:153], v[202:217]
	v_mfma_f32_32x32x16_bf16 v[226:241], v[138:141], v[154:157], v[226:241]
	s_waitcnt vmcnt(6)
	s_waitcnt lgkmcnt(0)
	s_barrier
	ds_read_b128 v[134:137], v113 offset:16384
	ds_read_b128 v[142:145], v119 offset:24576
	v_mfma_f32_32x32x16_bf16 v[32:47], v[158:161], v[166:169], v[32:47]
	ds_read_b128 v[146:149], v119 offset:26624
	ds_read_b128 v[150:153], v132 offset:40960
	v_mfma_f32_32x32x16_bf16 v[48:63], v[158:161], v[244:247], v[48:63]
	ds_read_b128 v[154:157], v132 offset:43008
	ds_read_b128 v[138:141], v113 offset:18432
	v_mfma_f32_32x32x16_bf16 v[170:185], v[158:161], v[250:253], v[170:185]
	v_mfma_f32_32x32x16_bf16 v[186:201], v[158:161], v[128:131], v[186:201]
	ds_read_b128 v[158:161], v122 offset:16384
	v_mfma_f32_32x32x16_bf16 v[16:31], v[162:165], v[166:169], v[16:31]
	ds_read_b128 v[166:169], v125 offset:24576
	v_mfma_f32_32x32x16_bf16 v[0:15], v[162:165], v[244:247], v[0:15]
	ds_read_b128 v[244:247], v125 offset:26624
	v_mfma_f32_32x32x16_bf16 v[202:217], v[162:165], v[250:253], v[202:217]
	ds_read_b128 v[250:253], v133 offset:40960
	v_mfma_f32_32x32x16_bf16 v[226:241], v[162:165], v[128:131], v[226:241]
	ds_read_b128 v[162:165], v122 offset:18432
	ds_read_b128 v[128:131], v133 offset:43008
	s_waitcnt lgkmcnt(6)
	v_mfma_f32_32x32x16_bf16 v[32:47], v[134:137], v[142:145], v[32:47]
	s_mov_b32 m0, s50
	v_lshl_add_u64 v[96:97], v[96:97], 0, s[44:45]
	global_load_lds_dwordx4 v[96:97], off sc1
	v_mfma_f32_32x32x16_bf16 v[48:63], v[134:137], v[146:149], v[48:63]
	global_load_lds_dwordx4 v[96:97], off offset:1024 sc1
	v_mfma_f32_32x32x16_bf16 v[170:185], v[134:137], v[150:153], v[170:185]
	s_mov_b32 m0, s53
	v_lshl_add_u64 v[98:99], v[98:99], 0, s[44:45]
	global_load_lds_dwordx4 v[98:99], off sc1
	v_mfma_f32_32x32x16_bf16 v[186:201], v[134:137], v[154:157], v[186:201]
	global_load_lds_dwordx4 v[98:99], off offset:1024 sc1
	v_mfma_f32_32x32x16_bf16 v[16:31], v[138:141], v[142:145], v[16:31]
	s_mov_b32 m0, s56
	v_lshl_add_u64 v[114:115], v[98:99], 0, s[72:73]
	global_load_lds_dwordx4 v[114:115], off sc1
	v_mfma_f32_32x32x16_bf16 v[0:15], v[138:141], v[146:149], v[0:15]
	global_load_lds_dwordx4 v[114:115], off offset:1024 sc1
	v_mfma_f32_32x32x16_bf16 v[202:217], v[138:141], v[150:153], v[202:217]
	v_mfma_f32_32x32x16_bf16 v[226:241], v[138:141], v[154:157], v[226:241]
	s_waitcnt vmcnt(6)
	s_waitcnt lgkmcnt(0)
	s_barrier
	ds_read_b128 v[134:137], v113 offset:32768
	ds_read_b128 v[142:145], v119 offset:40960
	v_mfma_f32_32x32x16_bf16 v[32:47], v[158:161], v[166:169], v[32:47]
	ds_read_b128 v[146:149], v119 offset:43008
	ds_read_b128 v[150:153], v132 offset:57344
	v_mfma_f32_32x32x16_bf16 v[48:63], v[158:161], v[244:247], v[48:63]
	ds_read_b128 v[154:157], v132 offset:59392
	ds_read_b128 v[138:141], v113 offset:34816
	v_mfma_f32_32x32x16_bf16 v[170:185], v[158:161], v[250:253], v[170:185]
	v_mfma_f32_32x32x16_bf16 v[186:201], v[158:161], v[128:131], v[186:201]
	ds_read_b128 v[158:161], v122 offset:32768
	v_mfma_f32_32x32x16_bf16 v[16:31], v[162:165], v[166:169], v[16:31]
	ds_read_b128 v[166:169], v125 offset:40960
	v_mfma_f32_32x32x16_bf16 v[0:15], v[162:165], v[244:247], v[0:15]
	ds_read_b128 v[244:247], v125 offset:43008
	v_mfma_f32_32x32x16_bf16 v[202:217], v[162:165], v[250:253], v[202:217]
	ds_read_b128 v[250:253], v133 offset:57344
	v_mfma_f32_32x32x16_bf16 v[226:241], v[162:165], v[128:131], v[226:241]
	ds_read_b128 v[162:165], v122 offset:34816
	ds_read_b128 v[128:131], v133 offset:59392
	s_waitcnt lgkmcnt(6)
	v_mfma_f32_32x32x16_bf16 v[32:47], v[134:137], v[142:145], v[32:47]
	s_mov_b32 m0, s51
	v_lshl_add_u64 v[96:97], v[96:97], 0, s[44:45]
	global_load_lds_dwordx4 v[96:97], off sc1
	v_mfma_f32_32x32x16_bf16 v[48:63], v[134:137], v[146:149], v[48:63]
	global_load_lds_dwordx4 v[96:97], off offset:1024 sc1
	v_mfma_f32_32x32x16_bf16 v[170:185], v[134:137], v[150:153], v[170:185]
	s_mov_b32 m0, s54
	v_lshl_add_u64 v[98:99], v[98:99], 0, s[44:45]
	global_load_lds_dwordx4 v[98:99], off sc1
	v_mfma_f32_32x32x16_bf16 v[186:201], v[134:137], v[154:157], v[186:201]
	global_load_lds_dwordx4 v[98:99], off offset:1024 sc1
	v_mfma_f32_32x32x16_bf16 v[16:31], v[138:141], v[142:145], v[16:31]
	s_mov_b32 m0, s57
	v_lshl_add_u64 v[114:115], v[98:99], 0, s[72:73]
	global_load_lds_dwordx4 v[114:115], off sc1
	v_mfma_f32_32x32x16_bf16 v[0:15], v[138:141], v[146:149], v[0:15]
	global_load_lds_dwordx4 v[114:115], off offset:1024 sc1
	v_mfma_f32_32x32x16_bf16 v[202:217], v[138:141], v[150:153], v[202:217]
	v_mfma_f32_32x32x16_bf16 v[226:241], v[138:141], v[154:157], v[226:241]
	s_waitcnt vmcnt(6)
	s_waitcnt lgkmcnt(0)
	s_barrier
	ds_read_b128 v[134:137], v113
	ds_read_b128 v[142:145], v119 offset:8192
	v_mfma_f32_32x32x16_bf16 v[32:47], v[158:161], v[166:169], v[32:47]
	ds_read_b128 v[146:149], v119 offset:10240
	ds_read_b128 v[150:153], v119 offset:49152
	v_mfma_f32_32x32x16_bf16 v[48:63], v[158:161], v[244:247], v[48:63]
	ds_read_b128 v[154:157], v119 offset:51200
	ds_read_b128 v[138:141], v113 offset:2048
	v_mfma_f32_32x32x16_bf16 v[170:185], v[158:161], v[250:253], v[170:185]
	v_mfma_f32_32x32x16_bf16 v[186:201], v[158:161], v[128:131], v[186:201]
	ds_read_b128 v[158:161], v122
	v_mfma_f32_32x32x16_bf16 v[16:31], v[162:165], v[166:169], v[16:31]
	ds_read_b128 v[166:169], v125 offset:8192
	v_mfma_f32_32x32x16_bf16 v[0:15], v[162:165], v[244:247], v[0:15]
	ds_read_b128 v[244:247], v125 offset:10240
	v_mfma_f32_32x32x16_bf16 v[202:217], v[162:165], v[250:253], v[202:217]
	ds_read_b128 v[250:253], v125 offset:49152
	v_mfma_f32_32x32x16_bf16 v[226:241], v[162:165], v[128:131], v[226:241]
	ds_read_b128 v[162:165], v122 offset:2048
	ds_read_b128 v[128:131], v125 offset:51200
	s_waitcnt lgkmcnt(6)
	v_mfma_f32_32x32x16_bf16 v[32:47], v[134:137], v[142:145], v[32:47]
	s_mov_b32 m0, s52
	v_lshl_add_u64 v[96:97], v[96:97], 0, s[44:45]
	global_load_lds_dwordx4 v[96:97], off sc1
	v_mfma_f32_32x32x16_bf16 v[48:63], v[134:137], v[146:149], v[48:63]
	global_load_lds_dwordx4 v[96:97], off offset:1024 sc1
	v_mfma_f32_32x32x16_bf16 v[170:185], v[134:137], v[150:153], v[170:185]
	s_mov_b32 m0, s55
	v_lshl_add_u64 v[98:99], v[98:99], 0, s[44:45]
	global_load_lds_dwordx4 v[98:99], off sc1
	v_mfma_f32_32x32x16_bf16 v[186:201], v[134:137], v[154:157], v[186:201]
	global_load_lds_dwordx4 v[98:99], off offset:1024 sc1
	v_mfma_f32_32x32x16_bf16 v[16:31], v[138:141], v[142:145], v[16:31]
	s_mov_b32 m0, s58
	v_lshl_add_u64 v[114:115], v[98:99], 0, s[72:73]
	global_load_lds_dwordx4 v[114:115], off sc1
	v_mfma_f32_32x32x16_bf16 v[0:15], v[138:141], v[146:149], v[0:15]
	global_load_lds_dwordx4 v[114:115], off offset:1024 sc1
	v_mfma_f32_32x32x16_bf16 v[202:217], v[138:141], v[150:153], v[202:217]
	v_mfma_f32_32x32x16_bf16 v[226:241], v[138:141], v[154:157], v[226:241]
	s_waitcnt vmcnt(6)
	s_waitcnt lgkmcnt(0)
	s_barrier
	ds_read_b128 v[134:137], v113 offset:16384
	ds_read_b128 v[142:145], v119 offset:24576
	v_mfma_f32_32x32x16_bf16 v[32:47], v[158:161], v[166:169], v[32:47]
	ds_read_b128 v[146:149], v119 offset:26624
	ds_read_b128 v[150:153], v132 offset:40960
	v_mfma_f32_32x32x16_bf16 v[48:63], v[158:161], v[244:247], v[48:63]
	ds_read_b128 v[154:157], v132 offset:43008
	ds_read_b128 v[138:141], v113 offset:18432
	v_mfma_f32_32x32x16_bf16 v[170:185], v[158:161], v[250:253], v[170:185]
	v_mfma_f32_32x32x16_bf16 v[186:201], v[158:161], v[128:131], v[186:201]
	ds_read_b128 v[158:161], v122 offset:16384
	v_mfma_f32_32x32x16_bf16 v[16:31], v[162:165], v[166:169], v[16:31]
	ds_read_b128 v[166:169], v125 offset:24576
	v_mfma_f32_32x32x16_bf16 v[0:15], v[162:165], v[244:247], v[0:15]
	ds_read_b128 v[244:247], v125 offset:26624
	v_mfma_f32_32x32x16_bf16 v[202:217], v[162:165], v[250:253], v[202:217]
	ds_read_b128 v[250:253], v133 offset:40960
	v_mfma_f32_32x32x16_bf16 v[226:241], v[162:165], v[128:131], v[226:241]
	ds_read_b128 v[162:165], v122 offset:18432
	ds_read_b128 v[128:131], v133 offset:43008
	s_waitcnt lgkmcnt(6)
	v_mfma_f32_32x32x16_bf16 v[32:47], v[134:137], v[142:145], v[32:47]
	s_mov_b32 m0, s50
	v_lshl_add_u64 v[96:97], v[96:97], 0, s[44:45]
	global_load_lds_dwordx4 v[96:97], off sc1
	v_mfma_f32_32x32x16_bf16 v[48:63], v[134:137], v[146:149], v[48:63]
	global_load_lds_dwordx4 v[96:97], off offset:1024 sc1
	v_mfma_f32_32x32x16_bf16 v[170:185], v[134:137], v[150:153], v[170:185]
	s_mov_b32 m0, s53
	v_lshl_add_u64 v[98:99], v[98:99], 0, s[44:45]
	global_load_lds_dwordx4 v[98:99], off sc1
	v_mfma_f32_32x32x16_bf16 v[186:201], v[134:137], v[154:157], v[186:201]
	global_load_lds_dwordx4 v[98:99], off offset:1024 sc1
	v_mfma_f32_32x32x16_bf16 v[16:31], v[138:141], v[142:145], v[16:31]
	s_mov_b32 m0, s56
	v_lshl_add_u64 v[114:115], v[98:99], 0, s[72:73]
	global_load_lds_dwordx4 v[114:115], off sc1
	v_mfma_f32_32x32x16_bf16 v[0:15], v[138:141], v[146:149], v[0:15]
	global_load_lds_dwordx4 v[114:115], off offset:1024 sc1
	v_mfma_f32_32x32x16_bf16 v[202:217], v[138:141], v[150:153], v[202:217]
	v_mfma_f32_32x32x16_bf16 v[226:241], v[138:141], v[154:157], v[226:241]
	s_waitcnt vmcnt(6)
	s_waitcnt lgkmcnt(0)
	s_barrier
	ds_read_b128 v[134:137], v113 offset:32768
	ds_read_b128 v[142:145], v119 offset:40960
	v_mfma_f32_32x32x16_bf16 v[32:47], v[158:161], v[166:169], v[32:47]
	ds_read_b128 v[146:149], v119 offset:43008
	ds_read_b128 v[150:153], v132 offset:57344
	v_mfma_f32_32x32x16_bf16 v[48:63], v[158:161], v[244:247], v[48:63]
	ds_read_b128 v[154:157], v132 offset:59392
	ds_read_b128 v[138:141], v113 offset:34816
	v_mfma_f32_32x32x16_bf16 v[170:185], v[158:161], v[250:253], v[170:185]
	v_mfma_f32_32x32x16_bf16 v[186:201], v[158:161], v[128:131], v[186:201]
	ds_read_b128 v[158:161], v122 offset:32768
	v_mfma_f32_32x32x16_bf16 v[16:31], v[162:165], v[166:169], v[16:31]
	ds_read_b128 v[166:169], v125 offset:40960
	v_mfma_f32_32x32x16_bf16 v[0:15], v[162:165], v[244:247], v[0:15]
	ds_read_b128 v[244:247], v125 offset:43008
	v_mfma_f32_32x32x16_bf16 v[202:217], v[162:165], v[250:253], v[202:217]
	ds_read_b128 v[250:253], v133 offset:57344
	v_mfma_f32_32x32x16_bf16 v[226:241], v[162:165], v[128:131], v[226:241]
	ds_read_b128 v[162:165], v122 offset:34816
	ds_read_b128 v[128:131], v133 offset:59392
	s_waitcnt lgkmcnt(6)
	v_mfma_f32_32x32x16_bf16 v[32:47], v[134:137], v[142:145], v[32:47]
	s_mov_b32 m0, s51
	v_lshl_add_u64 v[96:97], v[96:97], 0, s[44:45]
	global_load_lds_dwordx4 v[96:97], off sc1
	v_mfma_f32_32x32x16_bf16 v[48:63], v[134:137], v[146:149], v[48:63]
	global_load_lds_dwordx4 v[96:97], off offset:1024 sc1
	v_mfma_f32_32x32x16_bf16 v[170:185], v[134:137], v[150:153], v[170:185]
	s_mov_b32 m0, s54
	v_lshl_add_u64 v[98:99], v[98:99], 0, s[44:45]
	global_load_lds_dwordx4 v[98:99], off sc1
	v_mfma_f32_32x32x16_bf16 v[186:201], v[134:137], v[154:157], v[186:201]
	global_load_lds_dwordx4 v[98:99], off offset:1024 sc1
	v_mfma_f32_32x32x16_bf16 v[16:31], v[138:141], v[142:145], v[16:31]
	s_mov_b32 m0, s57
	v_lshl_add_u64 v[114:115], v[98:99], 0, s[72:73]
	global_load_lds_dwordx4 v[114:115], off sc1
	v_mfma_f32_32x32x16_bf16 v[0:15], v[138:141], v[146:149], v[0:15]
	global_load_lds_dwordx4 v[114:115], off offset:1024 sc1
	v_mfma_f32_32x32x16_bf16 v[202:217], v[138:141], v[150:153], v[202:217]
	v_mfma_f32_32x32x16_bf16 v[226:241], v[138:141], v[154:157], v[226:241]
	s_waitcnt vmcnt(6)
	s_waitcnt lgkmcnt(0)
	s_barrier
	ds_read_b128 v[134:137], v113
	ds_read_b128 v[142:145], v119 offset:8192
	v_mfma_f32_32x32x16_bf16 v[32:47], v[158:161], v[166:169], v[32:47]
	ds_read_b128 v[146:149], v119 offset:10240
	ds_read_b128 v[150:153], v119 offset:49152
	v_mfma_f32_32x32x16_bf16 v[48:63], v[158:161], v[244:247], v[48:63]
	ds_read_b128 v[154:157], v119 offset:51200
	ds_read_b128 v[138:141], v113 offset:2048
	v_mfma_f32_32x32x16_bf16 v[170:185], v[158:161], v[250:253], v[170:185]
	v_mfma_f32_32x32x16_bf16 v[186:201], v[158:161], v[128:131], v[186:201]
	ds_read_b128 v[158:161], v122
	v_mfma_f32_32x32x16_bf16 v[16:31], v[162:165], v[166:169], v[16:31]
	ds_read_b128 v[166:169], v125 offset:8192
	v_mfma_f32_32x32x16_bf16 v[0:15], v[162:165], v[244:247], v[0:15]
	ds_read_b128 v[244:247], v125 offset:10240
	v_mfma_f32_32x32x16_bf16 v[202:217], v[162:165], v[250:253], v[202:217]
	ds_read_b128 v[250:253], v125 offset:49152
	v_mfma_f32_32x32x16_bf16 v[226:241], v[162:165], v[128:131], v[226:241]
	ds_read_b128 v[162:165], v122 offset:2048
	ds_read_b128 v[128:131], v125 offset:51200
	s_waitcnt lgkmcnt(6)
	v_mfma_f32_32x32x16_bf16 v[32:47], v[134:137], v[142:145], v[32:47]
	s_mov_b32 m0, s52
	v_lshl_add_u64 v[96:97], v[96:97], 0, s[44:45]
	global_load_lds_dwordx4 v[96:97], off sc1
	v_mfma_f32_32x32x16_bf16 v[48:63], v[134:137], v[146:149], v[48:63]
	global_load_lds_dwordx4 v[96:97], off offset:1024 sc1
	v_mfma_f32_32x32x16_bf16 v[170:185], v[134:137], v[150:153], v[170:185]
	s_mov_b32 m0, s55
	v_lshl_add_u64 v[98:99], v[98:99], 0, s[44:45]
	global_load_lds_dwordx4 v[98:99], off sc1
	v_mfma_f32_32x32x16_bf16 v[186:201], v[134:137], v[154:157], v[186:201]
	global_load_lds_dwordx4 v[98:99], off offset:1024 sc1
	v_mfma_f32_32x32x16_bf16 v[16:31], v[138:141], v[142:145], v[16:31]
	s_mov_b32 m0, s58
	v_lshl_add_u64 v[114:115], v[98:99], 0, s[72:73]
	global_load_lds_dwordx4 v[114:115], off sc1
	v_mfma_f32_32x32x16_bf16 v[0:15], v[138:141], v[146:149], v[0:15]
	global_load_lds_dwordx4 v[114:115], off offset:1024 sc1
	v_mfma_f32_32x32x16_bf16 v[202:217], v[138:141], v[150:153], v[202:217]
	v_mfma_f32_32x32x16_bf16 v[226:241], v[138:141], v[154:157], v[226:241]
	s_waitcnt vmcnt(6)
	s_waitcnt lgkmcnt(0)
	s_barrier
	ds_read_b128 v[134:137], v113 offset:16384
	ds_read_b128 v[142:145], v119 offset:24576
	v_mfma_f32_32x32x16_bf16 v[32:47], v[158:161], v[166:169], v[32:47]
	ds_read_b128 v[146:149], v119 offset:26624
	ds_read_b128 v[150:153], v132 offset:40960
	v_mfma_f32_32x32x16_bf16 v[48:63], v[158:161], v[244:247], v[48:63]
	ds_read_b128 v[154:157], v132 offset:43008
	ds_read_b128 v[138:141], v113 offset:18432
	v_mfma_f32_32x32x16_bf16 v[170:185], v[158:161], v[250:253], v[170:185]
	v_mfma_f32_32x32x16_bf16 v[186:201], v[158:161], v[128:131], v[186:201]
	ds_read_b128 v[158:161], v122 offset:16384
	v_mfma_f32_32x32x16_bf16 v[16:31], v[162:165], v[166:169], v[16:31]
	ds_read_b128 v[166:169], v125 offset:24576
	v_mfma_f32_32x32x16_bf16 v[0:15], v[162:165], v[244:247], v[0:15]
	ds_read_b128 v[244:247], v125 offset:26624
	v_mfma_f32_32x32x16_bf16 v[202:217], v[162:165], v[250:253], v[202:217]
	ds_read_b128 v[250:253], v133 offset:40960
	v_mfma_f32_32x32x16_bf16 v[226:241], v[162:165], v[128:131], v[226:241]
	ds_read_b128 v[162:165], v122 offset:18432
	ds_read_b128 v[128:131], v133 offset:43008
	s_waitcnt lgkmcnt(6)
	v_mfma_f32_32x32x16_bf16 v[32:47], v[134:137], v[142:145], v[32:47]
	s_mov_b32 m0, s50
	v_lshl_add_u64 v[96:97], v[96:97], 0, s[44:45]
	global_load_lds_dwordx4 v[96:97], off sc1
	v_mfma_f32_32x32x16_bf16 v[48:63], v[134:137], v[146:149], v[48:63]
	global_load_lds_dwordx4 v[96:97], off offset:1024 sc1
	v_mfma_f32_32x32x16_bf16 v[170:185], v[134:137], v[150:153], v[170:185]
	s_mov_b32 m0, s53
	v_lshl_add_u64 v[98:99], v[98:99], 0, s[44:45]
	global_load_lds_dwordx4 v[98:99], off sc1
	v_mfma_f32_32x32x16_bf16 v[186:201], v[134:137], v[154:157], v[186:201]
	global_load_lds_dwordx4 v[98:99], off offset:1024 sc1
	v_mfma_f32_32x32x16_bf16 v[16:31], v[138:141], v[142:145], v[16:31]
	s_mov_b32 m0, s56
	v_lshl_add_u64 v[114:115], v[98:99], 0, s[72:73]
	global_load_lds_dwordx4 v[114:115], off sc1
	v_mfma_f32_32x32x16_bf16 v[0:15], v[138:141], v[146:149], v[0:15]
	global_load_lds_dwordx4 v[114:115], off offset:1024 sc1
	v_mfma_f32_32x32x16_bf16 v[202:217], v[138:141], v[150:153], v[202:217]
	v_mfma_f32_32x32x16_bf16 v[226:241], v[138:141], v[154:157], v[226:241]
	s_waitcnt vmcnt(6)
	s_waitcnt lgkmcnt(0)
	s_barrier
	ds_read_b128 v[134:137], v113 offset:32768
	ds_read_b128 v[142:145], v119 offset:40960
	v_mfma_f32_32x32x16_bf16 v[32:47], v[158:161], v[166:169], v[32:47]
	ds_read_b128 v[146:149], v119 offset:43008
	ds_read_b128 v[150:153], v132 offset:57344
	v_mfma_f32_32x32x16_bf16 v[48:63], v[158:161], v[244:247], v[48:63]
	ds_read_b128 v[154:157], v132 offset:59392
	ds_read_b128 v[138:141], v113 offset:34816
	v_mfma_f32_32x32x16_bf16 v[170:185], v[158:161], v[250:253], v[170:185]
	v_mfma_f32_32x32x16_bf16 v[186:201], v[158:161], v[128:131], v[186:201]
	ds_read_b128 v[158:161], v122 offset:32768
	v_mfma_f32_32x32x16_bf16 v[16:31], v[162:165], v[166:169], v[16:31]
	ds_read_b128 v[166:169], v125 offset:40960
	v_mfma_f32_32x32x16_bf16 v[0:15], v[162:165], v[244:247], v[0:15]
	ds_read_b128 v[244:247], v125 offset:43008
	v_mfma_f32_32x32x16_bf16 v[202:217], v[162:165], v[250:253], v[202:217]
	ds_read_b128 v[250:253], v133 offset:57344
	v_mfma_f32_32x32x16_bf16 v[226:241], v[162:165], v[128:131], v[226:241]
	ds_read_b128 v[162:165], v122 offset:34816
	ds_read_b128 v[128:131], v133 offset:59392
	s_waitcnt lgkmcnt(6)
	v_mfma_f32_32x32x16_bf16 v[32:47], v[134:137], v[142:145], v[32:47]
	s_mov_b32 m0, s51
	v_lshl_add_u64 v[96:97], v[96:97], 0, s[44:45]
	global_load_lds_dwordx4 v[96:97], off sc1
	v_mfma_f32_32x32x16_bf16 v[48:63], v[134:137], v[146:149], v[48:63]
	global_load_lds_dwordx4 v[96:97], off offset:1024 sc1
	v_mfma_f32_32x32x16_bf16 v[170:185], v[134:137], v[150:153], v[170:185]
	s_mov_b32 m0, s54
	v_lshl_add_u64 v[98:99], v[98:99], 0, s[44:45]
	global_load_lds_dwordx4 v[98:99], off sc1
	v_mfma_f32_32x32x16_bf16 v[186:201], v[134:137], v[154:157], v[186:201]
	global_load_lds_dwordx4 v[98:99], off offset:1024 sc1
	v_mfma_f32_32x32x16_bf16 v[16:31], v[138:141], v[142:145], v[16:31]
	s_mov_b32 m0, s57
	v_lshl_add_u64 v[114:115], v[98:99], 0, s[72:73]
	global_load_lds_dwordx4 v[114:115], off sc1
	v_mfma_f32_32x32x16_bf16 v[0:15], v[138:141], v[146:149], v[0:15]
	global_load_lds_dwordx4 v[114:115], off offset:1024 sc1
	v_mfma_f32_32x32x16_bf16 v[202:217], v[138:141], v[150:153], v[202:217]
	v_mfma_f32_32x32x16_bf16 v[226:241], v[138:141], v[154:157], v[226:241]
	s_waitcnt vmcnt(6)
	s_waitcnt lgkmcnt(0)
	s_barrier
	ds_read_b128 v[134:137], v113
	ds_read_b128 v[142:145], v119 offset:8192
	v_mfma_f32_32x32x16_bf16 v[32:47], v[158:161], v[166:169], v[32:47]
	ds_read_b128 v[146:149], v119 offset:10240
	ds_read_b128 v[150:153], v119 offset:49152
	v_mfma_f32_32x32x16_bf16 v[48:63], v[158:161], v[244:247], v[48:63]
	ds_read_b128 v[154:157], v119 offset:51200
	ds_read_b128 v[138:141], v113 offset:2048
	v_mfma_f32_32x32x16_bf16 v[170:185], v[158:161], v[250:253], v[170:185]
	v_mfma_f32_32x32x16_bf16 v[186:201], v[158:161], v[128:131], v[186:201]
	ds_read_b128 v[158:161], v122
	v_mfma_f32_32x32x16_bf16 v[16:31], v[162:165], v[166:169], v[16:31]
	ds_read_b128 v[166:169], v125 offset:8192
	v_mfma_f32_32x32x16_bf16 v[0:15], v[162:165], v[244:247], v[0:15]
	ds_read_b128 v[244:247], v125 offset:10240
	v_mfma_f32_32x32x16_bf16 v[202:217], v[162:165], v[250:253], v[202:217]
	ds_read_b128 v[250:253], v125 offset:49152
	v_mfma_f32_32x32x16_bf16 v[226:241], v[162:165], v[128:131], v[226:241]
	ds_read_b128 v[162:165], v122 offset:2048
	ds_read_b128 v[128:131], v125 offset:51200
	s_waitcnt lgkmcnt(6)
	v_mfma_f32_32x32x16_bf16 v[32:47], v[134:137], v[142:145], v[32:47]
	s_mov_b32 m0, s52
	v_lshl_add_u64 v[96:97], v[96:97], 0, s[44:45]
	global_load_lds_dwordx4 v[96:97], off sc1
	v_mfma_f32_32x32x16_bf16 v[48:63], v[134:137], v[146:149], v[48:63]
	global_load_lds_dwordx4 v[96:97], off offset:1024 sc1
	v_mfma_f32_32x32x16_bf16 v[170:185], v[134:137], v[150:153], v[170:185]
	s_mov_b32 m0, s55
	v_lshl_add_u64 v[98:99], v[98:99], 0, s[44:45]
	global_load_lds_dwordx4 v[98:99], off sc1
	v_mfma_f32_32x32x16_bf16 v[186:201], v[134:137], v[154:157], v[186:201]
	global_load_lds_dwordx4 v[98:99], off offset:1024 sc1
	v_mfma_f32_32x32x16_bf16 v[16:31], v[138:141], v[142:145], v[16:31]
	s_mov_b32 m0, s58
	v_lshl_add_u64 v[114:115], v[98:99], 0, s[72:73]
	global_load_lds_dwordx4 v[114:115], off sc1
	v_mfma_f32_32x32x16_bf16 v[0:15], v[138:141], v[146:149], v[0:15]
	global_load_lds_dwordx4 v[114:115], off offset:1024 sc1
	v_mfma_f32_32x32x16_bf16 v[202:217], v[138:141], v[150:153], v[202:217]
	v_mfma_f32_32x32x16_bf16 v[226:241], v[138:141], v[154:157], v[226:241]
	s_waitcnt vmcnt(6)
	s_waitcnt lgkmcnt(0)
	s_barrier
	ds_read_b128 v[134:137], v113 offset:16384
	ds_read_b128 v[142:145], v119 offset:24576
	v_mfma_f32_32x32x16_bf16 v[32:47], v[158:161], v[166:169], v[32:47]
	ds_read_b128 v[146:149], v119 offset:26624
	ds_read_b128 v[150:153], v132 offset:40960
	v_mfma_f32_32x32x16_bf16 v[48:63], v[158:161], v[244:247], v[48:63]
	ds_read_b128 v[154:157], v132 offset:43008
	ds_read_b128 v[138:141], v113 offset:18432
	v_mfma_f32_32x32x16_bf16 v[170:185], v[158:161], v[250:253], v[170:185]
	v_mfma_f32_32x32x16_bf16 v[186:201], v[158:161], v[128:131], v[186:201]
	ds_read_b128 v[158:161], v122 offset:16384
	v_mfma_f32_32x32x16_bf16 v[16:31], v[162:165], v[166:169], v[16:31]
	ds_read_b128 v[166:169], v125 offset:24576
	v_mfma_f32_32x32x16_bf16 v[0:15], v[162:165], v[244:247], v[0:15]
	ds_read_b128 v[244:247], v125 offset:26624
	v_mfma_f32_32x32x16_bf16 v[202:217], v[162:165], v[250:253], v[202:217]
	ds_read_b128 v[250:253], v133 offset:40960
	v_mfma_f32_32x32x16_bf16 v[226:241], v[162:165], v[128:131], v[226:241]
	ds_read_b128 v[162:165], v122 offset:18432
	ds_read_b128 v[128:131], v133 offset:43008
	s_waitcnt lgkmcnt(6)
	v_mfma_f32_32x32x16_bf16 v[32:47], v[134:137], v[142:145], v[32:47]
	s_mov_b32 m0, s50
	v_lshl_add_u64 v[96:97], v[96:97], 0, s[44:45]
	global_load_lds_dwordx4 v[96:97], off sc1
	v_mfma_f32_32x32x16_bf16 v[48:63], v[134:137], v[146:149], v[48:63]
	global_load_lds_dwordx4 v[96:97], off offset:1024 sc1
	v_mfma_f32_32x32x16_bf16 v[170:185], v[134:137], v[150:153], v[170:185]
	s_mov_b32 m0, s53
	v_lshl_add_u64 v[98:99], v[98:99], 0, s[44:45]
	global_load_lds_dwordx4 v[98:99], off sc1
	v_mfma_f32_32x32x16_bf16 v[186:201], v[134:137], v[154:157], v[186:201]
	global_load_lds_dwordx4 v[98:99], off offset:1024 sc1
	v_mfma_f32_32x32x16_bf16 v[16:31], v[138:141], v[142:145], v[16:31]
	s_mov_b32 m0, s56
	v_lshl_add_u64 v[114:115], v[98:99], 0, s[72:73]
	global_load_lds_dwordx4 v[114:115], off sc1
	v_mfma_f32_32x32x16_bf16 v[0:15], v[138:141], v[146:149], v[0:15]
	global_load_lds_dwordx4 v[114:115], off offset:1024 sc1
	v_mfma_f32_32x32x16_bf16 v[202:217], v[138:141], v[150:153], v[202:217]
	v_mfma_f32_32x32x16_bf16 v[226:241], v[138:141], v[154:157], v[226:241]
	s_waitcnt vmcnt(6)
	s_waitcnt lgkmcnt(0)
	s_barrier
	ds_read_b128 v[134:137], v113 offset:32768
	ds_read_b128 v[142:145], v119 offset:40960
	v_mfma_f32_32x32x16_bf16 v[32:47], v[158:161], v[166:169], v[32:47]
	ds_read_b128 v[146:149], v119 offset:43008
	ds_read_b128 v[150:153], v132 offset:57344
	v_mfma_f32_32x32x16_bf16 v[48:63], v[158:161], v[244:247], v[48:63]
	ds_read_b128 v[154:157], v132 offset:59392
	ds_read_b128 v[138:141], v113 offset:34816
	v_mfma_f32_32x32x16_bf16 v[170:185], v[158:161], v[250:253], v[170:185]
	v_mfma_f32_32x32x16_bf16 v[186:201], v[158:161], v[128:131], v[186:201]
	ds_read_b128 v[158:161], v122 offset:32768
	v_mfma_f32_32x32x16_bf16 v[16:31], v[162:165], v[166:169], v[16:31]
	ds_read_b128 v[166:169], v125 offset:40960
	v_mfma_f32_32x32x16_bf16 v[0:15], v[162:165], v[244:247], v[0:15]
	ds_read_b128 v[244:247], v125 offset:43008
	v_mfma_f32_32x32x16_bf16 v[202:217], v[162:165], v[250:253], v[202:217]
	ds_read_b128 v[250:253], v133 offset:57344
	v_mfma_f32_32x32x16_bf16 v[226:241], v[162:165], v[128:131], v[226:241]
	ds_read_b128 v[162:165], v122 offset:34816
	ds_read_b128 v[128:131], v133 offset:59392
	s_waitcnt lgkmcnt(6)
	v_mfma_f32_32x32x16_bf16 v[32:47], v[134:137], v[142:145], v[32:47]
	s_mov_b32 m0, s51
	v_lshl_add_u64 v[96:97], v[96:97], 0, s[44:45]
	global_load_lds_dwordx4 v[96:97], off sc1
	v_mfma_f32_32x32x16_bf16 v[48:63], v[134:137], v[146:149], v[48:63]
	global_load_lds_dwordx4 v[96:97], off offset:1024 sc1
	v_mfma_f32_32x32x16_bf16 v[170:185], v[134:137], v[150:153], v[170:185]
	s_mov_b32 m0, s54
	v_lshl_add_u64 v[98:99], v[98:99], 0, s[44:45]
	global_load_lds_dwordx4 v[98:99], off sc1
	v_mfma_f32_32x32x16_bf16 v[186:201], v[134:137], v[154:157], v[186:201]
	global_load_lds_dwordx4 v[98:99], off offset:1024 sc1
	v_mfma_f32_32x32x16_bf16 v[16:31], v[138:141], v[142:145], v[16:31]
	s_mov_b32 m0, s57
	v_lshl_add_u64 v[114:115], v[98:99], 0, s[72:73]
	global_load_lds_dwordx4 v[114:115], off sc1
	v_mfma_f32_32x32x16_bf16 v[0:15], v[138:141], v[146:149], v[0:15]
	global_load_lds_dwordx4 v[114:115], off offset:1024 sc1
	v_mfma_f32_32x32x16_bf16 v[202:217], v[138:141], v[150:153], v[202:217]
	v_mfma_f32_32x32x16_bf16 v[226:241], v[138:141], v[154:157], v[226:241]
	s_waitcnt vmcnt(6)
	s_waitcnt lgkmcnt(0)
	s_barrier
	ds_read_b128 v[134:137], v113
	ds_read_b128 v[142:145], v119 offset:8192
	v_mfma_f32_32x32x16_bf16 v[32:47], v[158:161], v[166:169], v[32:47]
	ds_read_b128 v[146:149], v119 offset:10240
	ds_read_b128 v[150:153], v119 offset:49152
	v_mfma_f32_32x32x16_bf16 v[48:63], v[158:161], v[244:247], v[48:63]
	ds_read_b128 v[154:157], v119 offset:51200
	ds_read_b128 v[138:141], v113 offset:2048
	v_mfma_f32_32x32x16_bf16 v[170:185], v[158:161], v[250:253], v[170:185]
	v_mfma_f32_32x32x16_bf16 v[186:201], v[158:161], v[128:131], v[186:201]
	ds_read_b128 v[158:161], v122
	v_mfma_f32_32x32x16_bf16 v[16:31], v[162:165], v[166:169], v[16:31]
	ds_read_b128 v[166:169], v125 offset:8192
	v_mfma_f32_32x32x16_bf16 v[0:15], v[162:165], v[244:247], v[0:15]
	ds_read_b128 v[244:247], v125 offset:10240
	v_mfma_f32_32x32x16_bf16 v[202:217], v[162:165], v[250:253], v[202:217]
	ds_read_b128 v[250:253], v125 offset:49152
	v_mfma_f32_32x32x16_bf16 v[226:241], v[162:165], v[128:131], v[226:241]
	ds_read_b128 v[162:165], v122 offset:2048
	ds_read_b128 v[128:131], v125 offset:51200
	s_waitcnt lgkmcnt(6)
	v_mfma_f32_32x32x16_bf16 v[32:47], v[134:137], v[142:145], v[32:47]
	s_mov_b32 m0, s52
	v_lshl_add_u64 v[96:97], v[96:97], 0, s[44:45]
	global_load_lds_dwordx4 v[96:97], off sc1
	v_mfma_f32_32x32x16_bf16 v[48:63], v[134:137], v[146:149], v[48:63]
	global_load_lds_dwordx4 v[96:97], off offset:1024 sc1
	v_mfma_f32_32x32x16_bf16 v[170:185], v[134:137], v[150:153], v[170:185]
	s_mov_b32 m0, s55
	v_lshl_add_u64 v[98:99], v[98:99], 0, s[44:45]
	global_load_lds_dwordx4 v[98:99], off sc1
	v_mfma_f32_32x32x16_bf16 v[186:201], v[134:137], v[154:157], v[186:201]
	global_load_lds_dwordx4 v[98:99], off offset:1024 sc1
	v_mfma_f32_32x32x16_bf16 v[16:31], v[138:141], v[142:145], v[16:31]
	s_mov_b32 m0, s58
	v_lshl_add_u64 v[114:115], v[98:99], 0, s[72:73]
	global_load_lds_dwordx4 v[114:115], off sc1
	v_mfma_f32_32x32x16_bf16 v[0:15], v[138:141], v[146:149], v[0:15]
	global_load_lds_dwordx4 v[114:115], off offset:1024 sc1
	v_mfma_f32_32x32x16_bf16 v[202:217], v[138:141], v[150:153], v[202:217]
	v_mfma_f32_32x32x16_bf16 v[226:241], v[138:141], v[154:157], v[226:241]
	s_waitcnt vmcnt(6)
	s_waitcnt lgkmcnt(0)
	s_barrier
	ds_read_b128 v[134:137], v113 offset:16384
	ds_read_b128 v[142:145], v119 offset:24576
	v_mfma_f32_32x32x16_bf16 v[32:47], v[158:161], v[166:169], v[32:47]
	ds_read_b128 v[146:149], v119 offset:26624
	ds_read_b128 v[150:153], v132 offset:40960
	v_mfma_f32_32x32x16_bf16 v[48:63], v[158:161], v[244:247], v[48:63]
	ds_read_b128 v[154:157], v132 offset:43008
	ds_read_b128 v[138:141], v113 offset:18432
	v_mfma_f32_32x32x16_bf16 v[170:185], v[158:161], v[250:253], v[170:185]
	v_mfma_f32_32x32x16_bf16 v[186:201], v[158:161], v[128:131], v[186:201]
	ds_read_b128 v[158:161], v122 offset:16384
	v_mfma_f32_32x32x16_bf16 v[16:31], v[162:165], v[166:169], v[16:31]
	ds_read_b128 v[166:169], v125 offset:24576
	v_mfma_f32_32x32x16_bf16 v[0:15], v[162:165], v[244:247], v[0:15]
	ds_read_b128 v[244:247], v125 offset:26624
	v_mfma_f32_32x32x16_bf16 v[202:217], v[162:165], v[250:253], v[202:217]
	ds_read_b128 v[250:253], v133 offset:40960
	v_mfma_f32_32x32x16_bf16 v[226:241], v[162:165], v[128:131], v[226:241]
	ds_read_b128 v[162:165], v122 offset:18432
	ds_read_b128 v[128:131], v133 offset:43008
	s_waitcnt lgkmcnt(6)
	v_mfma_f32_32x32x16_bf16 v[32:47], v[134:137], v[142:145], v[32:47]
	s_mov_b32 m0, s50
	v_lshl_add_u64 v[96:97], v[96:97], 0, s[44:45]
	global_load_lds_dwordx4 v[96:97], off sc1
	v_mfma_f32_32x32x16_bf16 v[48:63], v[134:137], v[146:149], v[48:63]
	global_load_lds_dwordx4 v[96:97], off offset:1024 sc1
	v_mfma_f32_32x32x16_bf16 v[170:185], v[134:137], v[150:153], v[170:185]
	s_mov_b32 m0, s53
	v_lshl_add_u64 v[98:99], v[98:99], 0, s[44:45]
	global_load_lds_dwordx4 v[98:99], off sc1
	v_mfma_f32_32x32x16_bf16 v[186:201], v[134:137], v[154:157], v[186:201]
	global_load_lds_dwordx4 v[98:99], off offset:1024 sc1
	v_mfma_f32_32x32x16_bf16 v[16:31], v[138:141], v[142:145], v[16:31]
	s_mov_b32 m0, s56
	v_lshl_add_u64 v[114:115], v[98:99], 0, s[72:73]
	global_load_lds_dwordx4 v[114:115], off sc1
	v_mfma_f32_32x32x16_bf16 v[0:15], v[138:141], v[146:149], v[0:15]
	global_load_lds_dwordx4 v[114:115], off offset:1024 sc1
	v_mfma_f32_32x32x16_bf16 v[202:217], v[138:141], v[150:153], v[202:217]
	v_mfma_f32_32x32x16_bf16 v[226:241], v[138:141], v[154:157], v[226:241]
	s_waitcnt vmcnt(6)
	s_waitcnt lgkmcnt(0)
	s_barrier
	ds_read_b128 v[134:137], v113 offset:32768
	ds_read_b128 v[142:145], v119 offset:40960
	v_mfma_f32_32x32x16_bf16 v[32:47], v[158:161], v[166:169], v[32:47]
	ds_read_b128 v[146:149], v119 offset:43008
	ds_read_b128 v[150:153], v132 offset:57344
	v_mfma_f32_32x32x16_bf16 v[48:63], v[158:161], v[244:247], v[48:63]
	ds_read_b128 v[154:157], v132 offset:59392
	ds_read_b128 v[138:141], v113 offset:34816
	v_mfma_f32_32x32x16_bf16 v[170:185], v[158:161], v[250:253], v[170:185]
	v_mfma_f32_32x32x16_bf16 v[186:201], v[158:161], v[128:131], v[186:201]
	ds_read_b128 v[158:161], v122 offset:32768
	v_mfma_f32_32x32x16_bf16 v[16:31], v[162:165], v[166:169], v[16:31]
	ds_read_b128 v[166:169], v125 offset:40960
	v_mfma_f32_32x32x16_bf16 v[0:15], v[162:165], v[244:247], v[0:15]
	ds_read_b128 v[244:247], v125 offset:43008
	v_mfma_f32_32x32x16_bf16 v[202:217], v[162:165], v[250:253], v[202:217]
	ds_read_b128 v[250:253], v133 offset:57344
	v_mfma_f32_32x32x16_bf16 v[226:241], v[162:165], v[128:131], v[226:241]
	ds_read_b128 v[162:165], v122 offset:34816
	ds_read_b128 v[128:131], v133 offset:59392
	s_waitcnt lgkmcnt(6)
	v_mfma_f32_32x32x16_bf16 v[32:47], v[134:137], v[142:145], v[32:47]
	s_mov_b32 m0, s51
	v_lshl_add_u64 v[96:97], v[96:97], 0, s[44:45]
	global_load_lds_dwordx4 v[96:97], off sc1
	v_mfma_f32_32x32x16_bf16 v[48:63], v[134:137], v[146:149], v[48:63]
	global_load_lds_dwordx4 v[96:97], off offset:1024 sc1
	v_mfma_f32_32x32x16_bf16 v[170:185], v[134:137], v[150:153], v[170:185]
	s_mov_b32 m0, s54
	v_lshl_add_u64 v[98:99], v[98:99], 0, s[44:45]
	global_load_lds_dwordx4 v[98:99], off sc1
	v_mfma_f32_32x32x16_bf16 v[186:201], v[134:137], v[154:157], v[186:201]
	global_load_lds_dwordx4 v[98:99], off offset:1024 sc1
	v_mfma_f32_32x32x16_bf16 v[16:31], v[138:141], v[142:145], v[16:31]
	s_mov_b32 m0, s57
	v_lshl_add_u64 v[114:115], v[98:99], 0, s[72:73]
	global_load_lds_dwordx4 v[114:115], off sc1
	v_mfma_f32_32x32x16_bf16 v[0:15], v[138:141], v[146:149], v[0:15]
	global_load_lds_dwordx4 v[114:115], off offset:1024 sc1
	v_mfma_f32_32x32x16_bf16 v[202:217], v[138:141], v[150:153], v[202:217]
	v_mfma_f32_32x32x16_bf16 v[226:241], v[138:141], v[154:157], v[226:241]
	s_waitcnt vmcnt(6)
	s_waitcnt lgkmcnt(0)
	s_barrier
	ds_read_b128 v[134:137], v113
	ds_read_b128 v[142:145], v119 offset:8192
	v_mfma_f32_32x32x16_bf16 v[32:47], v[158:161], v[166:169], v[32:47]
	ds_read_b128 v[146:149], v119 offset:10240
	ds_read_b128 v[150:153], v119 offset:49152
	v_mfma_f32_32x32x16_bf16 v[48:63], v[158:161], v[244:247], v[48:63]
	ds_read_b128 v[154:157], v119 offset:51200
	ds_read_b128 v[138:141], v113 offset:2048
	v_mfma_f32_32x32x16_bf16 v[170:185], v[158:161], v[250:253], v[170:185]
	v_mfma_f32_32x32x16_bf16 v[186:201], v[158:161], v[128:131], v[186:201]
	ds_read_b128 v[158:161], v122
	v_mfma_f32_32x32x16_bf16 v[16:31], v[162:165], v[166:169], v[16:31]
	ds_read_b128 v[166:169], v125 offset:8192
	v_mfma_f32_32x32x16_bf16 v[0:15], v[162:165], v[244:247], v[0:15]
	ds_read_b128 v[244:247], v125 offset:10240
	v_mfma_f32_32x32x16_bf16 v[202:217], v[162:165], v[250:253], v[202:217]
	ds_read_b128 v[250:253], v125 offset:49152
	v_mfma_f32_32x32x16_bf16 v[226:241], v[162:165], v[128:131], v[226:241]
	ds_read_b128 v[162:165], v122 offset:2048
	ds_read_b128 v[128:131], v125 offset:51200
	s_waitcnt lgkmcnt(6)
	v_mfma_f32_32x32x16_bf16 v[32:47], v[134:137], v[142:145], v[32:47]
	s_mov_b32 m0, s52
	v_lshl_add_u64 v[96:97], v[96:97], 0, s[44:45]
	global_load_lds_dwordx4 v[96:97], off sc1
	v_mfma_f32_32x32x16_bf16 v[48:63], v[134:137], v[146:149], v[48:63]
	global_load_lds_dwordx4 v[96:97], off offset:1024 sc1
	v_mfma_f32_32x32x16_bf16 v[170:185], v[134:137], v[150:153], v[170:185]
	s_mov_b32 m0, s55
	v_lshl_add_u64 v[98:99], v[98:99], 0, s[44:45]
	global_load_lds_dwordx4 v[98:99], off sc1
	v_mfma_f32_32x32x16_bf16 v[186:201], v[134:137], v[154:157], v[186:201]
	global_load_lds_dwordx4 v[98:99], off offset:1024 sc1
	v_mfma_f32_32x32x16_bf16 v[16:31], v[138:141], v[142:145], v[16:31]
	s_mov_b32 m0, s58
	v_lshl_add_u64 v[114:115], v[98:99], 0, s[72:73]
	global_load_lds_dwordx4 v[114:115], off sc1
	v_mfma_f32_32x32x16_bf16 v[0:15], v[138:141], v[146:149], v[0:15]
	global_load_lds_dwordx4 v[114:115], off offset:1024 sc1
	v_mfma_f32_32x32x16_bf16 v[202:217], v[138:141], v[150:153], v[202:217]
	v_mfma_f32_32x32x16_bf16 v[226:241], v[138:141], v[154:157], v[226:241]
	s_waitcnt vmcnt(6)
	s_waitcnt lgkmcnt(0)
	s_barrier
	ds_read_b128 v[134:137], v113 offset:16384
	ds_read_b128 v[142:145], v119 offset:24576
	v_mfma_f32_32x32x16_bf16 v[32:47], v[158:161], v[166:169], v[32:47]
	ds_read_b128 v[146:149], v119 offset:26624
	ds_read_b128 v[150:153], v132 offset:40960
	v_mfma_f32_32x32x16_bf16 v[48:63], v[158:161], v[244:247], v[48:63]
	ds_read_b128 v[154:157], v132 offset:43008
	ds_read_b128 v[138:141], v113 offset:18432
	v_mfma_f32_32x32x16_bf16 v[170:185], v[158:161], v[250:253], v[170:185]
	v_mfma_f32_32x32x16_bf16 v[186:201], v[158:161], v[128:131], v[186:201]
	ds_read_b128 v[158:161], v122 offset:16384
	v_mfma_f32_32x32x16_bf16 v[16:31], v[162:165], v[166:169], v[16:31]
	ds_read_b128 v[166:169], v125 offset:24576
	v_mfma_f32_32x32x16_bf16 v[0:15], v[162:165], v[244:247], v[0:15]
	ds_read_b128 v[244:247], v125 offset:26624
	v_mfma_f32_32x32x16_bf16 v[202:217], v[162:165], v[250:253], v[202:217]
	ds_read_b128 v[250:253], v133 offset:40960
	v_mfma_f32_32x32x16_bf16 v[226:241], v[162:165], v[128:131], v[226:241]
	ds_read_b128 v[162:165], v122 offset:18432
	ds_read_b128 v[128:131], v133 offset:43008
	s_waitcnt lgkmcnt(6)
	v_mfma_f32_32x32x16_bf16 v[32:47], v[134:137], v[142:145], v[32:47]
	s_mov_b32 m0, s50
	v_lshl_add_u64 v[96:97], v[96:97], 0, s[44:45]
	global_load_lds_dwordx4 v[96:97], off sc1
	v_mfma_f32_32x32x16_bf16 v[48:63], v[134:137], v[146:149], v[48:63]
	global_load_lds_dwordx4 v[96:97], off offset:1024 sc1
	v_mfma_f32_32x32x16_bf16 v[170:185], v[134:137], v[150:153], v[170:185]
	s_mov_b32 m0, s53
	v_lshl_add_u64 v[98:99], v[98:99], 0, s[44:45]
	global_load_lds_dwordx4 v[98:99], off sc1
	v_mfma_f32_32x32x16_bf16 v[186:201], v[134:137], v[154:157], v[186:201]
	global_load_lds_dwordx4 v[98:99], off offset:1024 sc1
	v_mfma_f32_32x32x16_bf16 v[16:31], v[138:141], v[142:145], v[16:31]
	s_mov_b32 m0, s56
	v_lshl_add_u64 v[114:115], v[98:99], 0, s[72:73]
	global_load_lds_dwordx4 v[114:115], off sc1
	v_mfma_f32_32x32x16_bf16 v[0:15], v[138:141], v[146:149], v[0:15]
	global_load_lds_dwordx4 v[114:115], off offset:1024 sc1
	v_mfma_f32_32x32x16_bf16 v[202:217], v[138:141], v[150:153], v[202:217]
	v_mfma_f32_32x32x16_bf16 v[226:241], v[138:141], v[154:157], v[226:241]
	s_waitcnt vmcnt(6)
	s_waitcnt lgkmcnt(0)
	s_barrier
	ds_read_b128 v[134:137], v113 offset:32768
	ds_read_b128 v[142:145], v119 offset:40960
	v_mfma_f32_32x32x16_bf16 v[32:47], v[158:161], v[166:169], v[32:47]
	ds_read_b128 v[146:149], v119 offset:43008
	ds_read_b128 v[150:153], v132 offset:57344
	v_mfma_f32_32x32x16_bf16 v[48:63], v[158:161], v[244:247], v[48:63]
	ds_read_b128 v[154:157], v132 offset:59392
	ds_read_b128 v[138:141], v113 offset:34816
	v_mfma_f32_32x32x16_bf16 v[170:185], v[158:161], v[250:253], v[170:185]
	v_mfma_f32_32x32x16_bf16 v[186:201], v[158:161], v[128:131], v[186:201]
	ds_read_b128 v[158:161], v122 offset:32768
	v_mfma_f32_32x32x16_bf16 v[16:31], v[162:165], v[166:169], v[16:31]
	ds_read_b128 v[166:169], v125 offset:40960
	v_mfma_f32_32x32x16_bf16 v[0:15], v[162:165], v[244:247], v[0:15]
	ds_read_b128 v[244:247], v125 offset:43008
	v_mfma_f32_32x32x16_bf16 v[202:217], v[162:165], v[250:253], v[202:217]
	ds_read_b128 v[250:253], v133 offset:57344
	v_mfma_f32_32x32x16_bf16 v[226:241], v[162:165], v[128:131], v[226:241]
	ds_read_b128 v[162:165], v122 offset:34816
	ds_read_b128 v[128:131], v133 offset:59392
	s_waitcnt lgkmcnt(6)
	v_mfma_f32_32x32x16_bf16 v[32:47], v[134:137], v[142:145], v[32:47]
	s_mov_b32 m0, s51
	v_lshl_add_u64 v[96:97], v[96:97], 0, s[44:45]
	global_load_lds_dwordx4 v[96:97], off sc1
	v_mfma_f32_32x32x16_bf16 v[48:63], v[134:137], v[146:149], v[48:63]
	global_load_lds_dwordx4 v[96:97], off offset:1024 sc1
	v_mfma_f32_32x32x16_bf16 v[170:185], v[134:137], v[150:153], v[170:185]
	s_mov_b32 m0, s54
	v_lshl_add_u64 v[98:99], v[98:99], 0, s[44:45]
	global_load_lds_dwordx4 v[98:99], off sc1
	v_mfma_f32_32x32x16_bf16 v[186:201], v[134:137], v[154:157], v[186:201]
	global_load_lds_dwordx4 v[98:99], off offset:1024 sc1
	v_mfma_f32_32x32x16_bf16 v[16:31], v[138:141], v[142:145], v[16:31]
	s_mov_b32 m0, s57
	v_lshl_add_u64 v[114:115], v[98:99], 0, s[72:73]
	global_load_lds_dwordx4 v[114:115], off sc1
	v_mfma_f32_32x32x16_bf16 v[0:15], v[138:141], v[146:149], v[0:15]
	global_load_lds_dwordx4 v[114:115], off offset:1024 sc1
	v_mfma_f32_32x32x16_bf16 v[202:217], v[138:141], v[150:153], v[202:217]
	v_mfma_f32_32x32x16_bf16 v[226:241], v[138:141], v[154:157], v[226:241]
	s_waitcnt vmcnt(6)
	s_waitcnt lgkmcnt(0)
	s_barrier
	ds_read_b128 v[134:137], v113
	ds_read_b128 v[142:145], v119 offset:8192
	v_mfma_f32_32x32x16_bf16 v[32:47], v[158:161], v[166:169], v[32:47]
	ds_read_b128 v[146:149], v119 offset:10240
	ds_read_b128 v[150:153], v119 offset:49152
	v_mfma_f32_32x32x16_bf16 v[48:63], v[158:161], v[244:247], v[48:63]
	ds_read_b128 v[154:157], v119 offset:51200
	ds_read_b128 v[138:141], v113 offset:2048
	v_mfma_f32_32x32x16_bf16 v[170:185], v[158:161], v[250:253], v[170:185]
	v_mfma_f32_32x32x16_bf16 v[186:201], v[158:161], v[128:131], v[186:201]
	ds_read_b128 v[158:161], v122
	v_mfma_f32_32x32x16_bf16 v[16:31], v[162:165], v[166:169], v[16:31]
	ds_read_b128 v[166:169], v125 offset:8192
	v_mfma_f32_32x32x16_bf16 v[0:15], v[162:165], v[244:247], v[0:15]
	ds_read_b128 v[244:247], v125 offset:10240
	v_mfma_f32_32x32x16_bf16 v[202:217], v[162:165], v[250:253], v[202:217]
	ds_read_b128 v[250:253], v125 offset:49152
	v_mfma_f32_32x32x16_bf16 v[226:241], v[162:165], v[128:131], v[226:241]
	ds_read_b128 v[162:165], v122 offset:2048
	ds_read_b128 v[128:131], v125 offset:51200
	s_waitcnt lgkmcnt(6)
	v_mfma_f32_32x32x16_bf16 v[32:47], v[134:137], v[142:145], v[32:47]
	s_mov_b32 m0, s52
	v_lshl_add_u64 v[96:97], v[96:97], 0, s[44:45]
	global_load_lds_dwordx4 v[96:97], off sc1
	v_mfma_f32_32x32x16_bf16 v[48:63], v[134:137], v[146:149], v[48:63]
	global_load_lds_dwordx4 v[96:97], off offset:1024 sc1
	v_mfma_f32_32x32x16_bf16 v[170:185], v[134:137], v[150:153], v[170:185]
	s_mov_b32 m0, s55
	v_lshl_add_u64 v[98:99], v[98:99], 0, s[44:45]
	global_load_lds_dwordx4 v[98:99], off sc1
	v_mfma_f32_32x32x16_bf16 v[186:201], v[134:137], v[154:157], v[186:201]
	global_load_lds_dwordx4 v[98:99], off offset:1024 sc1
	v_mfma_f32_32x32x16_bf16 v[16:31], v[138:141], v[142:145], v[16:31]
	s_mov_b32 m0, s58
	v_lshl_add_u64 v[114:115], v[98:99], 0, s[72:73]
	global_load_lds_dwordx4 v[114:115], off sc1
	v_mfma_f32_32x32x16_bf16 v[0:15], v[138:141], v[146:149], v[0:15]
	global_load_lds_dwordx4 v[114:115], off offset:1024 sc1
	v_mfma_f32_32x32x16_bf16 v[202:217], v[138:141], v[150:153], v[202:217]
	v_mfma_f32_32x32x16_bf16 v[226:241], v[138:141], v[154:157], v[226:241]
	s_waitcnt vmcnt(6)
	s_waitcnt lgkmcnt(0)
	s_barrier
	ds_read_b128 v[134:137], v113 offset:16384
	ds_read_b128 v[142:145], v119 offset:24576
	v_mfma_f32_32x32x16_bf16 v[32:47], v[158:161], v[166:169], v[32:47]
	ds_read_b128 v[146:149], v119 offset:26624
	ds_read_b128 v[150:153], v132 offset:40960
	v_mfma_f32_32x32x16_bf16 v[48:63], v[158:161], v[244:247], v[48:63]
	ds_read_b128 v[154:157], v132 offset:43008
	ds_read_b128 v[138:141], v113 offset:18432
	v_mfma_f32_32x32x16_bf16 v[170:185], v[158:161], v[250:253], v[170:185]
	v_mfma_f32_32x32x16_bf16 v[186:201], v[158:161], v[128:131], v[186:201]
	ds_read_b128 v[158:161], v122 offset:16384
	v_mfma_f32_32x32x16_bf16 v[16:31], v[162:165], v[166:169], v[16:31]
	ds_read_b128 v[166:169], v125 offset:24576
	v_mfma_f32_32x32x16_bf16 v[0:15], v[162:165], v[244:247], v[0:15]
	ds_read_b128 v[244:247], v125 offset:26624
	v_mfma_f32_32x32x16_bf16 v[202:217], v[162:165], v[250:253], v[202:217]
	ds_read_b128 v[250:253], v133 offset:40960
	v_mfma_f32_32x32x16_bf16 v[226:241], v[162:165], v[128:131], v[226:241]
	ds_read_b128 v[162:165], v122 offset:18432
	ds_read_b128 v[128:131], v133 offset:43008
	s_waitcnt lgkmcnt(6)
	v_mfma_f32_32x32x16_bf16 v[32:47], v[134:137], v[142:145], v[32:47]
	s_mov_b32 m0, s50
	v_lshl_add_u64 v[96:97], v[96:97], 0, s[44:45]
	global_load_lds_dwordx4 v[96:97], off sc1
	v_mfma_f32_32x32x16_bf16 v[48:63], v[134:137], v[146:149], v[48:63]
	global_load_lds_dwordx4 v[96:97], off offset:1024 sc1
	v_mfma_f32_32x32x16_bf16 v[170:185], v[134:137], v[150:153], v[170:185]
	s_mov_b32 m0, s53
	v_lshl_add_u64 v[98:99], v[98:99], 0, s[44:45]
	global_load_lds_dwordx4 v[98:99], off sc1
	v_mfma_f32_32x32x16_bf16 v[186:201], v[134:137], v[154:157], v[186:201]
	global_load_lds_dwordx4 v[98:99], off offset:1024 sc1
	v_mfma_f32_32x32x16_bf16 v[16:31], v[138:141], v[142:145], v[16:31]
	s_mov_b32 m0, s56
	v_lshl_add_u64 v[114:115], v[98:99], 0, s[72:73]
	global_load_lds_dwordx4 v[114:115], off sc1
	v_mfma_f32_32x32x16_bf16 v[0:15], v[138:141], v[146:149], v[0:15]
	global_load_lds_dwordx4 v[114:115], off offset:1024 sc1
	v_mfma_f32_32x32x16_bf16 v[202:217], v[138:141], v[150:153], v[202:217]
	v_mfma_f32_32x32x16_bf16 v[226:241], v[138:141], v[154:157], v[226:241]
	s_waitcnt vmcnt(6)
	s_waitcnt lgkmcnt(0)
	s_barrier
	ds_read_b128 v[134:137], v113 offset:32768
	ds_read_b128 v[142:145], v119 offset:40960
	v_mfma_f32_32x32x16_bf16 v[32:47], v[158:161], v[166:169], v[32:47]
	ds_read_b128 v[146:149], v119 offset:43008
	ds_read_b128 v[150:153], v132 offset:57344
	v_mfma_f32_32x32x16_bf16 v[48:63], v[158:161], v[244:247], v[48:63]
	ds_read_b128 v[154:157], v132 offset:59392
	ds_read_b128 v[138:141], v113 offset:34816
	v_mfma_f32_32x32x16_bf16 v[170:185], v[158:161], v[250:253], v[170:185]
	v_mfma_f32_32x32x16_bf16 v[186:201], v[158:161], v[128:131], v[186:201]
	ds_read_b128 v[158:161], v122 offset:32768
	v_mfma_f32_32x32x16_bf16 v[16:31], v[162:165], v[166:169], v[16:31]
	ds_read_b128 v[166:169], v125 offset:40960
	v_mfma_f32_32x32x16_bf16 v[0:15], v[162:165], v[244:247], v[0:15]
	ds_read_b128 v[244:247], v125 offset:43008
	v_mfma_f32_32x32x16_bf16 v[202:217], v[162:165], v[250:253], v[202:217]
	ds_read_b128 v[250:253], v133 offset:57344
	v_mfma_f32_32x32x16_bf16 v[226:241], v[162:165], v[128:131], v[226:241]
	ds_read_b128 v[162:165], v122 offset:34816
	ds_read_b128 v[128:131], v133 offset:59392
	s_waitcnt lgkmcnt(6)
	v_mfma_f32_32x32x16_bf16 v[32:47], v[134:137], v[142:145], v[32:47]
	s_mov_b32 m0, s51
	v_lshl_add_u64 v[96:97], v[96:97], 0, s[44:45]
	global_load_lds_dwordx4 v[96:97], off sc1
	v_mfma_f32_32x32x16_bf16 v[48:63], v[134:137], v[146:149], v[48:63]
	global_load_lds_dwordx4 v[96:97], off offset:1024 sc1
	v_mfma_f32_32x32x16_bf16 v[170:185], v[134:137], v[150:153], v[170:185]
	s_mov_b32 m0, s54
	v_lshl_add_u64 v[98:99], v[98:99], 0, s[44:45]
	global_load_lds_dwordx4 v[98:99], off sc1
	v_mfma_f32_32x32x16_bf16 v[186:201], v[134:137], v[154:157], v[186:201]
	global_load_lds_dwordx4 v[98:99], off offset:1024 sc1
	v_mfma_f32_32x32x16_bf16 v[16:31], v[138:141], v[142:145], v[16:31]
	s_mov_b32 m0, s57
	v_lshl_add_u64 v[114:115], v[98:99], 0, s[72:73]
	global_load_lds_dwordx4 v[114:115], off sc1
	v_mfma_f32_32x32x16_bf16 v[0:15], v[138:141], v[146:149], v[0:15]
	global_load_lds_dwordx4 v[114:115], off offset:1024 sc1
	v_mfma_f32_32x32x16_bf16 v[202:217], v[138:141], v[150:153], v[202:217]
	v_mfma_f32_32x32x16_bf16 v[226:241], v[138:141], v[154:157], v[226:241]
	s_waitcnt vmcnt(6)
	s_waitcnt lgkmcnt(0)
	s_barrier
	ds_read_b128 v[134:137], v113
	ds_read_b128 v[142:145], v119 offset:8192
	v_mfma_f32_32x32x16_bf16 v[32:47], v[158:161], v[166:169], v[32:47]
	ds_read_b128 v[146:149], v119 offset:10240
	ds_read_b128 v[150:153], v119 offset:49152
	v_mfma_f32_32x32x16_bf16 v[48:63], v[158:161], v[244:247], v[48:63]
	ds_read_b128 v[154:157], v119 offset:51200
	ds_read_b128 v[138:141], v113 offset:2048
	v_mfma_f32_32x32x16_bf16 v[170:185], v[158:161], v[250:253], v[170:185]
	v_mfma_f32_32x32x16_bf16 v[186:201], v[158:161], v[128:131], v[186:201]
	ds_read_b128 v[158:161], v122
	v_mfma_f32_32x32x16_bf16 v[16:31], v[162:165], v[166:169], v[16:31]
	ds_read_b128 v[166:169], v125 offset:8192
	v_mfma_f32_32x32x16_bf16 v[0:15], v[162:165], v[244:247], v[0:15]
	ds_read_b128 v[244:247], v125 offset:10240
	v_mfma_f32_32x32x16_bf16 v[202:217], v[162:165], v[250:253], v[202:217]
	ds_read_b128 v[250:253], v125 offset:49152
	v_mfma_f32_32x32x16_bf16 v[226:241], v[162:165], v[128:131], v[226:241]
	ds_read_b128 v[162:165], v122 offset:2048
	ds_read_b128 v[128:131], v125 offset:51200
	s_waitcnt lgkmcnt(6)
	v_mfma_f32_32x32x16_bf16 v[32:47], v[134:137], v[142:145], v[32:47]
	s_mov_b32 m0, s52
	v_lshl_add_u64 v[96:97], v[96:97], 0, s[44:45]
	global_load_lds_dwordx4 v[96:97], off sc1
	v_mfma_f32_32x32x16_bf16 v[48:63], v[134:137], v[146:149], v[48:63]
	global_load_lds_dwordx4 v[96:97], off offset:1024 sc1
	v_mfma_f32_32x32x16_bf16 v[170:185], v[134:137], v[150:153], v[170:185]
	s_mov_b32 m0, s55
	v_lshl_add_u64 v[98:99], v[98:99], 0, s[44:45]
	global_load_lds_dwordx4 v[98:99], off sc1
	v_mfma_f32_32x32x16_bf16 v[186:201], v[134:137], v[154:157], v[186:201]
	global_load_lds_dwordx4 v[98:99], off offset:1024 sc1
	v_mfma_f32_32x32x16_bf16 v[16:31], v[138:141], v[142:145], v[16:31]
	s_mov_b32 m0, s58
	v_lshl_add_u64 v[114:115], v[98:99], 0, s[72:73]
	global_load_lds_dwordx4 v[114:115], off sc1
	v_mfma_f32_32x32x16_bf16 v[0:15], v[138:141], v[146:149], v[0:15]
	global_load_lds_dwordx4 v[114:115], off offset:1024 sc1
	v_mfma_f32_32x32x16_bf16 v[202:217], v[138:141], v[150:153], v[202:217]
	v_mfma_f32_32x32x16_bf16 v[226:241], v[138:141], v[154:157], v[226:241]
	s_waitcnt vmcnt(6)
	s_waitcnt lgkmcnt(0)
	s_barrier
	ds_read_b128 v[134:137], v113 offset:16384
	ds_read_b128 v[142:145], v119 offset:24576
	v_mfma_f32_32x32x16_bf16 v[32:47], v[158:161], v[166:169], v[32:47]
	ds_read_b128 v[146:149], v119 offset:26624
	ds_read_b128 v[150:153], v132 offset:40960
	v_mfma_f32_32x32x16_bf16 v[48:63], v[158:161], v[244:247], v[48:63]
	ds_read_b128 v[154:157], v132 offset:43008
	ds_read_b128 v[138:141], v113 offset:18432
	v_mfma_f32_32x32x16_bf16 v[170:185], v[158:161], v[250:253], v[170:185]
	v_mfma_f32_32x32x16_bf16 v[186:201], v[158:161], v[128:131], v[186:201]
	ds_read_b128 v[158:161], v122 offset:16384
	v_mfma_f32_32x32x16_bf16 v[16:31], v[162:165], v[166:169], v[16:31]
	ds_read_b128 v[166:169], v125 offset:24576
	v_mfma_f32_32x32x16_bf16 v[0:15], v[162:165], v[244:247], v[0:15]
	ds_read_b128 v[244:247], v125 offset:26624
	v_mfma_f32_32x32x16_bf16 v[202:217], v[162:165], v[250:253], v[202:217]
	ds_read_b128 v[250:253], v133 offset:40960
	v_mfma_f32_32x32x16_bf16 v[226:241], v[162:165], v[128:131], v[226:241]
	ds_read_b128 v[162:165], v122 offset:18432
	ds_read_b128 v[128:131], v133 offset:43008
	s_waitcnt lgkmcnt(6)
	v_mfma_f32_32x32x16_bf16 v[32:47], v[134:137], v[142:145], v[32:47]
	s_mov_b32 m0, s50
	v_lshl_add_u64 v[96:97], v[96:97], 0, s[44:45]
	global_load_lds_dwordx4 v[96:97], off sc1
	v_mfma_f32_32x32x16_bf16 v[48:63], v[134:137], v[146:149], v[48:63]
	global_load_lds_dwordx4 v[96:97], off offset:1024 sc1
	v_mfma_f32_32x32x16_bf16 v[170:185], v[134:137], v[150:153], v[170:185]
	s_mov_b32 m0, s53
	v_lshl_add_u64 v[98:99], v[98:99], 0, s[44:45]
	global_load_lds_dwordx4 v[98:99], off sc1
	v_mfma_f32_32x32x16_bf16 v[186:201], v[134:137], v[154:157], v[186:201]
	global_load_lds_dwordx4 v[98:99], off offset:1024 sc1
	v_mfma_f32_32x32x16_bf16 v[16:31], v[138:141], v[142:145], v[16:31]
	s_mov_b32 m0, s56
	v_lshl_add_u64 v[114:115], v[98:99], 0, s[72:73]
	global_load_lds_dwordx4 v[114:115], off sc1
	v_mfma_f32_32x32x16_bf16 v[0:15], v[138:141], v[146:149], v[0:15]
	global_load_lds_dwordx4 v[114:115], off offset:1024 sc1
	v_mfma_f32_32x32x16_bf16 v[202:217], v[138:141], v[150:153], v[202:217]
	v_mfma_f32_32x32x16_bf16 v[226:241], v[138:141], v[154:157], v[226:241]
	s_waitcnt vmcnt(6)
	s_waitcnt lgkmcnt(0)
	s_barrier
	ds_read_b128 v[134:137], v113 offset:32768
	ds_read_b128 v[142:145], v119 offset:40960
	v_mfma_f32_32x32x16_bf16 v[32:47], v[158:161], v[166:169], v[32:47]
	ds_read_b128 v[146:149], v119 offset:43008
	ds_read_b128 v[150:153], v132 offset:57344
	v_mfma_f32_32x32x16_bf16 v[48:63], v[158:161], v[244:247], v[48:63]
	ds_read_b128 v[154:157], v132 offset:59392
	ds_read_b128 v[138:141], v113 offset:34816
	v_mfma_f32_32x32x16_bf16 v[170:185], v[158:161], v[250:253], v[170:185]
	v_mfma_f32_32x32x16_bf16 v[186:201], v[158:161], v[128:131], v[186:201]
	ds_read_b128 v[158:161], v122 offset:32768
	v_mfma_f32_32x32x16_bf16 v[16:31], v[162:165], v[166:169], v[16:31]
	ds_read_b128 v[166:169], v125 offset:40960
	v_mfma_f32_32x32x16_bf16 v[0:15], v[162:165], v[244:247], v[0:15]
	ds_read_b128 v[244:247], v125 offset:43008
	v_mfma_f32_32x32x16_bf16 v[202:217], v[162:165], v[250:253], v[202:217]
	ds_read_b128 v[250:253], v133 offset:57344
	v_mfma_f32_32x32x16_bf16 v[226:241], v[162:165], v[128:131], v[226:241]
	ds_read_b128 v[162:165], v122 offset:34816
	ds_read_b128 v[128:131], v133 offset:59392
	s_waitcnt lgkmcnt(6)
	v_mfma_f32_32x32x16_bf16 v[32:47], v[134:137], v[142:145], v[32:47]
	s_mov_b32 m0, s51
	v_lshl_add_u64 v[96:97], v[96:97], 0, s[44:45]
	global_load_lds_dwordx4 v[96:97], off sc1
	v_mfma_f32_32x32x16_bf16 v[48:63], v[134:137], v[146:149], v[48:63]
	global_load_lds_dwordx4 v[96:97], off offset:1024 sc1
	v_mfma_f32_32x32x16_bf16 v[170:185], v[134:137], v[150:153], v[170:185]
	s_mov_b32 m0, s54
	v_lshl_add_u64 v[98:99], v[98:99], 0, s[44:45]
	global_load_lds_dwordx4 v[98:99], off sc1
	v_mfma_f32_32x32x16_bf16 v[186:201], v[134:137], v[154:157], v[186:201]
	global_load_lds_dwordx4 v[98:99], off offset:1024 sc1
	v_mfma_f32_32x32x16_bf16 v[16:31], v[138:141], v[142:145], v[16:31]
	s_mov_b32 m0, s57
	v_lshl_add_u64 v[114:115], v[98:99], 0, s[72:73]
	global_load_lds_dwordx4 v[114:115], off sc1
	v_mfma_f32_32x32x16_bf16 v[0:15], v[138:141], v[146:149], v[0:15]
	global_load_lds_dwordx4 v[114:115], off offset:1024 sc1
	v_mfma_f32_32x32x16_bf16 v[202:217], v[138:141], v[150:153], v[202:217]
	v_mfma_f32_32x32x16_bf16 v[226:241], v[138:141], v[154:157], v[226:241]
	s_waitcnt vmcnt(6)
	s_waitcnt lgkmcnt(0)
	s_barrier
	ds_read_b128 v[134:137], v113
	ds_read_b128 v[142:145], v119 offset:8192
	v_mfma_f32_32x32x16_bf16 v[32:47], v[158:161], v[166:169], v[32:47]
	ds_read_b128 v[146:149], v119 offset:10240
	ds_read_b128 v[150:153], v119 offset:49152
	v_mfma_f32_32x32x16_bf16 v[48:63], v[158:161], v[244:247], v[48:63]
	ds_read_b128 v[154:157], v119 offset:51200
	ds_read_b128 v[138:141], v113 offset:2048
	v_mfma_f32_32x32x16_bf16 v[170:185], v[158:161], v[250:253], v[170:185]
	v_mfma_f32_32x32x16_bf16 v[186:201], v[158:161], v[128:131], v[186:201]
	ds_read_b128 v[158:161], v122
	v_mfma_f32_32x32x16_bf16 v[16:31], v[162:165], v[166:169], v[16:31]
	ds_read_b128 v[166:169], v125 offset:8192
	v_mfma_f32_32x32x16_bf16 v[0:15], v[162:165], v[244:247], v[0:15]
	ds_read_b128 v[244:247], v125 offset:10240
	v_mfma_f32_32x32x16_bf16 v[202:217], v[162:165], v[250:253], v[202:217]
	ds_read_b128 v[250:253], v125 offset:49152
	v_mfma_f32_32x32x16_bf16 v[226:241], v[162:165], v[128:131], v[226:241]
	ds_read_b128 v[162:165], v122 offset:2048
	ds_read_b128 v[128:131], v125 offset:51200
	s_waitcnt lgkmcnt(6)
	v_mfma_f32_32x32x16_bf16 v[32:47], v[134:137], v[142:145], v[32:47]
	v_mfma_f32_32x32x16_bf16 v[48:63], v[134:137], v[146:149], v[48:63]
	v_mfma_f32_32x32x16_bf16 v[170:185], v[134:137], v[150:153], v[170:185]
	v_mfma_f32_32x32x16_bf16 v[186:201], v[134:137], v[154:157], v[186:201]
	v_mfma_f32_32x32x16_bf16 v[16:31], v[138:141], v[142:145], v[16:31]
	v_mfma_f32_32x32x16_bf16 v[0:15], v[138:141], v[146:149], v[0:15]
	v_mfma_f32_32x32x16_bf16 v[202:217], v[138:141], v[150:153], v[202:217]
	v_mfma_f32_32x32x16_bf16 v[226:241], v[138:141], v[154:157], v[226:241]
	s_waitcnt vmcnt(0)
	s_waitcnt lgkmcnt(0)
	s_barrier
	ds_read_b128 v[134:137], v113 offset:16384
	ds_read_b128 v[142:145], v119 offset:24576
	v_mfma_f32_32x32x16_bf16 v[32:47], v[158:161], v[166:169], v[32:47]
	ds_read_b128 v[146:149], v119 offset:26624
	ds_read_b128 v[150:153], v132 offset:40960
	v_mfma_f32_32x32x16_bf16 v[48:63], v[158:161], v[244:247], v[48:63]
	ds_read_b128 v[154:157], v132 offset:43008
	ds_read_b128 v[138:141], v113 offset:18432
	v_mfma_f32_32x32x16_bf16 v[170:185], v[158:161], v[250:253], v[170:185]
	v_mfma_f32_32x32x16_bf16 v[186:201], v[158:161], v[128:131], v[186:201]
	ds_read_b128 v[158:161], v122 offset:16384
	v_mfma_f32_32x32x16_bf16 v[16:31], v[162:165], v[166:169], v[16:31]
	ds_read_b128 v[166:169], v125 offset:24576
	v_mfma_f32_32x32x16_bf16 v[0:15], v[162:165], v[244:247], v[0:15]
	ds_read_b128 v[244:247], v125 offset:26624
	v_mfma_f32_32x32x16_bf16 v[202:217], v[162:165], v[250:253], v[202:217]
	ds_read_b128 v[250:253], v133 offset:40960
	v_mfma_f32_32x32x16_bf16 v[226:241], v[162:165], v[128:131], v[226:241]
	ds_read_b128 v[162:165], v122 offset:18432
	ds_read_b128 v[128:131], v133 offset:43008
	s_waitcnt lgkmcnt(6)
	v_mfma_f32_32x32x16_bf16 v[32:47], v[134:137], v[142:145], v[32:47]
	v_mfma_f32_32x32x16_bf16 v[48:63], v[134:137], v[146:149], v[48:63]
	v_mfma_f32_32x32x16_bf16 v[170:185], v[134:137], v[150:153], v[170:185]
	v_mfma_f32_32x32x16_bf16 v[186:201], v[134:137], v[154:157], v[186:201]
	v_mfma_f32_32x32x16_bf16 v[16:31], v[138:141], v[142:145], v[16:31]
	v_mfma_f32_32x32x16_bf16 v[0:15], v[138:141], v[146:149], v[0:15]
	v_mfma_f32_32x32x16_bf16 v[202:217], v[138:141], v[150:153], v[202:217]
	v_mfma_f32_32x32x16_bf16 v[226:241], v[138:141], v[154:157], v[226:241]
	s_waitcnt lgkmcnt(0)
	v_mfma_f32_32x32x16_bf16 v[32:47], v[158:161], v[166:169], v[32:47]
	v_mfma_f32_32x32x16_bf16 v[48:63], v[158:161], v[244:247], v[48:63]
	v_mfma_f32_32x32x16_bf16 v[170:185], v[158:161], v[250:253], v[170:185]
	v_mfma_f32_32x32x16_bf16 v[186:201], v[158:161], v[128:131], v[186:201]
	v_mfma_f32_32x32x16_bf16 v[16:31], v[162:165], v[166:169], v[16:31]
	v_mfma_f32_32x32x16_bf16 v[0:15], v[162:165], v[244:247], v[0:15]
	v_mfma_f32_32x32x16_bf16 v[202:217], v[162:165], v[250:253], v[202:217]
	v_mfma_f32_32x32x16_bf16 v[226:241], v[162:165], v[128:131], v[226:241]
	v_add_u32_e32 v132, 0x400, v100
	v_add_u32_e32 v131, 0x2000, v100
	v_add_u32_e32 v130, 0x2400, v100
	v_add_u32_e32 v129, 0x4000, v100
	v_add_u32_e32 v128, 0x4400, v100
	v_add_u32_e32 v125, 0x6000, v100
	v_add_u32_e32 v122, 0x6400, v100
	v_add_u32_e32 v119, 0x8000, v100
	v_add_u32_e32 v115, 0x8400, v100
	v_add_u32_e32 v114, 0xa000, v100
	v_add_u32_e32 v113, 0xa400, v100
	s_branch .Lin_post
.Lin_single:
	v_add_u32_e32 v133, v101, v103
	v_add_u32_e32 v134, v102, v103
	v_add_u32_e32 v135, v101, v104
	v_add_u32_e32 v136, v102, v104
	v_readfirstlane_b32 s52, v100
	s_mov_b64 s[50:51], 0x4000
	s_add_u32 s53, s52, 0x4000
	s_add_u32 s54, s52, 0x8000
	s_add_u32 s55, s52, 0xc000
	s_add_u32 s56, s52, 0x2000
	s_add_u32 s57, s52, 0x6000
	s_add_u32 s58, s52, 0xa000
	s_add_u32 s59, s52, 0xe000
	v_lshl_add_u64 v[96:97], v[96:97], 0, s[50:51]
	v_lshl_add_u64 v[98:99], v[98:99], 0, s[50:51]
	s_waitcnt lgkmcnt(0)
	s_barrier
	ds_read_b128 v[140:143], v133
	ds_read_b128 v[148:151], v134 offset:8192
	ds_read_b128 v[152:155], v134 offset:10240
	ds_read_b128 v[144:147], v133 offset:2048
	ds_read_b128 v[156:159], v135
	ds_read_b128 v[164:167], v136 offset:8192
	ds_read_b128 v[168:171], v136 offset:10240
	ds_read_b128 v[160:163], v135 offset:2048
	s_mov_b32 m0, s55
	v_lshl_add_u64 v[96:97], v[96:97], 0, s[44:45]
	global_load_lds_dwordx4 v[96:97], off sc1
	global_load_lds_dwordx4 v[96:97], off offset:1024 sc1
	s_mov_b32 m0, s59
	v_lshl_add_u64 v[98:99], v[98:99], 0, s[44:45]
	global_load_lds_dwordx4 v[98:99], off sc1
	global_load_lds_dwordx4 v[98:99], off offset:1024 sc1
	s_waitcnt vmcnt(8)
	s_waitcnt lgkmcnt(0)
	s_barrier
	ds_read_b128 v[172:175], v133 offset:16384
	ds_read_b128 v[184:187], v134 offset:24576
	v_mfma_f32_32x32x16_bf16 v[32:47], v[140:143], v[148:151], 0
	ds_read_b128 v[188:191], v134 offset:26624
	ds_read_b128 v[176:179], v133 offset:18432
	v_mfma_f32_32x32x16_bf16 v[48:63], v[140:143], v[152:155], 0
	ds_read_b128 v[192:195], v135 offset:16384
	ds_read_b128 v[200:203], v136 offset:24576
	v_mfma_f32_32x32x16_bf16 v[16:31], v[144:147], v[148:151], 0
	ds_read_b128 v[204:207], v136 offset:26624
	ds_read_b128 v[196:199], v135 offset:18432
	v_mfma_f32_32x32x16_bf16 v[0:15], v[144:147], v[152:155], 0
	s_mov_b32 m0, s52
	v_lshl_add_u64 v[96:97], v[96:97], 0, s[44:45]
	global_load_lds_dwordx4 v[96:97], off sc1
	v_mfma_f32_32x32x16_bf16 v[32:47], v[156:159], v[164:167], v[32:47]
	global_load_lds_dwordx4 v[96:97], off offset:1024 sc1
	v_mfma_f32_32x32x16_bf16 v[48:63], v[156:159], v[168:171], v[48:63]
	s_mov_b32 m0, s56
	v_lshl_add_u64 v[98:99], v[98:99], 0, s[44:45]
	global_load_lds_dwordx4 v[98:99], off sc1
	v_mfma_f32_32x32x16_bf16 v[16:31], v[160:163], v[164:167], v[16:31]
	global_load_lds_dwordx4 v[98:99], off offset:1024 sc1
	v_mfma_f32_32x32x16_bf16 v[0:15], v[160:163], v[168:171], v[0:15]
	s_waitcnt vmcnt(8)
	s_waitcnt lgkmcnt(0)
	s_barrier
	ds_read_b128 v[140:143], v133 offset:32768
	ds_read_b128 v[148:151], v134 offset:40960
	v_mfma_f32_32x32x16_bf16 v[32:47], v[172:175], v[184:187], v[32:47]
	ds_read_b128 v[152:155], v134 offset:43008
	ds_read_b128 v[144:147], v133 offset:34816
	v_mfma_f32_32x32x16_bf16 v[48:63], v[172:175], v[188:191], v[48:63]
	ds_read_b128 v[156:159], v135 offset:32768
	ds_read_b128 v[164:167], v136 offset:40960
	v_mfma_f32_32x32x16_bf16 v[16:31], v[176:179], v[184:187], v[16:31]
	ds_read_b128 v[168:171], v136 offset:43008
	ds_read_b128 v[160:163], v135 offset:34816
	v_mfma_f32_32x32x16_bf16 v[0:15], v[176:179], v[188:191], v[0:15]
	s_mov_b32 m0, s53
	v_lshl_add_u64 v[96:97], v[96:97], 0, s[44:45]
	global_load_lds_dwordx4 v[96:97], off sc1
	v_mfma_f32_32x32x16_bf16 v[32:47], v[192:195], v[200:203], v[32:47]
	global_load_lds_dwordx4 v[96:97], off offset:1024 sc1
	v_mfma_f32_32x32x16_bf16 v[48:63], v[192:195], v[204:207], v[48:63]
	s_mov_b32 m0, s57
	v_lshl_add_u64 v[98:99], v[98:99], 0, s[44:45]
	global_load_lds_dwordx4 v[98:99], off sc1
	v_mfma_f32_32x32x16_bf16 v[16:31], v[196:199], v[200:203], v[16:31]
	global_load_lds_dwordx4 v[98:99], off offset:1024 sc1
	v_mfma_f32_32x32x16_bf16 v[0:15], v[196:199], v[204:207], v[0:15]
	s_waitcnt vmcnt(8)
	s_waitcnt lgkmcnt(0)
	s_barrier
	ds_read_b128 v[172:175], v133 offset:49152
	ds_read_b128 v[184:187], v134 offset:57344
	v_mfma_f32_32x32x16_bf16 v[32:47], v[140:143], v[148:151], v[32:47]
	ds_read_b128 v[188:191], v134 offset:59392
	ds_read_b128 v[176:179], v133 offset:51200
	v_mfma_f32_32x32x16_bf16 v[48:63], v[140:143], v[152:155], v[48:63]
	ds_read_b128 v[192:195], v135 offset:49152
	ds_read_b128 v[200:203], v136 offset:57344
	v_mfma_f32_32x32x16_bf16 v[16:31], v[144:147], v[148:151], v[16:31]
	ds_read_b128 v[204:207], v136 offset:59392
	ds_read_b128 v[196:199], v135 offset:51200
	v_mfma_f32_32x32x16_bf16 v[0:15], v[144:147], v[152:155], v[0:15]
	s_mov_b32 m0, s54
	v_lshl_add_u64 v[96:97], v[96:97], 0, s[44:45]
	global_load_lds_dwordx4 v[96:97], off sc1
	v_mfma_f32_32x32x16_bf16 v[32:47], v[156:159], v[164:167], v[32:47]
	global_load_lds_dwordx4 v[96:97], off offset:1024 sc1
	v_mfma_f32_32x32x16_bf16 v[48:63], v[156:159], v[168:171], v[48:63]
	s_mov_b32 m0, s58
	v_lshl_add_u64 v[98:99], v[98:99], 0, s[44:45]
	global_load_lds_dwordx4 v[98:99], off sc1
	v_mfma_f32_32x32x16_bf16 v[16:31], v[160:163], v[164:167], v[16:31]
	global_load_lds_dwordx4 v[98:99], off offset:1024 sc1
	v_mfma_f32_32x32x16_bf16 v[0:15], v[160:163], v[168:171], v[0:15]
	s_waitcnt vmcnt(8)
	s_waitcnt lgkmcnt(0)
	s_barrier
	ds_read_b128 v[140:143], v133
	ds_read_b128 v[148:151], v134 offset:8192
	v_mfma_f32_32x32x16_bf16 v[32:47], v[172:175], v[184:187], v[32:47]
	ds_read_b128 v[152:155], v134 offset:10240
	ds_read_b128 v[144:147], v133 offset:2048
	v_mfma_f32_32x32x16_bf16 v[48:63], v[172:175], v[188:191], v[48:63]
	ds_read_b128 v[156:159], v135
	ds_read_b128 v[164:167], v136 offset:8192
	v_mfma_f32_32x32x16_bf16 v[16:31], v[176:179], v[184:187], v[16:31]
	ds_read_b128 v[168:171], v136 offset:10240
	ds_read_b128 v[160:163], v135 offset:2048
	v_mfma_f32_32x32x16_bf16 v[0:15], v[176:179], v[188:191], v[0:15]
	s_mov_b32 m0, s55
	v_lshl_add_u64 v[96:97], v[96:97], 0, s[44:45]
	global_load_lds_dwordx4 v[96:97], off sc1
	v_mfma_f32_32x32x16_bf16 v[32:47], v[192:195], v[200:203], v[32:47]
	global_load_lds_dwordx4 v[96:97], off offset:1024 sc1
	v_mfma_f32_32x32x16_bf16 v[48:63], v[192:195], v[204:207], v[48:63]
	s_mov_b32 m0, s59
	v_lshl_add_u64 v[98:99], v[98:99], 0, s[44:45]
	global_load_lds_dwordx4 v[98:99], off sc1
	v_mfma_f32_32x32x16_bf16 v[16:31], v[196:199], v[200:203], v[16:31]
	global_load_lds_dwordx4 v[98:99], off offset:1024 sc1
	v_mfma_f32_32x32x16_bf16 v[0:15], v[196:199], v[204:207], v[0:15]
	s_waitcnt vmcnt(8)
	s_waitcnt lgkmcnt(0)
	s_barrier
	ds_read_b128 v[172:175], v133 offset:16384
	ds_read_b128 v[184:187], v134 offset:24576
	v_mfma_f32_32x32x16_bf16 v[32:47], v[140:143], v[148:151], v[32:47]
	ds_read_b128 v[188:191], v134 offset:26624
	ds_read_b128 v[176:179], v133 offset:18432
	v_mfma_f32_32x32x16_bf16 v[48:63], v[140:143], v[152:155], v[48:63]
	ds_read_b128 v[192:195], v135 offset:16384
	ds_read_b128 v[200:203], v136 offset:24576
	v_mfma_f32_32x32x16_bf16 v[16:31], v[144:147], v[148:151], v[16:31]
	ds_read_b128 v[204:207], v136 offset:26624
	ds_read_b128 v[196:199], v135 offset:18432
	v_mfma_f32_32x32x16_bf16 v[0:15], v[144:147], v[152:155], v[0:15]
	s_mov_b32 m0, s52
	v_lshl_add_u64 v[96:97], v[96:97], 0, s[44:45]
	global_load_lds_dwordx4 v[96:97], off sc1
	v_mfma_f32_32x32x16_bf16 v[32:47], v[156:159], v[164:167], v[32:47]
	global_load_lds_dwordx4 v[96:97], off offset:1024 sc1
	v_mfma_f32_32x32x16_bf16 v[48:63], v[156:159], v[168:171], v[48:63]
	s_mov_b32 m0, s56
	v_lshl_add_u64 v[98:99], v[98:99], 0, s[44:45]
	global_load_lds_dwordx4 v[98:99], off sc1
	v_mfma_f32_32x32x16_bf16 v[16:31], v[160:163], v[164:167], v[16:31]
	global_load_lds_dwordx4 v[98:99], off offset:1024 sc1
	v_mfma_f32_32x32x16_bf16 v[0:15], v[160:163], v[168:171], v[0:15]
	s_waitcnt vmcnt(8)
	s_waitcnt lgkmcnt(0)
	s_barrier
	ds_read_b128 v[140:143], v133 offset:32768
	ds_read_b128 v[148:151], v134 offset:40960
	v_mfma_f32_32x32x16_bf16 v[32:47], v[172:175], v[184:187], v[32:47]
	ds_read_b128 v[152:155], v134 offset:43008
	ds_read_b128 v[144:147], v133 offset:34816
	v_mfma_f32_32x32x16_bf16 v[48:63], v[172:175], v[188:191], v[48:63]
	ds_read_b128 v[156:159], v135 offset:32768
	ds_read_b128 v[164:167], v136 offset:40960
	v_mfma_f32_32x32x16_bf16 v[16:31], v[176:179], v[184:187], v[16:31]
	ds_read_b128 v[168:171], v136 offset:43008
	ds_read_b128 v[160:163], v135 offset:34816
	v_mfma_f32_32x32x16_bf16 v[0:15], v[176:179], v[188:191], v[0:15]
	s_mov_b32 m0, s53
	v_lshl_add_u64 v[96:97], v[96:97], 0, s[44:45]
	global_load_lds_dwordx4 v[96:97], off sc1
	v_mfma_f32_32x32x16_bf16 v[32:47], v[192:195], v[200:203], v[32:47]
	global_load_lds_dwordx4 v[96:97], off offset:1024 sc1
	v_mfma_f32_32x32x16_bf16 v[48:63], v[192:195], v[204:207], v[48:63]
	s_mov_b32 m0, s57
	v_lshl_add_u64 v[98:99], v[98:99], 0, s[44:45]
	global_load_lds_dwordx4 v[98:99], off sc1
	v_mfma_f32_32x32x16_bf16 v[16:31], v[196:199], v[200:203], v[16:31]
	global_load_lds_dwordx4 v[98:99], off offset:1024 sc1
	v_mfma_f32_32x32x16_bf16 v[0:15], v[196:199], v[204:207], v[0:15]
	s_waitcnt vmcnt(8)
	s_waitcnt lgkmcnt(0)
	s_barrier
	ds_read_b128 v[172:175], v133 offset:49152
	ds_read_b128 v[184:187], v134 offset:57344
	v_mfma_f32_32x32x16_bf16 v[32:47], v[140:143], v[148:151], v[32:47]
	ds_read_b128 v[188:191], v134 offset:59392
	ds_read_b128 v[176:179], v133 offset:51200
	v_mfma_f32_32x32x16_bf16 v[48:63], v[140:143], v[152:155], v[48:63]
	ds_read_b128 v[192:195], v135 offset:49152
	ds_read_b128 v[200:203], v136 offset:57344
	v_mfma_f32_32x32x16_bf16 v[16:31], v[144:147], v[148:151], v[16:31]
	ds_read_b128 v[204:207], v136 offset:59392
	ds_read_b128 v[196:199], v135 offset:51200
	v_mfma_f32_32x32x16_bf16 v[0:15], v[144:147], v[152:155], v[0:15]
	s_mov_b32 m0, s54
	v_lshl_add_u64 v[96:97], v[96:97], 0, s[44:45]
	global_load_lds_dwordx4 v[96:97], off sc1
	v_mfma_f32_32x32x16_bf16 v[32:47], v[156:159], v[164:167], v[32:47]
	global_load_lds_dwordx4 v[96:97], off offset:1024 sc1
	v_mfma_f32_32x32x16_bf16 v[48:63], v[156:159], v[168:171], v[48:63]
	s_mov_b32 m0, s58
	v_lshl_add_u64 v[98:99], v[98:99], 0, s[44:45]
	global_load_lds_dwordx4 v[98:99], off sc1
	v_mfma_f32_32x32x16_bf16 v[16:31], v[160:163], v[164:167], v[16:31]
	global_load_lds_dwordx4 v[98:99], off offset:1024 sc1
	v_mfma_f32_32x32x16_bf16 v[0:15], v[160:163], v[168:171], v[0:15]
	s_waitcnt vmcnt(8)
	s_waitcnt lgkmcnt(0)
	s_barrier
	ds_read_b128 v[140:143], v133
	ds_read_b128 v[148:151], v134 offset:8192
	v_mfma_f32_32x32x16_bf16 v[32:47], v[172:175], v[184:187], v[32:47]
	ds_read_b128 v[152:155], v134 offset:10240
	ds_read_b128 v[144:147], v133 offset:2048
	v_mfma_f32_32x32x16_bf16 v[48:63], v[172:175], v[188:191], v[48:63]
	ds_read_b128 v[156:159], v135
	ds_read_b128 v[164:167], v136 offset:8192
	v_mfma_f32_32x32x16_bf16 v[16:31], v[176:179], v[184:187], v[16:31]
	ds_read_b128 v[168:171], v136 offset:10240
	ds_read_b128 v[160:163], v135 offset:2048
	v_mfma_f32_32x32x16_bf16 v[0:15], v[176:179], v[188:191], v[0:15]
	s_mov_b32 m0, s55
	v_lshl_add_u64 v[96:97], v[96:97], 0, s[44:45]
	global_load_lds_dwordx4 v[96:97], off sc1
	v_mfma_f32_32x32x16_bf16 v[32:47], v[192:195], v[200:203], v[32:47]
	global_load_lds_dwordx4 v[96:97], off offset:1024 sc1
	v_mfma_f32_32x32x16_bf16 v[48:63], v[192:195], v[204:207], v[48:63]
	s_mov_b32 m0, s59
	v_lshl_add_u64 v[98:99], v[98:99], 0, s[44:45]
	global_load_lds_dwordx4 v[98:99], off sc1
	v_mfma_f32_32x32x16_bf16 v[16:31], v[196:199], v[200:203], v[16:31]
	global_load_lds_dwordx4 v[98:99], off offset:1024 sc1
	v_mfma_f32_32x32x16_bf16 v[0:15], v[196:199], v[204:207], v[0:15]
	s_waitcnt vmcnt(8)
	s_waitcnt lgkmcnt(0)
	s_barrier
	ds_read_b128 v[172:175], v133 offset:16384
	ds_read_b128 v[184:187], v134 offset:24576
	v_mfma_f32_32x32x16_bf16 v[32:47], v[140:143], v[148:151], v[32:47]
	ds_read_b128 v[188:191], v134 offset:26624
	ds_read_b128 v[176:179], v133 offset:18432
	v_mfma_f32_32x32x16_bf16 v[48:63], v[140:143], v[152:155], v[48:63]
	ds_read_b128 v[192:195], v135 offset:16384
	ds_read_b128 v[200:203], v136 offset:24576
	v_mfma_f32_32x32x16_bf16 v[16:31], v[144:147], v[148:151], v[16:31]
	ds_read_b128 v[204:207], v136 offset:26624
	ds_read_b128 v[196:199], v135 offset:18432
	v_mfma_f32_32x32x16_bf16 v[0:15], v[144:147], v[152:155], v[0:15]
	s_mov_b32 m0, s52
	v_lshl_add_u64 v[96:97], v[96:97], 0, s[44:45]
	global_load_lds_dwordx4 v[96:97], off sc1
	v_mfma_f32_32x32x16_bf16 v[32:47], v[156:159], v[164:167], v[32:47]
	global_load_lds_dwordx4 v[96:97], off offset:1024 sc1
	v_mfma_f32_32x32x16_bf16 v[48:63], v[156:159], v[168:171], v[48:63]
	s_mov_b32 m0, s56
	v_lshl_add_u64 v[98:99], v[98:99], 0, s[44:45]
	global_load_lds_dwordx4 v[98:99], off sc1
	v_mfma_f32_32x32x16_bf16 v[16:31], v[160:163], v[164:167], v[16:31]
	global_load_lds_dwordx4 v[98:99], off offset:1024 sc1
	v_mfma_f32_32x32x16_bf16 v[0:15], v[160:163], v[168:171], v[0:15]
	s_waitcnt vmcnt(8)
	s_waitcnt lgkmcnt(0)
	s_barrier
	ds_read_b128 v[140:143], v133 offset:32768
	ds_read_b128 v[148:151], v134 offset:40960
	v_mfma_f32_32x32x16_bf16 v[32:47], v[172:175], v[184:187], v[32:47]
	ds_read_b128 v[152:155], v134 offset:43008
	ds_read_b128 v[144:147], v133 offset:34816
	v_mfma_f32_32x32x16_bf16 v[48:63], v[172:175], v[188:191], v[48:63]
	ds_read_b128 v[156:159], v135 offset:32768
	ds_read_b128 v[164:167], v136 offset:40960
	v_mfma_f32_32x32x16_bf16 v[16:31], v[176:179], v[184:187], v[16:31]
	ds_read_b128 v[168:171], v136 offset:43008
	ds_read_b128 v[160:163], v135 offset:34816
	v_mfma_f32_32x32x16_bf16 v[0:15], v[176:179], v[188:191], v[0:15]
	s_mov_b32 m0, s53
	v_lshl_add_u64 v[96:97], v[96:97], 0, s[44:45]
	global_load_lds_dwordx4 v[96:97], off sc1
	v_mfma_f32_32x32x16_bf16 v[32:47], v[192:195], v[200:203], v[32:47]
	global_load_lds_dwordx4 v[96:97], off offset:1024 sc1
	v_mfma_f32_32x32x16_bf16 v[48:63], v[192:195], v[204:207], v[48:63]
	s_mov_b32 m0, s57
	v_lshl_add_u64 v[98:99], v[98:99], 0, s[44:45]
	global_load_lds_dwordx4 v[98:99], off sc1
	v_mfma_f32_32x32x16_bf16 v[16:31], v[196:199], v[200:203], v[16:31]
	global_load_lds_dwordx4 v[98:99], off offset:1024 sc1
	v_mfma_f32_32x32x16_bf16 v[0:15], v[196:199], v[204:207], v[0:15]
	s_waitcnt vmcnt(8)
	s_waitcnt lgkmcnt(0)
	s_barrier
	ds_read_b128 v[172:175], v133 offset:49152
	ds_read_b128 v[184:187], v134 offset:57344
	v_mfma_f32_32x32x16_bf16 v[32:47], v[140:143], v[148:151], v[32:47]
	ds_read_b128 v[188:191], v134 offset:59392
	ds_read_b128 v[176:179], v133 offset:51200
	v_mfma_f32_32x32x16_bf16 v[48:63], v[140:143], v[152:155], v[48:63]
	ds_read_b128 v[192:195], v135 offset:49152
	ds_read_b128 v[200:203], v136 offset:57344
	v_mfma_f32_32x32x16_bf16 v[16:31], v[144:147], v[148:151], v[16:31]
	ds_read_b128 v[204:207], v136 offset:59392
	ds_read_b128 v[196:199], v135 offset:51200
	v_mfma_f32_32x32x16_bf16 v[0:15], v[144:147], v[152:155], v[0:15]
	s_mov_b32 m0, s54
	v_lshl_add_u64 v[96:97], v[96:97], 0, s[44:45]
	global_load_lds_dwordx4 v[96:97], off sc1
	v_mfma_f32_32x32x16_bf16 v[32:47], v[156:159], v[164:167], v[32:47]
	global_load_lds_dwordx4 v[96:97], off offset:1024 sc1
	v_mfma_f32_32x32x16_bf16 v[48:63], v[156:159], v[168:171], v[48:63]
	s_mov_b32 m0, s58
	v_lshl_add_u64 v[98:99], v[98:99], 0, s[44:45]
	global_load_lds_dwordx4 v[98:99], off sc1
	v_mfma_f32_32x32x16_bf16 v[16:31], v[160:163], v[164:167], v[16:31]
	global_load_lds_dwordx4 v[98:99], off offset:1024 sc1
	v_mfma_f32_32x32x16_bf16 v[0:15], v[160:163], v[168:171], v[0:15]
	s_waitcnt vmcnt(8)
	s_waitcnt lgkmcnt(0)
	s_barrier
	ds_read_b128 v[140:143], v133
	ds_read_b128 v[148:151], v134 offset:8192
	v_mfma_f32_32x32x16_bf16 v[32:47], v[172:175], v[184:187], v[32:47]
	ds_read_b128 v[152:155], v134 offset:10240
	ds_read_b128 v[144:147], v133 offset:2048
	v_mfma_f32_32x32x16_bf16 v[48:63], v[172:175], v[188:191], v[48:63]
	ds_read_b128 v[156:159], v135
	ds_read_b128 v[164:167], v136 offset:8192
	v_mfma_f32_32x32x16_bf16 v[16:31], v[176:179], v[184:187], v[16:31]
	ds_read_b128 v[168:171], v136 offset:10240
	ds_read_b128 v[160:163], v135 offset:2048
	v_mfma_f32_32x32x16_bf16 v[0:15], v[176:179], v[188:191], v[0:15]
	s_mov_b32 m0, s55
	v_lshl_add_u64 v[96:97], v[96:97], 0, s[44:45]
	global_load_lds_dwordx4 v[96:97], off sc1
	v_mfma_f32_32x32x16_bf16 v[32:47], v[192:195], v[200:203], v[32:47]
	global_load_lds_dwordx4 v[96:97], off offset:1024 sc1
	v_mfma_f32_32x32x16_bf16 v[48:63], v[192:195], v[204:207], v[48:63]
	s_mov_b32 m0, s59
	v_lshl_add_u64 v[98:99], v[98:99], 0, s[44:45]
	global_load_lds_dwordx4 v[98:99], off sc1
	v_mfma_f32_32x32x16_bf16 v[16:31], v[196:199], v[200:203], v[16:31]
	global_load_lds_dwordx4 v[98:99], off offset:1024 sc1
	v_mfma_f32_32x32x16_bf16 v[0:15], v[196:199], v[204:207], v[0:15]
	s_waitcnt vmcnt(8)
	s_waitcnt lgkmcnt(0)
	s_barrier
	ds_read_b128 v[172:175], v133 offset:16384
	ds_read_b128 v[184:187], v134 offset:24576
	v_mfma_f32_32x32x16_bf16 v[32:47], v[140:143], v[148:151], v[32:47]
	ds_read_b128 v[188:191], v134 offset:26624
	ds_read_b128 v[176:179], v133 offset:18432
	v_mfma_f32_32x32x16_bf16 v[48:63], v[140:143], v[152:155], v[48:63]
	ds_read_b128 v[192:195], v135 offset:16384
	ds_read_b128 v[200:203], v136 offset:24576
	v_mfma_f32_32x32x16_bf16 v[16:31], v[144:147], v[148:151], v[16:31]
	ds_read_b128 v[204:207], v136 offset:26624
	ds_read_b128 v[196:199], v135 offset:18432
	v_mfma_f32_32x32x16_bf16 v[0:15], v[144:147], v[152:155], v[0:15]
	s_mov_b32 m0, s52
	v_lshl_add_u64 v[96:97], v[96:97], 0, s[44:45]
	global_load_lds_dwordx4 v[96:97], off sc1
	v_mfma_f32_32x32x16_bf16 v[32:47], v[156:159], v[164:167], v[32:47]
	global_load_lds_dwordx4 v[96:97], off offset:1024 sc1
	v_mfma_f32_32x32x16_bf16 v[48:63], v[156:159], v[168:171], v[48:63]
	s_mov_b32 m0, s56
	v_lshl_add_u64 v[98:99], v[98:99], 0, s[44:45]
	global_load_lds_dwordx4 v[98:99], off sc1
	v_mfma_f32_32x32x16_bf16 v[16:31], v[160:163], v[164:167], v[16:31]
	global_load_lds_dwordx4 v[98:99], off offset:1024 sc1
	v_mfma_f32_32x32x16_bf16 v[0:15], v[160:163], v[168:171], v[0:15]
	s_waitcnt vmcnt(8)
	s_waitcnt lgkmcnt(0)
	s_barrier
	ds_read_b128 v[140:143], v133 offset:32768
	ds_read_b128 v[148:151], v134 offset:40960
	v_mfma_f32_32x32x16_bf16 v[32:47], v[172:175], v[184:187], v[32:47]
	ds_read_b128 v[152:155], v134 offset:43008
	ds_read_b128 v[144:147], v133 offset:34816
	v_mfma_f32_32x32x16_bf16 v[48:63], v[172:175], v[188:191], v[48:63]
	ds_read_b128 v[156:159], v135 offset:32768
	ds_read_b128 v[164:167], v136 offset:40960
	v_mfma_f32_32x32x16_bf16 v[16:31], v[176:179], v[184:187], v[16:31]
	ds_read_b128 v[168:171], v136 offset:43008
	ds_read_b128 v[160:163], v135 offset:34816
	v_mfma_f32_32x32x16_bf16 v[0:15], v[176:179], v[188:191], v[0:15]
	s_mov_b32 m0, s53
	v_lshl_add_u64 v[96:97], v[96:97], 0, s[44:45]
	global_load_lds_dwordx4 v[96:97], off sc1
	v_mfma_f32_32x32x16_bf16 v[32:47], v[192:195], v[200:203], v[32:47]
	global_load_lds_dwordx4 v[96:97], off offset:1024 sc1
	v_mfma_f32_32x32x16_bf16 v[48:63], v[192:195], v[204:207], v[48:63]
	s_mov_b32 m0, s57
	v_lshl_add_u64 v[98:99], v[98:99], 0, s[44:45]
	global_load_lds_dwordx4 v[98:99], off sc1
	v_mfma_f32_32x32x16_bf16 v[16:31], v[196:199], v[200:203], v[16:31]
	global_load_lds_dwordx4 v[98:99], off offset:1024 sc1
	v_mfma_f32_32x32x16_bf16 v[0:15], v[196:199], v[204:207], v[0:15]
	s_waitcnt vmcnt(8)
	s_waitcnt lgkmcnt(0)
	s_barrier
	ds_read_b128 v[172:175], v133 offset:49152
	ds_read_b128 v[184:187], v134 offset:57344
	v_mfma_f32_32x32x16_bf16 v[32:47], v[140:143], v[148:151], v[32:47]
	ds_read_b128 v[188:191], v134 offset:59392
	ds_read_b128 v[176:179], v133 offset:51200
	v_mfma_f32_32x32x16_bf16 v[48:63], v[140:143], v[152:155], v[48:63]
	ds_read_b128 v[192:195], v135 offset:49152
	ds_read_b128 v[200:203], v136 offset:57344
	v_mfma_f32_32x32x16_bf16 v[16:31], v[144:147], v[148:151], v[16:31]
	ds_read_b128 v[204:207], v136 offset:59392
	ds_read_b128 v[196:199], v135 offset:51200
	v_mfma_f32_32x32x16_bf16 v[0:15], v[144:147], v[152:155], v[0:15]
	s_mov_b32 m0, s54
	v_lshl_add_u64 v[96:97], v[96:97], 0, s[44:45]
	global_load_lds_dwordx4 v[96:97], off sc1
	v_mfma_f32_32x32x16_bf16 v[32:47], v[156:159], v[164:167], v[32:47]
	global_load_lds_dwordx4 v[96:97], off offset:1024 sc1
	v_mfma_f32_32x32x16_bf16 v[48:63], v[156:159], v[168:171], v[48:63]
	s_mov_b32 m0, s58
	v_lshl_add_u64 v[98:99], v[98:99], 0, s[44:45]
	global_load_lds_dwordx4 v[98:99], off sc1
	v_mfma_f32_32x32x16_bf16 v[16:31], v[160:163], v[164:167], v[16:31]
	global_load_lds_dwordx4 v[98:99], off offset:1024 sc1
	v_mfma_f32_32x32x16_bf16 v[0:15], v[160:163], v[168:171], v[0:15]
	s_waitcnt vmcnt(8)
	s_waitcnt lgkmcnt(0)
	s_barrier
	ds_read_b128 v[140:143], v133
	ds_read_b128 v[148:151], v134 offset:8192
	v_mfma_f32_32x32x16_bf16 v[32:47], v[172:175], v[184:187], v[32:47]
	ds_read_b128 v[152:155], v134 offset:10240
	ds_read_b128 v[144:147], v133 offset:2048
	v_mfma_f32_32x32x16_bf16 v[48:63], v[172:175], v[188:191], v[48:63]
	ds_read_b128 v[156:159], v135
	ds_read_b128 v[164:167], v136 offset:8192
	v_mfma_f32_32x32x16_bf16 v[16:31], v[176:179], v[184:187], v[16:31]
	ds_read_b128 v[168:171], v136 offset:10240
	ds_read_b128 v[160:163], v135 offset:2048
	v_mfma_f32_32x32x16_bf16 v[0:15], v[176:179], v[188:191], v[0:15]
	s_mov_b32 m0, s55
	v_lshl_add_u64 v[96:97], v[96:97], 0, s[44:45]
	global_load_lds_dwordx4 v[96:97], off sc1
	v_mfma_f32_32x32x16_bf16 v[32:47], v[192:195], v[200:203], v[32:47]
	global_load_lds_dwordx4 v[96:97], off offset:1024 sc1
	v_mfma_f32_32x32x16_bf16 v[48:63], v[192:195], v[204:207], v[48:63]
	s_mov_b32 m0, s59
	v_lshl_add_u64 v[98:99], v[98:99], 0, s[44:45]
	global_load_lds_dwordx4 v[98:99], off sc1
	v_mfma_f32_32x32x16_bf16 v[16:31], v[196:199], v[200:203], v[16:31]
	global_load_lds_dwordx4 v[98:99], off offset:1024 sc1
	v_mfma_f32_32x32x16_bf16 v[0:15], v[196:199], v[204:207], v[0:15]
	s_waitcnt vmcnt(8)
	s_waitcnt lgkmcnt(0)
	s_barrier
	ds_read_b128 v[172:175], v133 offset:16384
	ds_read_b128 v[184:187], v134 offset:24576
	v_mfma_f32_32x32x16_bf16 v[32:47], v[140:143], v[148:151], v[32:47]
	ds_read_b128 v[188:191], v134 offset:26624
	ds_read_b128 v[176:179], v133 offset:18432
	v_mfma_f32_32x32x16_bf16 v[48:63], v[140:143], v[152:155], v[48:63]
	ds_read_b128 v[192:195], v135 offset:16384
	ds_read_b128 v[200:203], v136 offset:24576
	v_mfma_f32_32x32x16_bf16 v[16:31], v[144:147], v[148:151], v[16:31]
	ds_read_b128 v[204:207], v136 offset:26624
	ds_read_b128 v[196:199], v135 offset:18432
	v_mfma_f32_32x32x16_bf16 v[0:15], v[144:147], v[152:155], v[0:15]
	s_mov_b32 m0, s52
	v_lshl_add_u64 v[96:97], v[96:97], 0, s[44:45]
	global_load_lds_dwordx4 v[96:97], off sc1
	v_mfma_f32_32x32x16_bf16 v[32:47], v[156:159], v[164:167], v[32:47]
	global_load_lds_dwordx4 v[96:97], off offset:1024 sc1
	v_mfma_f32_32x32x16_bf16 v[48:63], v[156:159], v[168:171], v[48:63]
	s_mov_b32 m0, s56
	v_lshl_add_u64 v[98:99], v[98:99], 0, s[44:45]
	global_load_lds_dwordx4 v[98:99], off sc1
	v_mfma_f32_32x32x16_bf16 v[16:31], v[160:163], v[164:167], v[16:31]
	global_load_lds_dwordx4 v[98:99], off offset:1024 sc1
	v_mfma_f32_32x32x16_bf16 v[0:15], v[160:163], v[168:171], v[0:15]
	s_waitcnt vmcnt(8)
	s_waitcnt lgkmcnt(0)
	s_barrier
	ds_read_b128 v[140:143], v133 offset:32768
	ds_read_b128 v[148:151], v134 offset:40960
	v_mfma_f32_32x32x16_bf16 v[32:47], v[172:175], v[184:187], v[32:47]
	ds_read_b128 v[152:155], v134 offset:43008
	ds_read_b128 v[144:147], v133 offset:34816
	v_mfma_f32_32x32x16_bf16 v[48:63], v[172:175], v[188:191], v[48:63]
	ds_read_b128 v[156:159], v135 offset:32768
	ds_read_b128 v[164:167], v136 offset:40960
	v_mfma_f32_32x32x16_bf16 v[16:31], v[176:179], v[184:187], v[16:31]
	ds_read_b128 v[168:171], v136 offset:43008
	ds_read_b128 v[160:163], v135 offset:34816
	v_mfma_f32_32x32x16_bf16 v[0:15], v[176:179], v[188:191], v[0:15]
	s_mov_b32 m0, s53
	v_lshl_add_u64 v[96:97], v[96:97], 0, s[44:45]
	global_load_lds_dwordx4 v[96:97], off sc1
	v_mfma_f32_32x32x16_bf16 v[32:47], v[192:195], v[200:203], v[32:47]
	global_load_lds_dwordx4 v[96:97], off offset:1024 sc1
	v_mfma_f32_32x32x16_bf16 v[48:63], v[192:195], v[204:207], v[48:63]
	s_mov_b32 m0, s57
	v_lshl_add_u64 v[98:99], v[98:99], 0, s[44:45]
	global_load_lds_dwordx4 v[98:99], off sc1
	v_mfma_f32_32x32x16_bf16 v[16:31], v[196:199], v[200:203], v[16:31]
	global_load_lds_dwordx4 v[98:99], off offset:1024 sc1
	v_mfma_f32_32x32x16_bf16 v[0:15], v[196:199], v[204:207], v[0:15]
	s_waitcnt vmcnt(8)
	s_waitcnt lgkmcnt(0)
	s_barrier
	ds_read_b128 v[172:175], v133 offset:49152
	ds_read_b128 v[184:187], v134 offset:57344
	v_mfma_f32_32x32x16_bf16 v[32:47], v[140:143], v[148:151], v[32:47]
	ds_read_b128 v[188:191], v134 offset:59392
	ds_read_b128 v[176:179], v133 offset:51200
	v_mfma_f32_32x32x16_bf16 v[48:63], v[140:143], v[152:155], v[48:63]
	ds_read_b128 v[192:195], v135 offset:49152
	ds_read_b128 v[200:203], v136 offset:57344
	v_mfma_f32_32x32x16_bf16 v[16:31], v[144:147], v[148:151], v[16:31]
	ds_read_b128 v[204:207], v136 offset:59392
	ds_read_b128 v[196:199], v135 offset:51200
	v_mfma_f32_32x32x16_bf16 v[0:15], v[144:147], v[152:155], v[0:15]
	s_mov_b32 m0, s54
	v_lshl_add_u64 v[96:97], v[96:97], 0, s[44:45]
	global_load_lds_dwordx4 v[96:97], off sc1
	v_mfma_f32_32x32x16_bf16 v[32:47], v[156:159], v[164:167], v[32:47]
	global_load_lds_dwordx4 v[96:97], off offset:1024 sc1
	v_mfma_f32_32x32x16_bf16 v[48:63], v[156:159], v[168:171], v[48:63]
	s_mov_b32 m0, s58
	v_lshl_add_u64 v[98:99], v[98:99], 0, s[44:45]
	global_load_lds_dwordx4 v[98:99], off sc1
	v_mfma_f32_32x32x16_bf16 v[16:31], v[160:163], v[164:167], v[16:31]
	global_load_lds_dwordx4 v[98:99], off offset:1024 sc1
	v_mfma_f32_32x32x16_bf16 v[0:15], v[160:163], v[168:171], v[0:15]
	s_waitcnt vmcnt(8)
	s_waitcnt lgkmcnt(0)
	s_barrier
	ds_read_b128 v[140:143], v133
	ds_read_b128 v[148:151], v134 offset:8192
	v_mfma_f32_32x32x16_bf16 v[32:47], v[172:175], v[184:187], v[32:47]
	ds_read_b128 v[152:155], v134 offset:10240
	ds_read_b128 v[144:147], v133 offset:2048
	v_mfma_f32_32x32x16_bf16 v[48:63], v[172:175], v[188:191], v[48:63]
	ds_read_b128 v[156:159], v135
	ds_read_b128 v[164:167], v136 offset:8192
	v_mfma_f32_32x32x16_bf16 v[16:31], v[176:179], v[184:187], v[16:31]
	ds_read_b128 v[168:171], v136 offset:10240
	ds_read_b128 v[160:163], v135 offset:2048
	v_mfma_f32_32x32x16_bf16 v[0:15], v[176:179], v[188:191], v[0:15]
	s_mov_b32 m0, s55
	v_lshl_add_u64 v[96:97], v[96:97], 0, s[44:45]
	global_load_lds_dwordx4 v[96:97], off sc1
	v_mfma_f32_32x32x16_bf16 v[32:47], v[192:195], v[200:203], v[32:47]
	global_load_lds_dwordx4 v[96:97], off offset:1024 sc1
	v_mfma_f32_32x32x16_bf16 v[48:63], v[192:195], v[204:207], v[48:63]
	s_mov_b32 m0, s59
	v_lshl_add_u64 v[98:99], v[98:99], 0, s[44:45]
	global_load_lds_dwordx4 v[98:99], off sc1
	v_mfma_f32_32x32x16_bf16 v[16:31], v[196:199], v[200:203], v[16:31]
	global_load_lds_dwordx4 v[98:99], off offset:1024 sc1
	v_mfma_f32_32x32x16_bf16 v[0:15], v[196:199], v[204:207], v[0:15]
	s_waitcnt vmcnt(8)
	s_waitcnt lgkmcnt(0)
	s_barrier
	ds_read_b128 v[172:175], v133 offset:16384
	ds_read_b128 v[184:187], v134 offset:24576
	v_mfma_f32_32x32x16_bf16 v[32:47], v[140:143], v[148:151], v[32:47]
	ds_read_b128 v[188:191], v134 offset:26624
	ds_read_b128 v[176:179], v133 offset:18432
	v_mfma_f32_32x32x16_bf16 v[48:63], v[140:143], v[152:155], v[48:63]
	ds_read_b128 v[192:195], v135 offset:16384
	ds_read_b128 v[200:203], v136 offset:24576
	v_mfma_f32_32x32x16_bf16 v[16:31], v[144:147], v[148:151], v[16:31]
	ds_read_b128 v[204:207], v136 offset:26624
	ds_read_b128 v[196:199], v135 offset:18432
	v_mfma_f32_32x32x16_bf16 v[0:15], v[144:147], v[152:155], v[0:15]
	s_mov_b32 m0, s52
	v_lshl_add_u64 v[96:97], v[96:97], 0, s[44:45]
	global_load_lds_dwordx4 v[96:97], off sc1
	v_mfma_f32_32x32x16_bf16 v[32:47], v[156:159], v[164:167], v[32:47]
	global_load_lds_dwordx4 v[96:97], off offset:1024 sc1
	v_mfma_f32_32x32x16_bf16 v[48:63], v[156:159], v[168:171], v[48:63]
	s_mov_b32 m0, s56
	v_lshl_add_u64 v[98:99], v[98:99], 0, s[44:45]
	global_load_lds_dwordx4 v[98:99], off sc1
	v_mfma_f32_32x32x16_bf16 v[16:31], v[160:163], v[164:167], v[16:31]
	global_load_lds_dwordx4 v[98:99], off offset:1024 sc1
	v_mfma_f32_32x32x16_bf16 v[0:15], v[160:163], v[168:171], v[0:15]
	s_waitcnt vmcnt(8)
	s_waitcnt lgkmcnt(0)
	s_barrier
	ds_read_b128 v[140:143], v133 offset:32768
	ds_read_b128 v[148:151], v134 offset:40960
	v_mfma_f32_32x32x16_bf16 v[32:47], v[172:175], v[184:187], v[32:47]
	ds_read_b128 v[152:155], v134 offset:43008
	ds_read_b128 v[144:147], v133 offset:34816
	v_mfma_f32_32x32x16_bf16 v[48:63], v[172:175], v[188:191], v[48:63]
	ds_read_b128 v[156:159], v135 offset:32768
	ds_read_b128 v[164:167], v136 offset:40960
	v_mfma_f32_32x32x16_bf16 v[16:31], v[176:179], v[184:187], v[16:31]
	ds_read_b128 v[168:171], v136 offset:43008
	ds_read_b128 v[160:163], v135 offset:34816
	v_mfma_f32_32x32x16_bf16 v[0:15], v[176:179], v[188:191], v[0:15]
	s_mov_b32 m0, s53
	v_lshl_add_u64 v[96:97], v[96:97], 0, s[44:45]
	global_load_lds_dwordx4 v[96:97], off sc1
	v_mfma_f32_32x32x16_bf16 v[32:47], v[192:195], v[200:203], v[32:47]
	global_load_lds_dwordx4 v[96:97], off offset:1024 sc1
	v_mfma_f32_32x32x16_bf16 v[48:63], v[192:195], v[204:207], v[48:63]
	s_mov_b32 m0, s57
	v_lshl_add_u64 v[98:99], v[98:99], 0, s[44:45]
	global_load_lds_dwordx4 v[98:99], off sc1
	v_mfma_f32_32x32x16_bf16 v[16:31], v[196:199], v[200:203], v[16:31]
	global_load_lds_dwordx4 v[98:99], off offset:1024 sc1
	v_mfma_f32_32x32x16_bf16 v[0:15], v[196:199], v[204:207], v[0:15]
	s_waitcnt vmcnt(8)
	s_waitcnt lgkmcnt(0)
	s_barrier
	ds_read_b128 v[172:175], v133 offset:49152
	ds_read_b128 v[184:187], v134 offset:57344
	v_mfma_f32_32x32x16_bf16 v[32:47], v[140:143], v[148:151], v[32:47]
	ds_read_b128 v[188:191], v134 offset:59392
	ds_read_b128 v[176:179], v133 offset:51200
	v_mfma_f32_32x32x16_bf16 v[48:63], v[140:143], v[152:155], v[48:63]
	ds_read_b128 v[192:195], v135 offset:49152
	ds_read_b128 v[200:203], v136 offset:57344
	v_mfma_f32_32x32x16_bf16 v[16:31], v[144:147], v[148:151], v[16:31]
	ds_read_b128 v[204:207], v136 offset:59392
	ds_read_b128 v[196:199], v135 offset:51200
	v_mfma_f32_32x32x16_bf16 v[0:15], v[144:147], v[152:155], v[0:15]
	s_mov_b32 m0, s54
	v_lshl_add_u64 v[96:97], v[96:97], 0, s[44:45]
	global_load_lds_dwordx4 v[96:97], off sc1
	v_mfma_f32_32x32x16_bf16 v[32:47], v[156:159], v[164:167], v[32:47]
	global_load_lds_dwordx4 v[96:97], off offset:1024 sc1
	v_mfma_f32_32x32x16_bf16 v[48:63], v[156:159], v[168:171], v[48:63]
	s_mov_b32 m0, s58
	v_lshl_add_u64 v[98:99], v[98:99], 0, s[44:45]
	global_load_lds_dwordx4 v[98:99], off sc1
	v_mfma_f32_32x32x16_bf16 v[16:31], v[160:163], v[164:167], v[16:31]
	global_load_lds_dwordx4 v[98:99], off offset:1024 sc1
	v_mfma_f32_32x32x16_bf16 v[0:15], v[160:163], v[168:171], v[0:15]
	s_waitcnt vmcnt(8)
	s_waitcnt lgkmcnt(0)
	s_barrier
	ds_read_b128 v[140:143], v133
	ds_read_b128 v[148:151], v134 offset:8192
	v_mfma_f32_32x32x16_bf16 v[32:47], v[172:175], v[184:187], v[32:47]
	ds_read_b128 v[152:155], v134 offset:10240
	ds_read_b128 v[144:147], v133 offset:2048
	v_mfma_f32_32x32x16_bf16 v[48:63], v[172:175], v[188:191], v[48:63]
	ds_read_b128 v[156:159], v135
	ds_read_b128 v[164:167], v136 offset:8192
	v_mfma_f32_32x32x16_bf16 v[16:31], v[176:179], v[184:187], v[16:31]
	ds_read_b128 v[168:171], v136 offset:10240
	ds_read_b128 v[160:163], v135 offset:2048
	v_mfma_f32_32x32x16_bf16 v[0:15], v[176:179], v[188:191], v[0:15]
	s_mov_b32 m0, s55
	v_lshl_add_u64 v[96:97], v[96:97], 0, s[44:45]
	global_load_lds_dwordx4 v[96:97], off sc1
	v_mfma_f32_32x32x16_bf16 v[32:47], v[192:195], v[200:203], v[32:47]
	global_load_lds_dwordx4 v[96:97], off offset:1024 sc1
	v_mfma_f32_32x32x16_bf16 v[48:63], v[192:195], v[204:207], v[48:63]
	s_mov_b32 m0, s59
	v_lshl_add_u64 v[98:99], v[98:99], 0, s[44:45]
	global_load_lds_dwordx4 v[98:99], off sc1
	v_mfma_f32_32x32x16_bf16 v[16:31], v[196:199], v[200:203], v[16:31]
	global_load_lds_dwordx4 v[98:99], off offset:1024 sc1
	v_mfma_f32_32x32x16_bf16 v[0:15], v[196:199], v[204:207], v[0:15]
	s_waitcnt vmcnt(8)
	s_waitcnt lgkmcnt(0)
	s_barrier
	ds_read_b128 v[172:175], v133 offset:16384
	ds_read_b128 v[184:187], v134 offset:24576
	v_mfma_f32_32x32x16_bf16 v[32:47], v[140:143], v[148:151], v[32:47]
	ds_read_b128 v[188:191], v134 offset:26624
	ds_read_b128 v[176:179], v133 offset:18432
	v_mfma_f32_32x32x16_bf16 v[48:63], v[140:143], v[152:155], v[48:63]
	ds_read_b128 v[192:195], v135 offset:16384
	ds_read_b128 v[200:203], v136 offset:24576
	v_mfma_f32_32x32x16_bf16 v[16:31], v[144:147], v[148:151], v[16:31]
	ds_read_b128 v[204:207], v136 offset:26624
	ds_read_b128 v[196:199], v135 offset:18432
	v_mfma_f32_32x32x16_bf16 v[0:15], v[144:147], v[152:155], v[0:15]
	s_mov_b32 m0, s52
	v_lshl_add_u64 v[96:97], v[96:97], 0, s[44:45]
	global_load_lds_dwordx4 v[96:97], off sc1
	v_mfma_f32_32x32x16_bf16 v[32:47], v[156:159], v[164:167], v[32:47]
	global_load_lds_dwordx4 v[96:97], off offset:1024 sc1
	v_mfma_f32_32x32x16_bf16 v[48:63], v[156:159], v[168:171], v[48:63]
	s_mov_b32 m0, s56
	v_lshl_add_u64 v[98:99], v[98:99], 0, s[44:45]
	global_load_lds_dwordx4 v[98:99], off sc1
	v_mfma_f32_32x32x16_bf16 v[16:31], v[160:163], v[164:167], v[16:31]
	global_load_lds_dwordx4 v[98:99], off offset:1024 sc1
	v_mfma_f32_32x32x16_bf16 v[0:15], v[160:163], v[168:171], v[0:15]
	s_waitcnt vmcnt(8)
	s_waitcnt lgkmcnt(0)
	s_barrier
	ds_read_b128 v[140:143], v133 offset:32768
	ds_read_b128 v[148:151], v134 offset:40960
	v_mfma_f32_32x32x16_bf16 v[32:47], v[172:175], v[184:187], v[32:47]
	ds_read_b128 v[152:155], v134 offset:43008
	ds_read_b128 v[144:147], v133 offset:34816
	v_mfma_f32_32x32x16_bf16 v[48:63], v[172:175], v[188:191], v[48:63]
	ds_read_b128 v[156:159], v135 offset:32768
	ds_read_b128 v[164:167], v136 offset:40960
	v_mfma_f32_32x32x16_bf16 v[16:31], v[176:179], v[184:187], v[16:31]
	ds_read_b128 v[168:171], v136 offset:43008
	ds_read_b128 v[160:163], v135 offset:34816
	v_mfma_f32_32x32x16_bf16 v[0:15], v[176:179], v[188:191], v[0:15]
	s_mov_b32 m0, s53
	v_lshl_add_u64 v[96:97], v[96:97], 0, s[44:45]
	global_load_lds_dwordx4 v[96:97], off sc1
	v_mfma_f32_32x32x16_bf16 v[32:47], v[192:195], v[200:203], v[32:47]
	global_load_lds_dwordx4 v[96:97], off offset:1024 sc1
	v_mfma_f32_32x32x16_bf16 v[48:63], v[192:195], v[204:207], v[48:63]
	s_mov_b32 m0, s57
	v_lshl_add_u64 v[98:99], v[98:99], 0, s[44:45]
	global_load_lds_dwordx4 v[98:99], off sc1
	v_mfma_f32_32x32x16_bf16 v[16:31], v[196:199], v[200:203], v[16:31]
	global_load_lds_dwordx4 v[98:99], off offset:1024 sc1
	v_mfma_f32_32x32x16_bf16 v[0:15], v[196:199], v[204:207], v[0:15]
	s_waitcnt vmcnt(8)
	s_waitcnt lgkmcnt(0)
	s_barrier
	ds_read_b128 v[172:175], v133 offset:49152
	ds_read_b128 v[184:187], v134 offset:57344
	v_mfma_f32_32x32x16_bf16 v[32:47], v[140:143], v[148:151], v[32:47]
	ds_read_b128 v[188:191], v134 offset:59392
	ds_read_b128 v[176:179], v133 offset:51200
	v_mfma_f32_32x32x16_bf16 v[48:63], v[140:143], v[152:155], v[48:63]
	ds_read_b128 v[192:195], v135 offset:49152
	ds_read_b128 v[200:203], v136 offset:57344
	v_mfma_f32_32x32x16_bf16 v[16:31], v[144:147], v[148:151], v[16:31]
	ds_read_b128 v[204:207], v136 offset:59392
	ds_read_b128 v[196:199], v135 offset:51200
	v_mfma_f32_32x32x16_bf16 v[0:15], v[144:147], v[152:155], v[0:15]
	s_mov_b32 m0, s54
	v_lshl_add_u64 v[96:97], v[96:97], 0, s[44:45]
	global_load_lds_dwordx4 v[96:97], off sc1
	v_mfma_f32_32x32x16_bf16 v[32:47], v[156:159], v[164:167], v[32:47]
	global_load_lds_dwordx4 v[96:97], off offset:1024 sc1
	v_mfma_f32_32x32x16_bf16 v[48:63], v[156:159], v[168:171], v[48:63]
	s_mov_b32 m0, s58
	v_lshl_add_u64 v[98:99], v[98:99], 0, s[44:45]
	global_load_lds_dwordx4 v[98:99], off sc1
	v_mfma_f32_32x32x16_bf16 v[16:31], v[160:163], v[164:167], v[16:31]
	global_load_lds_dwordx4 v[98:99], off offset:1024 sc1
	v_mfma_f32_32x32x16_bf16 v[0:15], v[160:163], v[168:171], v[0:15]
	s_waitcnt vmcnt(8)
	s_waitcnt lgkmcnt(0)
	s_barrier
	ds_read_b128 v[140:143], v133
	ds_read_b128 v[148:151], v134 offset:8192
	v_mfma_f32_32x32x16_bf16 v[32:47], v[172:175], v[184:187], v[32:47]
	ds_read_b128 v[152:155], v134 offset:10240
	ds_read_b128 v[144:147], v133 offset:2048
	v_mfma_f32_32x32x16_bf16 v[48:63], v[172:175], v[188:191], v[48:63]
	ds_read_b128 v[156:159], v135
	ds_read_b128 v[164:167], v136 offset:8192
	v_mfma_f32_32x32x16_bf16 v[16:31], v[176:179], v[184:187], v[16:31]
	ds_read_b128 v[168:171], v136 offset:10240
	ds_read_b128 v[160:163], v135 offset:2048
	v_mfma_f32_32x32x16_bf16 v[0:15], v[176:179], v[188:191], v[0:15]
	s_mov_b32 m0, s55
	v_lshl_add_u64 v[96:97], v[96:97], 0, s[44:45]
	global_load_lds_dwordx4 v[96:97], off sc1
	v_mfma_f32_32x32x16_bf16 v[32:47], v[192:195], v[200:203], v[32:47]
	global_load_lds_dwordx4 v[96:97], off offset:1024 sc1
	v_mfma_f32_32x32x16_bf16 v[48:63], v[192:195], v[204:207], v[48:63]
	s_mov_b32 m0, s59
	v_lshl_add_u64 v[98:99], v[98:99], 0, s[44:45]
	global_load_lds_dwordx4 v[98:99], off sc1
	v_mfma_f32_32x32x16_bf16 v[16:31], v[196:199], v[200:203], v[16:31]
	global_load_lds_dwordx4 v[98:99], off offset:1024 sc1
	v_mfma_f32_32x32x16_bf16 v[0:15], v[196:199], v[204:207], v[0:15]
	s_waitcnt vmcnt(8)
	s_waitcnt lgkmcnt(0)
	s_barrier
	ds_read_b128 v[172:175], v133 offset:16384
	ds_read_b128 v[184:187], v134 offset:24576
	v_mfma_f32_32x32x16_bf16 v[32:47], v[140:143], v[148:151], v[32:47]
	ds_read_b128 v[188:191], v134 offset:26624
	ds_read_b128 v[176:179], v133 offset:18432
	v_mfma_f32_32x32x16_bf16 v[48:63], v[140:143], v[152:155], v[48:63]
	ds_read_b128 v[192:195], v135 offset:16384
	ds_read_b128 v[200:203], v136 offset:24576
	v_mfma_f32_32x32x16_bf16 v[16:31], v[144:147], v[148:151], v[16:31]
	ds_read_b128 v[204:207], v136 offset:26624
	ds_read_b128 v[196:199], v135 offset:18432
	v_mfma_f32_32x32x16_bf16 v[0:15], v[144:147], v[152:155], v[0:15]
	v_mfma_f32_32x32x16_bf16 v[32:47], v[156:159], v[164:167], v[32:47]
	v_mfma_f32_32x32x16_bf16 v[48:63], v[156:159], v[168:171], v[48:63]
	v_mfma_f32_32x32x16_bf16 v[16:31], v[160:163], v[164:167], v[16:31]
	v_mfma_f32_32x32x16_bf16 v[0:15], v[160:163], v[168:171], v[0:15]
	s_waitcnt vmcnt(4)
	s_waitcnt lgkmcnt(0)
	s_barrier
	ds_read_b128 v[140:143], v133 offset:32768
	ds_read_b128 v[148:151], v134 offset:40960
	v_mfma_f32_32x32x16_bf16 v[32:47], v[172:175], v[184:187], v[32:47]
	ds_read_b128 v[152:155], v134 offset:43008
	ds_read_b128 v[144:147], v133 offset:34816
	v_mfma_f32_32x32x16_bf16 v[48:63], v[172:175], v[188:191], v[48:63]
	ds_read_b128 v[156:159], v135 offset:32768
	ds_read_b128 v[164:167], v136 offset:40960
	v_mfma_f32_32x32x16_bf16 v[16:31], v[176:179], v[184:187], v[16:31]
	ds_read_b128 v[168:171], v136 offset:43008
	ds_read_b128 v[160:163], v135 offset:34816
	v_mfma_f32_32x32x16_bf16 v[0:15], v[176:179], v[188:191], v[0:15]
	v_mfma_f32_32x32x16_bf16 v[32:47], v[192:195], v[200:203], v[32:47]
	v_mfma_f32_32x32x16_bf16 v[48:63], v[192:195], v[204:207], v[48:63]
	v_mfma_f32_32x32x16_bf16 v[16:31], v[196:199], v[200:203], v[16:31]
	v_mfma_f32_32x32x16_bf16 v[0:15], v[196:199], v[204:207], v[0:15]
	s_waitcnt vmcnt(0)
	s_waitcnt lgkmcnt(0)
	s_barrier
	ds_read_b128 v[172:175], v133 offset:49152
	ds_read_b128 v[184:187], v134 offset:57344
	v_mfma_f32_32x32x16_bf16 v[32:47], v[140:143], v[148:151], v[32:47]
	ds_read_b128 v[188:191], v134 offset:59392
	ds_read_b128 v[176:179], v133 offset:51200
	v_mfma_f32_32x32x16_bf16 v[48:63], v[140:143], v[152:155], v[48:63]
	ds_read_b128 v[192:195], v135 offset:49152
	ds_read_b128 v[200:203], v136 offset:57344
	v_mfma_f32_32x32x16_bf16 v[16:31], v[144:147], v[148:151], v[16:31]
	ds_read_b128 v[204:207], v136 offset:59392
	ds_read_b128 v[196:199], v135 offset:51200
	v_mfma_f32_32x32x16_bf16 v[0:15], v[144:147], v[152:155], v[0:15]
	v_mfma_f32_32x32x16_bf16 v[32:47], v[156:159], v[164:167], v[32:47]
	v_mfma_f32_32x32x16_bf16 v[48:63], v[156:159], v[168:171], v[48:63]
	v_mfma_f32_32x32x16_bf16 v[16:31], v[160:163], v[164:167], v[16:31]
	v_mfma_f32_32x32x16_bf16 v[0:15], v[160:163], v[168:171], v[0:15]
	s_waitcnt lgkmcnt(0)
	v_mfma_f32_32x32x16_bf16 v[32:47], v[172:175], v[184:187], v[32:47]
	v_mfma_f32_32x32x16_bf16 v[48:63], v[172:175], v[188:191], v[48:63]
	v_mfma_f32_32x32x16_bf16 v[16:31], v[176:179], v[184:187], v[16:31]
	v_mfma_f32_32x32x16_bf16 v[0:15], v[176:179], v[188:191], v[0:15]
	v_mfma_f32_32x32x16_bf16 v[32:47], v[192:195], v[200:203], v[32:47]
	v_mfma_f32_32x32x16_bf16 v[48:63], v[192:195], v[204:207], v[48:63]
	v_mfma_f32_32x32x16_bf16 v[16:31], v[196:199], v[200:203], v[16:31]
	v_mfma_f32_32x32x16_bf16 v[0:15], v[196:199], v[204:207], v[0:15]

.LBB0_298:
	s_or_b64 exec, exec, s[16:17]
	s_waitcnt lgkmcnt(0)
	s_andn2_b64 vcc, exec, s[14:15]
	s_mov_b64 s[66:67], 0x2400
	s_barrier
	s_cbranch_vccnz .LBB0_300
	s_ashr_i32 s14, s48, 7
	s_ashr_i32 s15, s14, 31
	s_lshl_b64 s[14:15], s[14:15], 18
	v_lshl_add_u64 v[96:97], v[64:65], 0, s[14:15]
	s_ashr_i32 s14, s43, 7
	s_ashr_i32 s15, s14, 31
	s_lshl_b64 s[14:15], s[14:15], 18
	v_readfirstlane_b32 s11, v100
	v_lshl_add_u64 v[98:99], v[66:67], 0, s[14:15]
	s_mov_b64 s[14:15], 0x400
	s_mov_b32 m0, s11
	v_readfirstlane_b32 s11, v132
	v_lshl_add_u64 v[134:135], v[96:97], 0, s[14:15]
	global_load_lds_dwordx4 v[96:97], off sc1
	s_mov_b32 m0, s11
	v_readfirstlane_b32 s11, v131
	global_load_lds_dwordx4 v[134:135], off sc1
	s_mov_b32 m0, s11
	v_readfirstlane_b32 s11, v130
	global_load_lds_dwordx4 v[98:99], off sc1
	v_lshl_add_u64 v[132:133], v[98:99], 0, s[14:15]
	s_mov_b32 m0, s11
	v_readfirstlane_b32 s11, v129
	global_load_lds_dwordx4 v[132:133], off sc1
	v_lshl_add_u64 v[130:131], v[96:97], 0, s[44:45]
	s_mov_b32 m0, s11
	v_readfirstlane_b32 s11, v128
	global_load_lds_dwordx4 v[130:131], off sc1
	v_lshl_add_u64 v[130:131], v[96:97], 0, s[66:67]
	s_mov_b32 m0, s11
	v_readfirstlane_b32 s11, v125
	global_load_lds_dwordx4 v[130:131], off sc1
	v_lshl_add_u64 v[128:129], v[98:99], 0, s[44:45]
	s_mov_b32 m0, s11
	v_readfirstlane_b32 s11, v122
	global_load_lds_dwordx4 v[128:129], off sc1
	v_lshl_add_u64 v[128:129], v[98:99], 0, s[66:67]
	s_mov_b32 m0, s11
	v_readfirstlane_b32 s11, v119
	global_load_lds_dwordx4 v[128:129], off sc1
	v_lshl_add_u64 v[128:129], v[96:97], 0, s[28:29]
	s_mov_b32 m0, s11
	s_mov_b64 s[14:15], 0x4400
	v_readfirstlane_b32 s11, v115
	global_load_lds_dwordx4 v[128:129], off sc1
	v_lshl_add_u64 v[96:97], v[96:97], 0, s[14:15]
	s_mov_b32 m0, s11
	v_readfirstlane_b32 s11, v114
	global_load_lds_dwordx4 v[96:97], off sc1
	v_lshl_add_u64 v[96:97], v[98:99], 0, s[28:29]
	s_mov_b32 m0, s11
	v_readfirstlane_b32 s11, v113
	global_load_lds_dwordx4 v[96:97], off sc1
	v_lshl_add_u64 v[96:97], v[98:99], 0, s[14:15]
	s_mov_b32 m0, s11
	s_nop 0
	global_load_lds_dwordx4 v[96:97], off sc1

.LBB0_317:
	v_lshl_add_u32 v62, s15, 2, v1
	v_mov_b64_e32 v[50:51], s[8:9]
	s_movk_i32 s0, 0x1c00
	v_mad_i64_i32 v[50:51], s[0:1], v62, s0, v[50:51]
	v_lshlrev_b32_e32 v116, 1, v0
	v_lshl_add_u64 v[56:57], v[50:51], 0, v[116:117]
	global_load_dword v37, v[56:57], off sc1
	global_load_dword v74, v[56:57], off offset:256 sc1
	global_load_dword v81, v[56:57], off offset:512 sc1
	global_load_dword v80, v[56:57], off offset:768 sc1
	global_load_dword v79, v[56:57], off offset:1024 sc1
	global_load_dword v77, v[56:57], off offset:1536 sc1
	global_load_dword v76, v[56:57], off offset:1792 sc1
	global_load_dword v78, v[56:57], off offset:2048 sc1
	global_load_dword v49, v[56:57], off offset:2304 sc1
	global_load_dword v35, v[56:57], off offset:2560 sc1
	s_movk_i32 s0, 0x1000
	v_cmp_gt_i32_e64 s[42:43], s0, v62
	s_movk_i32 s0, 0xfff
	v_cmp_lt_i32_e64 s[40:41], s0, v62
	v_mov_b32_e32 v39, 0xff
	v_mov_b32_e32 v41, 0x3ff
	v_cndmask_b32_e64 v39, v39, v41, s[40:41]
	v_mov_b32_e32 v54, 0
	v_mov_b32_e32 v52, 1.0
	v_ashrrev_i32_e32 v63, 31, v62
	v_and_b32_e32 v47, v39, v62
	v_mov_b32_e32 v53, v52
	v_mov_b32_e32 v55, v54
	s_and_saveexec_b64 s[0:1], s[40:41]
	s_cbranch_execz .LBB0_319
	v_lshrrev_b32_e32 v39, 6, v47
	v_and_b32_e32 v41, 63, v62
	v_cndmask_b32_e64 v39, v41, v39, s[36:37]
	v_lshl_or_b32 v52, v39, 6, v122
	v_mov_b32_e32 v53, v117
	v_lshl_add_u64 v[54:55], s[10:11], 0, v[52:53]
	v_add_co_u32_e32 v54, vcc, 0x1000, v54
	s_nop 1
	v_addc_co_u32_e32 v55, vcc, 0, v55, vcc
	global_load_dwordx2 v[54:55], v[54:55], off sc1
	s_nop 0
	global_load_dwordx2 v[52:53], v52, s[10:11] sc1
	s_waitcnt vmcnt(1)
	v_cndmask_b32_e64 v54, v54, -v54, s[38:39]
	v_cndmask_b32_e64 v55, v55, -v55, s[38:39]
.LBB0_319:
	s_or_b64 exec, exec, s[0:1]
	global_load_dwordx2 v[64:65], v[8:9], off sc1
	global_load_dwordx2 v[60:61], v[10:11], off sc1
	global_load_dwordx2 v[58:59], v[12:13], off sc1
	global_load_dwordx2 v[70:71], v[6:7], off sc1
	v_and_b32_e32 v39, 64, v213
	v_add_u32_e32 v45, 64, v39
	s_waitcnt vmcnt(13)
	v_lshlrev_b32_e32 v66, 16, v37
	v_and_b32_e32 v67, 0xffff0000, v37
	v_xor_b32_e32 v37, 16, v213
	v_cmp_lt_i32_e32 vcc, v37, v45
	v_xor_b32_e32 v41, 4, v213
	v_xor_b32_e32 v43, 2, v213
	v_cndmask_b32_e32 v37, v213, v37, vcc
	v_lshlrev_b32_e32 v39, 2, v37
	v_xor_b32_e32 v37, 8, v213
	v_cmp_lt_i32_e32 vcc, v37, v45
	v_xor_b32_e32 v68, 1, v213
	s_mov_b32 s0, 0x800000
	v_cndmask_b32_e32 v37, v213, v37, vcc
	v_cmp_lt_i32_e32 vcc, v41, v45
	v_lshlrev_b32_e32 v37, 2, v37
	s_nop 0
	v_cndmask_b32_e32 v41, v213, v41, vcc
	v_cmp_lt_i32_e32 vcc, v43, v45
	v_lshlrev_b32_e32 v41, 2, v41
	s_nop 0
	v_cndmask_b32_e32 v43, v213, v43, vcc
	v_cmp_lt_i32_e32 vcc, v68, v45
	v_lshlrev_b32_e32 v43, 2, v43
	s_nop 0
	v_cndmask_b32_e32 v45, v213, v68, vcc
	v_pk_mul_f32 v[68:69], v[66:67], v[66:67]
	v_lshlrev_b32_e32 v45, 2, v45
	v_add_f32_e32 v68, v68, v69
	s_waitcnt lgkmcnt(0)
	s_nop 1
	v_add_f32_dpp v68, v68, v68 quad_perm:[1,0,3,2] row_mask:0xf bank_mask:0xf
	s_nop 1
	v_add_f32_dpp v68, v68, v68 quad_perm:[2,3,0,1] row_mask:0xf bank_mask:0xf
	s_nop 1
	v_add_f32_dpp v68, v68, v68 row_half_mirror row_mask:0xf bank_mask:0xf
	s_nop 1
	v_add_f32_dpp v68, v68, v68 row_mirror row_mask:0xf bank_mask:0xf
	v_mov_b32_e32 v69, v68
	s_nop 1
	v_permlane16_swap_b32_e32 v69, v68
	v_add_f32_e32 v68, v68, v69
	v_fmamk_f32 v68, v68, 0x3c800000, v212
	v_cmp_gt_f32_e32 vcc, s0, v68
	v_mul_f32_e32 v69, 0x4b800000, v68
	s_nop 0
	v_cndmask_b32_e32 v68, v68, v69, vcc
	v_rsq_f32_e32 v68, v68
	s_nop 0
	v_mul_f32_e32 v69, 0x45800000, v68
	v_cndmask_b32_e32 v68, v68, v69, vcc
	v_pk_mul_f32 v[66:67], v[68:69], v[66:67] op_sel_hi:[0,1]
	s_waitcnt vmcnt(0)
	v_pk_mul_f32 v[72:73], v[70:71], v[66:67]
	s_and_saveexec_b64 s[0:1], s[40:41]
	s_cbranch_execz .LBB0_321
	ds_bpermute_b32 v66, v37, v72
	ds_bpermute_b32 v67, v37, v73
	s_waitcnt lgkmcnt(0)
	v_pk_mul_f32 v[66:67], v[54:55], v[66:67]
	s_nop 0
	v_pk_fma_f32 v[72:73], v[52:53], v[72:73], v[66:67]

.LBB0_347:
	s_or_b64 exec, exec, s[0:1]
	v_mov_b32_e32 v35, 0x100
	v_mov_b32_e32 v37, 0x400
	v_cndmask_b32_e64 v49, v35, v37, s[40:41]
	v_add_u32_e32 v37, -1, v49
	v_cmp_lt_u32_e64 s[0:1], v47, v37
	v_subrev_co_u32_e32 v35, vcc, 1, v47
	s_nop 0
	v_cndmask_b32_e64 v60, 0, v222, s[0:1]
	v_mov_b32_e32 v61, v117
	v_cndmask_b32_e64 v54, 1.0, 0, vcc
	v_cndmask_b32_e64 v52, 0, 1.0, s[0:1]
	v_cndmask_b32_e64 v59, -1, 0, vcc
	v_cndmask_b32_e64 v58, v221, 0, vcc
	v_lshl_add_u64 v[60:61], v[50:51], 0, v[60:61]
	s_mov_b64 s[0:1], 0x1400
	v_cmp_lt_u32_e32 vcc, v35, v49
	v_lshl_add_u64 v[78:79], v[60:61], 0, s[0:1]
	v_lshl_add_u64 v[86:87], v[60:61], 0, v[116:117]
	v_cndmask_b32_e64 v61, 0, -1, vcc
	v_cndmask_b32_e32 v60, 0, v221, vcc
	v_ashrrev_i32_e32 v64, 7, v62
	v_lshl_add_u64 v[60:61], v[50:51], 0, v[60:61]
	s_mov_b64 s[18:19], 0x1800
	v_lshl_add_u64 v[58:59], v[50:51], 0, v[58:59]
	v_lshl_add_u64 v[82:83], v[50:51], 0, s[0:1]
	v_ashrrev_i32_e32 v65, 31, v64
	v_lshl_add_u64 v[72:73], v[60:61], 0, s[18:19]
	v_lshl_add_u64 v[80:81], v[58:59], 0, s[0:1]
	v_lshlrev_b64 v[68:69], 19, v[64:65]
	v_lshl_add_u64 v[64:65], v[82:83], 0, v[116:117]
	v_lshl_add_u64 v[84:85], v[58:59], 0, v[116:117]
	v_lshl_add_u64 v[58:59], v[78:79], 0, v[116:117]
	v_lshl_add_u64 v[60:61], v[72:73], 0, v[116:117]
	global_load_dword v39, v[64:65], off sc1
	global_load_dword v41, v[56:57], off offset:3072 sc1
	global_load_dword v45, v[84:85], off offset:3072 sc1
	global_load_dword v53, v[58:59], off sc1
	global_load_dword v35, v[60:61], off sc1
	v_lshl_add_u64 v[74:75], v[50:51], 0, s[18:19]
	v_lshl_add_u64 v[64:65], v[80:81], 0, v[116:117]
	v_lshl_add_u64 v[70:71], v[74:75], 0, v[116:117]
	global_load_dword v43, v[64:65], off sc1
	global_load_dword v55, v[86:87], off offset:3072 sc1
	global_load_dword v61, v[70:71], off sc1
	s_mov_b64 s[0:1], 0x1000
	v_lshl_add_u64 v[76:77], v[50:51], 0, s[0:1]
	v_lshl_add_u64 v[58:59], v[76:77], 0, v[116:117]
	global_load_dword v59, v[58:59], off sc1
	s_nop 0
	global_load_dwordx2 v[104:105], v[14:15], off sc1
	global_load_dwordx2 v[106:107], v[14:15], off offset:2048 sc1
	global_load_dwordx2 v[108:109], v[16:17], off sc1
	v_add_u32_e32 v37, 1, v47
	v_sub_u32_e64 v63, v47, 1 clamp
	v_min_u32_e32 v88, v37, v49
	v_cndmask_b32_e64 v58, 0, 1.0, vcc
	v_cmp_lt_u32_e32 vcc, v47, v49
	v_lshl_add_u64 v[68:69], s[2:3], 0, v[68:69]
	s_mov_b32 s16, 0x148ee000
	v_cndmask_b32_e64 v60, 0, 1.0, vcc
	s_movk_i32 s17, 0x1000
	v_mov_b32_e32 v141, v117
	s_waitcnt vmcnt(11)
	v_and_b32_e32 v91, 0xffff0000, v39
	s_waitcnt vmcnt(10)
	v_and_b32_e32 v93, 0xffff0000, v41
	v_lshlrev_b32_e32 v92, 16, v41
	s_waitcnt vmcnt(9)
	v_and_b32_e32 v97, 0xffff0000, v45
	s_waitcnt vmcnt(7)
	v_lshlrev_b32_e32 v64, 16, v35
	v_and_b32_e32 v65, 0xffff0000, v35
	v_sub_u32_e32 v35, v88, v63
	v_cvt_f32_i32_e32 v35, v35
	s_waitcnt vmcnt(6)
	v_and_b32_e32 v95, 0xffff0000, v43
	v_lshlrev_b32_e32 v94, 16, v43
	s_waitcnt vmcnt(4)
	v_lshlrev_b32_e32 v70, 16, v61
	v_and_b32_e32 v71, 0xffff0000, v61
	v_div_scale_f32 v61, s[0:1], v35, v35, 1.0
	v_rcp_f32_e32 v63, v61
	v_lshlrev_b32_e32 v96, 16, v45
	s_waitcnt vmcnt(3)
	v_pk_fma_f32 v[64:65], v[58:59], v[64:65], 0 op_sel_hi:[0,1,0]
	v_and_b32_e32 v99, 0xffff0000, v53
	v_fma_f32 v88, -v61, v63, 1.0
	v_fmac_f32_e32 v63, v88, v63
	v_div_scale_f32 v88, vcc, 1.0, v35, 1.0
	v_mul_f32_e32 v89, v88, v63
	v_fma_f32 v90, -v61, v89, v88
	v_fmac_f32_e32 v89, v90, v63
	v_fma_f32 v61, -v61, v89, v88
	v_lshlrev_b32_e32 v90, 16, v39
	v_div_fmas_f32 v61, v61, v63, v89
	v_pk_mul_f32 v[90:91], v[90:91], v[92:93]
	v_pk_mul_f32 v[92:93], v[94:95], v[96:97]
	v_div_fixup_f32 v88, v61, v35, 1.0
	v_pk_mul_f32 v[92:93], v[54:55], v[92:93] op_sel_hi:[0,1]
	s_waitcnt vmcnt(1)
	v_pk_mul_f32 v[90:91], v[90:91], v[106:107]
	v_pk_fma_f32 v[64:65], v[60:61], v[70:71], v[64:65] op_sel_hi:[0,1,1]
	v_mov_b32_e32 v35, v117
	v_lshlrev_b32_e32 v98, 16, v53
	v_and_b32_e32 v101, 0xffff0000, v55
	v_lshlrev_b32_e32 v100, 16, v55
	v_pk_fma_f32 v[90:91], v[104:105], v[92:93], v[90:91]
	v_pk_fma_f32 v[92:93], v[88:89], v[64:65], v[70:71] op_sel_hi:[0,1,1] neg_lo:[0,0,1] neg_hi:[0,0,1]
	v_lshl_add_u64 v[64:65], v[82:83], 0, v[34:35]
	v_pk_mul_f32 v[94:95], v[98:99], v[100:101]
	global_load_dword v39, v[64:65], off sc1
	global_load_dword v41, v[56:57], off offset:3328 sc1
	v_lshl_add_u64 v[64:65], v[80:81], 0, v[34:35]
	v_pk_mul_f32 v[94:95], v[52:53], v[94:95] op_sel_hi:[0,1]
	global_load_dword v43, v[64:65], off sc1
	global_load_dword v53, v[84:85], off offset:3328 sc1
	v_lshl_add_u64 v[64:65], v[78:79], 0, v[34:35]
	v_and_b32_e32 v103, 0xffff0000, v59
	v_lshlrev_b32_e32 v102, 16, v59
	global_load_dword v55, v[64:65], off sc1
	global_load_dword v59, v[86:87], off offset:3328 sc1
	v_lshl_add_u64 v[64:65], v[76:77], 0, v[34:35]
	global_load_dword v61, v[64:65], off sc1
	v_add_u32_e32 v64, -2, v47
	v_cmp_lt_u32_e32 vcc, v64, v49
	v_mov_b32_e32 v64, 0xffffc800
	s_waitcnt vmcnt(7)
	v_pk_fma_f32 v[90:91], v[94:95], v[108:109], v[90:91]
	v_cndmask_b32_e64 v65, 0, -1, vcc
	v_cndmask_b32_e32 v64, 0, v64, vcc
	v_cndmask_b32_e64 v70, 0, 1.0, vcc
	v_lshl_add_u64 v[64:65], v[50:51], 0, v[64:65]
	v_cmp_lt_u32_e32 vcc, v37, v49
	v_lshl_add_u64 v[88:89], v[64:65], 0, s[18:19]
	v_pk_mul_f32 v[94:95], v[90:91], v[102:103]
	v_cndmask_b32_e32 v116, 0, v222, vcc
	v_lshl_add_u64 v[64:65], v[88:89], 0, v[34:35]
	v_lshl_add_u64 v[90:91], v[50:51], 0, v[116:117]
	global_load_dword v97, v[64:65], off sc1
	v_lshl_add_u64 v[64:65], v[72:73], 0, v[34:35]
	v_lshl_add_u64 v[90:91], v[90:91], 0, s[18:19]
	global_load_dword v99, v[64:65], off sc1
	v_lshl_add_u64 v[64:65], v[74:75], 0, v[34:35]
	v_lshl_add_u64 v[102:103], v[90:91], 0, v[34:35]
	global_load_dword v65, v[64:65], off sc1
	v_add_u32_e32 v45, 2, v47
	global_load_dword v35, v[102:103], off sc1
	global_load_dwordx2 v[110:111], v[14:15], off offset:512 sc1
	global_load_dwordx2 v[134:135], v[14:15], off offset:2560 sc1
	global_load_dwordx2 v[136:137], v[18:19], off sc1
	v_sub_u32_e64 v63, v47, 2 clamp
	v_min_u32_e32 v71, v45, v49
	v_cndmask_b32_e64 v64, 0, 1.0, vcc
	s_waitcnt vmcnt(13)
	v_and_b32_e32 v129, 0xffff0000, v39
	v_lshlrev_b32_e32 v128, 16, v39
	v_mov_b32_e32 v39, v117
	s_waitcnt vmcnt(12)
	v_and_b32_e32 v133, 0xffff0000, v41
	v_lshlrev_b32_e32 v132, 16, v41
	s_waitcnt vmcnt(11)
	v_and_b32_e32 v115, 0xffff0000, v43
	v_lshlrev_b32_e32 v114, 16, v43
	s_waitcnt vmcnt(10)
	v_and_b32_e32 v131, 0xffff0000, v53
	v_lshlrev_b32_e32 v130, 16, v53
	s_waitcnt vmcnt(9)
	v_and_b32_e32 v109, 0xffff0000, v55
	v_lshlrev_b32_e32 v108, 16, v55
	s_waitcnt vmcnt(8)
	v_and_b32_e32 v113, 0xffff0000, v59
	v_lshlrev_b32_e32 v112, 16, v59
	v_pk_mul_f32 v[128:129], v[128:129], v[132:133]
	v_pk_mul_f32 v[114:115], v[114:115], v[130:131]
	v_mov_b32_e32 v41, v117
	v_pk_mul_f32 v[114:115], v[54:55], v[114:115] op_sel_hi:[0,1]
	v_pk_mul_f32 v[108:109], v[108:109], v[112:113]
	s_waitcnt vmcnt(7)
	v_and_b32_e32 v107, 0xffff0000, v61
	v_pk_mul_f32 v[108:109], v[52:53], v[108:109] op_sel_hi:[0,1]
	v_lshlrev_b32_e32 v106, 16, v61
	v_mov_b32_e32 v43, v117
	s_waitcnt vmcnt(6)
	v_lshlrev_b32_e32 v96, 16, v97
	v_and_b32_e32 v97, 0xffff0000, v97
	s_waitcnt vmcnt(5)
	v_lshlrev_b32_e32 v98, 16, v99
	v_and_b32_e32 v99, 0xffff0000, v99
	s_waitcnt vmcnt(4)
	v_lshlrev_b32_e32 v100, 16, v65
	v_and_b32_e32 v101, 0xffff0000, v65
	s_waitcnt vmcnt(3)
	v_lshlrev_b32_e32 v102, 16, v35
	v_and_b32_e32 v103, 0xffff0000, v35
	v_sub_u32_e32 v35, v71, v63
	v_cvt_f32_i32_e32 v35, v35
	s_waitcnt vmcnt(1)
	v_pk_mul_f32 v[112:113], v[128:129], v[134:135]
	v_div_scale_f32 v37, s[0:1], v35, v35, 1.0
	v_rcp_f32_e32 v63, v37
	v_pk_fma_f32 v[110:111], v[110:111], v[114:115], v[112:113]
	v_fma_f32 v65, -v37, v63, 1.0
	v_fmac_f32_e32 v63, v65, v63
	v_div_scale_f32 v65, vcc, 1.0, v35, 1.0
	v_mul_f32_e32 v71, v65, v63
	v_fma_f32 v104, -v37, v71, v65
	v_fmac_f32_e32 v71, v104, v63
	v_fma_f32 v37, -v37, v71, v65
	v_div_fmas_f32 v37, v37, v63, v71
	v_div_fixup_f32 v104, v37, v35, 1.0
	v_mov_b32_e32 v37, v117
	v_cvt_pk_bf16_f32 v35, v94, v95
	v_lshl_add_u64 v[94:95], v[68:69], 0, v[36:37]
	v_lshlrev_b32_e32 v37, 6, v62
	v_and_b32_e32 v116, 0x1fc0, v37
	v_lshl_add_u64 v[62:63], v[94:95], 0, v[116:117]
	v_lshl_add_u64 v[62:63], v[62:63], 0, v[38:39]
	v_add_co_u32_e32 v62, vcc, s16, v62
	v_pk_fma_f32 v[96:97], v[70:71], v[96:97], 0 op_sel_hi:[0,1,0]
	s_nop 0
	v_addc_co_u32_e32 v63, vcc, 0, v63, vcc
	global_store_dword v[62:63], v35, off
	v_lshl_add_u64 v[62:63], v[32:33], 0, v[66:67]
	v_lshl_add_u64 v[66:67], v[68:69], 0, v[40:41]
	v_pk_fma_f32 v[96:97], v[58:59], v[98:99], v[96:97] op_sel_hi:[0,1,1]
	v_lshl_add_u64 v[66:67], v[66:67], 0, v[116:117]
	s_waitcnt vmcnt(1)
	v_pk_fma_f32 v[108:109], v[108:109], v[136:137], v[110:111]
	v_pk_fma_f32 v[96:97], v[60:61], v[100:101], v[96:97] op_sel_hi:[0,1,1]
	v_lshl_add_u64 v[66:67], v[66:67], 0, v[38:39]
	v_pk_mul_f32 v[106:107], v[108:109], v[106:107]
	v_pk_fma_f32 v[96:97], v[64:65], v[102:103], v[96:97] op_sel_hi:[0,1,1]
	v_cvt_pk_bf16_f32 v35, v92, v93
	v_add_co_u32_e32 v66, vcc, s16, v66
	v_pk_fma_f32 v[96:97], v[104:105], v[96:97], v[100:101] op_sel_hi:[0,1,1] neg_lo:[0,0,1] neg_hi:[0,0,1]
	global_store_dword v[62:63], v35, off
	v_cvt_pk_bf16_f32 v35, v106, v107
	v_addc_co_u32_e32 v67, vcc, 0, v67, vcc
	global_store_dword v[66:67], v35, off
	v_cvt_pk_bf16_f32 v35, v96, v97
	global_store_dword v[62:63], v35, off offset:256
	v_lshl_add_u64 v[66:67], v[82:83], 0, v[42:43]
	global_load_dword v61, v[66:67], off sc1
	global_load_dword v65, v[56:57], off offset:3584 sc1
	v_lshl_add_u64 v[66:67], v[80:81], 0, v[42:43]
	global_load_dword v113, v[66:67], off sc1
	global_load_dword v125, v[84:85], off offset:3584 sc1
	v_lshl_add_u64 v[66:67], v[78:79], 0, v[42:43]
	v_add_u32_e32 v35, -4, v47
	global_load_dword v135, v[66:67], off sc1
	global_load_dword v136, v[86:87], off offset:3584 sc1
	v_lshl_add_u64 v[66:67], v[76:77], 0, v[42:43]
	v_cmp_lt_u32_e64 s[40:41], v35, v49
	v_mov_b32_e32 v35, 0xffff9000
	global_load_dword v134, v[66:67], off sc1
	v_cndmask_b32_e64 v67, 0, -1, s[40:41]
	v_cndmask_b32_e64 v66, 0, v35, s[40:41]
	v_lshl_add_u64 v[66:67], v[50:51], 0, v[66:67]
	v_lshl_add_u64 v[66:67], v[66:67], 0, s[18:19]
	v_add_u32_e32 v35, -3, v47
	v_lshl_add_u64 v[92:93], v[66:67], 0, v[42:43]
	v_cmp_lt_u32_e64 s[42:43], v35, v49
	v_mov_b32_e32 v35, 0xffffac00
	global_load_dword v71, v[92:93], off sc1
	v_cndmask_b32_e64 v93, 0, -1, s[42:43]
	v_cndmask_b32_e64 v92, 0, v35, s[42:43]
	v_lshl_add_u64 v[92:93], v[50:51], 0, v[92:93]
	v_lshl_add_u64 v[130:131], v[92:93], 0, s[18:19]
	v_lshl_add_u64 v[92:93], v[130:131], 0, v[42:43]
	global_load_dword v101, v[92:93], off sc1
	v_lshl_add_u64 v[92:93], v[88:89], 0, v[42:43]
	global_load_dword v103, v[92:93], off sc1
	v_lshl_add_u64 v[92:93], v[72:73], 0, v[42:43]
	global_load_dword v105, v[92:93], off sc1
	v_lshl_add_u64 v[92:93], v[74:75], 0, v[42:43]
	global_load_dword v109, v[92:93], off sc1
	v_lshl_add_u64 v[92:93], v[90:91], 0, v[42:43]
	v_cmp_lt_u32_e32 vcc, v45, v49
	v_mov_b32_e32 v35, 0x3800
	global_load_dword v137, v[92:93], off sc1
	v_cndmask_b32_e32 v92, 0, v35, vcc
	v_mov_b32_e32 v93, v117
	v_lshl_add_u64 v[92:93], v[50:51], 0, v[92:93]
	v_lshl_add_u64 v[92:93], v[92:93], 0, s[18:19]
	v_add_u32_e32 v35, 3, v47
	v_lshl_add_u64 v[94:95], v[92:93], 0, v[42:43]
	v_cmp_lt_u32_e64 s[0:1], v35, v49
	v_mov_b32_e32 v35, 0x5400
	global_load_dword v138, v[94:95], off sc1
	v_cndmask_b32_e64 v94, 0, v35, s[0:1]
	v_mov_b32_e32 v95, v117
	v_lshl_add_u64 v[94:95], v[50:51], 0, v[94:95]
	v_lshl_add_u64 v[94:95], v[94:95], 0, s[18:19]
	v_mov_b32_e32 v45, v117
	v_lshl_add_u64 v[96:97], v[94:95], 0, v[42:43]
	v_lshl_add_u64 v[82:83], v[82:83], 0, v[44:45]
	global_load_dword v139, v[96:97], off sc1
	global_load_dword v59, v[82:83], off sc1
	global_load_dword v53, v[56:57], off offset:3840 sc1
	v_lshl_add_u64 v[56:57], v[80:81], 0, v[44:45]
	global_load_dword v55, v[56:57], off sc1
	global_load_dword v41, v[84:85], off offset:3840 sc1
	v_lshl_add_u64 v[56:57], v[78:79], 0, v[44:45]
	global_load_dword v43, v[56:57], off sc1
	global_load_dword v35, v[86:87], off offset:3840 sc1
	v_lshl_add_u64 v[56:57], v[76:77], 0, v[44:45]
	v_lshl_add_u64 v[66:67], v[66:67], 0, v[44:45]
	v_lshl_add_u64 v[80:81], v[94:95], 0, v[44:45]
	global_load_dword v37, v[56:57], off sc1
	global_load_dword v97, v[66:67], off sc1
	v_mov_b32_e32 v84, 0x7000
	global_load_dword v81, v[80:81], off sc1
	v_add_u32_e32 v56, -8, v47
	v_cmp_lt_u32_e64 s[48:49], v56, v49
	v_mov_b32_e32 v56, 0xffff2000
	v_lshl_add_u64 v[66:67], v[130:131], 0, v[44:45]
	v_cndmask_b32_e64 v57, 0, -1, s[48:49]
	v_cndmask_b32_e64 v56, 0, v56, s[48:49]
	v_lshl_add_u64 v[56:57], v[50:51], 0, v[56:57]
	v_lshl_add_u64 v[56:57], v[56:57], 0, v[44:45]
	v_cndmask_b32_e64 v96, 0, 1.0, s[48:49]
	v_add_co_u32_e64 v56, s[48:49], s17, v56
	global_load_dword v131, v[66:67], off sc1
	s_nop 0
	v_addc_co_u32_e64 v57, s[48:49], 0, v57, s[48:49]
	global_load_dword v57, v[56:57], off offset:2048 sc1
	v_add_u32_e32 v56, -7, v47
	v_cmp_lt_u32_e64 s[48:49], v56, v49
	v_mov_b32_e32 v56, 0xffff3c00
	v_lshl_add_u64 v[66:67], v[88:89], 0, v[44:45]
	v_cndmask_b32_e64 v77, 0, -1, s[48:49]
	v_cndmask_b32_e64 v76, 0, v56, s[48:49]
	v_lshl_add_u64 v[76:77], v[50:51], 0, v[76:77]
	v_lshl_add_u64 v[76:77], v[76:77], 0, v[44:45]
	v_cndmask_b32_e64 v102, 0, 1.0, s[48:49]
	v_add_co_u32_e64 v76, s[48:49], s17, v76
	v_add_u32_e32 v56, -6, v47
	s_nop 0
	v_addc_co_u32_e64 v77, s[48:49], 0, v77, s[48:49]
	v_cmp_lt_u32_e64 s[48:49], v56, v49
	v_mov_b32_e32 v56, 0xffff5800
	global_load_dword v79, v[76:77], off offset:2048 sc1
	v_cndmask_b32_e64 v77, 0, -1, s[48:49]
	v_cndmask_b32_e64 v76, 0, v56, s[48:49]
	v_lshl_add_u64 v[76:77], v[50:51], 0, v[76:77]
	v_lshl_add_u64 v[76:77], v[76:77], 0, v[44:45]
	v_cndmask_b32_e64 v108, 0, 1.0, s[48:49]
	v_add_co_u32_e64 v76, s[48:49], s17, v76
	v_add_u32_e32 v56, -5, v47
	s_nop 0
	v_addc_co_u32_e64 v77, s[48:49], 0, v77, s[48:49]
	v_cmp_lt_u32_e64 s[48:49], v56, v49
	v_mov_b32_e32 v56, 0xffff7400
	global_load_dword v83, v[76:77], off offset:2048 sc1
	v_cndmask_b32_e64 v77, 0, -1, s[48:49]
	v_cndmask_b32_e64 v76, 0, v56, s[48:49]
	v_lshl_add_u64 v[76:77], v[50:51], 0, v[76:77]
	v_lshl_add_u64 v[76:77], v[76:77], 0, v[44:45]
	v_cndmask_b32_e64 v112, 0, 1.0, s[48:49]
	v_add_co_u32_e64 v76, s[48:49], s17, v76
	global_load_dword v133, v[66:67], off sc1
	s_nop 0
	v_addc_co_u32_e64 v77, s[48:49], 0, v77, s[48:49]
	global_load_dword v87, v[76:77], off offset:2048 sc1
	v_lshl_add_u64 v[76:77], v[92:93], 0, v[44:45]
	global_load_dword v77, v[76:77], off sc1
	v_lshl_add_u64 v[66:67], v[72:73], 0, v[44:45]
	v_lshl_add_u64 v[72:73], v[74:75], 0, v[44:45]
	global_load_dword v67, v[66:67], off sc1
	v_mov_b32_e32 v85, v117
	global_load_dword v75, v[72:73], off sc1
	v_lshl_add_u64 v[72:73], v[90:91], 0, v[44:45]
	v_add_u32_e32 v91, 4, v47
	global_load_dword v73, v[72:73], off sc1
	v_cndmask_b32_e64 v72, 0, 1.0, vcc
	v_cmp_lt_u32_e32 vcc, v91, v49
	v_add_u32_e32 v86, 5, v47
	v_mov_b32_e32 v88, 0x8c00
	v_cndmask_b32_e32 v84, 0, v84, vcc
	v_lshl_add_u64 v[84:85], v[50:51], 0, v[84:85]
	v_lshl_add_u64 v[84:85], v[84:85], 0, v[44:45]
	v_cndmask_b32_e64 v82, 0, 1.0, vcc
	v_add_co_u32_e32 v84, vcc, s17, v84
	v_mov_b32_e32 v89, v117
	s_nop 0
	v_addc_co_u32_e32 v85, vcc, 0, v85, vcc
	v_cmp_lt_u32_e32 vcc, v86, v49
	v_add_u32_e32 v90, 6, v47
	v_mov_b32_e32 v92, 0xa800
	v_cndmask_b32_e32 v88, 0, v88, vcc
	v_lshl_add_u64 v[88:89], v[50:51], 0, v[88:89]
	v_lshl_add_u64 v[88:89], v[88:89], 0, v[44:45]
	v_cndmask_b32_e64 v86, 0, 1.0, vcc
	v_add_co_u32_e32 v88, vcc, s17, v88
	v_mov_b32_e32 v93, v117
	s_nop 0
	v_addc_co_u32_e32 v89, vcc, 0, v89, vcc
	v_cmp_lt_u32_e32 vcc, v90, v49
	v_add_u32_e32 v94, 7, v47
	v_mov_b32_e32 v95, 0xc400
	v_cndmask_b32_e32 v92, 0, v92, vcc
	v_lshl_add_u64 v[92:93], v[50:51], 0, v[92:93]
	v_lshl_add_u64 v[92:93], v[92:93], 0, v[44:45]
	v_cndmask_b32_e64 v90, 0, 1.0, vcc
	v_add_co_u32_e32 v92, vcc, s17, v92
	s_waitcnt vmcnt(8)
	v_lshlrev_b32_e32 v98, 16, v57
	v_addc_co_u32_e32 v93, vcc, 0, v93, vcc
	v_cmp_lt_u32_e32 vcc, v94, v49
	v_and_b32_e32 v99, 0xffff0000, v57
	v_lshlrev_b32_e32 v128, 16, v97
	v_cndmask_b32_e32 v140, 0, v95, vcc
	v_lshl_add_u64 v[50:51], v[50:51], 0, v[140:141]
	v_lshl_add_u64 v[50:51], v[50:51], 0, v[44:45]
	v_cndmask_b32_e64 v94, 0, 1.0, vcc
	v_add_co_u32_e32 v50, vcc, s17, v50
	s_waitcnt vmcnt(7)
	v_lshlrev_b32_e32 v106, 16, v79
	v_addc_co_u32_e32 v51, vcc, 0, v51, vcc
	global_load_dword v45, v[50:51], off offset:2048 sc1
	v_and_b32_e32 v107, 0xffff0000, v79
	v_and_b32_e32 v129, 0xffff0000, v97
	v_pk_fma_f32 v[96:97], v[96:97], v[98:99], 0 op_sel_hi:[0,1,0]
	v_pk_fma_f32 v[96:97], v[102:103], v[106:107], v[96:97] op_sel_hi:[0,1,1]
	v_cndmask_b32_e64 v100, 0, 1.0, s[40:41]
	v_cndmask_b32_e64 v104, 0, 1.0, s[42:43]
	v_lshlrev_b32_e32 v130, 16, v131
	v_and_b32_e32 v131, 0xffff0000, v131
	s_waitcnt vmcnt(7)
	v_lshlrev_b32_e32 v110, 16, v83
	v_and_b32_e32 v111, 0xffff0000, v83
	v_pk_fma_f32 v[96:97], v[108:109], v[110:111], v[96:97] op_sel_hi:[0,1,1]
	global_load_dword v85, v[84:85], off offset:2048 sc1
	v_and_b32_e32 v107, 0xffff0000, v125
	global_load_dword v89, v[88:89], off offset:2048 sc1
	v_lshlrev_b32_e32 v106, 16, v125
	global_load_dword v93, v[92:93], off offset:2048 sc1
	s_waitcnt vmcnt(9)
	v_lshlrev_b32_e32 v132, 16, v133
	v_and_b32_e32 v133, 0xffff0000, v133
	v_cndmask_b32_e64 v76, 0, 1.0, s[0:1]
	s_waitcnt vmcnt(8)
	v_lshlrev_b32_e32 v114, 16, v87
	v_and_b32_e32 v115, 0xffff0000, v87
	v_pk_fma_f32 v[96:97], v[112:113], v[114:115], v[96:97] op_sel_hi:[0,1,1]
	v_pk_fma_f32 v[96:97], v[100:101], v[128:129], v[96:97] op_sel_hi:[0,1,1]
	v_pk_fma_f32 v[96:97], v[104:105], v[130:131], v[96:97] op_sel_hi:[0,1,1]
	v_and_b32_e32 v115, 0xffff0000, v71
	v_and_b32_e32 v129, 0xffff0000, v101
	v_lshlrev_b32_e32 v114, 16, v71
	v_lshlrev_b32_e32 v128, 16, v101
	v_and_b32_e32 v101, 0xffff0000, v113
	v_pk_fma_f32 v[96:97], v[70:71], v[132:133], v[96:97] op_sel_hi:[0,1,1]
	v_and_b32_e32 v133, 0xffff0000, v105
	v_lshlrev_b32_e32 v132, 16, v105
	v_and_b32_e32 v105, 0xffff0000, v135
	v_pk_fma_f32 v[114:115], v[100:101], v[114:115], 0 op_sel_hi:[0,1,0]
	v_and_b32_e32 v131, 0xffff0000, v103
	v_lshlrev_b32_e32 v130, 16, v103
	v_pk_fma_f32 v[114:115], v[104:105], v[128:129], v[114:115] op_sel_hi:[0,1,1]
	v_pk_fma_f32 v[70:71], v[70:71], v[130:131], v[114:115] op_sel_hi:[0,1,1]
	v_lshlrev_b32_e32 v100, 16, v113
	global_load_dwordx2 v[112:113], v[14:15], off offset:1024 sc1
	global_load_dwordx2 v[114:115], v[14:15], off offset:3072 sc1
	global_load_dwordx2 v[128:129], v[20:21], off sc1
	v_pk_fma_f32 v[70:71], v[58:59], v[132:133], v[70:71] op_sel_hi:[0,1,1]
	v_pk_mul_f32 v[100:101], v[100:101], v[106:107]
	global_load_dwordx2 v[106:107], v[14:15], off offset:1536 sc1
	global_load_dwordx2 v[130:131], v[14:15], off offset:3584 sc1
	global_load_dwordx2 v[132:133], v[22:23], off sc1
	s_waitcnt vmcnt(11)
	v_lshlrev_b32_e32 v56, 16, v75
	s_waitcnt vmcnt(10)
	v_lshlrev_b32_e32 v74, 16, v73
	v_and_b32_e32 v57, 0xffff0000, v75
	v_and_b32_e32 v75, 0xffff0000, v73
	v_sub_u32_e64 v73, v47, 8 clamp
	v_lshlrev_b32_e32 v78, 16, v77
	v_and_b32_e32 v79, 0xffff0000, v77
	v_and_b32_e32 v141, 0xffff0000, v109
	v_lshlrev_b32_e32 v140, 16, v109
	v_and_b32_e32 v103, 0xffff0000, v61
	v_and_b32_e32 v109, 0xffff0000, v65
	v_lshlrev_b32_e32 v102, 16, v61
	v_lshlrev_b32_e32 v108, 16, v65
	v_and_b32_e32 v111, 0xffff0000, v136
	v_lshlrev_b32_e32 v104, 16, v135
	v_lshlrev_b32_e32 v110, 16, v136
	v_pk_mul_f32 v[102:103], v[102:103], v[108:109]
	v_pk_mul_f32 v[104:105], v[104:105], v[110:111]
	v_pk_mul_f32 v[100:101], v[54:55], v[100:101] op_sel_hi:[0,1]
	v_pk_mul_f32 v[104:105], v[52:53], v[104:105] op_sel_hi:[0,1]
	v_and_b32_e32 v111, 0xffff0000, v55
	v_lshlrev_b32_e32 v110, 16, v55
	v_and_b32_e32 v109, 0xffff0000, v35
	v_lshlrev_b32_e32 v108, 16, v35
	v_pk_fma_f32 v[70:71], v[60:61], v[140:141], v[70:71] op_sel_hi:[0,1,1]
	v_and_b32_e32 v143, 0xffff0000, v137
	v_lshlrev_b32_e32 v142, 16, v137
	v_lshlrev_b32_e32 v66, 16, v67
	v_and_b32_e32 v67, 0xffff0000, v67
	v_and_b32_e32 v145, 0xffff0000, v138
	v_lshlrev_b32_e32 v144, 16, v138
	v_pk_fma_f32 v[70:71], v[64:65], v[142:143], v[70:71] op_sel_hi:[0,1,1]
	v_pk_fma_f32 v[70:71], v[72:73], v[144:145], v[70:71] op_sel_hi:[0,1,1]
	v_lshlrev_b32_e32 v80, 16, v81
	v_and_b32_e32 v81, 0xffff0000, v81
	v_and_b32_e32 v147, 0xffff0000, v139
	s_waitcnt vmcnt(9)
	v_lshlrev_b32_e32 v50, 16, v45
	v_and_b32_e32 v51, 0xffff0000, v45
	v_add_u32_e32 v45, 8, v47
	v_min_u32_e32 v45, v45, v49
	v_min_u32_e32 v49, v91, v49
	v_sub_u32_e64 v47, v47, 4 clamp
	v_sub_u32_e32 v47, v49, v47
	v_cvt_f32_i32_e32 v47, v47
	v_sub_u32_e32 v45, v45, v73
	v_cvt_f32_i32_e32 v45, v45
	v_lshlrev_b32_e32 v146, 16, v139
	v_div_scale_f32 v49, s[0:1], v47, v47, 1.0
	v_rcp_f32_e32 v77, v49
	s_waitcnt vmcnt(8)
	v_lshlrev_b32_e32 v84, 16, v85
	v_and_b32_e32 v85, 0xffff0000, v85
	s_waitcnt vmcnt(7)
	v_lshlrev_b32_e32 v88, 16, v89
	v_fma_f32 v83, -v49, v77, 1.0
	v_fmac_f32_e32 v77, v83, v77
	v_div_scale_f32 v83, vcc, 1.0, v47, 1.0
	v_mul_f32_e32 v87, v83, v77
	v_fma_f32 v91, -v49, v87, v83
	v_fmac_f32_e32 v87, v91, v77
	v_fma_f32 v49, -v49, v87, v83
	v_div_fmas_f32 v49, v49, v77, v87
	v_div_fixup_f32 v98, v49, v47, 1.0
	v_div_scale_f32 v47, s[0:1], v45, v45, 1.0
	v_rcp_f32_e32 v49, v47
	v_and_b32_e32 v89, 0xffff0000, v89
	v_and_b32_e32 v99, 0xffff0000, v134
	v_pk_fma_f32 v[70:71], v[76:77], v[146:147], v[70:71] op_sel_hi:[0,1,1]
	v_fma_f32 v61, -v47, v49, 1.0
	v_fmac_f32_e32 v49, v61, v49
	v_div_scale_f32 v61, vcc, 1.0, v45, 1.0
	v_mul_f32_e32 v65, v61, v49
	v_fma_f32 v73, -v47, v65, v61
	s_waitcnt vmcnt(4)
	v_pk_mul_f32 v[102:103], v[102:103], v[114:115]
	v_and_b32_e32 v115, 0xffff0000, v41
	v_pk_fma_f32 v[100:101], v[112:113], v[100:101], v[102:103]
	v_and_b32_e32 v113, 0xffff0000, v59
	s_waitcnt vmcnt(3)
	v_pk_fma_f32 v[100:101], v[104:105], v[128:129], v[100:101]
	v_lshlrev_b32_e32 v112, 16, v59
	v_and_b32_e32 v129, 0xffff0000, v53
	v_lshlrev_b32_e32 v128, 16, v53
	v_lshlrev_b32_e32 v114, 16, v41
	v_and_b32_e32 v105, 0xffff0000, v43
	v_lshlrev_b32_e32 v104, 16, v43
	v_pk_mul_f32 v[112:113], v[112:113], v[128:129]
	v_pk_mul_f32 v[110:111], v[110:111], v[114:115]
	v_pk_mul_f32 v[104:105], v[104:105], v[108:109]
	v_pk_mul_f32 v[54:55], v[54:55], v[110:111] op_sel_hi:[0,1]
	v_pk_mul_f32 v[52:53], v[52:53], v[104:105] op_sel_hi:[0,1]
	s_waitcnt vmcnt(1)
	v_pk_mul_f32 v[104:105], v[112:113], v[130:131]
	v_fmac_f32_e32 v65, v73, v49
	v_pk_fma_f32 v[54:55], v[106:107], v[54:55], v[104:105]
	v_fma_f32 v47, -v47, v65, v61
	s_waitcnt vmcnt(0)
	v_pk_fma_f32 v[52:53], v[52:53], v[132:133], v[54:55]
	v_pk_fma_f32 v[54:55], v[58:59], v[66:67], v[96:97] op_sel_hi:[0,1,1]
	v_pk_fma_f32 v[54:55], v[60:61], v[56:57], v[54:55] op_sel_hi:[0,1,1]
	v_pk_fma_f32 v[54:55], v[64:65], v[74:75], v[54:55] op_sel_hi:[0,1,1]
	v_pk_fma_f32 v[54:55], v[72:73], v[78:79], v[54:55] op_sel_hi:[0,1,1]
	v_pk_fma_f32 v[54:55], v[76:77], v[80:81], v[54:55] op_sel_hi:[0,1,1]
	v_pk_fma_f32 v[54:55], v[82:83], v[84:85], v[54:55] op_sel_hi:[0,1,1]
	v_lshlrev_b32_e32 v92, 16, v93
	v_and_b32_e32 v93, 0xffff0000, v93
	v_pk_fma_f32 v[70:71], v[98:99], v[70:71], v[140:141] op_sel_hi:[0,1,1] neg_lo:[0,0,1] neg_hi:[0,0,1]
	v_lshlrev_b32_e32 v98, 16, v134
	v_div_fmas_f32 v47, v47, v49, v65
	v_pk_fma_f32 v[54:55], v[86:87], v[88:89], v[54:55] op_sel_hi:[0,1,1]
	v_pk_mul_f32 v[98:99], v[100:101], v[98:99]
	v_div_fixup_f32 v100, v47, v45, 1.0
	v_pk_fma_f32 v[54:55], v[90:91], v[92:93], v[54:55] op_sel_hi:[0,1,1]
	v_mov_b32_e32 v47, v117
	v_pk_fma_f32 v[50:51], v[94:95], v[50:51], v[54:55] op_sel_hi:[0,1,1]
	v_lshl_add_u64 v[54:55], v[68:69], 0, v[46:47]
	v_lshl_add_u64 v[54:55], v[54:55], 0, v[116:117]
	v_lshl_add_u64 v[54:55], v[54:55], 0, v[38:39]
	v_add_co_u32_e32 v54, vcc, s16, v54
	v_and_b32_e32 v103, 0xffff0000, v37
	v_lshlrev_b32_e32 v102, 16, v37
	v_cvt_pk_bf16_f32 v35, v98, v99
	v_addc_co_u32_e32 v55, vcc, 0, v55, vcc
	v_pk_mul_f32 v[52:53], v[52:53], v[102:103]
	global_store_dword v[54:55], v35, off
	v_cvt_pk_bf16_f32 v35, v70, v71
	v_mov_b32_e32 v49, v117
	global_store_dword v[62:63], v35, off offset:512
	v_cvt_pk_bf16_f32 v35, v52, v53
	v_lshl_add_u64 v[52:53], v[68:69], 0, v[48:49]
	v_lshl_add_u64 v[52:53], v[52:53], 0, v[116:117]
	v_lshl_add_u64 v[52:53], v[52:53], 0, v[38:39]
	v_add_co_u32_e32 v52, vcc, 0x148ee000, v52
	v_pk_fma_f32 v[50:51], v[100:101], v[50:51], v[56:57] op_sel_hi:[0,1,1] neg_lo:[0,0,1] neg_hi:[0,0,1]
	s_nop 0
	v_addc_co_u32_e32 v53, vcc, 0, v53, vcc
	global_store_dword v[52:53], v35, off
	v_cvt_pk_bf16_f32 v35, v50, v51
	global_store_dword v[62:63], v35, off offset:768
	s_branch .LBB0_314

.LBB0_352:
	s_or_b64 exec, exec, s[0:1]
	s_movk_i32 s0, 0x1c00
	v_mad_i64_i32 v[56:57], s[0:1], v35, s0, v[24:25]
	v_add_co_u32_e32 v58, vcc, 0x1000, v56
	s_mov_b32 s0, 0x8000
	s_nop 0
	v_addc_co_u32_e32 v59, vcc, 0, v57, vcc
	global_load_dword v95, v[58:59], off offset:3072 sc1 nt
	v_add_co_u32_e32 v58, vcc, 0x3000, v56
	global_load_dword v35, v[56:57], off sc1 nt
	s_nop 0
	v_addc_co_u32_e32 v59, vcc, 0, v57, vcc
	global_load_dword v37, v[58:59], off offset:2048 sc1 nt
	v_add_co_u32_e32 v58, vcc, s76, v56
	s_nop 1
	v_addc_co_u32_e32 v59, vcc, 0, v57, vcc
	global_load_dword v96, v[58:59], off offset:1024 sc1 nt
	v_add_co_u32_e32 v58, vcc, 0x7000, v56
	s_nop 1
	v_addc_co_u32_e32 v59, vcc, 0, v57, vcc
	global_load_dword v39, v[58:59], off sc1 nt
	v_add_co_u32_e32 v58, vcc, s0, v56
	s_mov_b32 s0, 0xa000
	s_nop 0
	v_addc_co_u32_e32 v59, vcc, 0, v57, vcc
	global_load_dword v97, v[58:59], off offset:3072 sc1 nt
	v_add_co_u32_e32 v58, vcc, s0, v56
	s_mov_b32 s0, 0xc000
	s_nop 0
	v_addc_co_u32_e32 v59, vcc, 0, v57, vcc
	global_load_dword v41, v[58:59], off offset:2048 sc1 nt
	v_add_co_u32_e32 v58, vcc, s0, v56
	s_mov_b32 s0, 0xe000
	s_nop 0
	v_addc_co_u32_e32 v59, vcc, 0, v57, vcc
	global_load_dword v99, v[58:59], off offset:1024 sc1 nt
	v_add_co_u32_e32 v58, vcc, s0, v56
	s_mov_b32 s0, 0xf000
	s_nop 0
	v_addc_co_u32_e32 v59, vcc, 0, v57, vcc
	global_load_dword v43, v[58:59], off sc1 nt
	v_add_co_u32_e32 v58, vcc, s0, v56
	s_mov_b32 s0, 0x11000
	s_nop 0
	v_addc_co_u32_e32 v59, vcc, 0, v57, vcc
	global_load_dword v98, v[58:59], off offset:3072 sc1 nt
	v_add_co_u32_e32 v58, vcc, s0, v56
	s_mov_b32 s0, 0x13000
	s_nop 0
	v_addc_co_u32_e32 v59, vcc, 0, v57, vcc
	global_load_dword v45, v[58:59], off offset:2048 sc1 nt
	v_add_co_u32_e32 v58, vcc, s0, v56
	s_mov_b32 s0, 0x15000
	s_nop 0
	v_addc_co_u32_e32 v59, vcc, 0, v57, vcc
	global_load_dword v100, v[58:59], off offset:1024 sc1 nt
	v_add_co_u32_e32 v58, vcc, s0, v56
	s_mov_b32 s0, 0x16000
	s_nop 0
	v_addc_co_u32_e32 v59, vcc, 0, v57, vcc
	global_load_dword v47, v[58:59], off sc1 nt
	v_add_co_u32_e32 v58, vcc, s0, v56
	s_mov_b32 s0, 0x18000
	s_nop 0
	v_addc_co_u32_e32 v59, vcc, 0, v57, vcc
	global_load_dword v101, v[58:59], off offset:3072 sc1 nt
	v_add_co_u32_e32 v58, vcc, s0, v56
	s_mov_b32 s0, 0x1a000
	s_nop 0
	v_addc_co_u32_e32 v59, vcc, 0, v57, vcc
	global_load_dword v49, v[58:59], off offset:2048 sc1 nt
	v_add_co_u32_e32 v58, vcc, s0, v56
	s_mov_b32 s0, 0x1c000
	s_nop 0
	v_addc_co_u32_e32 v59, vcc, 0, v57, vcc
	global_load_dword v102, v[58:59], off offset:1024 sc1 nt
	v_add_co_u32_e32 v58, vcc, s0, v56
	s_mov_b32 s0, 0x1d000
	s_nop 0
	v_addc_co_u32_e32 v59, vcc, 0, v57, vcc
	global_load_dword v53, v[58:59], off sc1 nt
	v_add_co_u32_e32 v58, vcc, s0, v56
	s_mov_b32 s0, 0x1f000
	s_nop 0
	v_addc_co_u32_e32 v59, vcc, 0, v57, vcc
	global_load_dword v103, v[58:59], off offset:3072 sc1 nt
	v_add_co_u32_e32 v58, vcc, s0, v56
	s_mov_b32 s0, 0x21000
	s_nop 0
	v_addc_co_u32_e32 v59, vcc, 0, v57, vcc
	global_load_dword v88, v[58:59], off offset:2048 sc1 nt
	v_add_co_u32_e32 v58, vcc, s0, v56
	s_mov_b32 s0, 0x23000
	s_nop 0
	v_addc_co_u32_e32 v59, vcc, 0, v57, vcc
	global_load_dword v104, v[58:59], off offset:1024 sc1 nt
	v_add_co_u32_e32 v58, vcc, s0, v56
	s_mov_b32 s0, 0x24000
	s_nop 0
	v_addc_co_u32_e32 v59, vcc, 0, v57, vcc
	global_load_dword v89, v[58:59], off sc1 nt
	v_add_co_u32_e32 v58, vcc, s0, v56
	s_mov_b32 s0, 0x26000
	s_nop 0
	v_addc_co_u32_e32 v59, vcc, 0, v57, vcc
	global_load_dword v105, v[58:59], off offset:3072 sc1 nt
	v_add_co_u32_e32 v58, vcc, s0, v56
	s_mov_b32 s0, 0x28000
	s_nop 0
	v_addc_co_u32_e32 v59, vcc, 0, v57, vcc
	global_load_dword v90, v[58:59], off offset:2048 sc1 nt
	v_add_co_u32_e32 v58, vcc, s0, v56
	s_mov_b32 s0, 0x2a000
	s_nop 0
	v_addc_co_u32_e32 v59, vcc, 0, v57, vcc
	global_load_dword v106, v[58:59], off offset:1024 sc1 nt
	v_add_co_u32_e32 v58, vcc, s0, v56
	s_mov_b32 s0, 0x2b000
	s_nop 0
	v_addc_co_u32_e32 v59, vcc, 0, v57, vcc
	global_load_dword v91, v[58:59], off sc1 nt
	v_add_co_u32_e32 v58, vcc, s0, v56
	s_mov_b32 s0, 0x2d000
	s_nop 0
	v_addc_co_u32_e32 v59, vcc, 0, v57, vcc
	global_load_dword v107, v[58:59], off offset:3072 sc1 nt
	v_add_co_u32_e32 v58, vcc, s0, v56
	s_mov_b32 s0, 0x2f000
	s_nop 0
	v_addc_co_u32_e32 v59, vcc, 0, v57, vcc
	global_load_dword v92, v[58:59], off offset:2048 sc1 nt
	v_add_co_u32_e32 v58, vcc, s0, v56
	s_mov_b32 s0, 0x31000
	s_nop 0
	v_addc_co_u32_e32 v59, vcc, 0, v57, vcc
	global_load_dword v108, v[58:59], off offset:1024 sc1 nt
	v_add_co_u32_e32 v58, vcc, s0, v56
	s_nop 1
	v_addc_co_u32_e32 v59, vcc, 0, v57, vcc
	global_load_dword v93, v[58:59], off sc1 nt
	v_add_co_u32_e32 v58, vcc, 0x32000, v56
	s_nop 1
	v_addc_co_u32_e32 v59, vcc, 0, v57, vcc
	global_load_dword v109, v[58:59], off offset:3072 sc1 nt
	v_add_co_u32_e32 v58, vcc, 0x34000, v56
	s_nop 1
	v_addc_co_u32_e32 v59, vcc, 0, v57, vcc
	v_add_co_u32_e32 v56, vcc, 0x36000, v56
	global_load_dword v94, v[58:59], off offset:2048 sc1 nt
	s_nop 0
	v_addc_co_u32_e32 v57, vcc, 0, v57, vcc
	global_load_dword v110, v[56:57], off offset:1024 sc1 nt
	v_cmp_ne_u64_e32 vcc, 0, v[54:55]
	s_waitcnt vmcnt(31)
	v_lshlrev_b32_e32 v56, 16, v95
	v_and_b32_e32 v57, 0xffff0000, v95
	s_waitcnt vmcnt(28)
	v_lshlrev_b32_e32 v58, 16, v96
	v_and_b32_e32 v59, 0xffff0000, v96
	s_waitcnt vmcnt(26)
	v_lshlrev_b32_e32 v60, 16, v97
	v_and_b32_e32 v61, 0xffff0000, v97
	s_waitcnt vmcnt(24)
	v_lshlrev_b32_e32 v62, 16, v99
	v_and_b32_e32 v63, 0xffff0000, v99
	s_waitcnt vmcnt(22)
	v_lshlrev_b32_e32 v64, 16, v98
	v_and_b32_e32 v65, 0xffff0000, v98
	s_waitcnt vmcnt(20)
	v_lshlrev_b32_e32 v66, 16, v100
	v_and_b32_e32 v67, 0xffff0000, v100
	s_waitcnt vmcnt(18)
	v_lshlrev_b32_e32 v68, 16, v101
	v_and_b32_e32 v69, 0xffff0000, v101
	s_waitcnt vmcnt(16)
	v_lshlrev_b32_e32 v70, 16, v102
	v_and_b32_e32 v71, 0xffff0000, v102
	s_waitcnt vmcnt(14)
	v_lshlrev_b32_e32 v72, 16, v103
	v_and_b32_e32 v73, 0xffff0000, v103
	s_waitcnt vmcnt(12)
	v_lshlrev_b32_e32 v74, 16, v104
	v_and_b32_e32 v75, 0xffff0000, v104
	s_waitcnt vmcnt(10)
	v_lshlrev_b32_e32 v76, 16, v105
	v_and_b32_e32 v77, 0xffff0000, v105
	s_waitcnt vmcnt(8)
	v_lshlrev_b32_e32 v78, 16, v106
	v_and_b32_e32 v79, 0xffff0000, v106
	s_waitcnt vmcnt(6)
	v_lshlrev_b32_e32 v80, 16, v107
	v_and_b32_e32 v81, 0xffff0000, v107
	s_waitcnt vmcnt(4)
	v_lshlrev_b32_e32 v82, 16, v108
	v_and_b32_e32 v83, 0xffff0000, v108
	s_waitcnt vmcnt(2)
	v_lshlrev_b32_e32 v84, 16, v109
	v_and_b32_e32 v85, 0xffff0000, v109
	s_waitcnt vmcnt(0)
	v_lshlrev_b32_e32 v86, 16, v110
	v_and_b32_e32 v87, 0xffff0000, v110
	s_and_saveexec_b64 s[0:1], vcc
	s_xor_b64 s[0:1], exec, s[0:1]
	s_cbranch_execz .LBB0_313
	s_movk_i32 s16, 0x1000
	v_add_co_u32_e32 v72, vcc, s16, v54
	s_movk_i32 s16, 0x2000
	s_nop 0
	v_addc_co_u32_e32 v73, vcc, 0, v55, vcc
	v_add_co_u32_e32 v80, vcc, s16, v54
	v_lshlrev_b32_e32 v64, 16, v43
	v_and_b32_e32 v65, 0xffff0000, v43
	v_addc_co_u32_e32 v81, vcc, 0, v55, vcc
	v_lshlrev_b32_e32 v66, 16, v45
	v_and_b32_e32 v67, 0xffff0000, v45
	v_lshlrev_b32_e32 v68, 16, v47
	v_and_b32_e32 v69, 0xffff0000, v47
	v_lshlrev_b32_e32 v70, 16, v49
	v_and_b32_e32 v71, 0xffff0000, v49
	v_lshlrev_b32_e32 v56, 16, v35
	v_and_b32_e32 v57, 0xffff0000, v35
	v_lshlrev_b32_e32 v58, 16, v37
	v_and_b32_e32 v59, 0xffff0000, v37
	v_lshlrev_b32_e32 v60, 16, v39
	v_and_b32_e32 v61, 0xffff0000, v39
	v_lshlrev_b32_e32 v62, 16, v41
	v_and_b32_e32 v63, 0xffff0000, v41
	global_store_dwordx2 v[80:81], v[64:65], off offset:-4096 nt
	v_lshlrev_b32_e32 v64, 16, v98
	v_and_b32_e32 v65, 0xffff0000, v98
	global_store_dwordx2 v[72:73], v[66:67], off offset:1024 nt
	v_lshlrev_b32_e32 v66, 16, v100
	v_and_b32_e32 v67, 0xffff0000, v100
	global_store_dwordx2 v[72:73], v[68:69], off offset:2048 nt
	v_lshlrev_b32_e32 v68, 16, v101
	v_and_b32_e32 v69, 0xffff0000, v101
	global_store_dwordx2 v[72:73], v[70:71], off offset:3072 nt
	v_lshlrev_b32_e32 v70, 16, v102
	v_and_b32_e32 v71, 0xffff0000, v102
	global_store_dwordx2 v[54:55], v[56:57], off nt
	v_lshlrev_b32_e32 v56, 16, v95
	v_and_b32_e32 v57, 0xffff0000, v95
	global_store_dwordx2 v[54:55], v[58:59], off offset:1024 nt
	v_lshlrev_b32_e32 v58, 16, v96
	v_and_b32_e32 v59, 0xffff0000, v96
	global_store_dwordx2 v[54:55], v[60:61], off offset:2048 nt
	v_lshlrev_b32_e32 v60, 16, v97
	v_and_b32_e32 v61, 0xffff0000, v97
	global_store_dwordx2 v[54:55], v[62:63], off offset:3072 nt
	v_lshlrev_b32_e32 v62, 16, v99
	v_and_b32_e32 v63, 0xffff0000, v99
	global_store_dwordx2 v[72:73], v[64:65], off offset:512 nt
	global_store_dwordx2 v[72:73], v[66:67], off offset:1536 nt
	global_store_dwordx2 v[72:73], v[68:69], off offset:2560 nt
	global_store_dwordx2 v[72:73], v[70:71], off offset:3584 nt
	v_lshlrev_b32_e32 v72, 16, v53
	v_and_b32_e32 v73, 0xffff0000, v53
	v_lshlrev_b32_e32 v74, 16, v88
	v_and_b32_e32 v75, 0xffff0000, v88
	v_lshlrev_b32_e32 v76, 16, v89
	v_and_b32_e32 v77, 0xffff0000, v89
	v_lshlrev_b32_e32 v78, 16, v90
	v_and_b32_e32 v79, 0xffff0000, v90
	global_store_dwordx2 v[54:55], v[56:57], off offset:512 nt
	global_store_dwordx2 v[54:55], v[58:59], off offset:1536 nt
	global_store_dwordx2 v[54:55], v[60:61], off offset:2560 nt
	global_store_dwordx2 v[54:55], v[62:63], off offset:3584 nt
	global_store_dwordx2 v[80:81], v[72:73], off nt
	v_lshlrev_b32_e32 v72, 16, v103
	v_and_b32_e32 v73, 0xffff0000, v103
	global_store_dwordx2 v[80:81], v[74:75], off offset:1024 nt
	v_lshlrev_b32_e32 v74, 16, v104
	v_and_b32_e32 v75, 0xffff0000, v104
	global_store_dwordx2 v[80:81], v[76:77], off offset:2048 nt
	v_lshlrev_b32_e32 v76, 16, v105
	v_and_b32_e32 v77, 0xffff0000, v105
	global_store_dwordx2 v[80:81], v[78:79], off offset:3072 nt
	v_lshlrev_b32_e32 v78, 16, v106
	v_and_b32_e32 v79, 0xffff0000, v106
	v_add_co_u32_e32 v54, vcc, s79, v54
	global_store_dwordx2 v[80:81], v[72:73], off offset:512 nt
	global_store_dwordx2 v[80:81], v[74:75], off offset:1536 nt
	global_store_dwordx2 v[80:81], v[76:77], off offset:2560 nt
	global_store_dwordx2 v[80:81], v[78:79], off offset:3584 nt
	v_lshlrev_b32_e32 v80, 16, v91
	v_and_b32_e32 v81, 0xffff0000, v91
	v_addc_co_u32_e32 v55, vcc, 0, v55, vcc
	v_lshlrev_b32_e32 v82, 16, v92
	v_and_b32_e32 v83, 0xffff0000, v92
	v_lshlrev_b32_e32 v84, 16, v93
	v_and_b32_e32 v85, 0xffff0000, v93
	v_lshlrev_b32_e32 v86, 16, v94
	v_and_b32_e32 v87, 0xffff0000, v94
	global_store_dwordx2 v[54:55], v[80:81], off nt
	v_lshlrev_b32_e32 v80, 16, v107
	v_and_b32_e32 v81, 0xffff0000, v107
	global_store_dwordx2 v[54:55], v[82:83], off offset:1024 nt
	v_lshlrev_b32_e32 v82, 16, v108
	v_and_b32_e32 v83, 0xffff0000, v108
	global_store_dwordx2 v[54:55], v[84:85], off offset:2048 nt
	v_lshlrev_b32_e32 v84, 16, v109
	v_and_b32_e32 v85, 0xffff0000, v109
	global_store_dwordx2 v[54:55], v[86:87], off offset:3072 nt
	v_lshlrev_b32_e32 v86, 16, v110
	v_and_b32_e32 v87, 0xffff0000, v110
	global_store_dwordx2 v[54:55], v[80:81], off offset:512 nt
	global_store_dwordx2 v[54:55], v[82:83], off offset:1536 nt
	global_store_dwordx2 v[54:55], v[84:85], off offset:2560 nt
	global_store_dwordx2 v[54:55], v[86:87], off offset:3584 nt
	s_branch .LBB0_313

.LBB0_527:
	s_or_b64 exec, exec, s[2:3]
	v_cvt_f32_u32_e32 v4, v2
	s_waitcnt vmcnt(0)
	v_readfirstlane_b32 s2, v3
	v_sub_u32_e32 v3, 0, v2
	v_rcp_iflag_f32_e32 v4, v4
	v_add_u32_e32 v5, s2, v1
	v_mul_f32_e32 v4, 0x4f7ffffe, v4
	v_cvt_u32_f32_e32 v4, v4
	v_mul_lo_u32 v1, v3, v4
	v_mul_hi_u32 v1, v4, v1
	v_add_u32_e32 v1, v4, v1
	v_mul_hi_u32 v1, v5, v1
	v_mul_lo_u32 v3, v1, v2
	v_sub_u32_e32 v3, v5, v3
	v_add_u32_e32 v4, 1, v1
	v_cmp_ge_u32_e32 vcc, v3, v2
	s_nop 1
	v_cndmask_b32_e32 v1, v1, v4, vcc
	v_sub_u32_e32 v4, v3, v2
	v_cndmask_b32_e32 v3, v3, v4, vcc
	v_add_u32_e32 v4, 1, v1
	v_cmp_ge_u32_e32 vcc, v3, v2
	v_add_u32_e32 v3, 1, v5
	s_nop 0
	v_cndmask_b32_e32 v1, v1, v4, vcc
	v_mul_lo_u32 v4, v2, v1
	v_add_u32_e32 v2, v4, v2
	v_cmp_ne_u32_e32 vcc, v3, v2
	s_and_saveexec_b64 s[2:3], vcc
	s_xor_b64 s[2:3], exec, s[2:3]
	s_cbranch_execz .LBB0_541
	v_readlane_b32 s8, v254, 40
	v_readlane_b32 s9, v254, 41
	s_waitcnt lgkmcnt(0)
	s_nop 3
	s_cmp_gt_u32 s6, 2
	s_cbranch_scc1 .Lgbf_1
	buffer_inv sc1
